# v37 plus: the 320 weight-conversion stores carry the nt (streaming) hint
# speedup vs baseline: 1.0021x; 1.0021x over previous
; __device__ __forceinline__ void tr_item(const float* W, int ldw, int k0, int n0, bf16* WT, int ldk, int drow0, int lane) {
;     const int n4 = (lane & 15) * 4, kg = lane >> 4; f32x4 v[2][8];
; #pragma unroll
;     for (int kh = 0; kh < 2; ++kh) { const float* src = W + (size_t)(k0 + kh * 32 + kg * 8) * ldw + n0 + n4;
; #pragma unroll
;         for (int i = 0; i < 8; ++i) v[kh][i] = __builtin_nontemporal_load((const f32x4*)(src + (size_t)i * ldw)); }
; #pragma unroll
;     for (int kh = 0; kh < 2; ++kh)
; #pragma unroll
;         for (int e = 0; e < 4; ++e) { u32x4 o; o.x = cvt_pk_bf16(v[kh][0][e], v[kh][1][e]); o.y = cvt_pk_bf16(v[kh][2][e], v[kh][3][e]); o.z = cvt_pk_bf16(v[kh][4][e], v[kh][5][e]); o.w = cvt_pk_bf16(v[kh][6][e], v[kh][7][e]);
;             *(u32x4*)(WT + (size_t)(drow0 + n4 + e) * ldk + k0 + kh * 32 + kg * 8) = o; }
; }
; __device__ __forceinline__ void conv_item(int it, int lane) {
;     unsigned char* ws = WSP; int r = it;
;     if (r < 8 * IT_GU) { const int idx = r / IT_GU; r -= idx * IT_GU; const int kb = r / 168, nb = r % 168, n0 = 64 * nb;
;         const int drow = n0 < DFF ? (n0 >> 7) * 256 + (n0 & 127) : ((n0 - DFF) >> 7) * 256 + 128 + ((n0 - DFF) & 127);
;         tr_item(INP(I_WGU) + (size_t)idx * 2048 * 10752, 10752, 64 * kb, n0, (bf16*)(ws + WS_WGU) + (size_t)idx * 10752 * 2048, 2048, drow, lane); return; }
;     r -= 8 * IT_GU;
;     if (r < 8 * IT_D) { const int idx = r / IT_D; r -= idx * IT_D; const int kb = r / 32, nb = r % 32;
;         tr_item(INP(I_WD) + (size_t)idx * 5376 * 2048, 2048, 64 * kb, 64 * nb, (bf16*)(ws + WS_WD) + (size_t)idx * 2048 * 5376, 5376, 64 * nb, lane); return; }
;     r -= 8 * IT_D;
;     if (r < 2 * IT_INAB) { const int idx = r / IT_INAB; r -= idx * IT_INAB; const int kb = r / 80, nb = r % 80;
;         tr_item(INP(I_WINAB) + (size_t)idx * 2048 * 5120, 5120, 64 * kb, 64 * nb, (bf16*)(ws + WS_WINAB) + (size_t)idx * 5120 * 2048, 2048, 64 * nb, lane); return; }
;     r -= 2 * IT_INAB;
;     if (r < 2 * IT_GLU) { const int idx = r / IT_GLU; r -= idx * IT_GLU; const int kb = r / 16, nb = r % 16;
;         tr_item(INP(I_WGLU) + (size_t)idx * 1024 * 1024, 1024, 64 * kb, 64 * nb, (bf16*)(ws + WS_WGLU) + (size_t)idx * 1024 * 1024, 1024, 64 * nb, lane); return; }
;     r -= 2 * IT_GLU;
;     if (r < 2 * IT_OUTAB) { const int idx = r / IT_OUTAB; r -= idx * IT_OUTAB; const int kb = r / 32, nb = r % 32;
.LBB0_208:
	s_cmpk_gt_u32 s33, 0xfbff
	s_cbranch_scc0 .LBB0_226
	s_cmp_gt_u32 s33, 0x10fff
	s_cbranch_scc0 .LBB0_223
	s_cmp_gt_u32 s33, 0x111ff
	s_cbranch_scc0 .LBB0_220
	s_cmp_gt_u32 s33, 0x119ff
	s_cbranch_scc0 .LBB0_217
	s_cmp_gt_u32 s33, 0x12dff
	s_cbranch_scc0 .LBB0_214
	s_add_i32 s6, s33, 0xfffed200
	s_mul_hi_u32 s34, s6, 0xcccccccd
	s_lshr_b32 s37, s34, 10
	s_mul_i32 s34, s37, 0xfffffb00
	s_add_i32 s6, s34, s6
	s_ashr_i32 s34, s6, 31
	s_lshr_b32 s34, s34, 27
	s_add_i32 s36, s6, s34
	s_mov_b64 s[34:35], s[0:1]
	s_load_dwordx2 s[34:35], s[34:35], 0x128
	s_and_b32 s72, s36, 0x3ffffe0
	s_sub_i32 s6, s6, s72
	s_mul_i32 s73, s37, 0x1400000
	s_mul_hi_u32 s72, s37, 0x1400000
	s_waitcnt lgkmcnt(0)
	s_add_u32 s74, s34, s73
	s_addc_u32 s35, s35, s72
	s_lshl_b32 s34, s36, 1
	s_andn2_b32 s34, s34, 63
	s_lshl_b32 s36, s6, 6
	s_mul_hi_u32 s6, s37, 0xa00000
	s_mul_i32 s37, s37, 0xa00000
	s_add_u32 s75, s30, s37
	s_addc_u32 s6, s31, s6
	s_ashr_i32 s37, s36, 31
	s_lshl_b64 s[72:73], s[36:37], 2
	v_add_u32_e32 v38, s34, v2
	s_add_u32 s72, s74, s72
	s_addc_u32 s73, s35, s73
	v_ashrrev_i32_e32 v39, 31, v38
	v_lshl_add_u64 v[40:41], s[72:73], 0, v[4:5]
	v_lshlrev_b64 v[6:7], 13, v[38:39]
	v_lshl_add_u64 v[30:31], v[40:41], 0, v[6:7]
	v_add_co_u32_e32 v10, vcc, s43, v30
	v_add_u32_e32 v38, 32, v38
	s_nop 0
	v_addc_co_u32_e32 v11, vcc, 0, v31, vcc
	v_add_co_u32_e32 v14, vcc, s44, v30
	v_ashrrev_i32_e32 v39, 31, v38
	s_nop 0
	v_addc_co_u32_e32 v15, vcc, 0, v31, vcc
	v_add_co_u32_e32 v18, vcc, s45, v30
	v_lshlrev_b64 v[38:39], 13, v[38:39]
	s_nop 0
	v_addc_co_u32_e32 v19, vcc, 0, v31, vcc
	v_add_co_u32_e32 v22, vcc, s46, v30
	v_lshl_add_u64 v[62:63], v[40:41], 0, v[38:39]
	s_nop 0
	v_addc_co_u32_e32 v23, vcc, 0, v31, vcc
	v_add_co_u32_e32 v26, vcc, s47, v30
	global_load_dwordx4 v[6:9], v[30:31], off nt
	s_nop 0
	global_load_dwordx4 v[10:13], v[10:11], off nt
	v_addc_co_u32_e32 v27, vcc, 0, v31, vcc
	v_add_co_u32_e32 v32, vcc, s48, v30
	global_load_dwordx4 v[14:17], v[14:15], off nt
	s_nop 0
	global_load_dwordx4 v[18:21], v[18:19], off nt
	v_addc_co_u32_e32 v33, vcc, 0, v31, vcc
	v_add_co_u32_e32 v34, vcc, s49, v30
	global_load_dwordx4 v[22:25], v[22:23], off nt
	s_nop 0
	global_load_dwordx4 v[26:29], v[26:27], off nt
	v_addc_co_u32_e32 v35, vcc, 0, v31, vcc
	v_add_co_u32_e32 v42, vcc, s43, v62
	global_load_dwordx4 v[30:33], v[32:33], off nt
	s_nop 0
	global_load_dwordx4 v[34:37], v[34:35], off nt
	v_addc_co_u32_e32 v43, vcc, 0, v63, vcc
	v_add_co_u32_e32 v46, vcc, s44, v62
	global_load_dwordx4 v[38:41], v[62:63], off nt
	s_nop 0
	global_load_dwordx4 v[42:45], v[42:43], off nt
	v_addc_co_u32_e32 v47, vcc, 0, v63, vcc
	v_add_co_u32_e32 v50, vcc, s45, v62
	s_ashr_i32 s35, s34, 31
	s_nop 0
	v_addc_co_u32_e32 v51, vcc, 0, v63, vcc
	v_add_co_u32_e32 v54, vcc, s46, v62
	global_load_dwordx4 v[46:49], v[46:47], off nt
	s_nop 0
	global_load_dwordx4 v[50:53], v[50:51], off nt
	v_addc_co_u32_e32 v55, vcc, 0, v63, vcc
	v_add_co_u32_e32 v58, vcc, s47, v62
	s_lshl_b64 s[34:35], s[34:35], 1
	s_nop 0
	v_addc_co_u32_e32 v59, vcc, 0, v63, vcc
	v_add_co_u32_e32 v64, vcc, s48, v62
	global_load_dwordx4 v[54:57], v[54:55], off nt
	s_nop 0
	global_load_dwordx4 v[58:61], v[58:59], off nt
	v_addc_co_u32_e32 v65, vcc, 0, v63, vcc
	v_add_co_u32_e32 v66, vcc, s49, v62
	v_or_b32_e32 v1, s36, v0
	s_nop 0
	v_addc_co_u32_e32 v67, vcc, 0, v63, vcc
	global_load_dwordx4 v[62:65], v[64:65], off nt
	s_nop 0
	global_load_dwordx4 v[66:69], v[66:67], off nt
	s_add_u32 s34, s75, s34
	s_addc_u32 s35, s6, s35
	v_mul_lo_u32 v76, v1, s41
	v_lshl_add_u64 v[74:75], v[2:3], 1, s[34:35]
	v_ashrrev_i32_e32 v77, 31, v76
	v_lshl_add_u64 v[74:75], v[76:77], 1, v[74:75]
	v_add_co_u32_e32 v78, vcc, s50, v74
	s_waitcnt vmcnt(14)
	v_cvt_pk_bf16_f32 v70, v6, v10
	s_nop 0
	v_addc_co_u32_e32 v79, vcc, 0, v75, vcc
	v_add_co_u32_e32 v10, vcc, s51, v74
	s_waitcnt vmcnt(12)
	v_cvt_pk_bf16_f32 v71, v14, v18
	s_waitcnt vmcnt(10)
	v_cvt_pk_bf16_f32 v72, v22, v26
	s_waitcnt vmcnt(8)
	v_cvt_pk_bf16_f32 v73, v30, v34
	global_store_dwordx4 v[78:79], v[70:73], off nt
	v_lshl_add_u64 v[76:77], v[74:75], 0, s[10:11]
	s_mov_b64 s[34:35], 0
	v_cvt_pk_bf16_f32 v70, v7, v11
	v_addc_co_u32_e32 v11, vcc, 0, v75, vcc
	v_add_co_u32_e32 v14, vcc, s52, v74
	v_cvt_pk_bf16_f32 v71, v15, v19
	v_cvt_pk_bf16_f32 v72, v23, v27
	v_cvt_pk_bf16_f32 v73, v31, v35
	global_store_dwordx4 v[10:11], v[70:73], off offset:1024 nt
	s_nop 0
	v_addc_co_u32_e32 v15, vcc, 0, v75, vcc
	v_cvt_pk_bf16_f32 v70, v8, v12
	v_add_co_u32_e32 v12, vcc, s53, v74
	v_cvt_pk_bf16_f32 v71, v16, v20
	v_cvt_pk_bf16_f32 v72, v24, v28
	v_cvt_pk_bf16_f32 v73, v32, v36
	global_store_dwordx4 v[14:15], v[70:73], off offset:2048 nt
	v_cvt_pk_bf16_f32 v6, v9, v13
	v_cvt_pk_bf16_f32 v7, v17, v21
	v_cvt_pk_bf16_f32 v8, v25, v29
	v_cvt_pk_bf16_f32 v9, v33, v37
	s_nop 0
	v_addc_co_u32_e32 v13, vcc, 0, v75, vcc
	global_store_dwordx4 v[12:13], v[6:9], off offset:3072 nt
	s_waitcnt vmcnt(10)
	s_nop 0
	v_cvt_pk_bf16_f32 v6, v38, v42
	s_waitcnt vmcnt(8)
	v_cvt_pk_bf16_f32 v7, v46, v50
	s_waitcnt vmcnt(6)
	v_cvt_pk_bf16_f32 v8, v54, v58
	s_waitcnt vmcnt(4)
	v_cvt_pk_bf16_f32 v9, v62, v66
	global_store_dwordx4 v[76:77], v[6:9], off offset:64 nt
	s_nop 1
	v_cvt_pk_bf16_f32 v6, v39, v43
	v_cvt_pk_bf16_f32 v7, v47, v51
	v_cvt_pk_bf16_f32 v8, v55, v59
	v_cvt_pk_bf16_f32 v9, v63, v67
	global_store_dwordx4 v[10:11], v[6:9], off offset:1088 nt
	s_nop 1
	v_cvt_pk_bf16_f32 v6, v40, v44
	v_cvt_pk_bf16_f32 v7, v48, v52
	v_cvt_pk_bf16_f32 v8, v56, v60
	v_cvt_pk_bf16_f32 v9, v64, v68
	global_store_dwordx4 v[14:15], v[6:9], off offset:2112 nt
	s_nop 1
	v_cvt_pk_bf16_f32 v6, v41, v45
	v_cvt_pk_bf16_f32 v7, v49, v53
	v_cvt_pk_bf16_f32 v8, v57, v61
	v_cvt_pk_bf16_f32 v9, v65, v69
	global_store_dwordx4 v[12:13], v[6:9], off offset:3136 nt
; __device__ __forceinline__ unsigned cvt_pk_bf16(float lo, float hi) { unsigned r; asm volatile("v_cvt_pk_bf16_f32 %0, %1, %2" : "=v"(r) : "v"(lo), "v"(hi)); return r; }
; #define INP(i) ((const float*)(const GASP float*)kargs()[(i)])
; __device__ __forceinline__ void tr_item(const float* W, int ldw, int k0, int n0, bf16* WT, int ldk, int drow0, int lane) {
;     const int n4 = (lane & 15) * 4, kg = lane >> 4; f32x4 v[2][8];
; #pragma unroll
;     for (int kh = 0; kh < 2; ++kh) { const float* src = W + (size_t)(k0 + kh * 32 + kg * 8) * ldw + n0 + n4;
; #pragma unroll
;         for (int i = 0; i < 8; ++i) v[kh][i] = __builtin_nontemporal_load((const f32x4*)(src + (size_t)i * ldw)); }
; #pragma unroll
;     for (int kh = 0; kh < 2; ++kh)
; #pragma unroll
;         for (int e = 0; e < 4; ++e) { u32x4 o; o.x = cvt_pk_bf16(v[kh][0][e], v[kh][1][e]); o.y = cvt_pk_bf16(v[kh][2][e], v[kh][3][e]); o.z = cvt_pk_bf16(v[kh][4][e], v[kh][5][e]); o.w = cvt_pk_bf16(v[kh][6][e], v[kh][7][e]);
;             *(u32x4*)(WT + (size_t)(drow0 + n4 + e) * ldk + k0 + kh * 32 + kg * 8) = o; }
; }
; __device__ __forceinline__ void conv_item(int it, int lane) {
;     ...
;     if (r < 2 * IT_INC) { const int idx = r / IT_INC; r -= idx * IT_INC; const int kb = r / 80, nb = r % 80;
;         tr_item(INP(I_WINC) + (size_t)idx * 2048 * 5120, 5120, 64 * kb, 64 * nb, (bf16*)(ws + WS_WINC) + (size_t)idx * 5120 * 2048, 2048, 64 * nb, lane); return; }
.LBB0_214:
	s_andn2_b64 vcc, exec, s[34:35]
	s_cbranch_vccnz .LBB0_216
	s_add_i32 s6, s33, 0xfffee600
	s_cmpk_gt_u32 s6, 0x9ff
	s_cselect_b64 s[72:73], -1, 0
	s_and_b64 s[34:35], s[72:73], exec
	s_cselect_b32 s34, 0xf600, 0
	s_add_i32 s6, s34, s6
	s_sext_i32_i16 s34, s6
	s_mulk_i32 s34, 0x6667
	s_lshr_b32 s35, s34, 31
	s_ashr_i32 s34, s34, 21
	s_add_i32 s74, s34, s35
	s_mov_b64 s[34:35], s[0:1]
	s_load_dwordx2 s[34:35], s[34:35], 0xe8
	s_mul_i32 s36, s74, 0x50
	s_sub_i32 s6, s6, s36
	s_and_b64 s[36:37], s[72:73], exec
	s_cselect_b32 s36, 0x2800000, 0
	s_sext_i32_i16 s6, s6
	s_waitcnt lgkmcnt(0)
	s_add_u32 s75, s34, s36
	s_addc_u32 s35, s35, 0
	s_lshl_b32 s34, s74, 6
	s_lshl_b32 s36, s6, 6
	s_and_b64 s[72:73], s[72:73], exec
	s_cselect_b32 s6, 0x1400000, 0
	s_add_u32 s6, s30, s6
	s_addc_u32 s74, s31, 0
	s_ashr_i32 s37, s36, 31
	s_lshl_b64 s[72:73], s[36:37], 2
	s_add_u32 s72, s75, s72
	s_addc_u32 s73, s35, s73
	v_add_u32_e32 v1, s34, v2
	v_lshl_add_u64 v[38:39], s[72:73], 0, v[4:5]
	v_mad_i64_i32 v[30:31], s[72:73], v1, s55, v[38:39]
	v_add_co_u32_e32 v10, vcc, s55, v30
	v_add_u32_e32 v1, 32, v1
	s_nop 0
	v_addc_co_u32_e32 v11, vcc, 0, v31, vcc
	v_add_co_u32_e32 v14, vcc, s47, v30
	v_mad_i64_i32 v[62:63], s[72:73], v1, s55, v[38:39]
	s_nop 0
	v_addc_co_u32_e32 v15, vcc, 0, v31, vcc
	v_add_co_u32_e32 v18, vcc, s56, v30
	global_load_dwordx4 v[6:9], v[30:31], off nt
	s_nop 0
	global_load_dwordx4 v[10:13], v[10:11], off nt
	v_addc_co_u32_e32 v19, vcc, 0, v31, vcc
	v_add_co_u32_e32 v22, vcc, s57, v30
	global_load_dwordx4 v[14:17], v[14:15], off nt
	s_nop 0
	global_load_dwordx4 v[18:21], v[18:19], off nt
	v_addc_co_u32_e32 v23, vcc, 0, v31, vcc
	v_add_co_u32_e32 v26, vcc, s58, v30
	s_ashr_i32 s35, s34, 31
	s_nop 0
	v_addc_co_u32_e32 v27, vcc, 0, v31, vcc
	v_add_co_u32_e32 v32, vcc, s59, v30
	global_load_dwordx4 v[22:25], v[22:23], off nt
	s_nop 0
	global_load_dwordx4 v[26:29], v[26:27], off nt
	v_addc_co_u32_e32 v33, vcc, 0, v31, vcc
	v_add_co_u32_e32 v34, vcc, s60, v30
	s_lshl_b64 s[34:35], s[34:35], 1
	s_nop 0
	v_addc_co_u32_e32 v35, vcc, 0, v31, vcc
	v_add_co_u32_e32 v42, vcc, s55, v62
	global_load_dwordx4 v[30:33], v[32:33], off nt
	s_nop 0
	global_load_dwordx4 v[34:37], v[34:35], off nt
	v_addc_co_u32_e32 v43, vcc, 0, v63, vcc
	v_add_co_u32_e32 v46, vcc, s47, v62
	global_load_dwordx4 v[38:41], v[62:63], off nt
	s_nop 0
	global_load_dwordx4 v[42:45], v[42:43], off nt
	v_addc_co_u32_e32 v47, vcc, 0, v63, vcc
	v_add_co_u32_e32 v50, vcc, s56, v62
	s_add_u32 s34, s6, s34
	s_nop 0
	v_addc_co_u32_e32 v51, vcc, 0, v63, vcc
	v_add_co_u32_e32 v54, vcc, s57, v62
	global_load_dwordx4 v[46:49], v[46:47], off nt
	s_nop 0
	global_load_dwordx4 v[50:53], v[50:51], off nt
	v_addc_co_u32_e32 v55, vcc, 0, v63, vcc
	v_add_co_u32_e32 v58, vcc, s58, v62
	v_or_b32_e32 v74, s36, v0
	s_nop 0
	v_addc_co_u32_e32 v59, vcc, 0, v63, vcc
	v_add_co_u32_e32 v64, vcc, s59, v62
	global_load_dwordx4 v[54:57], v[54:55], off nt
	s_nop 0
	global_load_dwordx4 v[58:61], v[58:59], off nt
	v_addc_co_u32_e32 v65, vcc, 0, v63, vcc
	v_add_co_u32_e32 v66, vcc, s60, v62
	s_addc_u32 s35, s74, s35
	s_nop 0
	v_addc_co_u32_e32 v67, vcc, 0, v63, vcc
	global_load_dwordx4 v[62:65], v[64:65], off nt
	s_nop 0
	global_load_dwordx4 v[66:69], v[66:67], off nt
	v_lshl_add_u64 v[70:71], v[2:3], 1, s[34:35]
	v_ashrrev_i32_e32 v75, 31, v74
	v_lshl_add_u64 v[76:77], v[70:71], 0, s[12:13]
	v_lshlrev_b64 v[78:79], 12, v[74:75]
	s_waitcnt vmcnt(14)
	v_cvt_pk_bf16_f32 v70, v6, v10
	v_lshl_add_u64 v[78:79], v[76:77], 0, v[78:79]
	v_or_b32_e32 v6, 1, v74
	s_waitcnt vmcnt(12)
	v_cvt_pk_bf16_f32 v71, v14, v18
	s_waitcnt vmcnt(10)
	v_cvt_pk_bf16_f32 v72, v22, v26
	s_waitcnt vmcnt(8)
	v_cvt_pk_bf16_f32 v73, v30, v34
	global_store_dwordx4 v[78:79], v[70:73], off nt
	s_nop 1
	v_cvt_pk_bf16_f32 v70, v7, v11
	v_ashrrev_i32_e32 v7, 31, v6
	v_lshlrev_b64 v[6:7], 12, v[6:7]
	v_lshl_add_u64 v[10:11], v[76:77], 0, v[6:7]
	v_or_b32_e32 v6, 2, v74
	v_ashrrev_i32_e32 v7, 31, v6
	v_lshlrev_b64 v[6:7], 12, v[6:7]
	v_cvt_pk_bf16_f32 v71, v15, v19
	v_cvt_pk_bf16_f32 v72, v23, v27
	v_cvt_pk_bf16_f32 v73, v31, v35
	global_store_dwordx4 v[10:11], v[70:73], off nt
	v_lshl_add_u64 v[14:15], v[76:77], 0, v[6:7]
	s_nop 0
	v_cvt_pk_bf16_f32 v70, v8, v12
	v_or_b32_e32 v12, 3, v74
	v_cvt_pk_bf16_f32 v71, v16, v20
	v_cvt_pk_bf16_f32 v72, v24, v28
	v_cvt_pk_bf16_f32 v73, v32, v36
	global_store_dwordx4 v[14:15], v[70:73], off nt
	v_cvt_pk_bf16_f32 v6, v9, v13
	v_ashrrev_i32_e32 v13, 31, v12
	v_lshlrev_b64 v[12:13], 12, v[12:13]
	v_cvt_pk_bf16_f32 v7, v17, v21
	v_cvt_pk_bf16_f32 v8, v25, v29
	v_cvt_pk_bf16_f32 v9, v33, v37
	v_lshl_add_u64 v[12:13], v[76:77], 0, v[12:13]
	global_store_dwordx4 v[12:13], v[6:9], off nt
	s_waitcnt vmcnt(10)
	s_nop 0
	v_cvt_pk_bf16_f32 v6, v38, v42
	s_waitcnt vmcnt(8)
	v_cvt_pk_bf16_f32 v7, v46, v50
	s_waitcnt vmcnt(6)
	v_cvt_pk_bf16_f32 v8, v54, v58
	s_waitcnt vmcnt(4)
	v_cvt_pk_bf16_f32 v9, v62, v66
	global_store_dwordx4 v[78:79], v[6:9], off offset:64 nt
	s_nop 1
	v_cvt_pk_bf16_f32 v6, v39, v43
	v_cvt_pk_bf16_f32 v7, v47, v51
	v_cvt_pk_bf16_f32 v8, v55, v59
	v_cvt_pk_bf16_f32 v9, v63, v67
	global_store_dwordx4 v[10:11], v[6:9], off offset:64 nt
	s_nop 1
	v_cvt_pk_bf16_f32 v6, v40, v44
	v_cvt_pk_bf16_f32 v7, v48, v52
	v_cvt_pk_bf16_f32 v8, v56, v60
	v_cvt_pk_bf16_f32 v9, v64, v68
	global_store_dwordx4 v[14:15], v[6:9], off offset:64 nt
	s_nop 1
	v_cvt_pk_bf16_f32 v6, v41, v45
	v_cvt_pk_bf16_f32 v7, v49, v53
	v_cvt_pk_bf16_f32 v8, v57, v61
	v_cvt_pk_bf16_f32 v9, v65, v69
	global_store_dwordx4 v[12:13], v[6:9], off offset:64 nt

; __device__ __forceinline__ unsigned cvt_pk_bf16(float lo, float hi) { unsigned r; asm volatile("v_cvt_pk_bf16_f32 %0, %1, %2" : "=v"(r) : "v"(lo), "v"(hi)); return r; }
; #define INP(i) ((const float*)(const GASP float*)kargs()[(i)])
; __device__ __forceinline__ void tr_item(const float* W, int ldw, int k0, int n0, bf16* WT, int ldk, int drow0, int lane) {
;     const int n4 = (lane & 15) * 4, kg = lane >> 4; f32x4 v[2][8];
; #pragma unroll
;     for (int kh = 0; kh < 2; ++kh) { const float* src = W + (size_t)(k0 + kh * 32 + kg * 8) * ldw + n0 + n4;
; #pragma unroll
;         for (int i = 0; i < 8; ++i) v[kh][i] = __builtin_nontemporal_load((const f32x4*)(src + (size_t)i * ldw)); }
; #pragma unroll
;     for (int kh = 0; kh < 2; ++kh)
; #pragma unroll
;         for (int e = 0; e < 4; ++e) { u32x4 o; o.x = cvt_pk_bf16(v[kh][0][e], v[kh][1][e]); o.y = cvt_pk_bf16(v[kh][2][e], v[kh][3][e]); o.z = cvt_pk_bf16(v[kh][4][e], v[kh][5][e]); o.w = cvt_pk_bf16(v[kh][6][e], v[kh][7][e]);
;             *(u32x4*)(WT + (size_t)(drow0 + n4 + e) * ldk + k0 + kh * 32 + kg * 8) = o; }
; }
; __device__ __forceinline__ void conv_item(int it, int lane) {
;     ...
;     if (r < 2 * IT_OUTAB) { const int idx = r / IT_OUTAB; r -= idx * IT_OUTAB; const int kb = r / 32, nb = r % 32;
;         tr_item(INP(I_WOUTAB) + (size_t)idx * 2048 * 2048, 2048, 64 * kb, 64 * nb, (bf16*)(ws + WS_WOUTAB) + (size_t)idx * 2048 * 2048, 2048, 64 * nb, lane); return; }
.LBB0_217:
	s_andn2_b64 vcc, exec, s[34:35]
	s_cbranch_vccnz .LBB0_219
	s_mov_b64 s[34:35], s[0:1]
	s_load_dwordx2 s[34:35], s[34:35], 0xe0
	s_add_i32 s72, s33, 0xfffeee00
	s_lshr_b32 s6, s72, 10
	s_lshl_b64 s[36:37], s[6:7], 24
	v_mov_b32_e32 v79, v5
	s_waitcnt lgkmcnt(0)
	s_add_u32 s36, s34, s36
	s_addc_u32 s37, s35, s37
	s_lshl_b32 s34, s72, 1
	s_and_b32 s72, s34, 0x7c0
	s_lshl_b32 s34, s33, 6
	s_and_b32 s73, s34, 0x7c0
	s_lshl_b64 s[34:35], s[6:7], 23
	s_add_u32 s6, s30, s34
	s_addc_u32 s74, s31, s35
	s_lshl_b32 s34, s73, 2
	v_add_u32_e32 v38, s72, v2
	s_add_u32 s34, s36, s34
	s_addc_u32 s35, s37, 0
	v_ashrrev_i32_e32 v39, 31, v38
	v_lshl_add_u64 v[40:41], s[34:35], 0, v[4:5]
	v_lshlrev_b64 v[6:7], 13, v[38:39]
	v_lshl_add_u64 v[30:31], v[40:41], 0, v[6:7]
	v_add_co_u32_e32 v10, vcc, s43, v30
	v_add_u32_e32 v38, 32, v38
	s_nop 0
	v_addc_co_u32_e32 v11, vcc, 0, v31, vcc
	v_add_co_u32_e32 v14, vcc, s44, v30
	v_ashrrev_i32_e32 v39, 31, v38
	s_nop 0
	v_addc_co_u32_e32 v15, vcc, 0, v31, vcc
	v_add_co_u32_e32 v18, vcc, s45, v30
	v_lshlrev_b64 v[38:39], 13, v[38:39]
	s_nop 0
	v_addc_co_u32_e32 v19, vcc, 0, v31, vcc
	v_add_co_u32_e32 v22, vcc, s46, v30
	v_lshl_add_u64 v[62:63], v[40:41], 0, v[38:39]
	s_nop 0
	v_addc_co_u32_e32 v23, vcc, 0, v31, vcc
	v_add_co_u32_e32 v26, vcc, s47, v30
	global_load_dwordx4 v[6:9], v[30:31], off nt
	s_nop 0
	global_load_dwordx4 v[10:13], v[10:11], off nt
	v_addc_co_u32_e32 v27, vcc, 0, v31, vcc
	v_add_co_u32_e32 v32, vcc, s48, v30
	global_load_dwordx4 v[14:17], v[14:15], off nt
	s_nop 0
	global_load_dwordx4 v[18:21], v[18:19], off nt
	v_addc_co_u32_e32 v33, vcc, 0, v31, vcc
	v_add_co_u32_e32 v34, vcc, s49, v30
	global_load_dwordx4 v[22:25], v[22:23], off nt
	s_nop 0
	global_load_dwordx4 v[26:29], v[26:27], off nt
	v_addc_co_u32_e32 v35, vcc, 0, v31, vcc
	v_add_co_u32_e32 v42, vcc, s43, v62
	global_load_dwordx4 v[30:33], v[32:33], off nt
	s_nop 0
	global_load_dwordx4 v[34:37], v[34:35], off nt
	v_addc_co_u32_e32 v43, vcc, 0, v63, vcc
	v_add_co_u32_e32 v46, vcc, s44, v62
	global_load_dwordx4 v[38:41], v[62:63], off nt
	s_nop 0
	global_load_dwordx4 v[42:45], v[42:43], off nt
	v_addc_co_u32_e32 v47, vcc, 0, v63, vcc
	v_add_co_u32_e32 v50, vcc, s45, v62
	s_lshl_b32 s34, s72, 1
	s_nop 0
	v_addc_co_u32_e32 v51, vcc, 0, v63, vcc
	v_add_co_u32_e32 v54, vcc, s46, v62
	global_load_dwordx4 v[46:49], v[46:47], off nt
	s_nop 0
	global_load_dwordx4 v[50:53], v[50:51], off nt
	v_addc_co_u32_e32 v55, vcc, 0, v63, vcc
	v_add_co_u32_e32 v58, vcc, s47, v62
	s_add_u32 s34, s6, s34
	s_nop 0
	v_addc_co_u32_e32 v59, vcc, 0, v63, vcc
	v_add_co_u32_e32 v64, vcc, s48, v62
	global_load_dwordx4 v[54:57], v[54:55], off nt
	s_nop 0
	global_load_dwordx4 v[58:61], v[58:59], off nt
	v_addc_co_u32_e32 v65, vcc, 0, v63, vcc
	v_add_co_u32_e32 v66, vcc, s49, v62
	s_addc_u32 s35, s74, 0
	s_nop 0
	v_addc_co_u32_e32 v67, vcc, 0, v63, vcc
	global_load_dwordx4 v[62:65], v[64:65], off nt
	s_nop 0
	global_load_dwordx4 v[66:69], v[66:67], off nt
	v_or_b32_e32 v1, s73, v0
	v_lshl_add_u64 v[74:75], v[2:3], 1, s[34:35]
	v_lshl_add_u64 v[76:77], v[74:75], 0, s[14:15]
	v_lshlrev_b32_e32 v78, 12, v1
	s_waitcnt vmcnt(14)
	v_cvt_pk_bf16_f32 v70, v6, v10
	v_lshl_add_u64 v[80:81], v[76:77], 0, v[78:79]
	s_waitcnt vmcnt(12)
	v_cvt_pk_bf16_f32 v71, v14, v18
	s_waitcnt vmcnt(10)
	v_cvt_pk_bf16_f32 v72, v22, v26
	s_waitcnt vmcnt(8)
	v_cvt_pk_bf16_f32 v73, v30, v34
	global_store_dwordx4 v[80:81], v[70:73], off nt
	v_or_b32_e32 v10, 0x1000, v78
	v_or_b32_e32 v14, 0x2000, v78
	v_cvt_pk_bf16_f32 v70, v7, v11
	v_mov_b32_e32 v11, v5
	v_cvt_pk_bf16_f32 v71, v15, v19
	v_lshl_add_u64 v[6:7], v[76:77], 0, v[10:11]
	v_mov_b32_e32 v15, v5
	v_cvt_pk_bf16_f32 v72, v23, v27
	v_cvt_pk_bf16_f32 v73, v31, v35
	global_store_dwordx4 v[6:7], v[70:73], off nt
	v_lshl_add_u64 v[6:7], v[76:77], 0, v[14:15]
	s_nop 0
	v_cvt_pk_bf16_f32 v70, v8, v12
	v_cvt_pk_bf16_f32 v71, v16, v20
	v_cvt_pk_bf16_f32 v72, v24, v28
	v_cvt_pk_bf16_f32 v73, v32, v36
	global_store_dwordx4 v[6:7], v[70:73], off nt
	v_cvt_pk_bf16_f32 v6, v9, v13
	v_or_b32_e32 v12, 0x3000, v78
	v_mov_b32_e32 v13, v5
	v_cvt_pk_bf16_f32 v7, v17, v21
	v_lshl_add_u64 v[16:17], v[76:77], 0, v[12:13]
	v_cvt_pk_bf16_f32 v8, v25, v29
	v_cvt_pk_bf16_f32 v9, v33, v37
	global_store_dwordx4 v[16:17], v[6:9], off nt
	v_lshl_add_u64 v[16:17], v[74:75], 0, s[16:17]
	v_lshl_add_u64 v[10:11], v[16:17], 0, v[10:11]
	s_waitcnt vmcnt(10)
	v_cvt_pk_bf16_f32 v6, v38, v42
	s_waitcnt vmcnt(8)
	v_cvt_pk_bf16_f32 v7, v46, v50
	s_waitcnt vmcnt(6)
	v_cvt_pk_bf16_f32 v8, v54, v58
	s_waitcnt vmcnt(4)
	v_cvt_pk_bf16_f32 v9, v62, v66
	global_store_dwordx4 v[80:81], v[6:9], off offset:64 nt
	s_nop 1
	v_cvt_pk_bf16_f32 v6, v39, v43
	v_cvt_pk_bf16_f32 v7, v47, v51
	v_cvt_pk_bf16_f32 v8, v55, v59
	v_cvt_pk_bf16_f32 v9, v63, v67
	global_store_dwordx4 v[10:11], v[6:9], off nt
	v_lshl_add_u64 v[10:11], v[16:17], 0, v[14:15]
	s_nop 0
	v_cvt_pk_bf16_f32 v6, v40, v44
	v_cvt_pk_bf16_f32 v7, v48, v52
	v_cvt_pk_bf16_f32 v8, v56, v60
	v_cvt_pk_bf16_f32 v9, v64, v68
	global_store_dwordx4 v[10:11], v[6:9], off nt
	v_lshl_add_u64 v[10:11], v[16:17], 0, v[12:13]
	s_nop 0
	v_cvt_pk_bf16_f32 v6, v41, v45
	v_cvt_pk_bf16_f32 v7, v49, v53
	v_cvt_pk_bf16_f32 v8, v57, v61
	v_cvt_pk_bf16_f32 v9, v65, v69
	global_store_dwordx4 v[10:11], v[6:9], off nt

; __device__ __forceinline__ unsigned cvt_pk_bf16(float lo, float hi) { unsigned r; asm volatile("v_cvt_pk_bf16_f32 %0, %1, %2" : "=v"(r) : "v"(lo), "v"(hi)); return r; }
; #define INP(i) ((const float*)(const GASP float*)kargs()[(i)])
; __device__ __forceinline__ void tr_item(const float* W, int ldw, int k0, int n0, bf16* WT, int ldk, int drow0, int lane) {
;     const int n4 = (lane & 15) * 4, kg = lane >> 4; f32x4 v[2][8];
; #pragma unroll
;     for (int kh = 0; kh < 2; ++kh) { const float* src = W + (size_t)(k0 + kh * 32 + kg * 8) * ldw + n0 + n4;
; #pragma unroll
;         for (int i = 0; i < 8; ++i) v[kh][i] = __builtin_nontemporal_load((const f32x4*)(src + (size_t)i * ldw)); }
; #pragma unroll
;     for (int kh = 0; kh < 2; ++kh)
; #pragma unroll
;         for (int e = 0; e < 4; ++e) { u32x4 o; o.x = cvt_pk_bf16(v[kh][0][e], v[kh][1][e]); o.y = cvt_pk_bf16(v[kh][2][e], v[kh][3][e]); o.z = cvt_pk_bf16(v[kh][4][e], v[kh][5][e]); o.w = cvt_pk_bf16(v[kh][6][e], v[kh][7][e]);
;             *(u32x4*)(WT + (size_t)(drow0 + n4 + e) * ldk + k0 + kh * 32 + kg * 8) = o; }
; }
; __device__ __forceinline__ void conv_item(int it, int lane) {
;     ...
;     if (r < 2 * IT_INAB) { const int idx = r / IT_INAB; r -= idx * IT_INAB; const int kb = r / 80, nb = r % 80;
;         tr_item(INP(I_WINAB) + (size_t)idx * 2048 * 5120, 5120, 64 * kb, 64 * nb, (bf16*)(ws + WS_WINAB) + (size_t)idx * 5120 * 2048, 2048, 64 * nb, lane); return; }
.LBB0_223:
	s_andn2_b64 vcc, exec, s[34:35]
	s_cbranch_vccnz .LBB0_225
	s_add_i32 s6, s33, 0xffff0400
	s_cmpk_gt_u32 s6, 0x9ff
	s_cselect_b64 s[72:73], -1, 0
	s_and_b64 s[34:35], s[72:73], exec
	s_cselect_b32 s34, 0xf600, 0
	s_add_i32 s6, s34, s6
	s_sext_i32_i16 s34, s6
	s_mulk_i32 s34, 0x6667
	s_lshr_b32 s35, s34, 31
	s_ashr_i32 s34, s34, 21
	s_add_i32 s74, s34, s35
	s_mov_b64 s[34:35], s[0:1]
	s_load_dwordx2 s[34:35], s[34:35], 0x78
	s_mul_i32 s36, s74, 0x50
	s_sub_i32 s6, s6, s36
	s_and_b64 s[36:37], s[72:73], exec
	s_cselect_b32 s36, 0x2800000, 0
	s_sext_i32_i16 s6, s6
	s_waitcnt lgkmcnt(0)
	s_add_u32 s75, s34, s36
	s_addc_u32 s35, s35, 0
	s_lshl_b32 s34, s74, 6
	s_lshl_b32 s36, s6, 6
	s_and_b64 s[72:73], s[72:73], exec
	s_cselect_b32 s6, 0x1400000, 0
	s_add_u32 s6, s30, s6
	s_addc_u32 s74, s31, 0
	s_ashr_i32 s37, s36, 31
	s_lshl_b64 s[72:73], s[36:37], 2
	s_add_u32 s72, s75, s72
	s_addc_u32 s73, s35, s73
	v_add_u32_e32 v1, s34, v2
	v_lshl_add_u64 v[38:39], s[72:73], 0, v[4:5]
	v_mad_i64_i32 v[30:31], s[72:73], v1, s55, v[38:39]
	v_add_co_u32_e32 v10, vcc, s55, v30
	v_add_u32_e32 v1, 32, v1
	s_nop 0
	v_addc_co_u32_e32 v11, vcc, 0, v31, vcc
	v_add_co_u32_e32 v14, vcc, s47, v30
	v_mad_i64_i32 v[62:63], s[72:73], v1, s55, v[38:39]
	s_nop 0
	v_addc_co_u32_e32 v15, vcc, 0, v31, vcc
	v_add_co_u32_e32 v18, vcc, s56, v30
	global_load_dwordx4 v[6:9], v[30:31], off nt
	s_nop 0
	global_load_dwordx4 v[10:13], v[10:11], off nt
	v_addc_co_u32_e32 v19, vcc, 0, v31, vcc
	v_add_co_u32_e32 v22, vcc, s57, v30
	global_load_dwordx4 v[14:17], v[14:15], off nt
	s_nop 0
	global_load_dwordx4 v[18:21], v[18:19], off nt
	v_addc_co_u32_e32 v23, vcc, 0, v31, vcc
	v_add_co_u32_e32 v26, vcc, s58, v30
	s_ashr_i32 s35, s34, 31
	s_nop 0
	v_addc_co_u32_e32 v27, vcc, 0, v31, vcc
	v_add_co_u32_e32 v32, vcc, s59, v30
	global_load_dwordx4 v[22:25], v[22:23], off nt
	s_nop 0
	global_load_dwordx4 v[26:29], v[26:27], off nt
	v_addc_co_u32_e32 v33, vcc, 0, v31, vcc
	v_add_co_u32_e32 v34, vcc, s60, v30
	s_lshl_b64 s[34:35], s[34:35], 1
	s_nop 0
	v_addc_co_u32_e32 v35, vcc, 0, v31, vcc
	v_add_co_u32_e32 v42, vcc, s55, v62
	global_load_dwordx4 v[30:33], v[32:33], off nt
	s_nop 0
	global_load_dwordx4 v[34:37], v[34:35], off nt
	v_addc_co_u32_e32 v43, vcc, 0, v63, vcc
	v_add_co_u32_e32 v46, vcc, s47, v62
	global_load_dwordx4 v[38:41], v[62:63], off nt
	s_nop 0
	global_load_dwordx4 v[42:45], v[42:43], off nt
	v_addc_co_u32_e32 v47, vcc, 0, v63, vcc
	v_add_co_u32_e32 v50, vcc, s56, v62
	s_add_u32 s34, s6, s34
	s_nop 0
	v_addc_co_u32_e32 v51, vcc, 0, v63, vcc
	v_add_co_u32_e32 v54, vcc, s57, v62
	global_load_dwordx4 v[46:49], v[46:47], off nt
	s_nop 0
	global_load_dwordx4 v[50:53], v[50:51], off nt
	v_addc_co_u32_e32 v55, vcc, 0, v63, vcc
	v_add_co_u32_e32 v58, vcc, s58, v62
	v_or_b32_e32 v74, s36, v0
	s_nop 0
	v_addc_co_u32_e32 v59, vcc, 0, v63, vcc
	v_add_co_u32_e32 v64, vcc, s59, v62
	global_load_dwordx4 v[54:57], v[54:55], off nt
	s_nop 0
	global_load_dwordx4 v[58:61], v[58:59], off nt
	v_addc_co_u32_e32 v65, vcc, 0, v63, vcc
	v_add_co_u32_e32 v66, vcc, s60, v62
	s_addc_u32 s35, s74, s35
	s_nop 0
	v_addc_co_u32_e32 v67, vcc, 0, v63, vcc
	global_load_dwordx4 v[62:65], v[64:65], off nt
	s_nop 0
	global_load_dwordx4 v[66:69], v[66:67], off nt
	v_lshl_add_u64 v[70:71], v[2:3], 1, s[34:35]
	v_ashrrev_i32_e32 v75, 31, v74
	v_lshl_add_u64 v[76:77], v[70:71], 0, s[22:23]
	v_lshlrev_b64 v[78:79], 12, v[74:75]
	s_waitcnt vmcnt(14)
	v_cvt_pk_bf16_f32 v70, v6, v10
	v_lshl_add_u64 v[78:79], v[76:77], 0, v[78:79]
	v_or_b32_e32 v6, 1, v74
	s_waitcnt vmcnt(12)
	v_cvt_pk_bf16_f32 v71, v14, v18
	s_waitcnt vmcnt(10)
	v_cvt_pk_bf16_f32 v72, v22, v26
	s_waitcnt vmcnt(8)
	v_cvt_pk_bf16_f32 v73, v30, v34
	global_store_dwordx4 v[78:79], v[70:73], off nt
	s_nop 1
	v_cvt_pk_bf16_f32 v70, v7, v11
	v_ashrrev_i32_e32 v7, 31, v6
	v_lshlrev_b64 v[6:7], 12, v[6:7]
	v_lshl_add_u64 v[10:11], v[76:77], 0, v[6:7]
	v_or_b32_e32 v6, 2, v74
	v_ashrrev_i32_e32 v7, 31, v6
	v_lshlrev_b64 v[6:7], 12, v[6:7]
	v_cvt_pk_bf16_f32 v71, v15, v19
	v_cvt_pk_bf16_f32 v72, v23, v27
	v_cvt_pk_bf16_f32 v73, v31, v35
	global_store_dwordx4 v[10:11], v[70:73], off nt
	v_lshl_add_u64 v[14:15], v[76:77], 0, v[6:7]
	s_nop 0
	v_cvt_pk_bf16_f32 v70, v8, v12
	v_or_b32_e32 v12, 3, v74
	v_cvt_pk_bf16_f32 v71, v16, v20
	v_cvt_pk_bf16_f32 v72, v24, v28
	v_cvt_pk_bf16_f32 v73, v32, v36
	global_store_dwordx4 v[14:15], v[70:73], off nt
	v_cvt_pk_bf16_f32 v6, v9, v13
	v_ashrrev_i32_e32 v13, 31, v12
	v_lshlrev_b64 v[12:13], 12, v[12:13]
	v_cvt_pk_bf16_f32 v7, v17, v21
	v_cvt_pk_bf16_f32 v8, v25, v29
	v_cvt_pk_bf16_f32 v9, v33, v37
	v_lshl_add_u64 v[12:13], v[76:77], 0, v[12:13]
	global_store_dwordx4 v[12:13], v[6:9], off nt
	s_waitcnt vmcnt(10)
	s_nop 0
	v_cvt_pk_bf16_f32 v6, v38, v42
	s_waitcnt vmcnt(8)
	v_cvt_pk_bf16_f32 v7, v46, v50
	s_waitcnt vmcnt(6)
	v_cvt_pk_bf16_f32 v8, v54, v58
	s_waitcnt vmcnt(4)
	v_cvt_pk_bf16_f32 v9, v62, v66
	global_store_dwordx4 v[78:79], v[6:9], off offset:64 nt
	s_nop 1
	v_cvt_pk_bf16_f32 v6, v39, v43
	v_cvt_pk_bf16_f32 v7, v47, v51
	v_cvt_pk_bf16_f32 v8, v55, v59
	v_cvt_pk_bf16_f32 v9, v63, v67
	global_store_dwordx4 v[10:11], v[6:9], off offset:64 nt
	s_nop 1
	v_cvt_pk_bf16_f32 v6, v40, v44
	v_cvt_pk_bf16_f32 v7, v48, v52
	v_cvt_pk_bf16_f32 v8, v56, v60
	v_cvt_pk_bf16_f32 v9, v64, v68
	global_store_dwordx4 v[14:15], v[6:9], off offset:64 nt
	s_nop 1
	v_cvt_pk_bf16_f32 v6, v41, v45
	v_cvt_pk_bf16_f32 v7, v49, v53
	v_cvt_pk_bf16_f32 v8, v57, v61
	v_cvt_pk_bf16_f32 v9, v65, v69
	global_store_dwordx4 v[12:13], v[6:9], off offset:64 nt

; __device__ __forceinline__ unsigned cvt_pk_bf16(float lo, float hi) { unsigned r; asm volatile("v_cvt_pk_bf16_f32 %0, %1, %2" : "=v"(r) : "v"(lo), "v"(hi)); return r; }
; #define INP(i) ((const float*)(const GASP float*)kargs()[(i)])
; __device__ __forceinline__ void tr_item(const float* W, int ldw, int k0, int n0, bf16* WT, int ldk, int drow0, int lane) {
;     const int n4 = (lane & 15) * 4, kg = lane >> 4; f32x4 v[2][8];
; #pragma unroll
;     for (int kh = 0; kh < 2; ++kh) { const float* src = W + (size_t)(k0 + kh * 32 + kg * 8) * ldw + n0 + n4;
; #pragma unroll
;         for (int i = 0; i < 8; ++i) v[kh][i] = __builtin_nontemporal_load((const f32x4*)(src + (size_t)i * ldw)); }
; #pragma unroll
;     for (int kh = 0; kh < 2; ++kh)
; #pragma unroll
;         for (int e = 0; e < 4; ++e) { u32x4 o; o.x = cvt_pk_bf16(v[kh][0][e], v[kh][1][e]); o.y = cvt_pk_bf16(v[kh][2][e], v[kh][3][e]); o.z = cvt_pk_bf16(v[kh][4][e], v[kh][5][e]); o.w = cvt_pk_bf16(v[kh][6][e], v[kh][7][e]);
;             *(u32x4*)(WT + (size_t)(drow0 + n4 + e) * ldk + k0 + kh * 32 + kg * 8) = o; }
; }
; __device__ __forceinline__ void conv_item(int it, int lane) {
;     ...
;     if (r < 8 * IT_D) { const int idx = r / IT_D; r -= idx * IT_D; const int kb = r / 32, nb = r % 32;
;         tr_item(INP(I_WD) + (size_t)idx * 5376 * 2048, 2048, 64 * kb, 64 * nb, (bf16*)(ws + WS_WD) + (size_t)idx * 2048 * 5376, 5376, 64 * nb, lane); return; }
.LBB0_226:
	s_andn2_b64 vcc, exec, s[34:35]
	s_cbranch_vccnz .LBB0_228
	s_add_i32 s6, s33, 0xffff5800
	s_bfe_u32 s34, s6, 0x100007
	s_mulk_i32 s34, 0xc31
	s_lshr_b32 s37, s34, 16
	s_mul_i32 s34, s37, 0xf580
	s_add_i32 s6, s34, s6
	s_sext_i32_i16 s34, s6
	s_bfe_u32 s34, s34, 0x5001a
	s_add_i32 s36, s6, s34
	s_mov_b64 s[34:35], s[0:1]
	s_load_dwordx2 s[34:35], s[34:35], 0x70
	s_sext_i32_i16 s72, s36
	s_and_b32 s36, s36, 0xffe0
	s_sub_i32 s6, s6, s36
	s_mul_i32 s36, s37, 0x2a00000
	s_waitcnt lgkmcnt(0)
	s_add_u32 s74, s34, s36
	s_sext_i32_i16 s6, s6
	s_addc_u32 s35, s35, 0
	s_lshl_b32 s34, s72, 1
	s_andn2_b32 s34, s34, 63
	s_lshl_b32 s36, s6, 6
	s_mul_i32 s37, s37, 0x1500000
	s_add_u32 s6, s30, s37
	s_addc_u32 s75, s31, 0
	s_ashr_i32 s37, s36, 31
	s_lshl_b64 s[72:73], s[36:37], 2
	v_add_u32_e32 v38, s34, v2
	s_add_u32 s72, s74, s72
	s_addc_u32 s73, s35, s73
	v_ashrrev_i32_e32 v39, 31, v38
	v_lshl_add_u64 v[40:41], s[72:73], 0, v[4:5]
	v_lshlrev_b64 v[6:7], 13, v[38:39]
	v_lshl_add_u64 v[30:31], v[40:41], 0, v[6:7]
	v_add_co_u32_e32 v10, vcc, s43, v30
	v_add_u32_e32 v38, 32, v38
	s_nop 0
	v_addc_co_u32_e32 v11, vcc, 0, v31, vcc
	v_add_co_u32_e32 v14, vcc, s44, v30
	v_ashrrev_i32_e32 v39, 31, v38
	s_nop 0
	v_addc_co_u32_e32 v15, vcc, 0, v31, vcc
	v_add_co_u32_e32 v18, vcc, s45, v30
	v_lshlrev_b64 v[38:39], 13, v[38:39]
	s_nop 0
	v_addc_co_u32_e32 v19, vcc, 0, v31, vcc
	v_add_co_u32_e32 v22, vcc, s46, v30
	v_lshl_add_u64 v[62:63], v[40:41], 0, v[38:39]
	s_nop 0
	v_addc_co_u32_e32 v23, vcc, 0, v31, vcc
	v_add_co_u32_e32 v26, vcc, s47, v30
	global_load_dwordx4 v[6:9], v[30:31], off nt
	s_nop 0
	global_load_dwordx4 v[10:13], v[10:11], off nt
	v_addc_co_u32_e32 v27, vcc, 0, v31, vcc
	v_add_co_u32_e32 v32, vcc, s48, v30
	global_load_dwordx4 v[14:17], v[14:15], off nt
	s_nop 0
	global_load_dwordx4 v[18:21], v[18:19], off nt
	v_addc_co_u32_e32 v33, vcc, 0, v31, vcc
	v_add_co_u32_e32 v34, vcc, s49, v30
	global_load_dwordx4 v[22:25], v[22:23], off nt
	s_nop 0
	global_load_dwordx4 v[26:29], v[26:27], off nt
	v_addc_co_u32_e32 v35, vcc, 0, v31, vcc
	v_add_co_u32_e32 v42, vcc, s43, v62
	global_load_dwordx4 v[30:33], v[32:33], off nt
	s_nop 0
	global_load_dwordx4 v[34:37], v[34:35], off nt
	v_addc_co_u32_e32 v43, vcc, 0, v63, vcc
	v_add_co_u32_e32 v46, vcc, s44, v62
	global_load_dwordx4 v[38:41], v[62:63], off nt
	s_nop 0
	global_load_dwordx4 v[42:45], v[42:43], off nt
	v_addc_co_u32_e32 v47, vcc, 0, v63, vcc
	v_add_co_u32_e32 v50, vcc, s45, v62
	s_ashr_i32 s35, s34, 31
	s_nop 0
	v_addc_co_u32_e32 v51, vcc, 0, v63, vcc
	v_add_co_u32_e32 v54, vcc, s46, v62
	global_load_dwordx4 v[46:49], v[46:47], off nt
	s_nop 0
	global_load_dwordx4 v[50:53], v[50:51], off nt
	v_addc_co_u32_e32 v55, vcc, 0, v63, vcc
	v_add_co_u32_e32 v58, vcc, s47, v62
	s_lshl_b64 s[34:35], s[34:35], 1
	s_nop 0
	v_addc_co_u32_e32 v59, vcc, 0, v63, vcc
	v_add_co_u32_e32 v64, vcc, s48, v62
	global_load_dwordx4 v[54:57], v[54:55], off nt
	s_nop 0
	global_load_dwordx4 v[58:61], v[58:59], off nt
	v_addc_co_u32_e32 v65, vcc, 0, v63, vcc
	v_add_co_u32_e32 v66, vcc, s49, v62
	v_or_b32_e32 v1, s36, v0
	s_nop 0
	v_addc_co_u32_e32 v67, vcc, 0, v63, vcc
	global_load_dwordx4 v[62:65], v[64:65], off nt
	s_nop 0
	global_load_dwordx4 v[66:69], v[66:67], off nt
	s_add_u32 s34, s6, s34
	s_addc_u32 s35, s75, s35
	v_mul_i32_i24_e32 v76, 0x1500, v1
	v_lshl_add_u64 v[74:75], v[2:3], 1, s[34:35]
	v_ashrrev_i32_e32 v77, 31, v76
	v_lshl_add_u64 v[74:75], v[76:77], 1, v[74:75]
	v_add_co_u32_e32 v78, vcc, s62, v74
	s_waitcnt vmcnt(14)
	v_cvt_pk_bf16_f32 v70, v6, v10
	s_nop 0
	v_addc_co_u32_e32 v79, vcc, 0, v75, vcc
	v_add_co_u32_e32 v10, vcc, s63, v74
	s_waitcnt vmcnt(12)
	v_cvt_pk_bf16_f32 v71, v14, v18
	s_waitcnt vmcnt(10)
	v_cvt_pk_bf16_f32 v72, v22, v26
	s_waitcnt vmcnt(8)
	v_cvt_pk_bf16_f32 v73, v30, v34
	global_store_dwordx4 v[78:79], v[70:73], off nt
	v_lshl_add_u64 v[76:77], v[74:75], 0, s[26:27]
	s_nop 0
	v_cvt_pk_bf16_f32 v70, v7, v11
	v_addc_co_u32_e32 v11, vcc, 0, v75, vcc
	v_add_co_u32_e32 v14, vcc, s64, v74
	v_cvt_pk_bf16_f32 v71, v15, v19
	v_cvt_pk_bf16_f32 v72, v23, v27
	v_cvt_pk_bf16_f32 v73, v31, v35
	global_store_dwordx4 v[10:11], v[70:73], off offset:2560 nt
	s_nop 0
	v_addc_co_u32_e32 v15, vcc, 0, v75, vcc
	v_cvt_pk_bf16_f32 v70, v8, v12
	v_add_co_u32_e32 v12, vcc, s65, v74
	v_cvt_pk_bf16_f32 v71, v16, v20
	v_cvt_pk_bf16_f32 v72, v24, v28
	v_cvt_pk_bf16_f32 v73, v32, v36
	global_store_dwordx4 v[14:15], v[70:73], off offset:1024 nt
	v_cvt_pk_bf16_f32 v6, v9, v13
	v_cvt_pk_bf16_f32 v7, v17, v21
	v_cvt_pk_bf16_f32 v8, v25, v29
	v_cvt_pk_bf16_f32 v9, v33, v37
	s_nop 0
	v_addc_co_u32_e32 v13, vcc, 0, v75, vcc
	global_store_dwordx4 v[12:13], v[6:9], off offset:3584 nt
	s_waitcnt vmcnt(10)
	s_nop 0
	v_cvt_pk_bf16_f32 v6, v38, v42
	s_waitcnt vmcnt(8)
	v_cvt_pk_bf16_f32 v7, v46, v50
	s_waitcnt vmcnt(6)
	v_cvt_pk_bf16_f32 v8, v54, v58
	s_waitcnt vmcnt(4)
	v_cvt_pk_bf16_f32 v9, v62, v66
	global_store_dwordx4 v[76:77], v[6:9], off offset:64 nt
	s_nop 1
	v_cvt_pk_bf16_f32 v6, v39, v43
	v_cvt_pk_bf16_f32 v7, v47, v51
	v_cvt_pk_bf16_f32 v8, v55, v59
	v_cvt_pk_bf16_f32 v9, v63, v67
	global_store_dwordx4 v[10:11], v[6:9], off offset:2624 nt
	s_nop 1
	v_cvt_pk_bf16_f32 v6, v40, v44
	v_cvt_pk_bf16_f32 v7, v48, v52
	v_cvt_pk_bf16_f32 v8, v56, v60
	v_cvt_pk_bf16_f32 v9, v64, v68
	global_store_dwordx4 v[14:15], v[6:9], off offset:1088 nt
	s_nop 1
	v_cvt_pk_bf16_f32 v6, v41, v45
	v_cvt_pk_bf16_f32 v7, v49, v53
	v_cvt_pk_bf16_f32 v8, v57, v61
	v_cvt_pk_bf16_f32 v9, v65, v69
	global_store_dwordx4 v[12:13], v[6:9], off offset:3648 nt

; __device__ __forceinline__ void tr_item(const float* W, int ldw, int k0, int n0, bf16* WT, int ldk, int drow0, int lane) {
; __device__ __forceinline__ void conv_item(int it, int lane) {
;     ...
;     if (r < 8 * IT_GU) { const int idx = r / IT_GU; r -= idx * IT_GU; const int kb = r / 168, nb = r % 168, n0 = 64 * nb;
;         const int drow = n0 < DFF ? (n0 >> 7) * 256 + (n0 & 127) : ((n0 - DFF) >> 7) * 256 + 128 + ((n0 - DFF) & 127);
;         tr_item(INP(I_WGU) + (size_t)idx * 2048 * 10752, 10752, 64 * kb, n0, (bf16*)(ws + WS_WGU) + (size_t)idx * 10752 * 2048, 2048, drow, lane); return; }
;     r -= 8 * IT_GU;
;     if (r < 8 * IT_D) { const int idx = r / IT_D; r -= idx * IT_D; const int kb = r / 32, nb = r % 32;
;         tr_item(INP(I_WD) + (size_t)idx * 5376 * 2048, 2048, 64 * kb, 64 * nb, (bf16*)(ws + WS_WD) + (size_t)idx * 2048 * 5376, 5376, 64 * nb, lane); return; }
;     r -= 8 * IT_D;
;     if (r < 2 * IT_INAB) { const int idx = r / IT_INAB; r -= idx * IT_INAB; const int kb = r / 80, nb = r % 80;
;         tr_item(INP(I_WINAB) + (size_t)idx * 2048 * 5120, 5120, 64 * kb, 64 * nb, (bf16*)(ws + WS_WINAB) + (size_t)idx * 5120 * 2048, 2048, 64 * nb, lane); return; }
;     r -= 2 * IT_INAB;
;     if (r < 2 * IT_GLU) { const int idx = r / IT_GLU; r -= idx * IT_GLU; const int kb = r / 16, nb = r % 16;
;         tr_item(INP(I_WGLU) + (size_t)idx * 1024 * 1024, 1024, 64 * kb, 64 * nb, (bf16*)(ws + WS_WGLU) + (size_t)idx * 1024 * 1024, 1024, 64 * nb, lane); return; }
;     r -= 2 * IT_GLU;
;     if (r < 2 * IT_OUTAB) { const int idx = r / IT_OUTAB; r -= idx * IT_OUTAB; const int kb = r / 32, nb = r % 32;
;         tr_item(INP(I_WOUTAB) + (size_t)idx * 2048 * 2048, 2048, 64 * kb, 64 * nb, (bf16*)(ws + WS_WOUTAB) + (size_t)idx * 2048 * 2048, 2048, 64 * nb, lane); return; }
;     r -= 2 * IT_OUTAB;
;     if (r < 2 * IT_INC) { const int idx = r / IT_INC; r -= idx * IT_INC; const int kb = r / 80, nb = r % 80;
;         tr_item(INP(I_WINC) + (size_t)idx * 2048 * 5120, 5120, 64 * kb, 64 * nb, (bf16*)(ws + WS_WINC) + (size_t)idx * 5120 * 2048, 2048, 64 * nb, lane); return; }
;     r -= 2 * IT_INC;
;     { const int idx = r / IT_OUTC; r -= idx * IT_OUTC; const int kb = r / 32, nb = r % 32;
;       tr_item(INP(I_WOUTC) + (size_t)idx * 2560 * 2048, 2048, 64 * kb, 64 * nb, (bf16*)(ws + WS_WOUTC) + (size_t)idx * 2048 * 2560, 2560, 64 * nb, lane); }
.LBB0_277:
	s_cmpk_gt_u32 s33, 0xfbff
	s_cbranch_scc0 .LBB0_295
	s_cmp_gt_u32 s33, 0x10fff
	s_cbranch_scc0 .LBB0_292
	s_cmp_gt_u32 s33, 0x111ff
	s_cbranch_scc0 .LBB0_289
	s_cmp_gt_u32 s33, 0x119ff
	s_cbranch_scc0 .LBB0_286
	s_cmp_gt_u32 s33, 0x12dff
	s_cbranch_scc0 .LBB0_283
	s_add_i32 s10, s33, 0xfffed200
	s_mul_hi_u32 s36, s10, 0xcccccccd
	s_lshr_b32 s39, s36, 10
	s_mul_i32 s36, s39, 0xfffffb00
	s_add_i32 s10, s36, s10
	s_ashr_i32 s36, s10, 31
	s_lshr_b32 s36, s36, 27
	s_add_i32 s38, s10, s36
	s_mov_b64 s[36:37], s[0:1]
	s_load_dwordx2 s[36:37], s[36:37], 0x128
	s_and_b32 s73, s38, 0x3ffffe0
	s_sub_i32 s10, s10, s73
	s_mul_i32 s74, s39, 0x1400000
	s_mul_hi_u32 s73, s39, 0x1400000
	s_waitcnt lgkmcnt(0)
	s_add_u32 s76, s36, s74
	s_addc_u32 s37, s37, s73
	s_lshl_b32 s36, s38, 1
	s_andn2_b32 s36, s36, 63
	s_lshl_b32 s38, s10, 6
	s_mul_hi_u32 s10, s39, 0xa00000
	s_mul_i32 s39, s39, 0xa00000
	s_add_u32 s73, s34, s39
	s_addc_u32 s10, s35, s10
	s_ashr_i32 s39, s38, 31
	s_lshl_b64 s[74:75], s[38:39], 2
	v_add_u32_e32 v38, s36, v2
	s_add_u32 s74, s76, s74
	s_addc_u32 s75, s37, s75
	v_ashrrev_i32_e32 v39, 31, v38
	v_lshl_add_u64 v[40:41], s[74:75], 0, v[4:5]
	v_lshlrev_b64 v[6:7], 13, v[38:39]
	v_lshl_add_u64 v[30:31], v[40:41], 0, v[6:7]
	v_add_co_u32_e32 v10, vcc, s44, v30
	v_add_u32_e32 v38, 32, v38
	s_nop 0
	v_addc_co_u32_e32 v11, vcc, 0, v31, vcc
	v_add_co_u32_e32 v14, vcc, s45, v30
	v_ashrrev_i32_e32 v39, 31, v38
	s_nop 0
	v_addc_co_u32_e32 v15, vcc, 0, v31, vcc
	v_add_co_u32_e32 v18, vcc, s46, v30
	v_lshlrev_b64 v[38:39], 13, v[38:39]
	s_nop 0
	v_addc_co_u32_e32 v19, vcc, 0, v31, vcc
	v_add_co_u32_e32 v22, vcc, s47, v30
	v_lshl_add_u64 v[62:63], v[40:41], 0, v[38:39]
	s_nop 0
	v_addc_co_u32_e32 v23, vcc, 0, v31, vcc
	v_add_co_u32_e32 v26, vcc, s48, v30
	global_load_dwordx4 v[6:9], v[30:31], off nt
	s_nop 0
	global_load_dwordx4 v[10:13], v[10:11], off nt
	v_addc_co_u32_e32 v27, vcc, 0, v31, vcc
	v_add_co_u32_e32 v32, vcc, s49, v30
	global_load_dwordx4 v[14:17], v[14:15], off nt
	s_nop 0
	global_load_dwordx4 v[18:21], v[18:19], off nt
	v_addc_co_u32_e32 v33, vcc, 0, v31, vcc
	v_add_co_u32_e32 v34, vcc, s50, v30
	global_load_dwordx4 v[22:25], v[22:23], off nt
	s_nop 0
	global_load_dwordx4 v[26:29], v[26:27], off nt
	v_addc_co_u32_e32 v35, vcc, 0, v31, vcc
	v_add_co_u32_e32 v42, vcc, s44, v62
	global_load_dwordx4 v[30:33], v[32:33], off nt
	s_nop 0
	global_load_dwordx4 v[34:37], v[34:35], off nt
	v_addc_co_u32_e32 v43, vcc, 0, v63, vcc
	v_add_co_u32_e32 v46, vcc, s45, v62
	global_load_dwordx4 v[38:41], v[62:63], off nt
	s_nop 0
	global_load_dwordx4 v[42:45], v[42:43], off nt
	v_addc_co_u32_e32 v47, vcc, 0, v63, vcc
	v_add_co_u32_e32 v50, vcc, s46, v62
	s_ashr_i32 s37, s36, 31
	s_nop 0
	v_addc_co_u32_e32 v51, vcc, 0, v63, vcc
	v_add_co_u32_e32 v54, vcc, s47, v62
	global_load_dwordx4 v[46:49], v[46:47], off nt
	s_nop 0
	global_load_dwordx4 v[50:53], v[50:51], off nt
	v_addc_co_u32_e32 v55, vcc, 0, v63, vcc
	v_add_co_u32_e32 v58, vcc, s48, v62
	s_lshl_b64 s[36:37], s[36:37], 1
	s_nop 0
	v_addc_co_u32_e32 v59, vcc, 0, v63, vcc
	v_add_co_u32_e32 v64, vcc, s49, v62
	global_load_dwordx4 v[54:57], v[54:55], off nt
	s_nop 0
	global_load_dwordx4 v[58:61], v[58:59], off nt
	v_addc_co_u32_e32 v65, vcc, 0, v63, vcc
	v_add_co_u32_e32 v66, vcc, s50, v62
	v_or_b32_e32 v1, s38, v0
	s_nop 0
	v_addc_co_u32_e32 v67, vcc, 0, v63, vcc
	global_load_dwordx4 v[62:65], v[64:65], off nt
	s_nop 0
	global_load_dwordx4 v[66:69], v[66:67], off nt
	s_add_u32 s36, s73, s36
	s_addc_u32 s37, s10, s37
	v_mul_lo_u32 v76, v1, s42
	v_lshl_add_u64 v[74:75], v[2:3], 1, s[36:37]
	v_ashrrev_i32_e32 v77, 31, v76
	v_lshl_add_u64 v[74:75], v[76:77], 1, v[74:75]
	v_add_co_u32_e32 v78, vcc, s51, v74
	s_waitcnt vmcnt(14)
	v_cvt_pk_bf16_f32 v70, v6, v10
	s_nop 0
	v_addc_co_u32_e32 v79, vcc, 0, v75, vcc
	v_add_co_u32_e32 v10, vcc, s52, v74
	s_waitcnt vmcnt(12)
	v_cvt_pk_bf16_f32 v71, v14, v18
	s_waitcnt vmcnt(10)
	v_cvt_pk_bf16_f32 v72, v22, v26
	s_waitcnt vmcnt(8)
	v_cvt_pk_bf16_f32 v73, v30, v34
	global_store_dwordx4 v[78:79], v[70:73], off nt
	v_lshl_add_u64 v[76:77], v[74:75], 0, s[12:13]
	s_mov_b64 s[36:37], 0
	v_cvt_pk_bf16_f32 v70, v7, v11
	v_addc_co_u32_e32 v11, vcc, 0, v75, vcc
	v_add_co_u32_e32 v14, vcc, s53, v74
	v_cvt_pk_bf16_f32 v71, v15, v19
	v_cvt_pk_bf16_f32 v72, v23, v27
	v_cvt_pk_bf16_f32 v73, v31, v35
	global_store_dwordx4 v[10:11], v[70:73], off offset:1024 nt
	s_nop 0
	v_addc_co_u32_e32 v15, vcc, 0, v75, vcc
	v_cvt_pk_bf16_f32 v70, v8, v12
	v_add_co_u32_e32 v12, vcc, s55, v74
	v_cvt_pk_bf16_f32 v71, v16, v20
	v_cvt_pk_bf16_f32 v72, v24, v28
	v_cvt_pk_bf16_f32 v73, v32, v36
	global_store_dwordx4 v[14:15], v[70:73], off offset:2048 nt
	v_cvt_pk_bf16_f32 v6, v9, v13
	v_cvt_pk_bf16_f32 v7, v17, v21
	v_cvt_pk_bf16_f32 v8, v25, v29
	v_cvt_pk_bf16_f32 v9, v33, v37
	s_nop 0
	v_addc_co_u32_e32 v13, vcc, 0, v75, vcc
	global_store_dwordx4 v[12:13], v[6:9], off offset:3072 nt
	s_waitcnt vmcnt(10)
	s_nop 0
	v_cvt_pk_bf16_f32 v6, v38, v42
	s_waitcnt vmcnt(8)
	v_cvt_pk_bf16_f32 v7, v46, v50
	s_waitcnt vmcnt(6)
	v_cvt_pk_bf16_f32 v8, v54, v58
	s_waitcnt vmcnt(4)
	v_cvt_pk_bf16_f32 v9, v62, v66
	global_store_dwordx4 v[76:77], v[6:9], off offset:64 nt
	s_nop 1
	v_cvt_pk_bf16_f32 v6, v39, v43
	v_cvt_pk_bf16_f32 v7, v47, v51
	v_cvt_pk_bf16_f32 v8, v55, v59
	v_cvt_pk_bf16_f32 v9, v63, v67
	global_store_dwordx4 v[10:11], v[6:9], off offset:1088 nt
	s_nop 1
	v_cvt_pk_bf16_f32 v6, v40, v44
	v_cvt_pk_bf16_f32 v7, v48, v52
	v_cvt_pk_bf16_f32 v8, v56, v60
	v_cvt_pk_bf16_f32 v9, v64, v68
	global_store_dwordx4 v[14:15], v[6:9], off offset:2112 nt
	s_nop 1
	v_cvt_pk_bf16_f32 v6, v41, v45
	v_cvt_pk_bf16_f32 v7, v49, v53
	v_cvt_pk_bf16_f32 v8, v57, v61
	v_cvt_pk_bf16_f32 v9, v65, v69
	global_store_dwordx4 v[12:13], v[6:9], off offset:3136 nt
; __device__ __forceinline__ unsigned cvt_pk_bf16(float lo, float hi) { unsigned r; asm volatile("v_cvt_pk_bf16_f32 %0, %1, %2" : "=v"(r) : "v"(lo), "v"(hi)); return r; }
; #define INP(i) ((const float*)(const GASP float*)kargs()[(i)])
; __device__ __forceinline__ void tr_item(const float* W, int ldw, int k0, int n0, bf16* WT, int ldk, int drow0, int lane) {
;     const int n4 = (lane & 15) * 4, kg = lane >> 4; f32x4 v[2][8];
; #pragma unroll
;     for (int kh = 0; kh < 2; ++kh) { const float* src = W + (size_t)(k0 + kh * 32 + kg * 8) * ldw + n0 + n4;
; #pragma unroll
;         for (int i = 0; i < 8; ++i) v[kh][i] = __builtin_nontemporal_load((const f32x4*)(src + (size_t)i * ldw)); }
; #pragma unroll
;     for (int kh = 0; kh < 2; ++kh)
; #pragma unroll
;         for (int e = 0; e < 4; ++e) { u32x4 o; o.x = cvt_pk_bf16(v[kh][0][e], v[kh][1][e]); o.y = cvt_pk_bf16(v[kh][2][e], v[kh][3][e]); o.z = cvt_pk_bf16(v[kh][4][e], v[kh][5][e]); o.w = cvt_pk_bf16(v[kh][6][e], v[kh][7][e]);
;             *(u32x4*)(WT + (size_t)(drow0 + n4 + e) * ldk + k0 + kh * 32 + kg * 8) = o; }
; }
; __device__ __forceinline__ void conv_item(int it, int lane) {
;     ...
;     if (r < 2 * IT_INC) { const int idx = r / IT_INC; r -= idx * IT_INC; const int kb = r / 80, nb = r % 80;
;         tr_item(INP(I_WINC) + (size_t)idx * 2048 * 5120, 5120, 64 * kb, 64 * nb, (bf16*)(ws + WS_WINC) + (size_t)idx * 5120 * 2048, 2048, 64 * nb, lane); return; }
.LBB0_283:
	s_andn2_b64 vcc, exec, s[36:37]
	s_cbranch_vccnz .LBB0_285
	s_add_i32 s10, s33, 0xfffee600
	s_cmpk_gt_u32 s10, 0x9ff
	s_cselect_b64 s[74:75], -1, 0
	s_and_b64 s[36:37], s[74:75], exec
	s_cselect_b32 s36, 0xf600, 0
	s_add_i32 s10, s36, s10
	s_sext_i32_i16 s36, s10
	s_mulk_i32 s36, 0x6667
	s_lshr_b32 s37, s36, 31
	s_ashr_i32 s36, s36, 21
	s_add_i32 s73, s36, s37
	s_mov_b64 s[36:37], s[0:1]
	s_load_dwordx2 s[36:37], s[36:37], 0xe8
	s_mul_i32 s38, s73, 0x50
	s_sub_i32 s10, s10, s38
	s_and_b64 s[38:39], s[74:75], exec
	s_cselect_b32 s38, 0x2800000, 0
	s_sext_i32_i16 s10, s10
	s_waitcnt lgkmcnt(0)
	s_add_u32 s76, s36, s38
	s_addc_u32 s37, s37, 0
	s_lshl_b32 s36, s73, 6
	s_lshl_b32 s38, s10, 6
	s_and_b64 s[74:75], s[74:75], exec
	s_cselect_b32 s10, 0x1400000, 0
	s_add_u32 s10, s34, s10
	s_addc_u32 s73, s35, 0
	s_ashr_i32 s39, s38, 31
	s_lshl_b64 s[74:75], s[38:39], 2
	s_add_u32 s74, s76, s74
	s_addc_u32 s75, s37, s75
	v_add_u32_e32 v1, s36, v2
	v_lshl_add_u64 v[38:39], s[74:75], 0, v[4:5]
	v_mad_i64_i32 v[30:31], s[74:75], v1, s56, v[38:39]
	v_add_co_u32_e32 v10, vcc, s56, v30
	v_add_u32_e32 v1, 32, v1
	s_nop 0
	v_addc_co_u32_e32 v11, vcc, 0, v31, vcc
	v_add_co_u32_e32 v14, vcc, s48, v30
	v_mad_i64_i32 v[62:63], s[74:75], v1, s56, v[38:39]
	s_nop 0
	v_addc_co_u32_e32 v15, vcc, 0, v31, vcc
	v_add_co_u32_e32 v18, vcc, s57, v30
	global_load_dwordx4 v[6:9], v[30:31], off nt
	s_nop 0
	global_load_dwordx4 v[10:13], v[10:11], off nt
	v_addc_co_u32_e32 v19, vcc, 0, v31, vcc
	v_add_co_u32_e32 v22, vcc, s58, v30
	global_load_dwordx4 v[14:17], v[14:15], off nt
	s_nop 0
	global_load_dwordx4 v[18:21], v[18:19], off nt
	v_addc_co_u32_e32 v23, vcc, 0, v31, vcc
	v_add_co_u32_e32 v26, vcc, s59, v30
	s_ashr_i32 s37, s36, 31
	s_nop 0
	v_addc_co_u32_e32 v27, vcc, 0, v31, vcc
	v_add_co_u32_e32 v32, vcc, s60, v30
	global_load_dwordx4 v[22:25], v[22:23], off nt
	s_nop 0
	global_load_dwordx4 v[26:29], v[26:27], off nt
	v_addc_co_u32_e32 v33, vcc, 0, v31, vcc
	v_add_co_u32_e32 v34, vcc, s61, v30
	s_lshl_b64 s[36:37], s[36:37], 1
	s_nop 0
	v_addc_co_u32_e32 v35, vcc, 0, v31, vcc
	v_add_co_u32_e32 v42, vcc, s56, v62
	global_load_dwordx4 v[30:33], v[32:33], off nt
	s_nop 0
	global_load_dwordx4 v[34:37], v[34:35], off nt
	v_addc_co_u32_e32 v43, vcc, 0, v63, vcc
	v_add_co_u32_e32 v46, vcc, s48, v62
	global_load_dwordx4 v[38:41], v[62:63], off nt
	s_nop 0
	global_load_dwordx4 v[42:45], v[42:43], off nt
	v_addc_co_u32_e32 v47, vcc, 0, v63, vcc
	v_add_co_u32_e32 v50, vcc, s57, v62
	s_add_u32 s36, s10, s36
	s_nop 0
	v_addc_co_u32_e32 v51, vcc, 0, v63, vcc
	v_add_co_u32_e32 v54, vcc, s58, v62
	global_load_dwordx4 v[46:49], v[46:47], off nt
	s_nop 0
	global_load_dwordx4 v[50:53], v[50:51], off nt
	v_addc_co_u32_e32 v55, vcc, 0, v63, vcc
	v_add_co_u32_e32 v58, vcc, s59, v62
	v_or_b32_e32 v74, s38, v0
	s_nop 0
	v_addc_co_u32_e32 v59, vcc, 0, v63, vcc
	v_add_co_u32_e32 v64, vcc, s60, v62
	global_load_dwordx4 v[54:57], v[54:55], off nt
	s_nop 0
	global_load_dwordx4 v[58:61], v[58:59], off nt
	v_addc_co_u32_e32 v65, vcc, 0, v63, vcc
	v_add_co_u32_e32 v66, vcc, s61, v62
	s_addc_u32 s37, s73, s37
	s_nop 0
	v_addc_co_u32_e32 v67, vcc, 0, v63, vcc
	global_load_dwordx4 v[62:65], v[64:65], off nt
	s_nop 0
	global_load_dwordx4 v[66:69], v[66:67], off nt
	v_lshl_add_u64 v[70:71], v[2:3], 1, s[36:37]
	v_ashrrev_i32_e32 v75, 31, v74
	v_lshl_add_u64 v[76:77], v[70:71], 0, s[14:15]
	v_lshlrev_b64 v[78:79], 12, v[74:75]
	s_waitcnt vmcnt(14)
	v_cvt_pk_bf16_f32 v70, v6, v10
	v_lshl_add_u64 v[78:79], v[76:77], 0, v[78:79]
	v_or_b32_e32 v6, 1, v74
	s_waitcnt vmcnt(12)
	v_cvt_pk_bf16_f32 v71, v14, v18
	s_waitcnt vmcnt(10)
	v_cvt_pk_bf16_f32 v72, v22, v26
	s_waitcnt vmcnt(8)
	v_cvt_pk_bf16_f32 v73, v30, v34
	global_store_dwordx4 v[78:79], v[70:73], off nt
	s_nop 1
	v_cvt_pk_bf16_f32 v70, v7, v11
	v_ashrrev_i32_e32 v7, 31, v6
	v_lshlrev_b64 v[6:7], 12, v[6:7]
	v_lshl_add_u64 v[10:11], v[76:77], 0, v[6:7]
	v_or_b32_e32 v6, 2, v74
	v_ashrrev_i32_e32 v7, 31, v6
	v_lshlrev_b64 v[6:7], 12, v[6:7]
	v_cvt_pk_bf16_f32 v71, v15, v19
	v_cvt_pk_bf16_f32 v72, v23, v27
	v_cvt_pk_bf16_f32 v73, v31, v35
	global_store_dwordx4 v[10:11], v[70:73], off nt
	v_lshl_add_u64 v[14:15], v[76:77], 0, v[6:7]
	s_nop 0
	v_cvt_pk_bf16_f32 v70, v8, v12
	v_or_b32_e32 v12, 3, v74
	v_cvt_pk_bf16_f32 v71, v16, v20
	v_cvt_pk_bf16_f32 v72, v24, v28
	v_cvt_pk_bf16_f32 v73, v32, v36
	global_store_dwordx4 v[14:15], v[70:73], off nt
	v_cvt_pk_bf16_f32 v6, v9, v13
	v_ashrrev_i32_e32 v13, 31, v12
	v_lshlrev_b64 v[12:13], 12, v[12:13]
	v_cvt_pk_bf16_f32 v7, v17, v21
	v_cvt_pk_bf16_f32 v8, v25, v29
	v_cvt_pk_bf16_f32 v9, v33, v37
	v_lshl_add_u64 v[12:13], v[76:77], 0, v[12:13]
	global_store_dwordx4 v[12:13], v[6:9], off nt
	s_waitcnt vmcnt(10)
	s_nop 0
	v_cvt_pk_bf16_f32 v6, v38, v42
	s_waitcnt vmcnt(8)
	v_cvt_pk_bf16_f32 v7, v46, v50
	s_waitcnt vmcnt(6)
	v_cvt_pk_bf16_f32 v8, v54, v58
	s_waitcnt vmcnt(4)
	v_cvt_pk_bf16_f32 v9, v62, v66
	global_store_dwordx4 v[78:79], v[6:9], off offset:64 nt
	s_nop 1
	v_cvt_pk_bf16_f32 v6, v39, v43
	v_cvt_pk_bf16_f32 v7, v47, v51
	v_cvt_pk_bf16_f32 v8, v55, v59
	v_cvt_pk_bf16_f32 v9, v63, v67
	global_store_dwordx4 v[10:11], v[6:9], off offset:64 nt
	s_nop 1
	v_cvt_pk_bf16_f32 v6, v40, v44
	v_cvt_pk_bf16_f32 v7, v48, v52
	v_cvt_pk_bf16_f32 v8, v56, v60
	v_cvt_pk_bf16_f32 v9, v64, v68
	global_store_dwordx4 v[14:15], v[6:9], off offset:64 nt
	s_nop 1
	v_cvt_pk_bf16_f32 v6, v41, v45
	v_cvt_pk_bf16_f32 v7, v49, v53
	v_cvt_pk_bf16_f32 v8, v57, v61
	v_cvt_pk_bf16_f32 v9, v65, v69
	global_store_dwordx4 v[12:13], v[6:9], off offset:64 nt

; __device__ __forceinline__ unsigned cvt_pk_bf16(float lo, float hi) { unsigned r; asm volatile("v_cvt_pk_bf16_f32 %0, %1, %2" : "=v"(r) : "v"(lo), "v"(hi)); return r; }
; #define INP(i) ((const float*)(const GASP float*)kargs()[(i)])
; __device__ __forceinline__ void tr_item(const float* W, int ldw, int k0, int n0, bf16* WT, int ldk, int drow0, int lane) {
;     const int n4 = (lane & 15) * 4, kg = lane >> 4; f32x4 v[2][8];
; #pragma unroll
;     for (int kh = 0; kh < 2; ++kh) { const float* src = W + (size_t)(k0 + kh * 32 + kg * 8) * ldw + n0 + n4;
; #pragma unroll
;         for (int i = 0; i < 8; ++i) v[kh][i] = __builtin_nontemporal_load((const f32x4*)(src + (size_t)i * ldw)); }
; #pragma unroll
;     for (int kh = 0; kh < 2; ++kh)
; #pragma unroll
;         for (int e = 0; e < 4; ++e) { u32x4 o; o.x = cvt_pk_bf16(v[kh][0][e], v[kh][1][e]); o.y = cvt_pk_bf16(v[kh][2][e], v[kh][3][e]); o.z = cvt_pk_bf16(v[kh][4][e], v[kh][5][e]); o.w = cvt_pk_bf16(v[kh][6][e], v[kh][7][e]);
;             *(u32x4*)(WT + (size_t)(drow0 + n4 + e) * ldk + k0 + kh * 32 + kg * 8) = o; }
; }
; __device__ __forceinline__ void conv_item(int it, int lane) {
;     ...
;     if (r < 2 * IT_OUTAB) { const int idx = r / IT_OUTAB; r -= idx * IT_OUTAB; const int kb = r / 32, nb = r % 32;
;         tr_item(INP(I_WOUTAB) + (size_t)idx * 2048 * 2048, 2048, 64 * kb, 64 * nb, (bf16*)(ws + WS_WOUTAB) + (size_t)idx * 2048 * 2048, 2048, 64 * nb, lane); return; }
.LBB0_286:
	s_andn2_b64 vcc, exec, s[36:37]
	s_cbranch_vccnz .LBB0_288
	s_mov_b64 s[36:37], s[0:1]
	s_load_dwordx2 s[36:37], s[36:37], 0xe0
	s_add_i32 s73, s33, 0xfffeee00
	s_lshr_b32 s10, s73, 10
	s_lshl_b64 s[38:39], s[10:11], 24
	v_mov_b32_e32 v79, v5
	s_waitcnt lgkmcnt(0)
	s_add_u32 s38, s36, s38
	s_addc_u32 s39, s37, s39
	s_lshl_b32 s36, s73, 1
	s_and_b32 s73, s36, 0x7c0
	s_lshl_b32 s36, s33, 6
	s_and_b32 s74, s36, 0x7c0
	s_lshl_b64 s[36:37], s[10:11], 23
	s_add_u32 s10, s34, s36
	s_addc_u32 s75, s35, s37
	s_lshl_b32 s36, s74, 2
	v_add_u32_e32 v38, s73, v2
	s_add_u32 s36, s38, s36
	s_addc_u32 s37, s39, 0
	v_ashrrev_i32_e32 v39, 31, v38
	v_lshl_add_u64 v[40:41], s[36:37], 0, v[4:5]
	v_lshlrev_b64 v[6:7], 13, v[38:39]
	v_lshl_add_u64 v[30:31], v[40:41], 0, v[6:7]
	v_add_co_u32_e32 v10, vcc, s44, v30
	v_add_u32_e32 v38, 32, v38
	s_nop 0
	v_addc_co_u32_e32 v11, vcc, 0, v31, vcc
	v_add_co_u32_e32 v14, vcc, s45, v30
	v_ashrrev_i32_e32 v39, 31, v38
	s_nop 0
	v_addc_co_u32_e32 v15, vcc, 0, v31, vcc
	v_add_co_u32_e32 v18, vcc, s46, v30
	v_lshlrev_b64 v[38:39], 13, v[38:39]
	s_nop 0
	v_addc_co_u32_e32 v19, vcc, 0, v31, vcc
	v_add_co_u32_e32 v22, vcc, s47, v30
	v_lshl_add_u64 v[62:63], v[40:41], 0, v[38:39]
	s_nop 0
	v_addc_co_u32_e32 v23, vcc, 0, v31, vcc
	v_add_co_u32_e32 v26, vcc, s48, v30
	global_load_dwordx4 v[6:9], v[30:31], off nt
	s_nop 0
	global_load_dwordx4 v[10:13], v[10:11], off nt
	v_addc_co_u32_e32 v27, vcc, 0, v31, vcc
	v_add_co_u32_e32 v32, vcc, s49, v30
	global_load_dwordx4 v[14:17], v[14:15], off nt
	s_nop 0
	global_load_dwordx4 v[18:21], v[18:19], off nt
	v_addc_co_u32_e32 v33, vcc, 0, v31, vcc
	v_add_co_u32_e32 v34, vcc, s50, v30
	global_load_dwordx4 v[22:25], v[22:23], off nt
	s_nop 0
	global_load_dwordx4 v[26:29], v[26:27], off nt
	v_addc_co_u32_e32 v35, vcc, 0, v31, vcc
	v_add_co_u32_e32 v42, vcc, s44, v62
	global_load_dwordx4 v[30:33], v[32:33], off nt
	s_nop 0
	global_load_dwordx4 v[34:37], v[34:35], off nt
	v_addc_co_u32_e32 v43, vcc, 0, v63, vcc
	v_add_co_u32_e32 v46, vcc, s45, v62
	global_load_dwordx4 v[38:41], v[62:63], off nt
	s_nop 0
	global_load_dwordx4 v[42:45], v[42:43], off nt
	v_addc_co_u32_e32 v47, vcc, 0, v63, vcc
	v_add_co_u32_e32 v50, vcc, s46, v62
	s_lshl_b32 s36, s73, 1
	s_nop 0
	v_addc_co_u32_e32 v51, vcc, 0, v63, vcc
	v_add_co_u32_e32 v54, vcc, s47, v62
	global_load_dwordx4 v[46:49], v[46:47], off nt
	s_nop 0
	global_load_dwordx4 v[50:53], v[50:51], off nt
	v_addc_co_u32_e32 v55, vcc, 0, v63, vcc
	v_add_co_u32_e32 v58, vcc, s48, v62
	s_add_u32 s36, s10, s36
	s_nop 0
	v_addc_co_u32_e32 v59, vcc, 0, v63, vcc
	v_add_co_u32_e32 v64, vcc, s49, v62
	global_load_dwordx4 v[54:57], v[54:55], off nt
	s_nop 0
	global_load_dwordx4 v[58:61], v[58:59], off nt
	v_addc_co_u32_e32 v65, vcc, 0, v63, vcc
	v_add_co_u32_e32 v66, vcc, s50, v62
	s_addc_u32 s37, s75, 0
	s_nop 0
	v_addc_co_u32_e32 v67, vcc, 0, v63, vcc
	global_load_dwordx4 v[62:65], v[64:65], off nt
	s_nop 0
	global_load_dwordx4 v[66:69], v[66:67], off nt
	v_or_b32_e32 v1, s74, v0
	v_lshl_add_u64 v[74:75], v[2:3], 1, s[36:37]
	v_lshl_add_u64 v[76:77], v[74:75], 0, s[16:17]
	v_lshlrev_b32_e32 v78, 12, v1
	s_waitcnt vmcnt(14)
	v_cvt_pk_bf16_f32 v70, v6, v10
	v_lshl_add_u64 v[80:81], v[76:77], 0, v[78:79]
	s_waitcnt vmcnt(12)
	v_cvt_pk_bf16_f32 v71, v14, v18
	s_waitcnt vmcnt(10)
	v_cvt_pk_bf16_f32 v72, v22, v26
	s_waitcnt vmcnt(8)
	v_cvt_pk_bf16_f32 v73, v30, v34
	global_store_dwordx4 v[80:81], v[70:73], off nt
	v_or_b32_e32 v10, 0x1000, v78
	v_or_b32_e32 v14, 0x2000, v78
	v_cvt_pk_bf16_f32 v70, v7, v11
	v_mov_b32_e32 v11, v5
	v_cvt_pk_bf16_f32 v71, v15, v19
	v_lshl_add_u64 v[6:7], v[76:77], 0, v[10:11]
	v_mov_b32_e32 v15, v5
	v_cvt_pk_bf16_f32 v72, v23, v27
	v_cvt_pk_bf16_f32 v73, v31, v35
	global_store_dwordx4 v[6:7], v[70:73], off nt
	v_lshl_add_u64 v[6:7], v[76:77], 0, v[14:15]
	s_nop 0
	v_cvt_pk_bf16_f32 v70, v8, v12
	v_cvt_pk_bf16_f32 v71, v16, v20
	v_cvt_pk_bf16_f32 v72, v24, v28
	v_cvt_pk_bf16_f32 v73, v32, v36
	global_store_dwordx4 v[6:7], v[70:73], off nt
	v_cvt_pk_bf16_f32 v6, v9, v13
	v_or_b32_e32 v12, 0x3000, v78
	v_mov_b32_e32 v13, v5
	v_cvt_pk_bf16_f32 v7, v17, v21
	v_lshl_add_u64 v[16:17], v[76:77], 0, v[12:13]
	v_cvt_pk_bf16_f32 v8, v25, v29
	v_cvt_pk_bf16_f32 v9, v33, v37
	global_store_dwordx4 v[16:17], v[6:9], off nt
	v_lshl_add_u64 v[16:17], v[74:75], 0, s[18:19]
	v_lshl_add_u64 v[10:11], v[16:17], 0, v[10:11]
	s_waitcnt vmcnt(10)
	v_cvt_pk_bf16_f32 v6, v38, v42
	s_waitcnt vmcnt(8)
	v_cvt_pk_bf16_f32 v7, v46, v50
	s_waitcnt vmcnt(6)
	v_cvt_pk_bf16_f32 v8, v54, v58
	s_waitcnt vmcnt(4)
	v_cvt_pk_bf16_f32 v9, v62, v66
	global_store_dwordx4 v[80:81], v[6:9], off offset:64 nt
	s_nop 1
	v_cvt_pk_bf16_f32 v6, v39, v43
	v_cvt_pk_bf16_f32 v7, v47, v51
	v_cvt_pk_bf16_f32 v8, v55, v59
	v_cvt_pk_bf16_f32 v9, v63, v67
	global_store_dwordx4 v[10:11], v[6:9], off nt
	v_lshl_add_u64 v[10:11], v[16:17], 0, v[14:15]
	s_nop 0
	v_cvt_pk_bf16_f32 v6, v40, v44
	v_cvt_pk_bf16_f32 v7, v48, v52
	v_cvt_pk_bf16_f32 v8, v56, v60
	v_cvt_pk_bf16_f32 v9, v64, v68
	global_store_dwordx4 v[10:11], v[6:9], off nt
	v_lshl_add_u64 v[10:11], v[16:17], 0, v[12:13]
	s_nop 0
	v_cvt_pk_bf16_f32 v6, v41, v45
	v_cvt_pk_bf16_f32 v7, v49, v53
	v_cvt_pk_bf16_f32 v8, v57, v61
	v_cvt_pk_bf16_f32 v9, v65, v69
	global_store_dwordx4 v[10:11], v[6:9], off nt

; __device__ __forceinline__ unsigned cvt_pk_bf16(float lo, float hi) { unsigned r; asm volatile("v_cvt_pk_bf16_f32 %0, %1, %2" : "=v"(r) : "v"(lo), "v"(hi)); return r; }
; #define INP(i) ((const float*)(const GASP float*)kargs()[(i)])
; __device__ __forceinline__ void tr_item(const float* W, int ldw, int k0, int n0, bf16* WT, int ldk, int drow0, int lane) {
;     const int n4 = (lane & 15) * 4, kg = lane >> 4; f32x4 v[2][8];
; #pragma unroll
;     for (int kh = 0; kh < 2; ++kh) { const float* src = W + (size_t)(k0 + kh * 32 + kg * 8) * ldw + n0 + n4;
; #pragma unroll
;         for (int i = 0; i < 8; ++i) v[kh][i] = __builtin_nontemporal_load((const f32x4*)(src + (size_t)i * ldw)); }
; #pragma unroll
;     for (int kh = 0; kh < 2; ++kh)
; #pragma unroll
;         for (int e = 0; e < 4; ++e) { u32x4 o; o.x = cvt_pk_bf16(v[kh][0][e], v[kh][1][e]); o.y = cvt_pk_bf16(v[kh][2][e], v[kh][3][e]); o.z = cvt_pk_bf16(v[kh][4][e], v[kh][5][e]); o.w = cvt_pk_bf16(v[kh][6][e], v[kh][7][e]);
;             *(u32x4*)(WT + (size_t)(drow0 + n4 + e) * ldk + k0 + kh * 32 + kg * 8) = o; }
; }
; __device__ __forceinline__ void conv_item(int it, int lane) {
;     ...
;     if (r < 2 * IT_INAB) { const int idx = r / IT_INAB; r -= idx * IT_INAB; const int kb = r / 80, nb = r % 80;
;         tr_item(INP(I_WINAB) + (size_t)idx * 2048 * 5120, 5120, 64 * kb, 64 * nb, (bf16*)(ws + WS_WINAB) + (size_t)idx * 5120 * 2048, 2048, 64 * nb, lane); return; }
.LBB0_292:
	s_andn2_b64 vcc, exec, s[36:37]
	s_cbranch_vccnz .LBB0_294
	s_add_i32 s10, s33, 0xffff0400
	s_cmpk_gt_u32 s10, 0x9ff
	s_cselect_b64 s[74:75], -1, 0
	s_and_b64 s[36:37], s[74:75], exec
	s_cselect_b32 s36, 0xf600, 0
	s_add_i32 s10, s36, s10
	s_sext_i32_i16 s36, s10
	s_mulk_i32 s36, 0x6667
	s_lshr_b32 s37, s36, 31
	s_ashr_i32 s36, s36, 21
	s_add_i32 s73, s36, s37
	s_mov_b64 s[36:37], s[0:1]
	s_load_dwordx2 s[36:37], s[36:37], 0x78
	s_mul_i32 s38, s73, 0x50
	s_sub_i32 s10, s10, s38
	s_and_b64 s[38:39], s[74:75], exec
	s_cselect_b32 s38, 0x2800000, 0
	s_sext_i32_i16 s10, s10
	s_waitcnt lgkmcnt(0)
	s_add_u32 s76, s36, s38
	s_addc_u32 s37, s37, 0
	s_lshl_b32 s36, s73, 6
	s_lshl_b32 s38, s10, 6
	s_and_b64 s[74:75], s[74:75], exec
	s_cselect_b32 s10, 0x1400000, 0
	s_add_u32 s10, s34, s10
	s_addc_u32 s73, s35, 0
	s_ashr_i32 s39, s38, 31
	s_lshl_b64 s[74:75], s[38:39], 2
	s_add_u32 s74, s76, s74
	s_addc_u32 s75, s37, s75
	v_add_u32_e32 v1, s36, v2
	v_lshl_add_u64 v[38:39], s[74:75], 0, v[4:5]
	v_mad_i64_i32 v[30:31], s[74:75], v1, s56, v[38:39]
	v_add_co_u32_e32 v10, vcc, s56, v30
	v_add_u32_e32 v1, 32, v1
	s_nop 0
	v_addc_co_u32_e32 v11, vcc, 0, v31, vcc
	v_add_co_u32_e32 v14, vcc, s48, v30
	v_mad_i64_i32 v[62:63], s[74:75], v1, s56, v[38:39]
	s_nop 0
	v_addc_co_u32_e32 v15, vcc, 0, v31, vcc
	v_add_co_u32_e32 v18, vcc, s57, v30
	global_load_dwordx4 v[6:9], v[30:31], off nt
	s_nop 0
	global_load_dwordx4 v[10:13], v[10:11], off nt
	v_addc_co_u32_e32 v19, vcc, 0, v31, vcc
	v_add_co_u32_e32 v22, vcc, s58, v30
	global_load_dwordx4 v[14:17], v[14:15], off nt
	s_nop 0
	global_load_dwordx4 v[18:21], v[18:19], off nt
	v_addc_co_u32_e32 v23, vcc, 0, v31, vcc
	v_add_co_u32_e32 v26, vcc, s59, v30
	s_ashr_i32 s37, s36, 31
	s_nop 0
	v_addc_co_u32_e32 v27, vcc, 0, v31, vcc
	v_add_co_u32_e32 v32, vcc, s60, v30
	global_load_dwordx4 v[22:25], v[22:23], off nt
	s_nop 0
	global_load_dwordx4 v[26:29], v[26:27], off nt
	v_addc_co_u32_e32 v33, vcc, 0, v31, vcc
	v_add_co_u32_e32 v34, vcc, s61, v30
	s_lshl_b64 s[36:37], s[36:37], 1
	s_nop 0
	v_addc_co_u32_e32 v35, vcc, 0, v31, vcc
	v_add_co_u32_e32 v42, vcc, s56, v62
	global_load_dwordx4 v[30:33], v[32:33], off nt
	s_nop 0
	global_load_dwordx4 v[34:37], v[34:35], off nt
	v_addc_co_u32_e32 v43, vcc, 0, v63, vcc
	v_add_co_u32_e32 v46, vcc, s48, v62
	global_load_dwordx4 v[38:41], v[62:63], off nt
	s_nop 0
	global_load_dwordx4 v[42:45], v[42:43], off nt
	v_addc_co_u32_e32 v47, vcc, 0, v63, vcc
	v_add_co_u32_e32 v50, vcc, s57, v62
	s_add_u32 s36, s10, s36
	s_nop 0
	v_addc_co_u32_e32 v51, vcc, 0, v63, vcc
	v_add_co_u32_e32 v54, vcc, s58, v62
	global_load_dwordx4 v[46:49], v[46:47], off nt
	s_nop 0
	global_load_dwordx4 v[50:53], v[50:51], off nt
	v_addc_co_u32_e32 v55, vcc, 0, v63, vcc
	v_add_co_u32_e32 v58, vcc, s59, v62
	v_or_b32_e32 v74, s38, v0
	s_nop 0
	v_addc_co_u32_e32 v59, vcc, 0, v63, vcc
	v_add_co_u32_e32 v64, vcc, s60, v62
	global_load_dwordx4 v[54:57], v[54:55], off nt
	s_nop 0
	global_load_dwordx4 v[58:61], v[58:59], off nt
	v_addc_co_u32_e32 v65, vcc, 0, v63, vcc
	v_add_co_u32_e32 v66, vcc, s61, v62
	s_addc_u32 s37, s73, s37
	s_nop 0
	v_addc_co_u32_e32 v67, vcc, 0, v63, vcc
	global_load_dwordx4 v[62:65], v[64:65], off nt
	s_nop 0
	global_load_dwordx4 v[66:69], v[66:67], off nt
	v_lshl_add_u64 v[70:71], v[2:3], 1, s[36:37]
	v_ashrrev_i32_e32 v75, 31, v74
	v_lshl_add_u64 v[76:77], v[70:71], 0, s[26:27]
	v_lshlrev_b64 v[78:79], 12, v[74:75]
	s_waitcnt vmcnt(14)
	v_cvt_pk_bf16_f32 v70, v6, v10
	v_lshl_add_u64 v[78:79], v[76:77], 0, v[78:79]
	v_or_b32_e32 v6, 1, v74
	s_waitcnt vmcnt(12)
	v_cvt_pk_bf16_f32 v71, v14, v18
	s_waitcnt vmcnt(10)
	v_cvt_pk_bf16_f32 v72, v22, v26
	s_waitcnt vmcnt(8)
	v_cvt_pk_bf16_f32 v73, v30, v34
	global_store_dwordx4 v[78:79], v[70:73], off nt
	s_nop 1
	v_cvt_pk_bf16_f32 v70, v7, v11
	v_ashrrev_i32_e32 v7, 31, v6
	v_lshlrev_b64 v[6:7], 12, v[6:7]
	v_lshl_add_u64 v[10:11], v[76:77], 0, v[6:7]
	v_or_b32_e32 v6, 2, v74
	v_ashrrev_i32_e32 v7, 31, v6
	v_lshlrev_b64 v[6:7], 12, v[6:7]
	v_cvt_pk_bf16_f32 v71, v15, v19
	v_cvt_pk_bf16_f32 v72, v23, v27
	v_cvt_pk_bf16_f32 v73, v31, v35
	global_store_dwordx4 v[10:11], v[70:73], off nt
	v_lshl_add_u64 v[14:15], v[76:77], 0, v[6:7]
	s_nop 0
	v_cvt_pk_bf16_f32 v70, v8, v12
	v_or_b32_e32 v12, 3, v74
	v_cvt_pk_bf16_f32 v71, v16, v20
	v_cvt_pk_bf16_f32 v72, v24, v28
	v_cvt_pk_bf16_f32 v73, v32, v36
	global_store_dwordx4 v[14:15], v[70:73], off nt
	v_cvt_pk_bf16_f32 v6, v9, v13
	v_ashrrev_i32_e32 v13, 31, v12
	v_lshlrev_b64 v[12:13], 12, v[12:13]
	v_cvt_pk_bf16_f32 v7, v17, v21
	v_cvt_pk_bf16_f32 v8, v25, v29
	v_cvt_pk_bf16_f32 v9, v33, v37
	v_lshl_add_u64 v[12:13], v[76:77], 0, v[12:13]
	global_store_dwordx4 v[12:13], v[6:9], off nt
	s_waitcnt vmcnt(10)
	s_nop 0
	v_cvt_pk_bf16_f32 v6, v38, v42
	s_waitcnt vmcnt(8)
	v_cvt_pk_bf16_f32 v7, v46, v50
	s_waitcnt vmcnt(6)
	v_cvt_pk_bf16_f32 v8, v54, v58
	s_waitcnt vmcnt(4)
	v_cvt_pk_bf16_f32 v9, v62, v66
	global_store_dwordx4 v[78:79], v[6:9], off offset:64 nt
	s_nop 1
	v_cvt_pk_bf16_f32 v6, v39, v43
	v_cvt_pk_bf16_f32 v7, v47, v51
	v_cvt_pk_bf16_f32 v8, v55, v59
	v_cvt_pk_bf16_f32 v9, v63, v67
	global_store_dwordx4 v[10:11], v[6:9], off offset:64 nt
	s_nop 1
	v_cvt_pk_bf16_f32 v6, v40, v44
	v_cvt_pk_bf16_f32 v7, v48, v52
	v_cvt_pk_bf16_f32 v8, v56, v60
	v_cvt_pk_bf16_f32 v9, v64, v68
	global_store_dwordx4 v[14:15], v[6:9], off offset:64 nt
	s_nop 1
	v_cvt_pk_bf16_f32 v6, v41, v45
	v_cvt_pk_bf16_f32 v7, v49, v53
	v_cvt_pk_bf16_f32 v8, v57, v61
	v_cvt_pk_bf16_f32 v9, v65, v69
	global_store_dwordx4 v[12:13], v[6:9], off offset:64 nt

; __device__ __forceinline__ unsigned cvt_pk_bf16(float lo, float hi) { unsigned r; asm volatile("v_cvt_pk_bf16_f32 %0, %1, %2" : "=v"(r) : "v"(lo), "v"(hi)); return r; }
; #define INP(i) ((const float*)(const GASP float*)kargs()[(i)])
; __device__ __forceinline__ void tr_item(const float* W, int ldw, int k0, int n0, bf16* WT, int ldk, int drow0, int lane) {
;     const int n4 = (lane & 15) * 4, kg = lane >> 4; f32x4 v[2][8];
; #pragma unroll
;     for (int kh = 0; kh < 2; ++kh) { const float* src = W + (size_t)(k0 + kh * 32 + kg * 8) * ldw + n0 + n4;
; #pragma unroll
;         for (int i = 0; i < 8; ++i) v[kh][i] = __builtin_nontemporal_load((const f32x4*)(src + (size_t)i * ldw)); }
; #pragma unroll
;     for (int kh = 0; kh < 2; ++kh)
; #pragma unroll
;         for (int e = 0; e < 4; ++e) { u32x4 o; o.x = cvt_pk_bf16(v[kh][0][e], v[kh][1][e]); o.y = cvt_pk_bf16(v[kh][2][e], v[kh][3][e]); o.z = cvt_pk_bf16(v[kh][4][e], v[kh][5][e]); o.w = cvt_pk_bf16(v[kh][6][e], v[kh][7][e]);
;             *(u32x4*)(WT + (size_t)(drow0 + n4 + e) * ldk + k0 + kh * 32 + kg * 8) = o; }
; }
; __device__ __forceinline__ void conv_item(int it, int lane) {
;     ...
;     if (r < 8 * IT_D) { const int idx = r / IT_D; r -= idx * IT_D; const int kb = r / 32, nb = r % 32;
;         tr_item(INP(I_WD) + (size_t)idx * 5376 * 2048, 2048, 64 * kb, 64 * nb, (bf16*)(ws + WS_WD) + (size_t)idx * 2048 * 5376, 5376, 64 * nb, lane); return; }
.LBB0_295:
	s_andn2_b64 vcc, exec, s[36:37]
	s_cbranch_vccnz .LBB0_297
	s_add_i32 s10, s33, 0xffff5800
	s_bfe_u32 s36, s10, 0x100007
	s_mulk_i32 s36, 0xc31
	s_lshr_b32 s39, s36, 16
	s_mul_i32 s36, s39, 0xf580
	s_add_i32 s10, s36, s10
	s_sext_i32_i16 s36, s10
	s_bfe_u32 s36, s36, 0x5001a
	s_add_i32 s38, s10, s36
	s_mov_b64 s[36:37], s[0:1]
	s_load_dwordx2 s[36:37], s[36:37], 0x70
	s_sext_i32_i16 s73, s38
	s_and_b32 s38, s38, 0xffe0
	s_sub_i32 s10, s10, s38
	s_mul_i32 s38, s39, 0x2a00000
	s_waitcnt lgkmcnt(0)
	s_add_u32 s76, s36, s38
	s_sext_i32_i16 s10, s10
	s_addc_u32 s37, s37, 0
	s_lshl_b32 s36, s73, 1
	s_andn2_b32 s36, s36, 63
	s_lshl_b32 s38, s10, 6
	s_mul_i32 s39, s39, 0x1500000
	s_add_u32 s10, s34, s39
	s_addc_u32 s73, s35, 0
	s_ashr_i32 s39, s38, 31
	s_lshl_b64 s[74:75], s[38:39], 2
	v_add_u32_e32 v38, s36, v2
	s_add_u32 s74, s76, s74
	s_addc_u32 s75, s37, s75
	v_ashrrev_i32_e32 v39, 31, v38
	v_lshl_add_u64 v[40:41], s[74:75], 0, v[4:5]
	v_lshlrev_b64 v[6:7], 13, v[38:39]
	v_lshl_add_u64 v[30:31], v[40:41], 0, v[6:7]
	v_add_co_u32_e32 v10, vcc, s44, v30
	v_add_u32_e32 v38, 32, v38
	s_nop 0
	v_addc_co_u32_e32 v11, vcc, 0, v31, vcc
	v_add_co_u32_e32 v14, vcc, s45, v30
	v_ashrrev_i32_e32 v39, 31, v38
	s_nop 0
	v_addc_co_u32_e32 v15, vcc, 0, v31, vcc
	v_add_co_u32_e32 v18, vcc, s46, v30
	v_lshlrev_b64 v[38:39], 13, v[38:39]
	s_nop 0
	v_addc_co_u32_e32 v19, vcc, 0, v31, vcc
	v_add_co_u32_e32 v22, vcc, s47, v30
	v_lshl_add_u64 v[62:63], v[40:41], 0, v[38:39]
	s_nop 0
	v_addc_co_u32_e32 v23, vcc, 0, v31, vcc
	v_add_co_u32_e32 v26, vcc, s48, v30
	global_load_dwordx4 v[6:9], v[30:31], off nt
	s_nop 0
	global_load_dwordx4 v[10:13], v[10:11], off nt
	v_addc_co_u32_e32 v27, vcc, 0, v31, vcc
	v_add_co_u32_e32 v32, vcc, s49, v30
	global_load_dwordx4 v[14:17], v[14:15], off nt
	s_nop 0
	global_load_dwordx4 v[18:21], v[18:19], off nt
	v_addc_co_u32_e32 v33, vcc, 0, v31, vcc
	v_add_co_u32_e32 v34, vcc, s50, v30
	global_load_dwordx4 v[22:25], v[22:23], off nt
	s_nop 0
	global_load_dwordx4 v[26:29], v[26:27], off nt
	v_addc_co_u32_e32 v35, vcc, 0, v31, vcc
	v_add_co_u32_e32 v42, vcc, s44, v62
	global_load_dwordx4 v[30:33], v[32:33], off nt
	s_nop 0
	global_load_dwordx4 v[34:37], v[34:35], off nt
	v_addc_co_u32_e32 v43, vcc, 0, v63, vcc
	v_add_co_u32_e32 v46, vcc, s45, v62
	global_load_dwordx4 v[38:41], v[62:63], off nt
	s_nop 0
	global_load_dwordx4 v[42:45], v[42:43], off nt
	v_addc_co_u32_e32 v47, vcc, 0, v63, vcc
	v_add_co_u32_e32 v50, vcc, s46, v62
	s_ashr_i32 s37, s36, 31
	s_nop 0
	v_addc_co_u32_e32 v51, vcc, 0, v63, vcc
	v_add_co_u32_e32 v54, vcc, s47, v62
	global_load_dwordx4 v[46:49], v[46:47], off nt
	s_nop 0
	global_load_dwordx4 v[50:53], v[50:51], off nt
	v_addc_co_u32_e32 v55, vcc, 0, v63, vcc
	v_add_co_u32_e32 v58, vcc, s48, v62
	s_lshl_b64 s[36:37], s[36:37], 1
	s_nop 0
	v_addc_co_u32_e32 v59, vcc, 0, v63, vcc
	v_add_co_u32_e32 v64, vcc, s49, v62
	global_load_dwordx4 v[54:57], v[54:55], off nt
	s_nop 0
	global_load_dwordx4 v[58:61], v[58:59], off nt
	v_addc_co_u32_e32 v65, vcc, 0, v63, vcc
	v_add_co_u32_e32 v66, vcc, s50, v62
	v_or_b32_e32 v1, s38, v0
	s_nop 0
	v_addc_co_u32_e32 v67, vcc, 0, v63, vcc
	global_load_dwordx4 v[62:65], v[64:65], off nt
	s_nop 0
	global_load_dwordx4 v[66:69], v[66:67], off nt
	s_add_u32 s36, s10, s36
	s_addc_u32 s37, s73, s37
	v_mul_i32_i24_e32 v76, 0x1500, v1
	v_lshl_add_u64 v[74:75], v[2:3], 1, s[36:37]
	v_ashrrev_i32_e32 v77, 31, v76
	v_lshl_add_u64 v[74:75], v[76:77], 1, v[74:75]
	v_add_co_u32_e32 v78, vcc, s63, v74
	s_waitcnt vmcnt(14)
	v_cvt_pk_bf16_f32 v70, v6, v10
	s_nop 0
	v_addc_co_u32_e32 v79, vcc, 0, v75, vcc
	v_add_co_u32_e32 v10, vcc, s64, v74
	s_waitcnt vmcnt(12)
	v_cvt_pk_bf16_f32 v71, v14, v18
	s_waitcnt vmcnt(10)
	v_cvt_pk_bf16_f32 v72, v22, v26
	s_waitcnt vmcnt(8)
	v_cvt_pk_bf16_f32 v73, v30, v34
	global_store_dwordx4 v[78:79], v[70:73], off nt
	v_lshl_add_u64 v[76:77], v[74:75], 0, s[28:29]
	s_nop 0
	v_cvt_pk_bf16_f32 v70, v7, v11
	v_addc_co_u32_e32 v11, vcc, 0, v75, vcc
	v_add_co_u32_e32 v14, vcc, s65, v74
	v_cvt_pk_bf16_f32 v71, v15, v19
	v_cvt_pk_bf16_f32 v72, v23, v27
	v_cvt_pk_bf16_f32 v73, v31, v35
	global_store_dwordx4 v[10:11], v[70:73], off offset:2560 nt
	s_nop 0
	v_addc_co_u32_e32 v15, vcc, 0, v75, vcc
	v_cvt_pk_bf16_f32 v70, v8, v12
	v_add_co_u32_e32 v12, vcc, s66, v74
	v_cvt_pk_bf16_f32 v71, v16, v20
	v_cvt_pk_bf16_f32 v72, v24, v28
	v_cvt_pk_bf16_f32 v73, v32, v36
	global_store_dwordx4 v[14:15], v[70:73], off offset:1024 nt
	v_cvt_pk_bf16_f32 v6, v9, v13
	v_cvt_pk_bf16_f32 v7, v17, v21
	v_cvt_pk_bf16_f32 v8, v25, v29
	v_cvt_pk_bf16_f32 v9, v33, v37
	s_nop 0
	v_addc_co_u32_e32 v13, vcc, 0, v75, vcc
	global_store_dwordx4 v[12:13], v[6:9], off offset:3584 nt
	s_waitcnt vmcnt(10)
	s_nop 0
	v_cvt_pk_bf16_f32 v6, v38, v42
	s_waitcnt vmcnt(8)
	v_cvt_pk_bf16_f32 v7, v46, v50
	s_waitcnt vmcnt(6)
	v_cvt_pk_bf16_f32 v8, v54, v58
	s_waitcnt vmcnt(4)
	v_cvt_pk_bf16_f32 v9, v62, v66
	global_store_dwordx4 v[76:77], v[6:9], off offset:64 nt
	s_nop 1
	v_cvt_pk_bf16_f32 v6, v39, v43
	v_cvt_pk_bf16_f32 v7, v47, v51
	v_cvt_pk_bf16_f32 v8, v55, v59
	v_cvt_pk_bf16_f32 v9, v63, v67
	global_store_dwordx4 v[10:11], v[6:9], off offset:2624 nt
	s_nop 1
	v_cvt_pk_bf16_f32 v6, v40, v44
	v_cvt_pk_bf16_f32 v7, v48, v52
	v_cvt_pk_bf16_f32 v8, v56, v60
	v_cvt_pk_bf16_f32 v9, v64, v68
	global_store_dwordx4 v[14:15], v[6:9], off offset:1088 nt
	s_nop 1
	v_cvt_pk_bf16_f32 v6, v41, v45
	v_cvt_pk_bf16_f32 v7, v49, v53
	v_cvt_pk_bf16_f32 v8, v57, v61
	v_cvt_pk_bf16_f32 v9, v65, v69
	global_store_dwordx4 v[12:13], v[6:9], off offset:3648 nt

; __device__ __forceinline__ void tr_item(const float* W, int ldw, int k0, int n0, bf16* WT, int ldk, int drow0, int lane) {
; __device__ __forceinline__ void conv_item(int it, int lane) {
;     ...
;     if (r < 8 * IT_GU) { const int idx = r / IT_GU; r -= idx * IT_GU; const int kb = r / 168, nb = r % 168, n0 = 64 * nb;
;         const int drow = n0 < DFF ? (n0 >> 7) * 256 + (n0 & 127) : ((n0 - DFF) >> 7) * 256 + 128 + ((n0 - DFF) & 127);
;         tr_item(INP(I_WGU) + (size_t)idx * 2048 * 10752, 10752, 64 * kb, n0, (bf16*)(ws + WS_WGU) + (size_t)idx * 10752 * 2048, 2048, drow, lane); return; }
;     r -= 8 * IT_GU;
;     if (r < 8 * IT_D) { const int idx = r / IT_D; r -= idx * IT_D; const int kb = r / 32, nb = r % 32;
;         tr_item(INP(I_WD) + (size_t)idx * 5376 * 2048, 2048, 64 * kb, 64 * nb, (bf16*)(ws + WS_WD) + (size_t)idx * 2048 * 5376, 5376, 64 * nb, lane); return; }
;     r -= 8 * IT_D;
;     if (r < 2 * IT_INAB) { const int idx = r / IT_INAB; r -= idx * IT_INAB; const int kb = r / 80, nb = r % 80;
;         tr_item(INP(I_WINAB) + (size_t)idx * 2048 * 5120, 5120, 64 * kb, 64 * nb, (bf16*)(ws + WS_WINAB) + (size_t)idx * 5120 * 2048, 2048, 64 * nb, lane); return; }
;     r -= 2 * IT_INAB;
;     if (r < 2 * IT_GLU) { const int idx = r / IT_GLU; r -= idx * IT_GLU; const int kb = r / 16, nb = r % 16;
;         tr_item(INP(I_WGLU) + (size_t)idx * 1024 * 1024, 1024, 64 * kb, 64 * nb, (bf16*)(ws + WS_WGLU) + (size_t)idx * 1024 * 1024, 1024, 64 * nb, lane); return; }
;     r -= 2 * IT_GLU;
;     if (r < 2 * IT_OUTAB) { const int idx = r / IT_OUTAB; r -= idx * IT_OUTAB; const int kb = r / 32, nb = r % 32;
;         tr_item(INP(I_WOUTAB) + (size_t)idx * 2048 * 2048, 2048, 64 * kb, 64 * nb, (bf16*)(ws + WS_WOUTAB) + (size_t)idx * 2048 * 2048, 2048, 64 * nb, lane); return; }
;     r -= 2 * IT_OUTAB;
;     if (r < 2 * IT_INC) { const int idx = r / IT_INC; r -= idx * IT_INC; const int kb = r / 80, nb = r % 80;
;         tr_item(INP(I_WINC) + (size_t)idx * 2048 * 5120, 5120, 64 * kb, 64 * nb, (bf16*)(ws + WS_WINC) + (size_t)idx * 5120 * 2048, 2048, 64 * nb, lane); return; }
;     r -= 2 * IT_INC;
;     { const int idx = r / IT_OUTC; r -= idx * IT_OUTC; const int kb = r / 32, nb = r % 32;
;       tr_item(INP(I_WOUTC) + (size_t)idx * 2560 * 2048, 2048, 64 * kb, 64 * nb, (bf16*)(ws + WS_WOUTC) + (size_t)idx * 2048 * 2560, 2560, 64 * nb, lane); }
.LBB0_562:
	s_mov_b64 s[2:3], s[0:1]
	s_load_dwordx2 s[2:3], s[2:3], 0x138
	s_add_i32 s6, s12, s21
	s_mov_b64 s[22:23], -1
	s_cmp_gt_i32 s6, 0xa7ff
	s_cbranch_scc0 .LBB0_584
	s_cmpk_gt_u32 s6, 0xfbff
	s_cbranch_scc0 .LBB0_581
	s_cmp_gt_u32 s6, 0x10fff
	s_cbranch_scc0 .LBB0_578
	s_cmp_gt_u32 s6, 0x111ff
	s_cbranch_scc0 .LBB0_575
	s_cmp_gt_u32 s6, 0x119ff
	s_cbranch_scc0 .LBB0_572
	s_cmp_gt_u32 s6, 0x12dff
	s_cbranch_scc0 .LBB0_569
	s_add_i32 s11, s6, 0xfffed200
	s_mul_hi_u32 s12, s11, 0xcccccccd
	s_lshr_b32 s12, s12, 10
	s_mul_i32 s19, s12, 0xfffffb00
	s_mov_b64 s[20:21], s[0:1]
	s_add_i32 s11, s19, s11
	s_ashr_i32 s19, s11, 31
	s_load_dwordx2 s[20:21], s[20:21], 0x128
	s_lshr_b32 s19, s19, 27
	s_add_i32 s19, s11, s19
	s_and_b32 s22, s19, 0x3ffffe0
	s_sub_i32 s11, s11, s22
	s_mul_i32 s23, s12, 0x1400000
	s_mul_hi_u32 s22, s12, 0x1400000
	s_waitcnt lgkmcnt(0)
	s_add_u32 s23, s20, s23
	s_addc_u32 s28, s21, s22
	s_lshl_b32 s19, s19, 1
	s_and_b32 s22, s19, 0xffffffc0
	s_lshl_b32 s26, s11, 6
	s_mul_hi_u32 s11, s12, 0xa00000
	s_mul_i32 s12, s12, 0xa00000
	s_add_u32 s12, s2, s12
	s_addc_u32 s11, s3, s11
	s_ashr_i32 s27, s26, 31
	s_lshl_b64 s[20:21], s[26:27], 2
	v_add_u32_e32 v32, s22, v66
	s_add_u32 s20, s23, s20
	s_addc_u32 s21, s28, s21
	v_lshlrev_b32_e32 v172, 2, v64
	v_ashrrev_i32_e32 v33, 31, v32
	v_lshl_add_u64 v[34:35], s[20:21], 0, v[172:173]
	v_lshlrev_b64 v[0:1], 13, v[32:33]
	v_lshl_add_u64 v[24:25], v[34:35], 0, v[0:1]
	v_add_co_u32_e32 v4, vcc, s89, v24
	s_movk_i32 s20, 0x4000
	s_nop 0
	v_addc_co_u32_e32 v5, vcc, 0, v25, vcc
	v_add_co_u32_e32 v8, vcc, s20, v24
	s_movk_i32 s19, 0x6000
	s_nop 0
	v_addc_co_u32_e32 v9, vcc, 0, v25, vcc
	v_add_co_u32_e32 v12, vcc, s19, v24
	s_mov_b32 s21, 0x8000
	s_nop 0
	v_addc_co_u32_e32 v13, vcc, 0, v25, vcc
	v_add_co_u32_e32 v16, vcc, s21, v24
	v_add_u32_e32 v32, 32, v32
	s_nop 0
	v_addc_co_u32_e32 v17, vcc, 0, v25, vcc
	v_add_co_u32_e32 v20, vcc, s33, v24
	s_mov_b32 s23, 0xe000
	s_nop 0
	v_addc_co_u32_e32 v21, vcc, 0, v25, vcc
	v_add_co_u32_e32 v26, vcc, s38, v24
	v_ashrrev_i32_e32 v33, 31, v32
	s_nop 0
	v_addc_co_u32_e32 v27, vcc, 0, v25, vcc
	v_add_co_u32_e32 v28, vcc, s23, v24
	v_lshlrev_b64 v[32:33], 13, v[32:33]
	s_nop 0
	v_addc_co_u32_e32 v29, vcc, 0, v25, vcc
	v_lshl_add_u64 v[56:57], v[34:35], 0, v[32:33]
	v_add_co_u32_e32 v36, vcc, s89, v56
	global_load_dwordx4 v[0:3], v[24:25], off nt
	s_nop 0
	global_load_dwordx4 v[4:7], v[4:5], off nt
	v_addc_co_u32_e32 v37, vcc, 0, v57, vcc
	v_add_co_u32_e32 v40, vcc, s20, v56
	global_load_dwordx4 v[8:11], v[8:9], off nt
	s_nop 0
	global_load_dwordx4 v[12:15], v[12:13], off nt
	v_addc_co_u32_e32 v41, vcc, 0, v57, vcc
	v_add_co_u32_e32 v44, vcc, s19, v56
	global_load_dwordx4 v[16:19], v[16:17], off nt
	s_nop 0
	global_load_dwordx4 v[20:23], v[20:21], off nt
	v_addc_co_u32_e32 v45, vcc, 0, v57, vcc
	v_add_co_u32_e32 v48, vcc, s21, v56
	global_load_dwordx4 v[24:27], v[26:27], off nt
	s_nop 0
	global_load_dwordx4 v[28:31], v[28:29], off nt
	v_addc_co_u32_e32 v49, vcc, 0, v57, vcc
	v_add_co_u32_e32 v52, vcc, s33, v56
	global_load_dwordx4 v[32:35], v[56:57], off nt
	s_nop 0
	global_load_dwordx4 v[36:39], v[36:37], off nt
	v_addc_co_u32_e32 v53, vcc, 0, v57, vcc
	v_add_co_u32_e32 v58, vcc, s38, v56
	global_load_dwordx4 v[40:43], v[40:41], off nt
	s_nop 0
	global_load_dwordx4 v[44:47], v[44:45], off nt
	v_addc_co_u32_e32 v59, vcc, 0, v57, vcc
	v_add_co_u32_e32 v60, vcc, s23, v56
	global_load_dwordx4 v[48:51], v[48:49], off nt
	s_nop 0
	global_load_dwordx4 v[52:55], v[52:53], off nt
	v_addc_co_u32_e32 v61, vcc, 0, v57, vcc
	global_load_dwordx4 v[56:59], v[58:59], off nt
	s_nop 0
	global_load_dwordx4 v[60:63], v[60:61], off nt
	s_ashr_i32 s23, s22, 31
	s_lshl_b64 s[20:21], s[22:23], 1
	s_add_u32 s20, s12, s20
	v_or_b32_e32 v65, s26, v64
	s_addc_u32 s21, s11, s21
	s_movk_i32 s11, 0xa00
	v_mul_lo_u32 v74, v65, s11
	v_lshl_add_u64 v[72:73], v[66:67], 1, s[20:21]
	v_ashrrev_i32_e32 v75, 31, v74
	v_lshl_add_u64 v[72:73], v[74:75], 1, v[72:73]
	s_mov_b32 s11, 0x25d00000
	v_add_co_u32_e32 v76, vcc, s11, v72
	s_mov_b32 s11, 0x25d01000
	s_nop 0
	v_addc_co_u32_e32 v77, vcc, 0, v73, vcc
	s_waitcnt vmcnt(0)
	v_cvt_pk_bf16_f32 v68, v0, v4
	v_add_co_u32_e32 v4, vcc, s11, v72
	v_cvt_pk_bf16_f32 v69, v8, v12
	v_cvt_pk_bf16_f32 v70, v16, v20
	v_cvt_pk_bf16_f32 v71, v24, v28
	global_store_dwordx4 v[76:77], v[68:71], off nt
	s_mov_b32 s11, 0x25d02000
	s_mov_b64 s[20:21], 0x25d00000
	v_cvt_pk_bf16_f32 v68, v1, v5
	v_addc_co_u32_e32 v5, vcc, 0, v73, vcc
	v_add_co_u32_e32 v8, vcc, s11, v72
	v_cvt_pk_bf16_f32 v69, v9, v13
	s_mov_b32 s11, 0x25d03000
	s_nop 0
	v_addc_co_u32_e32 v9, vcc, 0, v73, vcc
	v_cvt_pk_bf16_f32 v70, v17, v21
	v_cvt_pk_bf16_f32 v71, v25, v29
	global_store_dwordx4 v[4:5], v[68:71], off offset:1024 nt
	v_lshl_add_u64 v[74:75], v[72:73], 0, s[20:21]
	s_mov_b64 s[22:23], 0
	v_cvt_pk_bf16_f32 v68, v2, v6
	v_add_co_u32_e32 v6, vcc, s11, v72
	v_cvt_pk_bf16_f32 v69, v10, v14
	v_cvt_pk_bf16_f32 v70, v18, v22
	v_cvt_pk_bf16_f32 v71, v26, v30
	global_store_dwordx4 v[8:9], v[68:71], off offset:2048 nt
	v_cvt_pk_bf16_f32 v0, v3, v7
	v_cvt_pk_bf16_f32 v1, v11, v15
	v_cvt_pk_bf16_f32 v2, v19, v23
	v_cvt_pk_bf16_f32 v3, v27, v31
	s_nop 0
	v_addc_co_u32_e32 v7, vcc, 0, v73, vcc
	global_store_dwordx4 v[6:7], v[0:3], off offset:3072 nt
	s_nop 1
	v_cvt_pk_bf16_f32 v0, v32, v36
	v_cvt_pk_bf16_f32 v1, v40, v44
	v_cvt_pk_bf16_f32 v2, v48, v52
	v_cvt_pk_bf16_f32 v3, v56, v60
	global_store_dwordx4 v[74:75], v[0:3], off offset:64 nt
	s_nop 1
	v_cvt_pk_bf16_f32 v0, v33, v37
	v_cvt_pk_bf16_f32 v1, v41, v45
	v_cvt_pk_bf16_f32 v2, v49, v53
	v_cvt_pk_bf16_f32 v3, v57, v61
	global_store_dwordx4 v[4:5], v[0:3], off offset:1088 nt
	s_nop 1
	v_cvt_pk_bf16_f32 v0, v34, v38
	v_cvt_pk_bf16_f32 v1, v42, v46
	v_cvt_pk_bf16_f32 v2, v50, v54
	v_cvt_pk_bf16_f32 v3, v58, v62
	global_store_dwordx4 v[8:9], v[0:3], off offset:2112 nt
	s_nop 1
	v_cvt_pk_bf16_f32 v0, v35, v39
	v_cvt_pk_bf16_f32 v1, v43, v47
	v_cvt_pk_bf16_f32 v2, v51, v55
	v_cvt_pk_bf16_f32 v3, v59, v63
	global_store_dwordx4 v[6:7], v[0:3], off offset:3136 nt
; __device__ __forceinline__ unsigned cvt_pk_bf16(float lo, float hi) { unsigned r; asm volatile("v_cvt_pk_bf16_f32 %0, %1, %2" : "=v"(r) : "v"(lo), "v"(hi)); return r; }
; #define INP(i) ((const float*)(const GASP float*)kargs()[(i)])
; __device__ __forceinline__ void tr_item(const float* W, int ldw, int k0, int n0, bf16* WT, int ldk, int drow0, int lane) {
;     const int n4 = (lane & 15) * 4, kg = lane >> 4; f32x4 v[2][8];
; #pragma unroll
;     for (int kh = 0; kh < 2; ++kh) { const float* src = W + (size_t)(k0 + kh * 32 + kg * 8) * ldw + n0 + n4;
; #pragma unroll
;         for (int i = 0; i < 8; ++i) v[kh][i] = __builtin_nontemporal_load((const f32x4*)(src + (size_t)i * ldw)); }
; #pragma unroll
;     for (int kh = 0; kh < 2; ++kh)
; #pragma unroll
;         for (int e = 0; e < 4; ++e) { u32x4 o; o.x = cvt_pk_bf16(v[kh][0][e], v[kh][1][e]); o.y = cvt_pk_bf16(v[kh][2][e], v[kh][3][e]); o.z = cvt_pk_bf16(v[kh][4][e], v[kh][5][e]); o.w = cvt_pk_bf16(v[kh][6][e], v[kh][7][e]);
;             *(u32x4*)(WT + (size_t)(drow0 + n4 + e) * ldk + k0 + kh * 32 + kg * 8) = o; }
; }
; __device__ __forceinline__ void conv_item(int it, int lane) {
;     ...
;     if (r < 2 * IT_INC) { const int idx = r / IT_INC; r -= idx * IT_INC; const int kb = r / 80, nb = r % 80;
;         tr_item(INP(I_WINC) + (size_t)idx * 2048 * 5120, 5120, 64 * kb, 64 * nb, (bf16*)(ws + WS_WINC) + (size_t)idx * 5120 * 2048, 2048, 64 * nb, lane); return; }
.LBB0_569:
	s_andn2_b64 vcc, exec, s[22:23]
	s_cbranch_vccnz .LBB0_571
	s_add_i32 s11, s6, 0xfffee600
	s_cmpk_gt_u32 s11, 0x9ff
	s_cselect_b64 s[20:21], -1, 0
	s_and_b64 s[22:23], s[20:21], exec
	s_cselect_b32 s12, 0xf600, 0
	s_add_i32 s12, s12, s11
	s_sext_i32_i16 s11, s12
	s_mulk_i32 s11, 0x6667
	s_mov_b64 s[22:23], s[0:1]
	s_lshr_b32 s19, s11, 31
	s_ashr_i32 s11, s11, 21
	s_add_i32 s11, s11, s19
	s_load_dwordx2 s[22:23], s[22:23], 0xe8
	s_mul_i32 s19, s11, 0x50
	s_sub_i32 s12, s12, s19
	s_and_b64 s[26:27], s[20:21], exec
	s_cselect_b32 s19, 0x2800000, 0
	s_sext_i32_i16 s12, s12
	s_waitcnt lgkmcnt(0)
	s_add_u32 s19, s22, s19
	s_addc_u32 s23, s23, 0
	s_lshl_b32 s22, s11, 6
	s_lshl_b32 s26, s12, 6
	s_and_b64 s[20:21], s[20:21], exec
	s_cselect_b32 s11, 0x1400000, 0
	s_add_u32 s11, s2, s11
	s_addc_u32 s12, s3, 0
	s_ashr_i32 s27, s26, 31
	s_lshl_b64 s[20:21], s[26:27], 2
	s_add_u32 s20, s19, s20
	s_addc_u32 s21, s23, s21
	v_lshlrev_b32_e32 v172, 2, v64
	v_add_u32_e32 v34, s22, v66
	v_lshl_add_u64 v[32:33], s[20:21], 0, v[172:173]
	s_movk_i32 s27, 0x5000
	v_mad_i64_i32 v[24:25], s[20:21], v34, s27, v[32:33]
	v_add_co_u32_e32 v4, vcc, s27, v24
	s_mov_b32 s19, 0x14000
	s_nop 0
	v_addc_co_u32_e32 v5, vcc, 0, v25, vcc
	v_add_co_u32_e32 v8, vcc, s33, v24
	s_mov_b32 s28, 0x19000
	s_nop 0
	v_addc_co_u32_e32 v9, vcc, 0, v25, vcc
	v_add_co_u32_e32 v12, vcc, s76, v24
	s_mov_b32 s23, 0x1e000
	s_nop 0
	v_addc_co_u32_e32 v13, vcc, 0, v25, vcc
	v_add_co_u32_e32 v16, vcc, s19, v24
	v_add_u32_e32 v34, 32, v34
	s_nop 0
	v_addc_co_u32_e32 v17, vcc, 0, v25, vcc
	v_add_co_u32_e32 v20, vcc, s28, v24
	v_mad_i64_i32 v[56:57], s[20:21], v34, s27, v[32:33]
	s_nop 0
	v_addc_co_u32_e32 v21, vcc, 0, v25, vcc
	v_add_co_u32_e32 v26, vcc, s23, v24
	global_load_dwordx4 v[0:3], v[24:25], off nt
	s_nop 0
	global_load_dwordx4 v[4:7], v[4:5], off nt
	v_addc_co_u32_e32 v27, vcc, 0, v25, vcc
	v_add_co_u32_e32 v28, vcc, s77, v24
	global_load_dwordx4 v[8:11], v[8:9], off nt
	s_nop 0
	global_load_dwordx4 v[12:15], v[12:13], off nt
	v_addc_co_u32_e32 v29, vcc, 0, v25, vcc
	v_add_co_u32_e32 v36, vcc, s27, v56
	global_load_dwordx4 v[16:19], v[16:17], off nt
	s_nop 0
	global_load_dwordx4 v[20:23], v[20:21], off nt
	v_addc_co_u32_e32 v37, vcc, 0, v57, vcc
	v_add_co_u32_e32 v40, vcc, s33, v56
	global_load_dwordx4 v[24:27], v[26:27], off nt
	s_nop 0
	global_load_dwordx4 v[28:31], v[28:29], off nt
	v_addc_co_u32_e32 v41, vcc, 0, v57, vcc
	v_add_co_u32_e32 v44, vcc, s76, v56
	global_load_dwordx4 v[32:35], v[56:57], off nt
	s_nop 0
	global_load_dwordx4 v[36:39], v[36:37], off nt
	v_addc_co_u32_e32 v45, vcc, 0, v57, vcc
	v_add_co_u32_e32 v48, vcc, s19, v56
	global_load_dwordx4 v[40:43], v[40:41], off nt
	s_nop 0
	global_load_dwordx4 v[44:47], v[44:45], off nt
	v_addc_co_u32_e32 v49, vcc, 0, v57, vcc
	v_add_co_u32_e32 v52, vcc, s28, v56
	v_or_b32_e32 v72, s26, v64
	s_nop 0
	v_addc_co_u32_e32 v53, vcc, 0, v57, vcc
	v_add_co_u32_e32 v58, vcc, s23, v56
	global_load_dwordx4 v[48:51], v[48:49], off nt
	s_nop 0
	global_load_dwordx4 v[52:55], v[52:53], off nt
	v_addc_co_u32_e32 v59, vcc, 0, v57, vcc
	v_add_co_u32_e32 v60, vcc, s77, v56
	s_ashr_i32 s23, s22, 31
	s_nop 0
	v_addc_co_u32_e32 v61, vcc, 0, v57, vcc
	global_load_dwordx4 v[56:59], v[58:59], off nt
	s_nop 0
	global_load_dwordx4 v[60:63], v[60:61], off nt
	s_lshl_b64 s[20:21], s[22:23], 1
	s_add_u32 s20, s11, s20
	s_addc_u32 s21, s12, s21
	v_lshl_add_u64 v[68:69], v[66:67], 1, s[20:21]
	s_mov_b64 s[20:21], 0x23500000
	v_ashrrev_i32_e32 v73, 31, v72
	v_lshl_add_u64 v[74:75], v[68:69], 0, s[20:21]
	v_lshlrev_b64 v[76:77], 12, v[72:73]
	s_waitcnt vmcnt(0)
	v_cvt_pk_bf16_f32 v68, v0, v4
	v_lshl_add_u64 v[76:77], v[74:75], 0, v[76:77]
	v_or_b32_e32 v0, 1, v72
	v_cvt_pk_bf16_f32 v69, v8, v12
	v_cvt_pk_bf16_f32 v70, v16, v20
	v_cvt_pk_bf16_f32 v71, v24, v28
	global_store_dwordx4 v[76:77], v[68:71], off nt
	s_nop 1
	v_cvt_pk_bf16_f32 v68, v1, v5
	v_ashrrev_i32_e32 v1, 31, v0
	v_lshlrev_b64 v[0:1], 12, v[0:1]
	v_lshl_add_u64 v[4:5], v[74:75], 0, v[0:1]
	v_or_b32_e32 v0, 2, v72
	v_ashrrev_i32_e32 v1, 31, v0
	v_lshlrev_b64 v[0:1], 12, v[0:1]
	v_cvt_pk_bf16_f32 v69, v9, v13
	v_cvt_pk_bf16_f32 v70, v17, v21
	v_cvt_pk_bf16_f32 v71, v25, v29
	global_store_dwordx4 v[4:5], v[68:71], off nt
	v_lshl_add_u64 v[8:9], v[74:75], 0, v[0:1]
	s_nop 0
	v_cvt_pk_bf16_f32 v68, v2, v6
	v_or_b32_e32 v6, 3, v72
	v_cvt_pk_bf16_f32 v69, v10, v14
	v_cvt_pk_bf16_f32 v70, v18, v22
	v_cvt_pk_bf16_f32 v71, v26, v30
	global_store_dwordx4 v[8:9], v[68:71], off nt
	v_cvt_pk_bf16_f32 v0, v3, v7
	v_ashrrev_i32_e32 v7, 31, v6
	v_lshlrev_b64 v[6:7], 12, v[6:7]
	v_cvt_pk_bf16_f32 v1, v11, v15
	v_cvt_pk_bf16_f32 v2, v19, v23
	v_cvt_pk_bf16_f32 v3, v27, v31
	v_lshl_add_u64 v[6:7], v[74:75], 0, v[6:7]
	global_store_dwordx4 v[6:7], v[0:3], off nt
	s_nop 1
	v_cvt_pk_bf16_f32 v0, v32, v36
	v_cvt_pk_bf16_f32 v1, v40, v44
	v_cvt_pk_bf16_f32 v2, v48, v52
	v_cvt_pk_bf16_f32 v3, v56, v60
	global_store_dwordx4 v[76:77], v[0:3], off offset:64 nt
	s_nop 1
	v_cvt_pk_bf16_f32 v0, v33, v37
	v_cvt_pk_bf16_f32 v1, v41, v45
	v_cvt_pk_bf16_f32 v2, v49, v53
	v_cvt_pk_bf16_f32 v3, v57, v61
	global_store_dwordx4 v[4:5], v[0:3], off offset:64 nt
	s_nop 1
	v_cvt_pk_bf16_f32 v0, v34, v38
	v_cvt_pk_bf16_f32 v1, v42, v46
	v_cvt_pk_bf16_f32 v2, v50, v54
	v_cvt_pk_bf16_f32 v3, v58, v62
	global_store_dwordx4 v[8:9], v[0:3], off offset:64 nt
	s_nop 1
	v_cvt_pk_bf16_f32 v0, v35, v39
	v_cvt_pk_bf16_f32 v1, v43, v47
	v_cvt_pk_bf16_f32 v2, v51, v55
	v_cvt_pk_bf16_f32 v3, v59, v63
	global_store_dwordx4 v[6:7], v[0:3], off offset:64 nt

; __device__ __forceinline__ unsigned cvt_pk_bf16(float lo, float hi) { unsigned r; asm volatile("v_cvt_pk_bf16_f32 %0, %1, %2" : "=v"(r) : "v"(lo), "v"(hi)); return r; }
; #define INP(i) ((const float*)(const GASP float*)kargs()[(i)])
; __device__ __forceinline__ void tr_item(const float* W, int ldw, int k0, int n0, bf16* WT, int ldk, int drow0, int lane) {
;     const int n4 = (lane & 15) * 4, kg = lane >> 4; f32x4 v[2][8];
; #pragma unroll
;     for (int kh = 0; kh < 2; ++kh) { const float* src = W + (size_t)(k0 + kh * 32 + kg * 8) * ldw + n0 + n4;
; #pragma unroll
;         for (int i = 0; i < 8; ++i) v[kh][i] = __builtin_nontemporal_load((const f32x4*)(src + (size_t)i * ldw)); }
; #pragma unroll
;     for (int kh = 0; kh < 2; ++kh)
; #pragma unroll
;         for (int e = 0; e < 4; ++e) { u32x4 o; o.x = cvt_pk_bf16(v[kh][0][e], v[kh][1][e]); o.y = cvt_pk_bf16(v[kh][2][e], v[kh][3][e]); o.z = cvt_pk_bf16(v[kh][4][e], v[kh][5][e]); o.w = cvt_pk_bf16(v[kh][6][e], v[kh][7][e]);
;             *(u32x4*)(WT + (size_t)(drow0 + n4 + e) * ldk + k0 + kh * 32 + kg * 8) = o; }
; }
; __device__ __forceinline__ void conv_item(int it, int lane) {
;     ...
;     if (r < 2 * IT_OUTAB) { const int idx = r / IT_OUTAB; r -= idx * IT_OUTAB; const int kb = r / 32, nb = r % 32;
;         tr_item(INP(I_WOUTAB) + (size_t)idx * 2048 * 2048, 2048, 64 * kb, 64 * nb, (bf16*)(ws + WS_WOUTAB) + (size_t)idx * 2048 * 2048, 2048, 64 * nb, lane); return; }
.LBB0_572:
	s_andn2_b64 vcc, exec, s[22:23]
	s_cbranch_vccnz .LBB0_574
	s_mov_b64 s[20:21], s[0:1]
	s_load_dwordx2 s[20:21], s[20:21], 0xe0
	s_add_i32 s11, s6, 0xfffeee00
	s_lshr_b32 s38, s11, 10
	s_lshl_b64 s[22:23], s[38:39], 24
	v_lshlrev_b32_e32 v172, 2, v64
	s_waitcnt lgkmcnt(0)
	s_add_u32 s12, s20, s22
	s_addc_u32 s19, s21, s23
	s_lshl_b32 s11, s11, 1
	s_lshl_b32 s20, s6, 6
	s_and_b32 s11, s11, 0x7c0
	s_and_b32 s22, s20, 0x7c0
	s_lshl_b64 s[20:21], s[38:39], 23
	s_add_u32 s23, s2, s20
	s_addc_u32 s26, s3, s21
	s_lshl_b32 s20, s22, 2
	v_add_u32_e32 v32, s11, v66
	s_add_u32 s20, s12, s20
	s_addc_u32 s21, s19, 0
	v_ashrrev_i32_e32 v33, 31, v32
	v_lshl_add_u64 v[34:35], s[20:21], 0, v[172:173]
	v_lshlrev_b64 v[0:1], 13, v[32:33]
	v_lshl_add_u64 v[24:25], v[34:35], 0, v[0:1]
	v_add_co_u32_e32 v4, vcc, s89, v24
	s_movk_i32 s19, 0x4000
	s_nop 0
	v_addc_co_u32_e32 v5, vcc, 0, v25, vcc
	v_add_co_u32_e32 v8, vcc, s19, v24
	s_movk_i32 s12, 0x6000
	s_nop 0
	v_addc_co_u32_e32 v9, vcc, 0, v25, vcc
	v_add_co_u32_e32 v12, vcc, s12, v24
	s_mov_b32 s20, 0x8000
	s_nop 0
	v_addc_co_u32_e32 v13, vcc, 0, v25, vcc
	v_add_co_u32_e32 v16, vcc, s20, v24
	s_mov_b32 s38, 0xc000
	s_nop 0
	v_addc_co_u32_e32 v17, vcc, 0, v25, vcc
	v_add_co_u32_e32 v20, vcc, s33, v24
	v_add_u32_e32 v32, 32, v32
	s_nop 0
	v_addc_co_u32_e32 v21, vcc, 0, v25, vcc
	v_add_co_u32_e32 v26, vcc, s38, v24
	s_mov_b32 s21, 0xe000
	s_nop 0
	v_addc_co_u32_e32 v27, vcc, 0, v25, vcc
	v_ashrrev_i32_e32 v33, 31, v32
	v_add_co_u32_e32 v28, vcc, s21, v24
	v_lshlrev_b64 v[32:33], 13, v[32:33]
	s_nop 0
	v_addc_co_u32_e32 v29, vcc, 0, v25, vcc
	v_lshl_add_u64 v[56:57], v[34:35], 0, v[32:33]
	v_add_co_u32_e32 v36, vcc, s89, v56
	global_load_dwordx4 v[0:3], v[24:25], off nt
	s_nop 0
	global_load_dwordx4 v[4:7], v[4:5], off nt
	v_addc_co_u32_e32 v37, vcc, 0, v57, vcc
	v_add_co_u32_e32 v40, vcc, s19, v56
	global_load_dwordx4 v[8:11], v[8:9], off nt
	s_nop 0
	global_load_dwordx4 v[12:15], v[12:13], off nt
	v_addc_co_u32_e32 v41, vcc, 0, v57, vcc
	v_add_co_u32_e32 v44, vcc, s12, v56
	global_load_dwordx4 v[16:19], v[16:17], off nt
	s_nop 0
	global_load_dwordx4 v[20:23], v[20:21], off nt
	v_addc_co_u32_e32 v45, vcc, 0, v57, vcc
	v_add_co_u32_e32 v48, vcc, s20, v56
	global_load_dwordx4 v[24:27], v[26:27], off nt
	s_nop 0
	global_load_dwordx4 v[28:31], v[28:29], off nt
	v_addc_co_u32_e32 v49, vcc, 0, v57, vcc
	v_add_co_u32_e32 v52, vcc, s33, v56
	global_load_dwordx4 v[32:35], v[56:57], off nt
	s_nop 0
	global_load_dwordx4 v[36:39], v[36:37], off nt
	v_addc_co_u32_e32 v53, vcc, 0, v57, vcc
	v_add_co_u32_e32 v58, vcc, s38, v56
	global_load_dwordx4 v[40:43], v[40:41], off nt
	s_nop 0
	global_load_dwordx4 v[44:47], v[44:45], off nt
	v_addc_co_u32_e32 v59, vcc, 0, v57, vcc
	v_add_co_u32_e32 v60, vcc, s21, v56
	global_load_dwordx4 v[48:51], v[48:49], off nt
	s_nop 0
	global_load_dwordx4 v[52:55], v[52:53], off nt
	v_addc_co_u32_e32 v61, vcc, 0, v57, vcc
	global_load_dwordx4 v[56:59], v[58:59], off nt
	s_nop 0
	global_load_dwordx4 v[60:63], v[60:61], off nt
	s_lshl_b32 s11, s11, 1
	s_add_u32 s20, s23, s11
	s_addc_u32 s21, s26, 0
	v_or_b32_e32 v65, s22, v64
	v_lshl_add_u64 v[72:73], v[66:67], 1, s[20:21]
	s_mov_b64 s[20:21], 0x22500000
	v_lshl_add_u64 v[74:75], v[72:73], 0, s[20:21]
	v_lshlrev_b32_e32 v172, 12, v65
	s_waitcnt vmcnt(0)
	v_cvt_pk_bf16_f32 v68, v0, v4
	v_lshl_add_u64 v[76:77], v[74:75], 0, v[172:173]
	v_cvt_pk_bf16_f32 v69, v8, v12
	v_cvt_pk_bf16_f32 v70, v16, v20
	v_cvt_pk_bf16_f32 v71, v24, v28
	global_store_dwordx4 v[76:77], v[68:71], off nt
	v_or_b32_e32 v4, 0x1000, v172
	v_or_b32_e32 v8, 0x2000, v172
	v_cvt_pk_bf16_f32 v68, v1, v5
	v_mov_b32_e32 v5, v173
	v_cvt_pk_bf16_f32 v69, v9, v13
	v_lshl_add_u64 v[0:1], v[74:75], 0, v[4:5]
	v_mov_b32_e32 v9, v173
	v_cvt_pk_bf16_f32 v70, v17, v21
	v_cvt_pk_bf16_f32 v71, v25, v29
	global_store_dwordx4 v[0:1], v[68:71], off nt
	v_lshl_add_u64 v[0:1], v[74:75], 0, v[8:9]
	v_or_b32_e32 v172, 0x3000, v172
	v_cvt_pk_bf16_f32 v68, v2, v6
	v_cvt_pk_bf16_f32 v69, v10, v14
	v_cvt_pk_bf16_f32 v70, v18, v22
	v_cvt_pk_bf16_f32 v71, v26, v30
	global_store_dwordx4 v[0:1], v[68:71], off nt
	v_cvt_pk_bf16_f32 v0, v3, v7
	v_lshl_add_u64 v[6:7], v[74:75], 0, v[172:173]
	s_mov_b64 s[20:21], 0x22500040
	v_cvt_pk_bf16_f32 v1, v11, v15
	v_cvt_pk_bf16_f32 v2, v19, v23
	v_cvt_pk_bf16_f32 v3, v27, v31
	global_store_dwordx4 v[6:7], v[0:3], off nt
	v_lshl_add_u64 v[6:7], v[72:73], 0, s[20:21]
	v_lshl_add_u64 v[4:5], v[6:7], 0, v[4:5]
	v_cvt_pk_bf16_f32 v0, v32, v36
	v_cvt_pk_bf16_f32 v1, v40, v44
	v_cvt_pk_bf16_f32 v2, v48, v52
	v_cvt_pk_bf16_f32 v3, v56, v60
	global_store_dwordx4 v[76:77], v[0:3], off offset:64 nt
	s_nop 1
	v_cvt_pk_bf16_f32 v0, v33, v37
	v_cvt_pk_bf16_f32 v1, v41, v45
	v_cvt_pk_bf16_f32 v2, v49, v53
	v_cvt_pk_bf16_f32 v3, v57, v61
	global_store_dwordx4 v[4:5], v[0:3], off nt
	v_lshl_add_u64 v[4:5], v[6:7], 0, v[8:9]
	s_nop 0
	v_cvt_pk_bf16_f32 v0, v34, v38
	v_cvt_pk_bf16_f32 v1, v42, v46
	v_cvt_pk_bf16_f32 v2, v50, v54
	v_cvt_pk_bf16_f32 v3, v58, v62
	global_store_dwordx4 v[4:5], v[0:3], off nt
	v_lshl_add_u64 v[4:5], v[6:7], 0, v[172:173]
	s_nop 0
	v_cvt_pk_bf16_f32 v0, v35, v39
	v_cvt_pk_bf16_f32 v1, v43, v47
	v_cvt_pk_bf16_f32 v2, v51, v55
	v_cvt_pk_bf16_f32 v3, v59, v63
	global_store_dwordx4 v[4:5], v[0:3], off nt

; __device__ __forceinline__ unsigned cvt_pk_bf16(float lo, float hi) { unsigned r; asm volatile("v_cvt_pk_bf16_f32 %0, %1, %2" : "=v"(r) : "v"(lo), "v"(hi)); return r; }
; #define INP(i) ((const float*)(const GASP float*)kargs()[(i)])
; __device__ __forceinline__ void tr_item(const float* W, int ldw, int k0, int n0, bf16* WT, int ldk, int drow0, int lane) {
;     const int n4 = (lane & 15) * 4, kg = lane >> 4; f32x4 v[2][8];
; #pragma unroll
;     for (int kh = 0; kh < 2; ++kh) { const float* src = W + (size_t)(k0 + kh * 32 + kg * 8) * ldw + n0 + n4;
; #pragma unroll
;         for (int i = 0; i < 8; ++i) v[kh][i] = __builtin_nontemporal_load((const f32x4*)(src + (size_t)i * ldw)); }
; #pragma unroll
;     for (int kh = 0; kh < 2; ++kh)
; #pragma unroll
;         for (int e = 0; e < 4; ++e) { u32x4 o; o.x = cvt_pk_bf16(v[kh][0][e], v[kh][1][e]); o.y = cvt_pk_bf16(v[kh][2][e], v[kh][3][e]); o.z = cvt_pk_bf16(v[kh][4][e], v[kh][5][e]); o.w = cvt_pk_bf16(v[kh][6][e], v[kh][7][e]);
;             *(u32x4*)(WT + (size_t)(drow0 + n4 + e) * ldk + k0 + kh * 32 + kg * 8) = o; }
; }
; __device__ __forceinline__ void conv_item(int it, int lane) {
;     ...
;     if (r < 2 * IT_INAB) { const int idx = r / IT_INAB; r -= idx * IT_INAB; const int kb = r / 80, nb = r % 80;
;         tr_item(INP(I_WINAB) + (size_t)idx * 2048 * 5120, 5120, 64 * kb, 64 * nb, (bf16*)(ws + WS_WINAB) + (size_t)idx * 5120 * 2048, 2048, 64 * nb, lane); return; }
.LBB0_578:
	s_andn2_b64 vcc, exec, s[22:23]
	s_cbranch_vccnz .LBB0_580
	s_add_i32 s11, s6, 0xffff0400
	s_cmpk_gt_u32 s11, 0x9ff
	s_cselect_b64 s[20:21], -1, 0
	s_and_b64 s[22:23], s[20:21], exec
	s_cselect_b32 s12, 0xf600, 0
	s_add_i32 s12, s12, s11
	s_sext_i32_i16 s11, s12
	s_mulk_i32 s11, 0x6667
	s_mov_b64 s[22:23], s[0:1]
	s_lshr_b32 s19, s11, 31
	s_ashr_i32 s11, s11, 21
	s_add_i32 s11, s11, s19
	s_load_dwordx2 s[22:23], s[22:23], 0x78
	s_mul_i32 s19, s11, 0x50
	s_sub_i32 s12, s12, s19
	s_and_b64 s[26:27], s[20:21], exec
	s_cselect_b32 s19, 0x2800000, 0
	s_sext_i32_i16 s12, s12
	s_waitcnt lgkmcnt(0)
	s_add_u32 s19, s22, s19
	s_addc_u32 s23, s23, 0
	s_lshl_b32 s22, s11, 6
	s_lshl_b32 s26, s12, 6
	s_and_b64 s[20:21], s[20:21], exec
	s_cselect_b32 s11, 0x1400000, 0
	s_add_u32 s11, s2, s11
	s_addc_u32 s12, s3, 0
	s_ashr_i32 s27, s26, 31
	s_lshl_b64 s[20:21], s[26:27], 2
	s_add_u32 s20, s19, s20
	s_addc_u32 s21, s23, s21
	v_lshlrev_b32_e32 v172, 2, v64
	v_add_u32_e32 v34, s22, v66
	v_lshl_add_u64 v[32:33], s[20:21], 0, v[172:173]
	s_movk_i32 s27, 0x5000
	v_mad_i64_i32 v[24:25], s[20:21], v34, s27, v[32:33]
	v_add_co_u32_e32 v4, vcc, s27, v24
	s_mov_b32 s19, 0x14000
	s_nop 0
	v_addc_co_u32_e32 v5, vcc, 0, v25, vcc
	v_add_co_u32_e32 v8, vcc, s33, v24
	s_mov_b32 s28, 0x19000
	s_nop 0
	v_addc_co_u32_e32 v9, vcc, 0, v25, vcc
	v_add_co_u32_e32 v12, vcc, s76, v24
	s_mov_b32 s23, 0x1e000
	s_nop 0
	v_addc_co_u32_e32 v13, vcc, 0, v25, vcc
	v_add_co_u32_e32 v16, vcc, s19, v24
	v_add_u32_e32 v34, 32, v34
	s_nop 0
	v_addc_co_u32_e32 v17, vcc, 0, v25, vcc
	v_add_co_u32_e32 v20, vcc, s28, v24
	v_mad_i64_i32 v[56:57], s[20:21], v34, s27, v[32:33]
	s_nop 0
	v_addc_co_u32_e32 v21, vcc, 0, v25, vcc
	v_add_co_u32_e32 v26, vcc, s23, v24
	global_load_dwordx4 v[0:3], v[24:25], off nt
	s_nop 0
	global_load_dwordx4 v[4:7], v[4:5], off nt
	v_addc_co_u32_e32 v27, vcc, 0, v25, vcc
	v_add_co_u32_e32 v28, vcc, s77, v24
	global_load_dwordx4 v[8:11], v[8:9], off nt
	s_nop 0
	global_load_dwordx4 v[12:15], v[12:13], off nt
	v_addc_co_u32_e32 v29, vcc, 0, v25, vcc
	v_add_co_u32_e32 v36, vcc, s27, v56
	global_load_dwordx4 v[16:19], v[16:17], off nt
	s_nop 0
	global_load_dwordx4 v[20:23], v[20:21], off nt
	v_addc_co_u32_e32 v37, vcc, 0, v57, vcc
	v_add_co_u32_e32 v40, vcc, s33, v56
	global_load_dwordx4 v[24:27], v[26:27], off nt
	s_nop 0
	global_load_dwordx4 v[28:31], v[28:29], off nt
	v_addc_co_u32_e32 v41, vcc, 0, v57, vcc
	v_add_co_u32_e32 v44, vcc, s76, v56
	global_load_dwordx4 v[32:35], v[56:57], off nt
	s_nop 0
	global_load_dwordx4 v[36:39], v[36:37], off nt
	v_addc_co_u32_e32 v45, vcc, 0, v57, vcc
	v_add_co_u32_e32 v48, vcc, s19, v56
	global_load_dwordx4 v[40:43], v[40:41], off nt
	s_nop 0
	global_load_dwordx4 v[44:47], v[44:45], off nt
	v_addc_co_u32_e32 v49, vcc, 0, v57, vcc
	v_add_co_u32_e32 v52, vcc, s28, v56
	v_or_b32_e32 v72, s26, v64
	s_nop 0
	v_addc_co_u32_e32 v53, vcc, 0, v57, vcc
	v_add_co_u32_e32 v58, vcc, s23, v56
	global_load_dwordx4 v[48:51], v[48:49], off nt
	s_nop 0
	global_load_dwordx4 v[52:55], v[52:53], off nt
	v_addc_co_u32_e32 v59, vcc, 0, v57, vcc
	v_add_co_u32_e32 v60, vcc, s77, v56
	s_ashr_i32 s23, s22, 31
	s_nop 0
	v_addc_co_u32_e32 v61, vcc, 0, v57, vcc
	global_load_dwordx4 v[56:59], v[58:59], off nt
	s_nop 0
	global_load_dwordx4 v[60:63], v[60:61], off nt
	s_lshl_b64 s[20:21], s[22:23], 1
	s_add_u32 s20, s11, s20
	s_addc_u32 s21, s12, s21
	v_lshl_add_u64 v[68:69], v[66:67], 1, s[20:21]
	s_mov_b64 s[20:21], 0x1f900000
	v_ashrrev_i32_e32 v73, 31, v72
	v_lshl_add_u64 v[74:75], v[68:69], 0, s[20:21]
	v_lshlrev_b64 v[76:77], 12, v[72:73]
	s_waitcnt vmcnt(0)
	v_cvt_pk_bf16_f32 v68, v0, v4
	v_lshl_add_u64 v[76:77], v[74:75], 0, v[76:77]
	v_or_b32_e32 v0, 1, v72
	v_cvt_pk_bf16_f32 v69, v8, v12
	v_cvt_pk_bf16_f32 v70, v16, v20
	v_cvt_pk_bf16_f32 v71, v24, v28
	global_store_dwordx4 v[76:77], v[68:71], off nt
	s_nop 1
	v_cvt_pk_bf16_f32 v68, v1, v5
	v_ashrrev_i32_e32 v1, 31, v0
	v_lshlrev_b64 v[0:1], 12, v[0:1]
	v_lshl_add_u64 v[4:5], v[74:75], 0, v[0:1]
	v_or_b32_e32 v0, 2, v72
	v_ashrrev_i32_e32 v1, 31, v0
	v_lshlrev_b64 v[0:1], 12, v[0:1]
	v_cvt_pk_bf16_f32 v69, v9, v13
	v_cvt_pk_bf16_f32 v70, v17, v21
	v_cvt_pk_bf16_f32 v71, v25, v29
	global_store_dwordx4 v[4:5], v[68:71], off nt
	v_lshl_add_u64 v[8:9], v[74:75], 0, v[0:1]
	s_nop 0
	v_cvt_pk_bf16_f32 v68, v2, v6
	v_or_b32_e32 v6, 3, v72
	v_cvt_pk_bf16_f32 v69, v10, v14
	v_cvt_pk_bf16_f32 v70, v18, v22
	v_cvt_pk_bf16_f32 v71, v26, v30
	global_store_dwordx4 v[8:9], v[68:71], off nt
	v_cvt_pk_bf16_f32 v0, v3, v7
	v_ashrrev_i32_e32 v7, 31, v6
	v_lshlrev_b64 v[6:7], 12, v[6:7]
	v_cvt_pk_bf16_f32 v1, v11, v15
	v_cvt_pk_bf16_f32 v2, v19, v23
	v_cvt_pk_bf16_f32 v3, v27, v31
	v_lshl_add_u64 v[6:7], v[74:75], 0, v[6:7]
	global_store_dwordx4 v[6:7], v[0:3], off nt
	s_nop 1
	v_cvt_pk_bf16_f32 v0, v32, v36
	v_cvt_pk_bf16_f32 v1, v40, v44
	v_cvt_pk_bf16_f32 v2, v48, v52
	v_cvt_pk_bf16_f32 v3, v56, v60
	global_store_dwordx4 v[76:77], v[0:3], off offset:64 nt
	s_nop 1
	v_cvt_pk_bf16_f32 v0, v33, v37
	v_cvt_pk_bf16_f32 v1, v41, v45
	v_cvt_pk_bf16_f32 v2, v49, v53
	v_cvt_pk_bf16_f32 v3, v57, v61
	global_store_dwordx4 v[4:5], v[0:3], off offset:64 nt
	s_nop 1
	v_cvt_pk_bf16_f32 v0, v34, v38
	v_cvt_pk_bf16_f32 v1, v42, v46
	v_cvt_pk_bf16_f32 v2, v50, v54
	v_cvt_pk_bf16_f32 v3, v58, v62
	global_store_dwordx4 v[8:9], v[0:3], off offset:64 nt
	s_nop 1
	v_cvt_pk_bf16_f32 v0, v35, v39
	v_cvt_pk_bf16_f32 v1, v43, v47
	v_cvt_pk_bf16_f32 v2, v51, v55
	v_cvt_pk_bf16_f32 v3, v59, v63
	global_store_dwordx4 v[6:7], v[0:3], off offset:64 nt

; __device__ __forceinline__ unsigned cvt_pk_bf16(float lo, float hi) { unsigned r; asm volatile("v_cvt_pk_bf16_f32 %0, %1, %2" : "=v"(r) : "v"(lo), "v"(hi)); return r; }
; #define INP(i) ((const float*)(const GASP float*)kargs()[(i)])
; __device__ __forceinline__ void tr_item(const float* W, int ldw, int k0, int n0, bf16* WT, int ldk, int drow0, int lane) {
;     const int n4 = (lane & 15) * 4, kg = lane >> 4; f32x4 v[2][8];
; #pragma unroll
;     for (int kh = 0; kh < 2; ++kh) { const float* src = W + (size_t)(k0 + kh * 32 + kg * 8) * ldw + n0 + n4;
; #pragma unroll
;         for (int i = 0; i < 8; ++i) v[kh][i] = __builtin_nontemporal_load((const f32x4*)(src + (size_t)i * ldw)); }
; #pragma unroll
;     for (int kh = 0; kh < 2; ++kh)
; #pragma unroll
;         for (int e = 0; e < 4; ++e) { u32x4 o; o.x = cvt_pk_bf16(v[kh][0][e], v[kh][1][e]); o.y = cvt_pk_bf16(v[kh][2][e], v[kh][3][e]); o.z = cvt_pk_bf16(v[kh][4][e], v[kh][5][e]); o.w = cvt_pk_bf16(v[kh][6][e], v[kh][7][e]);
;             *(u32x4*)(WT + (size_t)(drow0 + n4 + e) * ldk + k0 + kh * 32 + kg * 8) = o; }
; }
; __device__ __forceinline__ void conv_item(int it, int lane) {
;     ...
;     if (r < 8 * IT_D) { const int idx = r / IT_D; r -= idx * IT_D; const int kb = r / 32, nb = r % 32;
;         tr_item(INP(I_WD) + (size_t)idx * 5376 * 2048, 2048, 64 * kb, 64 * nb, (bf16*)(ws + WS_WD) + (size_t)idx * 2048 * 5376, 5376, 64 * nb, lane); return; }
.LBB0_581:
	s_andn2_b64 vcc, exec, s[22:23]
	s_cbranch_vccnz .LBB0_583
	s_add_i32 s11, s6, 0xffff5800
	s_bfe_u32 s12, s11, 0x100007
	s_mulk_i32 s12, 0xc31
	s_lshr_b32 s12, s12, 16
	s_mul_i32 s19, s12, 0xf580
	s_mov_b64 s[20:21], s[0:1]
	s_add_i32 s11, s19, s11
	s_sext_i32_i16 s19, s11
	s_load_dwordx2 s[20:21], s[20:21], 0x70
	s_bfe_u32 s19, s19, 0x5001a
	s_add_i32 s19, s11, s19
	s_sext_i32_i16 s22, s19
	s_and_b32 s19, s19, 0xffe0
	s_sub_i32 s11, s11, s19
	s_mul_i32 s19, s12, 0x2a00000
	s_waitcnt lgkmcnt(0)
	s_add_u32 s19, s20, s19
	s_sext_i32_i16 s11, s11
	s_addc_u32 s23, s21, 0
	s_lshl_b32 s20, s22, 1
	s_and_b32 s22, s20, 0xffffffc0
	s_lshl_b32 s26, s11, 6
	s_mul_i32 s12, s12, 0x1500000
	s_add_u32 s11, s2, s12
	s_addc_u32 s12, s3, 0
	s_ashr_i32 s27, s26, 31
	s_lshl_b64 s[20:21], s[26:27], 2
	v_add_u32_e32 v32, s22, v66
	s_add_u32 s20, s19, s20
	s_addc_u32 s21, s23, s21
	v_lshlrev_b32_e32 v172, 2, v64
	v_ashrrev_i32_e32 v33, 31, v32
	v_lshl_add_u64 v[34:35], s[20:21], 0, v[172:173]
	v_lshlrev_b64 v[0:1], 13, v[32:33]
	v_lshl_add_u64 v[24:25], v[34:35], 0, v[0:1]
	v_add_co_u32_e32 v4, vcc, s89, v24
	s_movk_i32 s20, 0x4000
	s_nop 0
	v_addc_co_u32_e32 v5, vcc, 0, v25, vcc
	v_add_co_u32_e32 v8, vcc, s20, v24
	s_movk_i32 s19, 0x6000
	s_nop 0
	v_addc_co_u32_e32 v9, vcc, 0, v25, vcc
	v_add_co_u32_e32 v12, vcc, s19, v24
	s_mov_b32 s21, 0x8000
	s_nop 0
	v_addc_co_u32_e32 v13, vcc, 0, v25, vcc
	v_add_co_u32_e32 v16, vcc, s21, v24
	v_add_u32_e32 v32, 32, v32
	s_nop 0
	v_addc_co_u32_e32 v17, vcc, 0, v25, vcc
	v_add_co_u32_e32 v20, vcc, s33, v24
	s_mov_b32 s23, 0xe000
	s_nop 0
	v_addc_co_u32_e32 v21, vcc, 0, v25, vcc
	v_add_co_u32_e32 v26, vcc, s38, v24
	v_ashrrev_i32_e32 v33, 31, v32
	s_nop 0
	v_addc_co_u32_e32 v27, vcc, 0, v25, vcc
	v_add_co_u32_e32 v28, vcc, s23, v24
	v_lshlrev_b64 v[32:33], 13, v[32:33]
	s_nop 0
	v_addc_co_u32_e32 v29, vcc, 0, v25, vcc
	v_lshl_add_u64 v[56:57], v[34:35], 0, v[32:33]
	v_add_co_u32_e32 v36, vcc, s89, v56
	global_load_dwordx4 v[0:3], v[24:25], off nt
	s_nop 0
	global_load_dwordx4 v[4:7], v[4:5], off nt
	v_addc_co_u32_e32 v37, vcc, 0, v57, vcc
	v_add_co_u32_e32 v40, vcc, s20, v56
	global_load_dwordx4 v[8:11], v[8:9], off nt
	s_nop 0
	global_load_dwordx4 v[12:15], v[12:13], off nt
	v_addc_co_u32_e32 v41, vcc, 0, v57, vcc
	v_add_co_u32_e32 v44, vcc, s19, v56
	global_load_dwordx4 v[16:19], v[16:17], off nt
	s_nop 0
	global_load_dwordx4 v[20:23], v[20:21], off nt
	v_addc_co_u32_e32 v45, vcc, 0, v57, vcc
	v_add_co_u32_e32 v48, vcc, s21, v56
	global_load_dwordx4 v[24:27], v[26:27], off nt
	s_nop 0
	global_load_dwordx4 v[28:31], v[28:29], off nt
	v_addc_co_u32_e32 v49, vcc, 0, v57, vcc
	v_add_co_u32_e32 v52, vcc, s33, v56
	global_load_dwordx4 v[32:35], v[56:57], off nt
	s_nop 0
	global_load_dwordx4 v[36:39], v[36:37], off nt
	v_addc_co_u32_e32 v53, vcc, 0, v57, vcc
	v_add_co_u32_e32 v58, vcc, s38, v56
	global_load_dwordx4 v[40:43], v[40:41], off nt
	s_nop 0
	global_load_dwordx4 v[44:47], v[44:45], off nt
	v_addc_co_u32_e32 v59, vcc, 0, v57, vcc
	v_add_co_u32_e32 v60, vcc, s23, v56
	global_load_dwordx4 v[48:51], v[48:49], off nt
	s_nop 0
	global_load_dwordx4 v[52:55], v[52:53], off nt
	v_addc_co_u32_e32 v61, vcc, 0, v57, vcc
	global_load_dwordx4 v[56:59], v[58:59], off nt
	s_nop 0
	global_load_dwordx4 v[60:63], v[60:61], off nt
	s_ashr_i32 s23, s22, 31
	s_lshl_b64 s[20:21], s[22:23], 1
	v_or_b32_e32 v65, s26, v64
	s_add_u32 s20, s11, s20
	s_addc_u32 s21, s12, s21
	v_mul_i32_i24_e32 v74, 0x1500, v65
	v_lshl_add_u64 v[72:73], v[66:67], 1, s[20:21]
	v_ashrrev_i32_e32 v75, 31, v74
	v_lshl_add_u64 v[72:73], v[74:75], 1, v[72:73]
	s_mov_b32 s11, 0x15100000
	v_add_co_u32_e32 v76, vcc, s11, v72
	s_mov_b32 s11, 0x15102000
	s_nop 0
	v_addc_co_u32_e32 v77, vcc, 0, v73, vcc
	s_waitcnt vmcnt(0)
	v_cvt_pk_bf16_f32 v68, v0, v4
	v_add_co_u32_e32 v4, vcc, s11, v72
	v_cvt_pk_bf16_f32 v69, v8, v12
	v_cvt_pk_bf16_f32 v70, v16, v20
	v_cvt_pk_bf16_f32 v71, v24, v28
	global_store_dwordx4 v[76:77], v[68:71], off nt
	s_mov_b32 s11, 0x15105000
	s_mov_b64 s[20:21], 0x15100000
	v_cvt_pk_bf16_f32 v68, v1, v5
	v_addc_co_u32_e32 v5, vcc, 0, v73, vcc
	v_add_co_u32_e32 v8, vcc, s11, v72
	v_cvt_pk_bf16_f32 v69, v9, v13
	s_mov_b32 s11, 0x15107000
	s_nop 0
	v_addc_co_u32_e32 v9, vcc, 0, v73, vcc
	v_cvt_pk_bf16_f32 v70, v17, v21
	v_cvt_pk_bf16_f32 v71, v25, v29
	global_store_dwordx4 v[4:5], v[68:71], off offset:2560 nt
	v_lshl_add_u64 v[74:75], v[72:73], 0, s[20:21]
	s_nop 0
	v_cvt_pk_bf16_f32 v68, v2, v6
	v_add_co_u32_e32 v6, vcc, s11, v72
	v_cvt_pk_bf16_f32 v69, v10, v14
	v_cvt_pk_bf16_f32 v70, v18, v22
	v_cvt_pk_bf16_f32 v71, v26, v30
	global_store_dwordx4 v[8:9], v[68:71], off offset:1024 nt
	v_cvt_pk_bf16_f32 v0, v3, v7
	v_cvt_pk_bf16_f32 v1, v11, v15
	v_cvt_pk_bf16_f32 v2, v19, v23
	v_cvt_pk_bf16_f32 v3, v27, v31
	s_nop 0
	v_addc_co_u32_e32 v7, vcc, 0, v73, vcc
	global_store_dwordx4 v[6:7], v[0:3], off offset:3584 nt
	s_nop 1
	v_cvt_pk_bf16_f32 v0, v32, v36
	v_cvt_pk_bf16_f32 v1, v40, v44
	v_cvt_pk_bf16_f32 v2, v48, v52
	v_cvt_pk_bf16_f32 v3, v56, v60
	global_store_dwordx4 v[74:75], v[0:3], off offset:64 nt
	s_nop 1
	v_cvt_pk_bf16_f32 v0, v33, v37
	v_cvt_pk_bf16_f32 v1, v41, v45
	v_cvt_pk_bf16_f32 v2, v49, v53
	v_cvt_pk_bf16_f32 v3, v57, v61
	global_store_dwordx4 v[4:5], v[0:3], off offset:2624 nt
	s_nop 1
	v_cvt_pk_bf16_f32 v0, v34, v38
	v_cvt_pk_bf16_f32 v1, v42, v46
	v_cvt_pk_bf16_f32 v2, v50, v54
	v_cvt_pk_bf16_f32 v3, v58, v62
	global_store_dwordx4 v[8:9], v[0:3], off offset:1088 nt
	s_nop 1
	v_cvt_pk_bf16_f32 v0, v35, v39
	v_cvt_pk_bf16_f32 v1, v43, v47
	v_cvt_pk_bf16_f32 v2, v51, v55
	v_cvt_pk_bf16_f32 v3, v59, v63
	global_store_dwordx4 v[6:7], v[0:3], off offset:3648 nt

; __device__ __forceinline__ void tr_item(const float* W, int ldw, int k0, int n0, bf16* WT, int ldk, int drow0, int lane) {
; __device__ __forceinline__ void conv_item(int it, int lane) {
;     ...
;     if (r < 8 * IT_GU) { const int idx = r / IT_GU; r -= idx * IT_GU; const int kb = r / 168, nb = r % 168, n0 = 64 * nb;
;         const int drow = n0 < DFF ? (n0 >> 7) * 256 + (n0 & 127) : ((n0 - DFF) >> 7) * 256 + 128 + ((n0 - DFF) & 127);
;         tr_item(INP(I_WGU) + (size_t)idx * 2048 * 10752, 10752, 64 * kb, n0, (bf16*)(ws + WS_WGU) + (size_t)idx * 10752 * 2048, 2048, drow, lane); return; }
;     r -= 8 * IT_GU;
;     if (r < 8 * IT_D) { const int idx = r / IT_D; r -= idx * IT_D; const int kb = r / 32, nb = r % 32;
;         tr_item(INP(I_WD) + (size_t)idx * 5376 * 2048, 2048, 64 * kb, 64 * nb, (bf16*)(ws + WS_WD) + (size_t)idx * 2048 * 5376, 5376, 64 * nb, lane); return; }
;     r -= 8 * IT_D;
;     if (r < 2 * IT_INAB) { const int idx = r / IT_INAB; r -= idx * IT_INAB; const int kb = r / 80, nb = r % 80;
;         tr_item(INP(I_WINAB) + (size_t)idx * 2048 * 5120, 5120, 64 * kb, 64 * nb, (bf16*)(ws + WS_WINAB) + (size_t)idx * 5120 * 2048, 2048, 64 * nb, lane); return; }
;     r -= 2 * IT_INAB;
;     if (r < 2 * IT_GLU) { const int idx = r / IT_GLU; r -= idx * IT_GLU; const int kb = r / 16, nb = r % 16;
;         tr_item(INP(I_WGLU) + (size_t)idx * 1024 * 1024, 1024, 64 * kb, 64 * nb, (bf16*)(ws + WS_WGLU) + (size_t)idx * 1024 * 1024, 1024, 64 * nb, lane); return; }
;     r -= 2 * IT_GLU;
;     if (r < 2 * IT_OUTAB) { const int idx = r / IT_OUTAB; r -= idx * IT_OUTAB; const int kb = r / 32, nb = r % 32;
;         tr_item(INP(I_WOUTAB) + (size_t)idx * 2048 * 2048, 2048, 64 * kb, 64 * nb, (bf16*)(ws + WS_WOUTAB) + (size_t)idx * 2048 * 2048, 2048, 64 * nb, lane); return; }
;     r -= 2 * IT_OUTAB;
;     if (r < 2 * IT_INC) { const int idx = r / IT_INC; r -= idx * IT_INC; const int kb = r / 80, nb = r % 80;
;         tr_item(INP(I_WINC) + (size_t)idx * 2048 * 5120, 5120, 64 * kb, 64 * nb, (bf16*)(ws + WS_WINC) + (size_t)idx * 5120 * 2048, 2048, 64 * nb, lane); return; }
;     r -= 2 * IT_INC;
;     { const int idx = r / IT_OUTC; r -= idx * IT_OUTC; const int kb = r / 32, nb = r % 32;
;       tr_item(INP(I_WOUTC) + (size_t)idx * 2560 * 2048, 2048, 64 * kb, 64 * nb, (bf16*)(ws + WS_WOUTC) + (size_t)idx * 2048 * 2560, 2560, 64 * nb, lane); }
.LBB0_1345:
	s_add_i32 s6, s12, s16
	s_mov_b64 s[12:13], s[0:1]
	s_load_dwordx2 s[26:27], s[12:13], 0x138
	v_lshlrev_b32_e32 v0, 2, v174
	s_waitcnt vmcnt(0)
	v_and_b32_e32 v72, 60, v0
	v_ashrrev_i32_e32 v0, 1, v174
	v_and_b32_e32 v64, -8, v0
	v_ashrrev_i32_e32 v65, 31, v64
	s_mov_b64 s[22:23], -1
	s_cmp_gt_i32 s6, 0xa7ff
	s_cbranch_scc0 .LBB0_1367
	s_cmpk_gt_u32 s6, 0xfbff
	s_cbranch_scc0 .LBB0_1364
	s_cmp_gt_u32 s6, 0x10fff
	s_cbranch_scc0 .LBB0_1361
	s_cmp_gt_u32 s6, 0x111ff
	s_cbranch_scc0 .LBB0_1358
	s_cmp_gt_u32 s6, 0x119ff
	s_cbranch_scc0 .LBB0_1355
	s_cmp_gt_u32 s6, 0x12dff
	s_cbranch_scc0 .LBB0_1352
	s_add_i32 s11, s6, 0xfffed200
	s_mul_hi_u32 s12, s11, 0xcccccccd
	s_lshr_b32 s15, s12, 10
	s_mul_i32 s12, s15, 0xfffffb00
	s_add_i32 s11, s12, s11
	s_ashr_i32 s12, s11, 31
	s_lshr_b32 s12, s12, 27
	s_add_i32 s16, s11, s12
	s_mov_b64 s[12:13], s[0:1]
	s_load_dwordx2 s[12:13], s[12:13], 0x128
	s_and_b32 s17, s16, 0x3ffffe0
	s_sub_i32 s11, s11, s17
	s_mul_i32 s18, s15, 0x1400000
	s_mul_hi_u32 s17, s15, 0x1400000
	s_waitcnt lgkmcnt(0)
	s_add_u32 s18, s12, s18
	s_addc_u32 s17, s13, s17
	s_lshl_b32 s12, s16, 1
	s_and_b32 s22, s12, 0xffffffc0
	s_lshl_b32 s28, s11, 6
	s_mul_hi_u32 s11, s15, 0xa00000
	s_mul_i32 s15, s15, 0xa00000
	s_add_u32 s15, s26, s15
	s_addc_u32 s11, s27, s11
	s_ashr_i32 s29, s28, 31
	s_lshl_b64 s[12:13], s[28:29], 2
	v_add_u32_e32 v32, s22, v64
	s_add_u32 s12, s18, s12
	s_addc_u32 s13, s17, s13
	v_lshlrev_b32_e32 v172, 2, v72
	v_ashrrev_i32_e32 v33, 31, v32
	v_lshl_add_u64 v[34:35], s[12:13], 0, v[172:173]
	v_lshlrev_b64 v[0:1], 13, v[32:33]
	v_lshl_add_u64 v[24:25], v[34:35], 0, v[0:1]
	v_add_co_u32_e32 v4, vcc, s89, v24
	s_movk_i32 s13, 0x4000
	s_nop 0
	v_addc_co_u32_e32 v5, vcc, 0, v25, vcc
	v_add_co_u32_e32 v8, vcc, s13, v24
	s_movk_i32 s12, 0x6000
	s_nop 0
	v_addc_co_u32_e32 v9, vcc, 0, v25, vcc
	v_add_co_u32_e32 v12, vcc, s12, v24
	s_mov_b32 s16, 0x8000
	s_nop 0
	v_addc_co_u32_e32 v13, vcc, 0, v25, vcc
	v_add_co_u32_e32 v16, vcc, s16, v24
	v_add_u32_e32 v32, 32, v32
	s_nop 0
	v_addc_co_u32_e32 v17, vcc, 0, v25, vcc
	v_add_co_u32_e32 v20, vcc, s33, v24
	s_mov_b32 s17, 0xe000
	s_nop 0
	v_addc_co_u32_e32 v21, vcc, 0, v25, vcc
	v_add_co_u32_e32 v26, vcc, s38, v24
	v_ashrrev_i32_e32 v33, 31, v32
	s_nop 0
	v_addc_co_u32_e32 v27, vcc, 0, v25, vcc
	v_add_co_u32_e32 v28, vcc, s17, v24
	v_lshlrev_b64 v[32:33], 13, v[32:33]
	s_nop 0
	v_addc_co_u32_e32 v29, vcc, 0, v25, vcc
	v_lshl_add_u64 v[56:57], v[34:35], 0, v[32:33]
	v_add_co_u32_e32 v36, vcc, s89, v56
	global_load_dwordx4 v[0:3], v[24:25], off nt
	s_nop 0
	global_load_dwordx4 v[4:7], v[4:5], off nt
	v_addc_co_u32_e32 v37, vcc, 0, v57, vcc
	v_add_co_u32_e32 v40, vcc, s13, v56
	global_load_dwordx4 v[8:11], v[8:9], off nt
	s_nop 0
	global_load_dwordx4 v[12:15], v[12:13], off nt
	v_addc_co_u32_e32 v41, vcc, 0, v57, vcc
	v_add_co_u32_e32 v44, vcc, s12, v56
	global_load_dwordx4 v[16:19], v[16:17], off nt
	s_nop 0
	global_load_dwordx4 v[20:23], v[20:21], off nt
	v_addc_co_u32_e32 v45, vcc, 0, v57, vcc
	v_add_co_u32_e32 v48, vcc, s16, v56
	global_load_dwordx4 v[24:27], v[26:27], off nt
	s_nop 0
	global_load_dwordx4 v[28:31], v[28:29], off nt
	v_addc_co_u32_e32 v49, vcc, 0, v57, vcc
	v_add_co_u32_e32 v52, vcc, s33, v56
	global_load_dwordx4 v[32:35], v[56:57], off nt
	s_nop 0
	global_load_dwordx4 v[36:39], v[36:37], off nt
	v_addc_co_u32_e32 v53, vcc, 0, v57, vcc
	v_add_co_u32_e32 v58, vcc, s38, v56
	global_load_dwordx4 v[40:43], v[40:41], off nt
	s_nop 0
	global_load_dwordx4 v[44:47], v[44:45], off nt
	v_addc_co_u32_e32 v59, vcc, 0, v57, vcc
	v_add_co_u32_e32 v60, vcc, s17, v56
	global_load_dwordx4 v[48:51], v[48:49], off nt
	s_nop 0
	global_load_dwordx4 v[52:55], v[52:53], off nt
	v_addc_co_u32_e32 v61, vcc, 0, v57, vcc
	global_load_dwordx4 v[56:59], v[58:59], off nt
	s_nop 0
	global_load_dwordx4 v[60:63], v[60:61], off nt
	s_ashr_i32 s23, s22, 31
	s_lshl_b64 s[12:13], s[22:23], 1
	s_add_u32 s12, s15, s12
	v_or_b32_e32 v73, s28, v72
	s_addc_u32 s13, s11, s13
	s_movk_i32 s11, 0xa00
	v_mul_lo_u32 v74, v73, s11
	v_lshl_add_u64 v[70:71], v[64:65], 1, s[12:13]
	v_ashrrev_i32_e32 v75, 31, v74
	v_lshl_add_u64 v[70:71], v[74:75], 1, v[70:71]
	s_mov_b32 s11, 0x25d00000
	v_add_co_u32_e32 v76, vcc, s11, v70
	s_mov_b32 s11, 0x25d01000
	s_nop 0
	v_addc_co_u32_e32 v77, vcc, 0, v71, vcc
	s_waitcnt vmcnt(14)
	v_cvt_pk_bf16_f32 v66, v0, v4
	v_add_co_u32_e32 v4, vcc, s11, v70
	s_waitcnt vmcnt(12)
	v_cvt_pk_bf16_f32 v67, v8, v12
	s_waitcnt vmcnt(10)
	v_cvt_pk_bf16_f32 v68, v16, v20
	s_waitcnt vmcnt(8)
	v_cvt_pk_bf16_f32 v69, v24, v28
	global_store_dwordx4 v[76:77], v[66:69], off nt
	s_mov_b32 s11, 0x25d02000
	s_mov_b64 s[12:13], 0x25d00000
	v_cvt_pk_bf16_f32 v66, v1, v5
	v_addc_co_u32_e32 v5, vcc, 0, v71, vcc
	v_add_co_u32_e32 v8, vcc, s11, v70
	v_cvt_pk_bf16_f32 v67, v9, v13
	s_mov_b32 s11, 0x25d03000
	s_nop 0
	v_addc_co_u32_e32 v9, vcc, 0, v71, vcc
	v_cvt_pk_bf16_f32 v68, v17, v21
	v_cvt_pk_bf16_f32 v69, v25, v29
	global_store_dwordx4 v[4:5], v[66:69], off offset:1024 nt
	v_lshl_add_u64 v[74:75], v[70:71], 0, s[12:13]
	s_mov_b64 s[22:23], 0
	v_cvt_pk_bf16_f32 v66, v2, v6
	v_add_co_u32_e32 v6, vcc, s11, v70
	v_cvt_pk_bf16_f32 v67, v10, v14
	v_cvt_pk_bf16_f32 v68, v18, v22
	v_cvt_pk_bf16_f32 v69, v26, v30
	global_store_dwordx4 v[8:9], v[66:69], off offset:2048 nt
	v_cvt_pk_bf16_f32 v0, v3, v7
	v_cvt_pk_bf16_f32 v1, v11, v15
	v_cvt_pk_bf16_f32 v2, v19, v23
	v_cvt_pk_bf16_f32 v3, v27, v31
	s_nop 0
	v_addc_co_u32_e32 v7, vcc, 0, v71, vcc
	global_store_dwordx4 v[6:7], v[0:3], off offset:3072 nt
	s_waitcnt vmcnt(10)
	s_nop 0
	v_cvt_pk_bf16_f32 v0, v32, v36
	s_waitcnt vmcnt(8)
	v_cvt_pk_bf16_f32 v1, v40, v44
	s_waitcnt vmcnt(6)
	v_cvt_pk_bf16_f32 v2, v48, v52
	s_waitcnt vmcnt(4)
	v_cvt_pk_bf16_f32 v3, v56, v60
	global_store_dwordx4 v[74:75], v[0:3], off offset:64 nt
	s_nop 1
	v_cvt_pk_bf16_f32 v0, v33, v37
	v_cvt_pk_bf16_f32 v1, v41, v45
	v_cvt_pk_bf16_f32 v2, v49, v53
	v_cvt_pk_bf16_f32 v3, v57, v61
	global_store_dwordx4 v[4:5], v[0:3], off offset:1088 nt
	s_nop 1
	v_cvt_pk_bf16_f32 v0, v34, v38
	v_cvt_pk_bf16_f32 v1, v42, v46
	v_cvt_pk_bf16_f32 v2, v50, v54
	v_cvt_pk_bf16_f32 v3, v58, v62
	global_store_dwordx4 v[8:9], v[0:3], off offset:2112 nt
	s_nop 1
	v_cvt_pk_bf16_f32 v0, v35, v39
	v_cvt_pk_bf16_f32 v1, v43, v47
	v_cvt_pk_bf16_f32 v2, v51, v55
	v_cvt_pk_bf16_f32 v3, v59, v63
	global_store_dwordx4 v[6:7], v[0:3], off offset:3136 nt
; __device__ __forceinline__ unsigned cvt_pk_bf16(float lo, float hi) { unsigned r; asm volatile("v_cvt_pk_bf16_f32 %0, %1, %2" : "=v"(r) : "v"(lo), "v"(hi)); return r; }
; #define INP(i) ((const float*)(const GASP float*)kargs()[(i)])
; __device__ __forceinline__ void tr_item(const float* W, int ldw, int k0, int n0, bf16* WT, int ldk, int drow0, int lane) {
;     const int n4 = (lane & 15) * 4, kg = lane >> 4; f32x4 v[2][8];
; #pragma unroll
;     for (int kh = 0; kh < 2; ++kh) { const float* src = W + (size_t)(k0 + kh * 32 + kg * 8) * ldw + n0 + n4;
; #pragma unroll
;         for (int i = 0; i < 8; ++i) v[kh][i] = __builtin_nontemporal_load((const f32x4*)(src + (size_t)i * ldw)); }
; #pragma unroll
;     for (int kh = 0; kh < 2; ++kh)
; #pragma unroll
;         for (int e = 0; e < 4; ++e) { u32x4 o; o.x = cvt_pk_bf16(v[kh][0][e], v[kh][1][e]); o.y = cvt_pk_bf16(v[kh][2][e], v[kh][3][e]); o.z = cvt_pk_bf16(v[kh][4][e], v[kh][5][e]); o.w = cvt_pk_bf16(v[kh][6][e], v[kh][7][e]);
;             *(u32x4*)(WT + (size_t)(drow0 + n4 + e) * ldk + k0 + kh * 32 + kg * 8) = o; }
; }
; __device__ __forceinline__ void conv_item(int it, int lane) {
;     ...
;     if (r < 2 * IT_INC) { const int idx = r / IT_INC; r -= idx * IT_INC; const int kb = r / 80, nb = r % 80;
;         tr_item(INP(I_WINC) + (size_t)idx * 2048 * 5120, 5120, 64 * kb, 64 * nb, (bf16*)(ws + WS_WINC) + (size_t)idx * 5120 * 2048, 2048, 64 * nb, lane); return; }
.LBB0_1352:
	s_andn2_b64 vcc, exec, s[22:23]
	s_cbranch_vccnz .LBB0_1354
	s_add_i32 s11, s6, 0xfffee600
	s_cmpk_gt_u32 s11, 0x9ff
	s_cselect_b64 s[12:13], -1, 0
	s_and_b64 s[16:17], s[12:13], exec
	s_cselect_b32 s15, 0xf600, 0
	s_add_i32 s15, s15, s11
	s_sext_i32_i16 s11, s15
	s_mulk_i32 s11, 0x6667
	s_lshr_b32 s16, s11, 31
	s_ashr_i32 s11, s11, 21
	s_add_i32 s11, s11, s16
	s_mov_b64 s[16:17], s[0:1]
	s_load_dwordx2 s[16:17], s[16:17], 0xe8
	s_mul_i32 s18, s11, 0x50
	s_sub_i32 s15, s15, s18
	s_and_b64 s[18:19], s[12:13], exec
	s_cselect_b32 s18, 0x2800000, 0
	s_sext_i32_i16 s15, s15
	s_waitcnt lgkmcnt(0)
	s_add_u32 s16, s16, s18
	s_addc_u32 s17, s17, 0
	s_lshl_b32 s22, s11, 6
	s_lshl_b32 s28, s15, 6
	s_and_b64 s[12:13], s[12:13], exec
	s_cselect_b32 s11, 0x1400000, 0
	s_add_u32 s11, s26, s11
	s_addc_u32 s15, s27, 0
	s_ashr_i32 s29, s28, 31
	s_lshl_b64 s[12:13], s[28:29], 2
	s_add_u32 s12, s16, s12
	s_addc_u32 s13, s17, s13
	v_lshlrev_b32_e32 v172, 2, v72
	v_add_u32_e32 v34, s22, v64
	v_lshl_add_u64 v[32:33], s[12:13], 0, v[172:173]
	s_movk_i32 s18, 0x5000
	v_mad_i64_i32 v[24:25], s[12:13], v34, s18, v[32:33]
	v_add_co_u32_e32 v4, vcc, s18, v24
	s_mov_b32 s16, 0x14000
	s_nop 0
	v_addc_co_u32_e32 v5, vcc, 0, v25, vcc
	v_add_co_u32_e32 v8, vcc, s33, v24
	s_mov_b32 s19, 0x19000
	s_nop 0
	v_addc_co_u32_e32 v9, vcc, 0, v25, vcc
	v_add_co_u32_e32 v12, vcc, s76, v24
	s_mov_b32 s17, 0x1e000
	s_nop 0
	v_addc_co_u32_e32 v13, vcc, 0, v25, vcc
	v_add_co_u32_e32 v16, vcc, s16, v24
	v_add_u32_e32 v34, 32, v34
	s_nop 0
	v_addc_co_u32_e32 v17, vcc, 0, v25, vcc
	v_add_co_u32_e32 v20, vcc, s19, v24
	v_mad_i64_i32 v[56:57], s[12:13], v34, s18, v[32:33]
	s_nop 0
	v_addc_co_u32_e32 v21, vcc, 0, v25, vcc
	v_add_co_u32_e32 v26, vcc, s17, v24
	global_load_dwordx4 v[0:3], v[24:25], off nt
	s_nop 0
	global_load_dwordx4 v[4:7], v[4:5], off nt
	v_addc_co_u32_e32 v27, vcc, 0, v25, vcc
	v_add_co_u32_e32 v28, vcc, s77, v24
	global_load_dwordx4 v[8:11], v[8:9], off nt
	s_nop 0
	global_load_dwordx4 v[12:15], v[12:13], off nt
	v_addc_co_u32_e32 v29, vcc, 0, v25, vcc
	v_add_co_u32_e32 v36, vcc, s18, v56
	global_load_dwordx4 v[16:19], v[16:17], off nt
	s_nop 0
	global_load_dwordx4 v[20:23], v[20:21], off nt
	v_addc_co_u32_e32 v37, vcc, 0, v57, vcc
	v_add_co_u32_e32 v40, vcc, s33, v56
	global_load_dwordx4 v[24:27], v[26:27], off nt
	s_nop 0
	global_load_dwordx4 v[28:31], v[28:29], off nt
	v_addc_co_u32_e32 v41, vcc, 0, v57, vcc
	v_add_co_u32_e32 v44, vcc, s76, v56
	global_load_dwordx4 v[32:35], v[56:57], off nt
	s_nop 0
	global_load_dwordx4 v[36:39], v[36:37], off nt
	v_addc_co_u32_e32 v45, vcc, 0, v57, vcc
	v_add_co_u32_e32 v48, vcc, s16, v56
	global_load_dwordx4 v[40:43], v[40:41], off nt
	s_nop 0
	global_load_dwordx4 v[44:47], v[44:45], off nt
	v_addc_co_u32_e32 v49, vcc, 0, v57, vcc
	v_add_co_u32_e32 v52, vcc, s19, v56
	s_ashr_i32 s23, s22, 31
	s_nop 0
	v_addc_co_u32_e32 v53, vcc, 0, v57, vcc
	v_add_co_u32_e32 v58, vcc, s17, v56
	global_load_dwordx4 v[48:51], v[48:49], off nt
	s_nop 0
	global_load_dwordx4 v[52:55], v[52:53], off nt
	v_addc_co_u32_e32 v59, vcc, 0, v57, vcc
	v_add_co_u32_e32 v60, vcc, s77, v56
	s_lshl_b64 s[12:13], s[22:23], 1
	s_nop 0
	v_addc_co_u32_e32 v61, vcc, 0, v57, vcc
	global_load_dwordx4 v[56:59], v[58:59], off nt
	s_nop 0
	global_load_dwordx4 v[60:63], v[60:61], off nt
	s_add_u32 s12, s11, s12
	v_or_b32_e32 v70, s28, v72
	s_addc_u32 s13, s15, s13
	v_lshl_add_u64 v[66:67], v[64:65], 1, s[12:13]
	s_mov_b64 s[12:13], 0x23500000
	v_ashrrev_i32_e32 v71, 31, v70
	v_lshl_add_u64 v[74:75], v[66:67], 0, s[12:13]
	v_lshlrev_b64 v[76:77], 12, v[70:71]
	s_waitcnt vmcnt(14)
	v_cvt_pk_bf16_f32 v66, v0, v4
	v_lshl_add_u64 v[76:77], v[74:75], 0, v[76:77]
	v_or_b32_e32 v0, 1, v70
	s_waitcnt vmcnt(12)
	v_cvt_pk_bf16_f32 v67, v8, v12
	s_waitcnt vmcnt(10)
	v_cvt_pk_bf16_f32 v68, v16, v20
	s_waitcnt vmcnt(8)
	v_cvt_pk_bf16_f32 v69, v24, v28
	global_store_dwordx4 v[76:77], v[66:69], off nt
	s_nop 1
	v_cvt_pk_bf16_f32 v66, v1, v5
	v_ashrrev_i32_e32 v1, 31, v0
	v_lshlrev_b64 v[0:1], 12, v[0:1]
	v_lshl_add_u64 v[4:5], v[74:75], 0, v[0:1]
	v_or_b32_e32 v0, 2, v70
	v_ashrrev_i32_e32 v1, 31, v0
	v_lshlrev_b64 v[0:1], 12, v[0:1]
	v_cvt_pk_bf16_f32 v67, v9, v13
	v_cvt_pk_bf16_f32 v68, v17, v21
	v_cvt_pk_bf16_f32 v69, v25, v29
	global_store_dwordx4 v[4:5], v[66:69], off nt
	v_lshl_add_u64 v[8:9], v[74:75], 0, v[0:1]
	s_nop 0
	v_cvt_pk_bf16_f32 v66, v2, v6
	v_or_b32_e32 v6, 3, v70
	v_cvt_pk_bf16_f32 v67, v10, v14
	v_cvt_pk_bf16_f32 v68, v18, v22
	v_cvt_pk_bf16_f32 v69, v26, v30
	global_store_dwordx4 v[8:9], v[66:69], off nt
	v_cvt_pk_bf16_f32 v0, v3, v7
	v_ashrrev_i32_e32 v7, 31, v6
	v_lshlrev_b64 v[6:7], 12, v[6:7]
	v_cvt_pk_bf16_f32 v1, v11, v15
	v_cvt_pk_bf16_f32 v2, v19, v23
	v_cvt_pk_bf16_f32 v3, v27, v31
	v_lshl_add_u64 v[6:7], v[74:75], 0, v[6:7]
	global_store_dwordx4 v[6:7], v[0:3], off nt
	s_waitcnt vmcnt(10)
	s_nop 0
	v_cvt_pk_bf16_f32 v0, v32, v36
	s_waitcnt vmcnt(8)
	v_cvt_pk_bf16_f32 v1, v40, v44
	s_waitcnt vmcnt(6)
	v_cvt_pk_bf16_f32 v2, v48, v52
	s_waitcnt vmcnt(4)
	v_cvt_pk_bf16_f32 v3, v56, v60
	global_store_dwordx4 v[76:77], v[0:3], off offset:64 nt
	s_nop 1
	v_cvt_pk_bf16_f32 v0, v33, v37
	v_cvt_pk_bf16_f32 v1, v41, v45
	v_cvt_pk_bf16_f32 v2, v49, v53
	v_cvt_pk_bf16_f32 v3, v57, v61
	global_store_dwordx4 v[4:5], v[0:3], off offset:64 nt
	s_nop 1
	v_cvt_pk_bf16_f32 v0, v34, v38
	v_cvt_pk_bf16_f32 v1, v42, v46
	v_cvt_pk_bf16_f32 v2, v50, v54
	v_cvt_pk_bf16_f32 v3, v58, v62
	global_store_dwordx4 v[8:9], v[0:3], off offset:64 nt
	s_nop 1
	v_cvt_pk_bf16_f32 v0, v35, v39
	v_cvt_pk_bf16_f32 v1, v43, v47
	v_cvt_pk_bf16_f32 v2, v51, v55
	v_cvt_pk_bf16_f32 v3, v59, v63
	global_store_dwordx4 v[6:7], v[0:3], off offset:64 nt

; __device__ __forceinline__ unsigned cvt_pk_bf16(float lo, float hi) { unsigned r; asm volatile("v_cvt_pk_bf16_f32 %0, %1, %2" : "=v"(r) : "v"(lo), "v"(hi)); return r; }
; #define INP(i) ((const float*)(const GASP float*)kargs()[(i)])
; __device__ __forceinline__ void tr_item(const float* W, int ldw, int k0, int n0, bf16* WT, int ldk, int drow0, int lane) {
;     const int n4 = (lane & 15) * 4, kg = lane >> 4; f32x4 v[2][8];
; #pragma unroll
;     for (int kh = 0; kh < 2; ++kh) { const float* src = W + (size_t)(k0 + kh * 32 + kg * 8) * ldw + n0 + n4;
; #pragma unroll
;         for (int i = 0; i < 8; ++i) v[kh][i] = __builtin_nontemporal_load((const f32x4*)(src + (size_t)i * ldw)); }
; #pragma unroll
;     for (int kh = 0; kh < 2; ++kh)
; #pragma unroll
;         for (int e = 0; e < 4; ++e) { u32x4 o; o.x = cvt_pk_bf16(v[kh][0][e], v[kh][1][e]); o.y = cvt_pk_bf16(v[kh][2][e], v[kh][3][e]); o.z = cvt_pk_bf16(v[kh][4][e], v[kh][5][e]); o.w = cvt_pk_bf16(v[kh][6][e], v[kh][7][e]);
;             *(u32x4*)(WT + (size_t)(drow0 + n4 + e) * ldk + k0 + kh * 32 + kg * 8) = o; }
; }
; __device__ __forceinline__ void conv_item(int it, int lane) {
;     ...
;     if (r < 2 * IT_OUTAB) { const int idx = r / IT_OUTAB; r -= idx * IT_OUTAB; const int kb = r / 32, nb = r % 32;
;         tr_item(INP(I_WOUTAB) + (size_t)idx * 2048 * 2048, 2048, 64 * kb, 64 * nb, (bf16*)(ws + WS_WOUTAB) + (size_t)idx * 2048 * 2048, 2048, 64 * nb, lane); return; }
.LBB0_1355:
	s_andn2_b64 vcc, exec, s[22:23]
	s_cbranch_vccnz .LBB0_1357
	s_mov_b64 s[12:13], s[0:1]
	s_load_dwordx2 s[12:13], s[12:13], 0xe0
	s_add_i32 s11, s6, 0xfffeee00
	s_lshr_b32 s38, s11, 10
	s_lshl_b64 s[16:17], s[38:39], 24
	v_lshlrev_b32_e32 v172, 2, v72
	s_waitcnt lgkmcnt(0)
	s_add_u32 s15, s12, s16
	s_addc_u32 s16, s13, s17
	s_lshl_b32 s11, s11, 1
	s_lshl_b32 s12, s6, 6
	s_and_b32 s11, s11, 0x7c0
	s_and_b32 s17, s12, 0x7c0
	s_lshl_b64 s[12:13], s[38:39], 23
	s_add_u32 s18, s26, s12
	s_addc_u32 s19, s27, s13
	s_lshl_b32 s12, s17, 2
	v_add_u32_e32 v32, s11, v64
	s_add_u32 s12, s15, s12
	s_addc_u32 s13, s16, 0
	v_ashrrev_i32_e32 v33, 31, v32
	v_lshl_add_u64 v[34:35], s[12:13], 0, v[172:173]
	v_lshlrev_b64 v[0:1], 13, v[32:33]
	v_lshl_add_u64 v[24:25], v[34:35], 0, v[0:1]
	v_add_co_u32_e32 v4, vcc, s89, v24
	s_movk_i32 s13, 0x4000
	s_nop 0
	v_addc_co_u32_e32 v5, vcc, 0, v25, vcc
	v_add_co_u32_e32 v8, vcc, s13, v24
	s_movk_i32 s12, 0x6000
	s_nop 0
	v_addc_co_u32_e32 v9, vcc, 0, v25, vcc
	v_add_co_u32_e32 v12, vcc, s12, v24
	s_mov_b32 s15, 0x8000
	s_nop 0
	v_addc_co_u32_e32 v13, vcc, 0, v25, vcc
	v_add_co_u32_e32 v16, vcc, s15, v24
	s_mov_b32 s38, 0xc000
	s_nop 0
	v_addc_co_u32_e32 v17, vcc, 0, v25, vcc
	v_add_co_u32_e32 v20, vcc, s33, v24
	v_add_u32_e32 v32, 32, v32
	s_nop 0
	v_addc_co_u32_e32 v21, vcc, 0, v25, vcc
	v_add_co_u32_e32 v26, vcc, s38, v24
	s_mov_b32 s16, 0xe000
	s_nop 0
	v_addc_co_u32_e32 v27, vcc, 0, v25, vcc
	v_ashrrev_i32_e32 v33, 31, v32
	v_add_co_u32_e32 v28, vcc, s16, v24
	v_lshlrev_b64 v[32:33], 13, v[32:33]
	s_nop 0
	v_addc_co_u32_e32 v29, vcc, 0, v25, vcc
	v_lshl_add_u64 v[56:57], v[34:35], 0, v[32:33]
	v_add_co_u32_e32 v36, vcc, s89, v56
	global_load_dwordx4 v[0:3], v[24:25], off nt
	s_nop 0
	global_load_dwordx4 v[4:7], v[4:5], off nt
	v_addc_co_u32_e32 v37, vcc, 0, v57, vcc
	v_add_co_u32_e32 v40, vcc, s13, v56
	global_load_dwordx4 v[8:11], v[8:9], off nt
	s_nop 0
	global_load_dwordx4 v[12:15], v[12:13], off nt
	v_addc_co_u32_e32 v41, vcc, 0, v57, vcc
	v_add_co_u32_e32 v44, vcc, s12, v56
	global_load_dwordx4 v[16:19], v[16:17], off nt
	s_nop 0
	global_load_dwordx4 v[20:23], v[20:21], off nt
	v_addc_co_u32_e32 v45, vcc, 0, v57, vcc
	v_add_co_u32_e32 v48, vcc, s15, v56
	global_load_dwordx4 v[24:27], v[26:27], off nt
	s_nop 0
	global_load_dwordx4 v[28:31], v[28:29], off nt
	v_addc_co_u32_e32 v49, vcc, 0, v57, vcc
	v_add_co_u32_e32 v52, vcc, s33, v56
	global_load_dwordx4 v[32:35], v[56:57], off nt
	s_nop 0
	global_load_dwordx4 v[36:39], v[36:37], off nt
	v_addc_co_u32_e32 v53, vcc, 0, v57, vcc
	v_add_co_u32_e32 v58, vcc, s38, v56
	global_load_dwordx4 v[40:43], v[40:41], off nt
	s_nop 0
	global_load_dwordx4 v[44:47], v[44:45], off nt
	v_addc_co_u32_e32 v59, vcc, 0, v57, vcc
	v_add_co_u32_e32 v60, vcc, s16, v56
	global_load_dwordx4 v[48:51], v[48:49], off nt
	s_nop 0
	global_load_dwordx4 v[52:55], v[52:53], off nt
	v_addc_co_u32_e32 v61, vcc, 0, v57, vcc
	global_load_dwordx4 v[56:59], v[58:59], off nt
	s_nop 0
	global_load_dwordx4 v[60:63], v[60:61], off nt
	s_lshl_b32 s11, s11, 1
	s_add_u32 s12, s18, s11
	s_addc_u32 s13, s19, 0
	v_or_b32_e32 v73, s17, v72
	v_lshl_add_u64 v[70:71], v[64:65], 1, s[12:13]
	s_mov_b64 s[12:13], 0x22500000
	v_lshl_add_u64 v[74:75], v[70:71], 0, s[12:13]
	v_lshlrev_b32_e32 v172, 12, v73
	s_waitcnt vmcnt(14)
	v_cvt_pk_bf16_f32 v66, v0, v4
	v_lshl_add_u64 v[76:77], v[74:75], 0, v[172:173]
	s_waitcnt vmcnt(12)
	v_cvt_pk_bf16_f32 v67, v8, v12
	s_waitcnt vmcnt(10)
	v_cvt_pk_bf16_f32 v68, v16, v20
	s_waitcnt vmcnt(8)
	v_cvt_pk_bf16_f32 v69, v24, v28
	global_store_dwordx4 v[76:77], v[66:69], off nt
	v_or_b32_e32 v4, 0x1000, v172
	v_or_b32_e32 v8, 0x2000, v172
	v_cvt_pk_bf16_f32 v66, v1, v5
	v_mov_b32_e32 v5, v173
	v_cvt_pk_bf16_f32 v67, v9, v13
	v_lshl_add_u64 v[0:1], v[74:75], 0, v[4:5]
	v_mov_b32_e32 v9, v173
	v_cvt_pk_bf16_f32 v68, v17, v21
	v_cvt_pk_bf16_f32 v69, v25, v29
	global_store_dwordx4 v[0:1], v[66:69], off nt
	v_lshl_add_u64 v[0:1], v[74:75], 0, v[8:9]
	v_or_b32_e32 v172, 0x3000, v172
	v_cvt_pk_bf16_f32 v66, v2, v6
	v_cvt_pk_bf16_f32 v67, v10, v14
	v_cvt_pk_bf16_f32 v68, v18, v22
	v_cvt_pk_bf16_f32 v69, v26, v30
	global_store_dwordx4 v[0:1], v[66:69], off nt
	v_cvt_pk_bf16_f32 v0, v3, v7
	v_lshl_add_u64 v[6:7], v[74:75], 0, v[172:173]
	s_mov_b64 s[12:13], 0x22500040
	v_cvt_pk_bf16_f32 v1, v11, v15
	v_cvt_pk_bf16_f32 v2, v19, v23
	v_cvt_pk_bf16_f32 v3, v27, v31
	global_store_dwordx4 v[6:7], v[0:3], off nt
	v_lshl_add_u64 v[6:7], v[70:71], 0, s[12:13]
	v_lshl_add_u64 v[4:5], v[6:7], 0, v[4:5]
	s_waitcnt vmcnt(10)
	v_cvt_pk_bf16_f32 v0, v32, v36
	s_waitcnt vmcnt(8)
	v_cvt_pk_bf16_f32 v1, v40, v44
	s_waitcnt vmcnt(6)
	v_cvt_pk_bf16_f32 v2, v48, v52
	s_waitcnt vmcnt(4)
	v_cvt_pk_bf16_f32 v3, v56, v60
	global_store_dwordx4 v[76:77], v[0:3], off offset:64 nt
	s_nop 1
	v_cvt_pk_bf16_f32 v0, v33, v37
	v_cvt_pk_bf16_f32 v1, v41, v45
	v_cvt_pk_bf16_f32 v2, v49, v53
	v_cvt_pk_bf16_f32 v3, v57, v61
	global_store_dwordx4 v[4:5], v[0:3], off nt
	v_lshl_add_u64 v[4:5], v[6:7], 0, v[8:9]
	s_nop 0
	v_cvt_pk_bf16_f32 v0, v34, v38
	v_cvt_pk_bf16_f32 v1, v42, v46
	v_cvt_pk_bf16_f32 v2, v50, v54
	v_cvt_pk_bf16_f32 v3, v58, v62
	global_store_dwordx4 v[4:5], v[0:3], off nt
	v_lshl_add_u64 v[4:5], v[6:7], 0, v[172:173]
	s_nop 0
	v_cvt_pk_bf16_f32 v0, v35, v39
	v_cvt_pk_bf16_f32 v1, v43, v47
	v_cvt_pk_bf16_f32 v2, v51, v55
	v_cvt_pk_bf16_f32 v3, v59, v63
	global_store_dwordx4 v[4:5], v[0:3], off nt

; __device__ __forceinline__ unsigned cvt_pk_bf16(float lo, float hi) { unsigned r; asm volatile("v_cvt_pk_bf16_f32 %0, %1, %2" : "=v"(r) : "v"(lo), "v"(hi)); return r; }
; #define INP(i) ((const float*)(const GASP float*)kargs()[(i)])
; __device__ __forceinline__ void tr_item(const float* W, int ldw, int k0, int n0, bf16* WT, int ldk, int drow0, int lane) {
;     const int n4 = (lane & 15) * 4, kg = lane >> 4; f32x4 v[2][8];
; #pragma unroll
;     for (int kh = 0; kh < 2; ++kh) { const float* src = W + (size_t)(k0 + kh * 32 + kg * 8) * ldw + n0 + n4;
; #pragma unroll
;         for (int i = 0; i < 8; ++i) v[kh][i] = __builtin_nontemporal_load((const f32x4*)(src + (size_t)i * ldw)); }
; #pragma unroll
;     for (int kh = 0; kh < 2; ++kh)
; #pragma unroll
;         for (int e = 0; e < 4; ++e) { u32x4 o; o.x = cvt_pk_bf16(v[kh][0][e], v[kh][1][e]); o.y = cvt_pk_bf16(v[kh][2][e], v[kh][3][e]); o.z = cvt_pk_bf16(v[kh][4][e], v[kh][5][e]); o.w = cvt_pk_bf16(v[kh][6][e], v[kh][7][e]);
;             *(u32x4*)(WT + (size_t)(drow0 + n4 + e) * ldk + k0 + kh * 32 + kg * 8) = o; }
; }
; __device__ __forceinline__ void conv_item(int it, int lane) {
;     ...
;     if (r < 2 * IT_INAB) { const int idx = r / IT_INAB; r -= idx * IT_INAB; const int kb = r / 80, nb = r % 80;
;         tr_item(INP(I_WINAB) + (size_t)idx * 2048 * 5120, 5120, 64 * kb, 64 * nb, (bf16*)(ws + WS_WINAB) + (size_t)idx * 5120 * 2048, 2048, 64 * nb, lane); return; }
.LBB0_1361:
	s_andn2_b64 vcc, exec, s[22:23]
	s_cbranch_vccnz .LBB0_1363
	s_add_i32 s11, s6, 0xffff0400
	s_cmpk_gt_u32 s11, 0x9ff
	s_cselect_b64 s[12:13], -1, 0
	s_and_b64 s[16:17], s[12:13], exec
	s_cselect_b32 s15, 0xf600, 0
	s_add_i32 s15, s15, s11
	s_sext_i32_i16 s11, s15
	s_mulk_i32 s11, 0x6667
	s_lshr_b32 s16, s11, 31
	s_ashr_i32 s11, s11, 21
	s_add_i32 s11, s11, s16
	s_mov_b64 s[16:17], s[0:1]
	s_load_dwordx2 s[16:17], s[16:17], 0x78
	s_mul_i32 s18, s11, 0x50
	s_sub_i32 s15, s15, s18
	s_and_b64 s[18:19], s[12:13], exec
	s_cselect_b32 s18, 0x2800000, 0
	s_sext_i32_i16 s15, s15
	s_waitcnt lgkmcnt(0)
	s_add_u32 s16, s16, s18
	s_addc_u32 s17, s17, 0
	s_lshl_b32 s22, s11, 6
	s_lshl_b32 s28, s15, 6
	s_and_b64 s[12:13], s[12:13], exec
	s_cselect_b32 s11, 0x1400000, 0
	s_add_u32 s11, s26, s11
	s_addc_u32 s15, s27, 0
	s_ashr_i32 s29, s28, 31
	s_lshl_b64 s[12:13], s[28:29], 2
	s_add_u32 s12, s16, s12
	s_addc_u32 s13, s17, s13
	v_lshlrev_b32_e32 v172, 2, v72
	v_add_u32_e32 v34, s22, v64
	v_lshl_add_u64 v[32:33], s[12:13], 0, v[172:173]
	s_movk_i32 s18, 0x5000
	v_mad_i64_i32 v[24:25], s[12:13], v34, s18, v[32:33]
	v_add_co_u32_e32 v4, vcc, s18, v24
	s_mov_b32 s16, 0x14000
	s_nop 0
	v_addc_co_u32_e32 v5, vcc, 0, v25, vcc
	v_add_co_u32_e32 v8, vcc, s33, v24
	s_mov_b32 s19, 0x19000
	s_nop 0
	v_addc_co_u32_e32 v9, vcc, 0, v25, vcc
	v_add_co_u32_e32 v12, vcc, s76, v24
	s_mov_b32 s17, 0x1e000
	s_nop 0
	v_addc_co_u32_e32 v13, vcc, 0, v25, vcc
	v_add_co_u32_e32 v16, vcc, s16, v24
	v_add_u32_e32 v34, 32, v34
	s_nop 0
	v_addc_co_u32_e32 v17, vcc, 0, v25, vcc
	v_add_co_u32_e32 v20, vcc, s19, v24
	v_mad_i64_i32 v[56:57], s[12:13], v34, s18, v[32:33]
	s_nop 0
	v_addc_co_u32_e32 v21, vcc, 0, v25, vcc
	v_add_co_u32_e32 v26, vcc, s17, v24
	global_load_dwordx4 v[0:3], v[24:25], off nt
	s_nop 0
	global_load_dwordx4 v[4:7], v[4:5], off nt
	v_addc_co_u32_e32 v27, vcc, 0, v25, vcc
	v_add_co_u32_e32 v28, vcc, s77, v24
	global_load_dwordx4 v[8:11], v[8:9], off nt
	s_nop 0
	global_load_dwordx4 v[12:15], v[12:13], off nt
	v_addc_co_u32_e32 v29, vcc, 0, v25, vcc
	v_add_co_u32_e32 v36, vcc, s18, v56
	global_load_dwordx4 v[16:19], v[16:17], off nt
	s_nop 0
	global_load_dwordx4 v[20:23], v[20:21], off nt
	v_addc_co_u32_e32 v37, vcc, 0, v57, vcc
	v_add_co_u32_e32 v40, vcc, s33, v56
	global_load_dwordx4 v[24:27], v[26:27], off nt
	s_nop 0
	global_load_dwordx4 v[28:31], v[28:29], off nt
	v_addc_co_u32_e32 v41, vcc, 0, v57, vcc
	v_add_co_u32_e32 v44, vcc, s76, v56
	global_load_dwordx4 v[32:35], v[56:57], off nt
	s_nop 0
	global_load_dwordx4 v[36:39], v[36:37], off nt
	v_addc_co_u32_e32 v45, vcc, 0, v57, vcc
	v_add_co_u32_e32 v48, vcc, s16, v56
	global_load_dwordx4 v[40:43], v[40:41], off nt
	s_nop 0
	global_load_dwordx4 v[44:47], v[44:45], off nt
	v_addc_co_u32_e32 v49, vcc, 0, v57, vcc
	v_add_co_u32_e32 v52, vcc, s19, v56
	s_ashr_i32 s23, s22, 31
	s_nop 0
	v_addc_co_u32_e32 v53, vcc, 0, v57, vcc
	v_add_co_u32_e32 v58, vcc, s17, v56
	global_load_dwordx4 v[48:51], v[48:49], off nt
	s_nop 0
	global_load_dwordx4 v[52:55], v[52:53], off nt
	v_addc_co_u32_e32 v59, vcc, 0, v57, vcc
	v_add_co_u32_e32 v60, vcc, s77, v56
	s_lshl_b64 s[12:13], s[22:23], 1
	s_nop 0
	v_addc_co_u32_e32 v61, vcc, 0, v57, vcc
	global_load_dwordx4 v[56:59], v[58:59], off nt
	s_nop 0
	global_load_dwordx4 v[60:63], v[60:61], off nt
	s_add_u32 s12, s11, s12
	v_or_b32_e32 v70, s28, v72
	s_addc_u32 s13, s15, s13
	v_lshl_add_u64 v[66:67], v[64:65], 1, s[12:13]
	s_mov_b64 s[12:13], 0x1f900000
	v_ashrrev_i32_e32 v71, 31, v70
	v_lshl_add_u64 v[74:75], v[66:67], 0, s[12:13]
	v_lshlrev_b64 v[76:77], 12, v[70:71]
	s_waitcnt vmcnt(14)
	v_cvt_pk_bf16_f32 v66, v0, v4
	v_lshl_add_u64 v[76:77], v[74:75], 0, v[76:77]
	v_or_b32_e32 v0, 1, v70
	s_waitcnt vmcnt(12)
	v_cvt_pk_bf16_f32 v67, v8, v12
	s_waitcnt vmcnt(10)
	v_cvt_pk_bf16_f32 v68, v16, v20
	s_waitcnt vmcnt(8)
	v_cvt_pk_bf16_f32 v69, v24, v28
	global_store_dwordx4 v[76:77], v[66:69], off nt
	s_nop 1
	v_cvt_pk_bf16_f32 v66, v1, v5
	v_ashrrev_i32_e32 v1, 31, v0
	v_lshlrev_b64 v[0:1], 12, v[0:1]
	v_lshl_add_u64 v[4:5], v[74:75], 0, v[0:1]
	v_or_b32_e32 v0, 2, v70
	v_ashrrev_i32_e32 v1, 31, v0
	v_lshlrev_b64 v[0:1], 12, v[0:1]
	v_cvt_pk_bf16_f32 v67, v9, v13
	v_cvt_pk_bf16_f32 v68, v17, v21
	v_cvt_pk_bf16_f32 v69, v25, v29
	global_store_dwordx4 v[4:5], v[66:69], off nt
	v_lshl_add_u64 v[8:9], v[74:75], 0, v[0:1]
	s_nop 0
	v_cvt_pk_bf16_f32 v66, v2, v6
	v_or_b32_e32 v6, 3, v70
	v_cvt_pk_bf16_f32 v67, v10, v14
	v_cvt_pk_bf16_f32 v68, v18, v22
	v_cvt_pk_bf16_f32 v69, v26, v30
	global_store_dwordx4 v[8:9], v[66:69], off nt
	v_cvt_pk_bf16_f32 v0, v3, v7
	v_ashrrev_i32_e32 v7, 31, v6
	v_lshlrev_b64 v[6:7], 12, v[6:7]
	v_cvt_pk_bf16_f32 v1, v11, v15
	v_cvt_pk_bf16_f32 v2, v19, v23
	v_cvt_pk_bf16_f32 v3, v27, v31
	v_lshl_add_u64 v[6:7], v[74:75], 0, v[6:7]
	global_store_dwordx4 v[6:7], v[0:3], off nt
	s_waitcnt vmcnt(10)
	s_nop 0
	v_cvt_pk_bf16_f32 v0, v32, v36
	s_waitcnt vmcnt(8)
	v_cvt_pk_bf16_f32 v1, v40, v44
	s_waitcnt vmcnt(6)
	v_cvt_pk_bf16_f32 v2, v48, v52
	s_waitcnt vmcnt(4)
	v_cvt_pk_bf16_f32 v3, v56, v60
	global_store_dwordx4 v[76:77], v[0:3], off offset:64 nt
	s_nop 1
	v_cvt_pk_bf16_f32 v0, v33, v37
	v_cvt_pk_bf16_f32 v1, v41, v45
	v_cvt_pk_bf16_f32 v2, v49, v53
	v_cvt_pk_bf16_f32 v3, v57, v61
	global_store_dwordx4 v[4:5], v[0:3], off offset:64 nt
	s_nop 1
	v_cvt_pk_bf16_f32 v0, v34, v38
	v_cvt_pk_bf16_f32 v1, v42, v46
	v_cvt_pk_bf16_f32 v2, v50, v54
	v_cvt_pk_bf16_f32 v3, v58, v62
	global_store_dwordx4 v[8:9], v[0:3], off offset:64 nt
	s_nop 1
	v_cvt_pk_bf16_f32 v0, v35, v39
	v_cvt_pk_bf16_f32 v1, v43, v47
	v_cvt_pk_bf16_f32 v2, v51, v55
	v_cvt_pk_bf16_f32 v3, v59, v63
	global_store_dwordx4 v[6:7], v[0:3], off offset:64 nt

; __device__ __forceinline__ unsigned cvt_pk_bf16(float lo, float hi) { unsigned r; asm volatile("v_cvt_pk_bf16_f32 %0, %1, %2" : "=v"(r) : "v"(lo), "v"(hi)); return r; }
; #define INP(i) ((const float*)(const GASP float*)kargs()[(i)])
; __device__ __forceinline__ void tr_item(const float* W, int ldw, int k0, int n0, bf16* WT, int ldk, int drow0, int lane) {
;     const int n4 = (lane & 15) * 4, kg = lane >> 4; f32x4 v[2][8];
; #pragma unroll
;     for (int kh = 0; kh < 2; ++kh) { const float* src = W + (size_t)(k0 + kh * 32 + kg * 8) * ldw + n0 + n4;
; #pragma unroll
;         for (int i = 0; i < 8; ++i) v[kh][i] = __builtin_nontemporal_load((const f32x4*)(src + (size_t)i * ldw)); }
; #pragma unroll
;     for (int kh = 0; kh < 2; ++kh)
; #pragma unroll
;         for (int e = 0; e < 4; ++e) { u32x4 o; o.x = cvt_pk_bf16(v[kh][0][e], v[kh][1][e]); o.y = cvt_pk_bf16(v[kh][2][e], v[kh][3][e]); o.z = cvt_pk_bf16(v[kh][4][e], v[kh][5][e]); o.w = cvt_pk_bf16(v[kh][6][e], v[kh][7][e]);
;             *(u32x4*)(WT + (size_t)(drow0 + n4 + e) * ldk + k0 + kh * 32 + kg * 8) = o; }
; }
; __device__ __forceinline__ void conv_item(int it, int lane) {
;     ...
;     if (r < 8 * IT_D) { const int idx = r / IT_D; r -= idx * IT_D; const int kb = r / 32, nb = r % 32;
;         tr_item(INP(I_WD) + (size_t)idx * 5376 * 2048, 2048, 64 * kb, 64 * nb, (bf16*)(ws + WS_WD) + (size_t)idx * 2048 * 5376, 5376, 64 * nb, lane); return; }
.LBB0_1364:
	s_andn2_b64 vcc, exec, s[22:23]
	s_cbranch_vccnz .LBB0_1366
	s_add_i32 s11, s6, 0xffff5800
	s_bfe_u32 s12, s11, 0x100007
	s_mulk_i32 s12, 0xc31
	s_lshr_b32 s15, s12, 16
	s_mul_i32 s12, s15, 0xf580
	s_add_i32 s11, s12, s11
	s_sext_i32_i16 s12, s11
	s_bfe_u32 s12, s12, 0x5001a
	s_add_i32 s16, s11, s12
	s_mov_b64 s[12:13], s[0:1]
	s_load_dwordx2 s[12:13], s[12:13], 0x70
	s_sext_i32_i16 s17, s16
	s_and_b32 s16, s16, 0xffe0
	s_sub_i32 s11, s11, s16
	s_mul_i32 s16, s15, 0x2a00000
	s_waitcnt lgkmcnt(0)
	s_add_u32 s16, s12, s16
	s_sext_i32_i16 s11, s11
	s_addc_u32 s18, s13, 0
	s_lshl_b32 s12, s17, 1
	s_and_b32 s22, s12, 0xffffffc0
	s_lshl_b32 s28, s11, 6
	s_mul_i32 s15, s15, 0x1500000
	s_add_u32 s11, s26, s15
	s_addc_u32 s15, s27, 0
	s_ashr_i32 s29, s28, 31
	s_lshl_b64 s[12:13], s[28:29], 2
	v_add_u32_e32 v32, s22, v64
	s_add_u32 s12, s16, s12
	s_addc_u32 s13, s18, s13
	v_lshlrev_b32_e32 v172, 2, v72
	v_ashrrev_i32_e32 v33, 31, v32
	v_lshl_add_u64 v[34:35], s[12:13], 0, v[172:173]
	v_lshlrev_b64 v[0:1], 13, v[32:33]
	v_lshl_add_u64 v[24:25], v[34:35], 0, v[0:1]
	v_add_co_u32_e32 v4, vcc, s89, v24
	s_movk_i32 s13, 0x4000
	s_nop 0
	v_addc_co_u32_e32 v5, vcc, 0, v25, vcc
	v_add_co_u32_e32 v8, vcc, s13, v24
	s_movk_i32 s12, 0x6000
	s_nop 0
	v_addc_co_u32_e32 v9, vcc, 0, v25, vcc
	v_add_co_u32_e32 v12, vcc, s12, v24
	s_mov_b32 s16, 0x8000
	s_nop 0
	v_addc_co_u32_e32 v13, vcc, 0, v25, vcc
	v_add_co_u32_e32 v16, vcc, s16, v24
	v_add_u32_e32 v32, 32, v32
	s_nop 0
	v_addc_co_u32_e32 v17, vcc, 0, v25, vcc
	v_add_co_u32_e32 v20, vcc, s33, v24
	s_mov_b32 s17, 0xe000
	s_nop 0
	v_addc_co_u32_e32 v21, vcc, 0, v25, vcc
	v_add_co_u32_e32 v26, vcc, s38, v24
	v_ashrrev_i32_e32 v33, 31, v32
	s_nop 0
	v_addc_co_u32_e32 v27, vcc, 0, v25, vcc
	v_add_co_u32_e32 v28, vcc, s17, v24
	v_lshlrev_b64 v[32:33], 13, v[32:33]
	s_nop 0
	v_addc_co_u32_e32 v29, vcc, 0, v25, vcc
	v_lshl_add_u64 v[56:57], v[34:35], 0, v[32:33]
	v_add_co_u32_e32 v36, vcc, s89, v56
	global_load_dwordx4 v[0:3], v[24:25], off nt
	s_nop 0
	global_load_dwordx4 v[4:7], v[4:5], off nt
	v_addc_co_u32_e32 v37, vcc, 0, v57, vcc
	v_add_co_u32_e32 v40, vcc, s13, v56
	global_load_dwordx4 v[8:11], v[8:9], off nt
	s_nop 0
	global_load_dwordx4 v[12:15], v[12:13], off nt
	v_addc_co_u32_e32 v41, vcc, 0, v57, vcc
	v_add_co_u32_e32 v44, vcc, s12, v56
	global_load_dwordx4 v[16:19], v[16:17], off nt
	s_nop 0
	global_load_dwordx4 v[20:23], v[20:21], off nt
	v_addc_co_u32_e32 v45, vcc, 0, v57, vcc
	v_add_co_u32_e32 v48, vcc, s16, v56
	global_load_dwordx4 v[24:27], v[26:27], off nt
	s_nop 0
	global_load_dwordx4 v[28:31], v[28:29], off nt
	v_addc_co_u32_e32 v49, vcc, 0, v57, vcc
	v_add_co_u32_e32 v52, vcc, s33, v56
	global_load_dwordx4 v[32:35], v[56:57], off nt
	s_nop 0
	global_load_dwordx4 v[36:39], v[36:37], off nt
	v_addc_co_u32_e32 v53, vcc, 0, v57, vcc
	v_add_co_u32_e32 v58, vcc, s38, v56
	global_load_dwordx4 v[40:43], v[40:41], off nt
	s_nop 0
	global_load_dwordx4 v[44:47], v[44:45], off nt
	v_addc_co_u32_e32 v59, vcc, 0, v57, vcc
	v_add_co_u32_e32 v60, vcc, s17, v56
	global_load_dwordx4 v[48:51], v[48:49], off nt
	s_nop 0
	global_load_dwordx4 v[52:55], v[52:53], off nt
	v_addc_co_u32_e32 v61, vcc, 0, v57, vcc
	global_load_dwordx4 v[56:59], v[58:59], off nt
	s_nop 0
	global_load_dwordx4 v[60:63], v[60:61], off nt
	s_ashr_i32 s23, s22, 31
	s_lshl_b64 s[12:13], s[22:23], 1
	v_or_b32_e32 v73, s28, v72
	s_add_u32 s12, s11, s12
	s_addc_u32 s13, s15, s13
	v_mul_i32_i24_e32 v74, 0x1500, v73
	v_lshl_add_u64 v[70:71], v[64:65], 1, s[12:13]
	v_ashrrev_i32_e32 v75, 31, v74
	v_lshl_add_u64 v[70:71], v[74:75], 1, v[70:71]
	s_mov_b32 s11, 0x15100000
	v_add_co_u32_e32 v76, vcc, s11, v70
	s_mov_b32 s11, 0x15102000
	s_nop 0
	v_addc_co_u32_e32 v77, vcc, 0, v71, vcc
	s_waitcnt vmcnt(14)
	v_cvt_pk_bf16_f32 v66, v0, v4
	v_add_co_u32_e32 v4, vcc, s11, v70
	s_waitcnt vmcnt(12)
	v_cvt_pk_bf16_f32 v67, v8, v12
	s_waitcnt vmcnt(10)
	v_cvt_pk_bf16_f32 v68, v16, v20
	s_waitcnt vmcnt(8)
	v_cvt_pk_bf16_f32 v69, v24, v28
	global_store_dwordx4 v[76:77], v[66:69], off nt
	s_mov_b32 s11, 0x15105000
	s_mov_b64 s[12:13], 0x15100000
	v_cvt_pk_bf16_f32 v66, v1, v5
	v_addc_co_u32_e32 v5, vcc, 0, v71, vcc
	v_add_co_u32_e32 v8, vcc, s11, v70
	v_cvt_pk_bf16_f32 v67, v9, v13
	s_mov_b32 s11, 0x15107000
	s_nop 0
	v_addc_co_u32_e32 v9, vcc, 0, v71, vcc
	v_cvt_pk_bf16_f32 v68, v17, v21
	v_cvt_pk_bf16_f32 v69, v25, v29
	global_store_dwordx4 v[4:5], v[66:69], off offset:2560 nt
	v_lshl_add_u64 v[74:75], v[70:71], 0, s[12:13]
	s_nop 0
	v_cvt_pk_bf16_f32 v66, v2, v6
	v_add_co_u32_e32 v6, vcc, s11, v70
	v_cvt_pk_bf16_f32 v67, v10, v14
	v_cvt_pk_bf16_f32 v68, v18, v22
	v_cvt_pk_bf16_f32 v69, v26, v30
	global_store_dwordx4 v[8:9], v[66:69], off offset:1024 nt
	v_cvt_pk_bf16_f32 v0, v3, v7
	v_cvt_pk_bf16_f32 v1, v11, v15
	v_cvt_pk_bf16_f32 v2, v19, v23
	v_cvt_pk_bf16_f32 v3, v27, v31
	s_nop 0
	v_addc_co_u32_e32 v7, vcc, 0, v71, vcc
	global_store_dwordx4 v[6:7], v[0:3], off offset:3584 nt
	s_waitcnt vmcnt(10)
	s_nop 0
	v_cvt_pk_bf16_f32 v0, v32, v36
	s_waitcnt vmcnt(8)
	v_cvt_pk_bf16_f32 v1, v40, v44
	s_waitcnt vmcnt(6)
	v_cvt_pk_bf16_f32 v2, v48, v52
	s_waitcnt vmcnt(4)
	v_cvt_pk_bf16_f32 v3, v56, v60
	global_store_dwordx4 v[74:75], v[0:3], off offset:64 nt
	s_nop 1
	v_cvt_pk_bf16_f32 v0, v33, v37
	v_cvt_pk_bf16_f32 v1, v41, v45
	v_cvt_pk_bf16_f32 v2, v49, v53
	v_cvt_pk_bf16_f32 v3, v57, v61
	global_store_dwordx4 v[4:5], v[0:3], off offset:2624 nt
	s_nop 1
	v_cvt_pk_bf16_f32 v0, v34, v38
	v_cvt_pk_bf16_f32 v1, v42, v46
	v_cvt_pk_bf16_f32 v2, v50, v54
	v_cvt_pk_bf16_f32 v3, v58, v62
	global_store_dwordx4 v[8:9], v[0:3], off offset:1088 nt
	s_nop 1
	v_cvt_pk_bf16_f32 v0, v35, v39
	v_cvt_pk_bf16_f32 v1, v43, v47
	v_cvt_pk_bf16_f32 v2, v51, v55
	v_cvt_pk_bf16_f32 v3, v59, v63
	global_store_dwordx4 v[6:7], v[0:3], off offset:3648 nt

; __device__ __forceinline__ void tr_item(const float* W, int ldw, int k0, int n0, bf16* WT, int ldk, int drow0, int lane) {
; __device__ __forceinline__ void conv_item(int it, int lane) {
;     ...
;     if (r < 8 * IT_GU) { const int idx = r / IT_GU; r -= idx * IT_GU; const int kb = r / 168, nb = r % 168, n0 = 64 * nb;
;         const int drow = n0 < DFF ? (n0 >> 7) * 256 + (n0 & 127) : ((n0 - DFF) >> 7) * 256 + 128 + ((n0 - DFF) & 127);
;         tr_item(INP(I_WGU) + (size_t)idx * 2048 * 10752, 10752, 64 * kb, n0, (bf16*)(ws + WS_WGU) + (size_t)idx * 10752 * 2048, 2048, drow, lane); return; }
;     r -= 8 * IT_GU;
;     if (r < 8 * IT_D) { const int idx = r / IT_D; r -= idx * IT_D; const int kb = r / 32, nb = r % 32;
;         tr_item(INP(I_WD) + (size_t)idx * 5376 * 2048, 2048, 64 * kb, 64 * nb, (bf16*)(ws + WS_WD) + (size_t)idx * 2048 * 5376, 5376, 64 * nb, lane); return; }
;     r -= 8 * IT_D;
;     if (r < 2 * IT_INAB) { const int idx = r / IT_INAB; r -= idx * IT_INAB; const int kb = r / 80, nb = r % 80;
;         tr_item(INP(I_WINAB) + (size_t)idx * 2048 * 5120, 5120, 64 * kb, 64 * nb, (bf16*)(ws + WS_WINAB) + (size_t)idx * 5120 * 2048, 2048, 64 * nb, lane); return; }
;     r -= 2 * IT_INAB;
;     if (r < 2 * IT_GLU) { const int idx = r / IT_GLU; r -= idx * IT_GLU; const int kb = r / 16, nb = r % 16;
;         tr_item(INP(I_WGLU) + (size_t)idx * 1024 * 1024, 1024, 64 * kb, 64 * nb, (bf16*)(ws + WS_WGLU) + (size_t)idx * 1024 * 1024, 1024, 64 * nb, lane); return; }
;     r -= 2 * IT_GLU;
;     if (r < 2 * IT_OUTAB) { const int idx = r / IT_OUTAB; r -= idx * IT_OUTAB; const int kb = r / 32, nb = r % 32;
;         tr_item(INP(I_WOUTAB) + (size_t)idx * 2048 * 2048, 2048, 64 * kb, 64 * nb, (bf16*)(ws + WS_WOUTAB) + (size_t)idx * 2048 * 2048, 2048, 64 * nb, lane); return; }
;     r -= 2 * IT_OUTAB;
;     if (r < 2 * IT_INC) { const int idx = r / IT_INC; r -= idx * IT_INC; const int kb = r / 80, nb = r % 80;
;         tr_item(INP(I_WINC) + (size_t)idx * 2048 * 5120, 5120, 64 * kb, 64 * nb, (bf16*)(ws + WS_WINC) + (size_t)idx * 5120 * 2048, 2048, 64 * nb, lane); return; }
;     r -= 2 * IT_INC;
;     { const int idx = r / IT_OUTC; r -= idx * IT_OUTC; const int kb = r / 32, nb = r % 32;
;       tr_item(INP(I_WOUTC) + (size_t)idx * 2560 * 2048, 2048, 64 * kb, 64 * nb, (bf16*)(ws + WS_WOUTC) + (size_t)idx * 2048 * 2560, 2560, 64 * nb, lane); }
.LBB0_1497:
	s_mov_b64 s[2:3], s[0:1]
	s_load_dwordx2 s[2:3], s[2:3], 0x138
	s_add_i32 s6, s12, s21
	s_mov_b64 s[22:23], -1
	s_cmp_gt_i32 s6, 0xa7ff
	s_cbranch_scc0 .LBB0_1519
	s_cmpk_gt_u32 s6, 0xfbff
	s_cbranch_scc0 .LBB0_1516
	s_cmp_gt_u32 s6, 0x10fff
	s_cbranch_scc0 .LBB0_1513
	s_cmp_gt_u32 s6, 0x111ff
	s_cbranch_scc0 .LBB0_1510
	s_cmp_gt_u32 s6, 0x119ff
	s_cbranch_scc0 .LBB0_1507
	s_cmp_gt_u32 s6, 0x12dff
	s_cbranch_scc0 .LBB0_1504
	s_add_i32 s11, s6, 0xfffed200
	s_mul_hi_u32 s12, s11, 0xcccccccd
	s_lshr_b32 s12, s12, 10
	s_mul_i32 s19, s12, 0xfffffb00
	s_mov_b64 s[20:21], s[0:1]
	s_add_i32 s11, s19, s11
	s_ashr_i32 s19, s11, 31
	s_load_dwordx2 s[20:21], s[20:21], 0x128
	s_lshr_b32 s19, s19, 27
	s_add_i32 s19, s11, s19
	s_and_b32 s22, s19, 0x3ffffe0
	s_sub_i32 s11, s11, s22
	s_mul_i32 s23, s12, 0x1400000
	s_mul_hi_u32 s22, s12, 0x1400000
	s_waitcnt lgkmcnt(0)
	s_add_u32 s23, s20, s23
	s_addc_u32 s28, s21, s22
	s_lshl_b32 s19, s19, 1
	s_and_b32 s22, s19, 0xffffffc0
	s_lshl_b32 s26, s11, 6
	s_mul_hi_u32 s11, s12, 0xa00000
	s_mul_i32 s12, s12, 0xa00000
	s_add_u32 s12, s2, s12
	s_addc_u32 s11, s3, s11
	s_ashr_i32 s27, s26, 31
	s_lshl_b64 s[20:21], s[26:27], 2
	v_add_u32_e32 v32, s22, v66
	s_add_u32 s20, s23, s20
	s_addc_u32 s21, s28, s21
	v_lshlrev_b32_e32 v172, 2, v64
	v_ashrrev_i32_e32 v33, 31, v32
	v_lshl_add_u64 v[34:35], s[20:21], 0, v[172:173]
	v_lshlrev_b64 v[0:1], 13, v[32:33]
	v_lshl_add_u64 v[24:25], v[34:35], 0, v[0:1]
	v_add_co_u32_e32 v4, vcc, s89, v24
	s_movk_i32 s20, 0x4000
	s_nop 0
	v_addc_co_u32_e32 v5, vcc, 0, v25, vcc
	v_add_co_u32_e32 v8, vcc, s20, v24
	s_movk_i32 s19, 0x6000
	s_nop 0
	v_addc_co_u32_e32 v9, vcc, 0, v25, vcc
	v_add_co_u32_e32 v12, vcc, s19, v24
	s_mov_b32 s21, 0x8000
	s_nop 0
	v_addc_co_u32_e32 v13, vcc, 0, v25, vcc
	v_add_co_u32_e32 v16, vcc, s21, v24
	v_add_u32_e32 v32, 32, v32
	s_nop 0
	v_addc_co_u32_e32 v17, vcc, 0, v25, vcc
	v_add_co_u32_e32 v20, vcc, s33, v24
	s_mov_b32 s23, 0xe000
	s_nop 0
	v_addc_co_u32_e32 v21, vcc, 0, v25, vcc
	v_add_co_u32_e32 v26, vcc, s38, v24
	v_ashrrev_i32_e32 v33, 31, v32
	s_nop 0
	v_addc_co_u32_e32 v27, vcc, 0, v25, vcc
	v_add_co_u32_e32 v28, vcc, s23, v24
	v_lshlrev_b64 v[32:33], 13, v[32:33]
	s_nop 0
	v_addc_co_u32_e32 v29, vcc, 0, v25, vcc
	v_lshl_add_u64 v[56:57], v[34:35], 0, v[32:33]
	v_add_co_u32_e32 v36, vcc, s89, v56
	global_load_dwordx4 v[0:3], v[24:25], off nt
	s_nop 0
	global_load_dwordx4 v[4:7], v[4:5], off nt
	v_addc_co_u32_e32 v37, vcc, 0, v57, vcc
	v_add_co_u32_e32 v40, vcc, s20, v56
	global_load_dwordx4 v[8:11], v[8:9], off nt
	s_nop 0
	global_load_dwordx4 v[12:15], v[12:13], off nt
	v_addc_co_u32_e32 v41, vcc, 0, v57, vcc
	v_add_co_u32_e32 v44, vcc, s19, v56
	global_load_dwordx4 v[16:19], v[16:17], off nt
	s_nop 0
	global_load_dwordx4 v[20:23], v[20:21], off nt
	v_addc_co_u32_e32 v45, vcc, 0, v57, vcc
	v_add_co_u32_e32 v48, vcc, s21, v56
	global_load_dwordx4 v[24:27], v[26:27], off nt
	s_nop 0
	global_load_dwordx4 v[28:31], v[28:29], off nt
	v_addc_co_u32_e32 v49, vcc, 0, v57, vcc
	v_add_co_u32_e32 v52, vcc, s33, v56
	global_load_dwordx4 v[32:35], v[56:57], off nt
	s_nop 0
	global_load_dwordx4 v[36:39], v[36:37], off nt
	v_addc_co_u32_e32 v53, vcc, 0, v57, vcc
	v_add_co_u32_e32 v58, vcc, s38, v56
	global_load_dwordx4 v[40:43], v[40:41], off nt
	s_nop 0
	global_load_dwordx4 v[44:47], v[44:45], off nt
	v_addc_co_u32_e32 v59, vcc, 0, v57, vcc
	v_add_co_u32_e32 v60, vcc, s23, v56
	global_load_dwordx4 v[48:51], v[48:49], off nt
	s_nop 0
	global_load_dwordx4 v[52:55], v[52:53], off nt
	v_addc_co_u32_e32 v61, vcc, 0, v57, vcc
	global_load_dwordx4 v[56:59], v[58:59], off nt
	s_nop 0
	global_load_dwordx4 v[60:63], v[60:61], off nt
	s_ashr_i32 s23, s22, 31
	s_lshl_b64 s[20:21], s[22:23], 1
	s_add_u32 s20, s12, s20
	v_or_b32_e32 v65, s26, v64
	s_addc_u32 s21, s11, s21
	s_movk_i32 s11, 0xa00
	v_mul_lo_u32 v74, v65, s11
	v_lshl_add_u64 v[72:73], v[66:67], 1, s[20:21]
	v_ashrrev_i32_e32 v75, 31, v74
	v_lshl_add_u64 v[72:73], v[74:75], 1, v[72:73]
	s_mov_b32 s11, 0x25d00000
	v_add_co_u32_e32 v76, vcc, s11, v72
	s_mov_b32 s11, 0x25d01000
	s_nop 0
	v_addc_co_u32_e32 v77, vcc, 0, v73, vcc
	s_waitcnt vmcnt(14)
	v_cvt_pk_bf16_f32 v68, v0, v4
	v_add_co_u32_e32 v4, vcc, s11, v72
	s_waitcnt vmcnt(12)
	v_cvt_pk_bf16_f32 v69, v8, v12
	s_waitcnt vmcnt(10)
	v_cvt_pk_bf16_f32 v70, v16, v20
	s_waitcnt vmcnt(8)
	v_cvt_pk_bf16_f32 v71, v24, v28
	global_store_dwordx4 v[76:77], v[68:71], off nt
	s_mov_b32 s11, 0x25d02000
	s_mov_b64 s[20:21], 0x25d00000
	v_cvt_pk_bf16_f32 v68, v1, v5
	v_addc_co_u32_e32 v5, vcc, 0, v73, vcc
	v_add_co_u32_e32 v8, vcc, s11, v72
	v_cvt_pk_bf16_f32 v69, v9, v13
	s_mov_b32 s11, 0x25d03000
	s_nop 0
	v_addc_co_u32_e32 v9, vcc, 0, v73, vcc
	v_cvt_pk_bf16_f32 v70, v17, v21
	v_cvt_pk_bf16_f32 v71, v25, v29
	global_store_dwordx4 v[4:5], v[68:71], off offset:1024 nt
	v_lshl_add_u64 v[74:75], v[72:73], 0, s[20:21]
	s_mov_b64 s[22:23], 0
	v_cvt_pk_bf16_f32 v68, v2, v6
	v_add_co_u32_e32 v6, vcc, s11, v72
	v_cvt_pk_bf16_f32 v69, v10, v14
	v_cvt_pk_bf16_f32 v70, v18, v22
	v_cvt_pk_bf16_f32 v71, v26, v30
	global_store_dwordx4 v[8:9], v[68:71], off offset:2048 nt
	v_cvt_pk_bf16_f32 v0, v3, v7
	v_cvt_pk_bf16_f32 v1, v11, v15
	v_cvt_pk_bf16_f32 v2, v19, v23
	v_cvt_pk_bf16_f32 v3, v27, v31
	s_nop 0
	v_addc_co_u32_e32 v7, vcc, 0, v73, vcc
	global_store_dwordx4 v[6:7], v[0:3], off offset:3072 nt
	s_waitcnt vmcnt(10)
	s_nop 0
	v_cvt_pk_bf16_f32 v0, v32, v36
	s_waitcnt vmcnt(8)
	v_cvt_pk_bf16_f32 v1, v40, v44
	s_waitcnt vmcnt(6)
	v_cvt_pk_bf16_f32 v2, v48, v52
	s_waitcnt vmcnt(4)
	v_cvt_pk_bf16_f32 v3, v56, v60
	global_store_dwordx4 v[74:75], v[0:3], off offset:64 nt
	s_nop 1
	v_cvt_pk_bf16_f32 v0, v33, v37
	v_cvt_pk_bf16_f32 v1, v41, v45
	v_cvt_pk_bf16_f32 v2, v49, v53
	v_cvt_pk_bf16_f32 v3, v57, v61
	global_store_dwordx4 v[4:5], v[0:3], off offset:1088 nt
	s_nop 1
	v_cvt_pk_bf16_f32 v0, v34, v38
	v_cvt_pk_bf16_f32 v1, v42, v46
	v_cvt_pk_bf16_f32 v2, v50, v54
	v_cvt_pk_bf16_f32 v3, v58, v62
	global_store_dwordx4 v[8:9], v[0:3], off offset:2112 nt
	s_nop 1
	v_cvt_pk_bf16_f32 v0, v35, v39
	v_cvt_pk_bf16_f32 v1, v43, v47
	v_cvt_pk_bf16_f32 v2, v51, v55
	v_cvt_pk_bf16_f32 v3, v59, v63
	global_store_dwordx4 v[6:7], v[0:3], off offset:3136 nt
; __device__ __forceinline__ unsigned cvt_pk_bf16(float lo, float hi) { unsigned r; asm volatile("v_cvt_pk_bf16_f32 %0, %1, %2" : "=v"(r) : "v"(lo), "v"(hi)); return r; }
; #define INP(i) ((const float*)(const GASP float*)kargs()[(i)])
; __device__ __forceinline__ void tr_item(const float* W, int ldw, int k0, int n0, bf16* WT, int ldk, int drow0, int lane) {
;     const int n4 = (lane & 15) * 4, kg = lane >> 4; f32x4 v[2][8];
; #pragma unroll
;     for (int kh = 0; kh < 2; ++kh) { const float* src = W + (size_t)(k0 + kh * 32 + kg * 8) * ldw + n0 + n4;
; #pragma unroll
;         for (int i = 0; i < 8; ++i) v[kh][i] = __builtin_nontemporal_load((const f32x4*)(src + (size_t)i * ldw)); }
; #pragma unroll
;     for (int kh = 0; kh < 2; ++kh)
; #pragma unroll
;         for (int e = 0; e < 4; ++e) { u32x4 o; o.x = cvt_pk_bf16(v[kh][0][e], v[kh][1][e]); o.y = cvt_pk_bf16(v[kh][2][e], v[kh][3][e]); o.z = cvt_pk_bf16(v[kh][4][e], v[kh][5][e]); o.w = cvt_pk_bf16(v[kh][6][e], v[kh][7][e]);
;             *(u32x4*)(WT + (size_t)(drow0 + n4 + e) * ldk + k0 + kh * 32 + kg * 8) = o; }
; }
; __device__ __forceinline__ void conv_item(int it, int lane) {
;     ...
;     if (r < 2 * IT_INC) { const int idx = r / IT_INC; r -= idx * IT_INC; const int kb = r / 80, nb = r % 80;
;         tr_item(INP(I_WINC) + (size_t)idx * 2048 * 5120, 5120, 64 * kb, 64 * nb, (bf16*)(ws + WS_WINC) + (size_t)idx * 5120 * 2048, 2048, 64 * nb, lane); return; }
.LBB0_1504:
	s_andn2_b64 vcc, exec, s[22:23]
	s_cbranch_vccnz .LBB0_1506
	s_add_i32 s11, s6, 0xfffee600
	s_cmpk_gt_u32 s11, 0x9ff
	s_cselect_b64 s[20:21], -1, 0
	s_and_b64 s[22:23], s[20:21], exec
	s_cselect_b32 s12, 0xf600, 0
	s_add_i32 s12, s12, s11
	s_sext_i32_i16 s11, s12
	s_mulk_i32 s11, 0x6667
	s_mov_b64 s[22:23], s[0:1]
	s_lshr_b32 s19, s11, 31
	s_ashr_i32 s11, s11, 21
	s_add_i32 s11, s11, s19
	s_load_dwordx2 s[22:23], s[22:23], 0xe8
	s_mul_i32 s19, s11, 0x50
	s_sub_i32 s12, s12, s19
	s_and_b64 s[26:27], s[20:21], exec
	s_cselect_b32 s19, 0x2800000, 0
	s_sext_i32_i16 s12, s12
	s_waitcnt lgkmcnt(0)
	s_add_u32 s19, s22, s19
	s_addc_u32 s23, s23, 0
	s_lshl_b32 s22, s11, 6
	s_lshl_b32 s26, s12, 6
	s_and_b64 s[20:21], s[20:21], exec
	s_cselect_b32 s11, 0x1400000, 0
	s_add_u32 s11, s2, s11
	s_addc_u32 s12, s3, 0
	s_ashr_i32 s27, s26, 31
	s_lshl_b64 s[20:21], s[26:27], 2
	s_add_u32 s20, s19, s20
	s_addc_u32 s21, s23, s21
	v_lshlrev_b32_e32 v172, 2, v64
	v_add_u32_e32 v34, s22, v66
	v_lshl_add_u64 v[32:33], s[20:21], 0, v[172:173]
	s_movk_i32 s27, 0x5000
	v_mad_i64_i32 v[24:25], s[20:21], v34, s27, v[32:33]
	v_add_co_u32_e32 v4, vcc, s27, v24
	s_mov_b32 s19, 0x14000
	s_nop 0
	v_addc_co_u32_e32 v5, vcc, 0, v25, vcc
	v_add_co_u32_e32 v8, vcc, s33, v24
	s_mov_b32 s28, 0x19000
	s_nop 0
	v_addc_co_u32_e32 v9, vcc, 0, v25, vcc
	v_add_co_u32_e32 v12, vcc, s76, v24
	s_mov_b32 s23, 0x1e000
	s_nop 0
	v_addc_co_u32_e32 v13, vcc, 0, v25, vcc
	v_add_co_u32_e32 v16, vcc, s19, v24
	v_add_u32_e32 v34, 32, v34
	s_nop 0
	v_addc_co_u32_e32 v17, vcc, 0, v25, vcc
	v_add_co_u32_e32 v20, vcc, s28, v24
	v_mad_i64_i32 v[56:57], s[20:21], v34, s27, v[32:33]
	s_nop 0
	v_addc_co_u32_e32 v21, vcc, 0, v25, vcc
	v_add_co_u32_e32 v26, vcc, s23, v24
	global_load_dwordx4 v[0:3], v[24:25], off nt
	s_nop 0
	global_load_dwordx4 v[4:7], v[4:5], off nt
	v_addc_co_u32_e32 v27, vcc, 0, v25, vcc
	v_add_co_u32_e32 v28, vcc, s77, v24
	global_load_dwordx4 v[8:11], v[8:9], off nt
	s_nop 0
	global_load_dwordx4 v[12:15], v[12:13], off nt
	v_addc_co_u32_e32 v29, vcc, 0, v25, vcc
	v_add_co_u32_e32 v36, vcc, s27, v56
	global_load_dwordx4 v[16:19], v[16:17], off nt
	s_nop 0
	global_load_dwordx4 v[20:23], v[20:21], off nt
	v_addc_co_u32_e32 v37, vcc, 0, v57, vcc
	v_add_co_u32_e32 v40, vcc, s33, v56
	global_load_dwordx4 v[24:27], v[26:27], off nt
	s_nop 0
	global_load_dwordx4 v[28:31], v[28:29], off nt
	v_addc_co_u32_e32 v41, vcc, 0, v57, vcc
	v_add_co_u32_e32 v44, vcc, s76, v56
	global_load_dwordx4 v[32:35], v[56:57], off nt
	s_nop 0
	global_load_dwordx4 v[36:39], v[36:37], off nt
	v_addc_co_u32_e32 v45, vcc, 0, v57, vcc
	v_add_co_u32_e32 v48, vcc, s19, v56
	global_load_dwordx4 v[40:43], v[40:41], off nt
	s_nop 0
	global_load_dwordx4 v[44:47], v[44:45], off nt
	v_addc_co_u32_e32 v49, vcc, 0, v57, vcc
	v_add_co_u32_e32 v52, vcc, s28, v56
	v_or_b32_e32 v72, s26, v64
	s_nop 0
	v_addc_co_u32_e32 v53, vcc, 0, v57, vcc
	v_add_co_u32_e32 v58, vcc, s23, v56
	global_load_dwordx4 v[48:51], v[48:49], off nt
	s_nop 0
	global_load_dwordx4 v[52:55], v[52:53], off nt
	v_addc_co_u32_e32 v59, vcc, 0, v57, vcc
	v_add_co_u32_e32 v60, vcc, s77, v56
	s_ashr_i32 s23, s22, 31
	s_nop 0
	v_addc_co_u32_e32 v61, vcc, 0, v57, vcc
	global_load_dwordx4 v[56:59], v[58:59], off nt
	s_nop 0
	global_load_dwordx4 v[60:63], v[60:61], off nt
	s_lshl_b64 s[20:21], s[22:23], 1
	s_add_u32 s20, s11, s20
	s_addc_u32 s21, s12, s21
	v_lshl_add_u64 v[68:69], v[66:67], 1, s[20:21]
	s_mov_b64 s[20:21], 0x23500000
	v_ashrrev_i32_e32 v73, 31, v72
	v_lshl_add_u64 v[74:75], v[68:69], 0, s[20:21]
	v_lshlrev_b64 v[76:77], 12, v[72:73]
	s_waitcnt vmcnt(14)
	v_cvt_pk_bf16_f32 v68, v0, v4
	v_lshl_add_u64 v[76:77], v[74:75], 0, v[76:77]
	v_or_b32_e32 v0, 1, v72
	s_waitcnt vmcnt(12)
	v_cvt_pk_bf16_f32 v69, v8, v12
	s_waitcnt vmcnt(10)
	v_cvt_pk_bf16_f32 v70, v16, v20
	s_waitcnt vmcnt(8)
	v_cvt_pk_bf16_f32 v71, v24, v28
	global_store_dwordx4 v[76:77], v[68:71], off nt
	s_nop 1
	v_cvt_pk_bf16_f32 v68, v1, v5
	v_ashrrev_i32_e32 v1, 31, v0
	v_lshlrev_b64 v[0:1], 12, v[0:1]
	v_lshl_add_u64 v[4:5], v[74:75], 0, v[0:1]
	v_or_b32_e32 v0, 2, v72
	v_ashrrev_i32_e32 v1, 31, v0
	v_lshlrev_b64 v[0:1], 12, v[0:1]
	v_cvt_pk_bf16_f32 v69, v9, v13
	v_cvt_pk_bf16_f32 v70, v17, v21
	v_cvt_pk_bf16_f32 v71, v25, v29
	global_store_dwordx4 v[4:5], v[68:71], off nt
	v_lshl_add_u64 v[8:9], v[74:75], 0, v[0:1]
	s_nop 0
	v_cvt_pk_bf16_f32 v68, v2, v6
	v_or_b32_e32 v6, 3, v72
	v_cvt_pk_bf16_f32 v69, v10, v14
	v_cvt_pk_bf16_f32 v70, v18, v22
	v_cvt_pk_bf16_f32 v71, v26, v30
	global_store_dwordx4 v[8:9], v[68:71], off nt
	v_cvt_pk_bf16_f32 v0, v3, v7
	v_ashrrev_i32_e32 v7, 31, v6
	v_lshlrev_b64 v[6:7], 12, v[6:7]
	v_cvt_pk_bf16_f32 v1, v11, v15
	v_cvt_pk_bf16_f32 v2, v19, v23
	v_cvt_pk_bf16_f32 v3, v27, v31
	v_lshl_add_u64 v[6:7], v[74:75], 0, v[6:7]
	global_store_dwordx4 v[6:7], v[0:3], off nt
	s_waitcnt vmcnt(10)
	s_nop 0
	v_cvt_pk_bf16_f32 v0, v32, v36
	s_waitcnt vmcnt(8)
	v_cvt_pk_bf16_f32 v1, v40, v44
	s_waitcnt vmcnt(6)
	v_cvt_pk_bf16_f32 v2, v48, v52
	s_waitcnt vmcnt(4)
	v_cvt_pk_bf16_f32 v3, v56, v60
	global_store_dwordx4 v[76:77], v[0:3], off offset:64 nt
	s_nop 1
	v_cvt_pk_bf16_f32 v0, v33, v37
	v_cvt_pk_bf16_f32 v1, v41, v45
	v_cvt_pk_bf16_f32 v2, v49, v53
	v_cvt_pk_bf16_f32 v3, v57, v61
	global_store_dwordx4 v[4:5], v[0:3], off offset:64 nt
	s_nop 1
	v_cvt_pk_bf16_f32 v0, v34, v38
	v_cvt_pk_bf16_f32 v1, v42, v46
	v_cvt_pk_bf16_f32 v2, v50, v54
	v_cvt_pk_bf16_f32 v3, v58, v62
	global_store_dwordx4 v[8:9], v[0:3], off offset:64 nt
	s_nop 1
	v_cvt_pk_bf16_f32 v0, v35, v39
	v_cvt_pk_bf16_f32 v1, v43, v47
	v_cvt_pk_bf16_f32 v2, v51, v55
	v_cvt_pk_bf16_f32 v3, v59, v63
	global_store_dwordx4 v[6:7], v[0:3], off offset:64 nt

; __device__ __forceinline__ unsigned cvt_pk_bf16(float lo, float hi) { unsigned r; asm volatile("v_cvt_pk_bf16_f32 %0, %1, %2" : "=v"(r) : "v"(lo), "v"(hi)); return r; }
; #define INP(i) ((const float*)(const GASP float*)kargs()[(i)])
; __device__ __forceinline__ void tr_item(const float* W, int ldw, int k0, int n0, bf16* WT, int ldk, int drow0, int lane) {
;     const int n4 = (lane & 15) * 4, kg = lane >> 4; f32x4 v[2][8];
; #pragma unroll
;     for (int kh = 0; kh < 2; ++kh) { const float* src = W + (size_t)(k0 + kh * 32 + kg * 8) * ldw + n0 + n4;
; #pragma unroll
;         for (int i = 0; i < 8; ++i) v[kh][i] = __builtin_nontemporal_load((const f32x4*)(src + (size_t)i * ldw)); }
; #pragma unroll
;     for (int kh = 0; kh < 2; ++kh)
; #pragma unroll
;         for (int e = 0; e < 4; ++e) { u32x4 o; o.x = cvt_pk_bf16(v[kh][0][e], v[kh][1][e]); o.y = cvt_pk_bf16(v[kh][2][e], v[kh][3][e]); o.z = cvt_pk_bf16(v[kh][4][e], v[kh][5][e]); o.w = cvt_pk_bf16(v[kh][6][e], v[kh][7][e]);
;             *(u32x4*)(WT + (size_t)(drow0 + n4 + e) * ldk + k0 + kh * 32 + kg * 8) = o; }
; }
; __device__ __forceinline__ void conv_item(int it, int lane) {
;     ...
;     if (r < 2 * IT_OUTAB) { const int idx = r / IT_OUTAB; r -= idx * IT_OUTAB; const int kb = r / 32, nb = r % 32;
;         tr_item(INP(I_WOUTAB) + (size_t)idx * 2048 * 2048, 2048, 64 * kb, 64 * nb, (bf16*)(ws + WS_WOUTAB) + (size_t)idx * 2048 * 2048, 2048, 64 * nb, lane); return; }
.LBB0_1507:
	s_andn2_b64 vcc, exec, s[22:23]
	s_cbranch_vccnz .LBB0_1509
	s_mov_b64 s[20:21], s[0:1]
	s_load_dwordx2 s[20:21], s[20:21], 0xe0
	s_add_i32 s11, s6, 0xfffeee00
	s_lshr_b32 s38, s11, 10
	s_lshl_b64 s[22:23], s[38:39], 24
	v_lshlrev_b32_e32 v172, 2, v64
	s_waitcnt lgkmcnt(0)
	s_add_u32 s12, s20, s22
	s_addc_u32 s19, s21, s23
	s_lshl_b32 s11, s11, 1
	s_lshl_b32 s20, s6, 6
	s_and_b32 s11, s11, 0x7c0
	s_and_b32 s22, s20, 0x7c0
	s_lshl_b64 s[20:21], s[38:39], 23
	s_add_u32 s23, s2, s20
	s_addc_u32 s26, s3, s21
	s_lshl_b32 s20, s22, 2
	v_add_u32_e32 v32, s11, v66
	s_add_u32 s20, s12, s20
	s_addc_u32 s21, s19, 0
	v_ashrrev_i32_e32 v33, 31, v32
	v_lshl_add_u64 v[34:35], s[20:21], 0, v[172:173]
	v_lshlrev_b64 v[0:1], 13, v[32:33]
	v_lshl_add_u64 v[24:25], v[34:35], 0, v[0:1]
	v_add_co_u32_e32 v4, vcc, s89, v24
	s_movk_i32 s19, 0x4000
	s_nop 0
	v_addc_co_u32_e32 v5, vcc, 0, v25, vcc
	v_add_co_u32_e32 v8, vcc, s19, v24
	s_movk_i32 s12, 0x6000
	s_nop 0
	v_addc_co_u32_e32 v9, vcc, 0, v25, vcc
	v_add_co_u32_e32 v12, vcc, s12, v24
	s_mov_b32 s20, 0x8000
	s_nop 0
	v_addc_co_u32_e32 v13, vcc, 0, v25, vcc
	v_add_co_u32_e32 v16, vcc, s20, v24
	s_mov_b32 s38, 0xc000
	s_nop 0
	v_addc_co_u32_e32 v17, vcc, 0, v25, vcc
	v_add_co_u32_e32 v20, vcc, s33, v24
	v_add_u32_e32 v32, 32, v32
	s_nop 0
	v_addc_co_u32_e32 v21, vcc, 0, v25, vcc
	v_add_co_u32_e32 v26, vcc, s38, v24
	s_mov_b32 s21, 0xe000
	s_nop 0
	v_addc_co_u32_e32 v27, vcc, 0, v25, vcc
	v_ashrrev_i32_e32 v33, 31, v32
	v_add_co_u32_e32 v28, vcc, s21, v24
	v_lshlrev_b64 v[32:33], 13, v[32:33]
	s_nop 0
	v_addc_co_u32_e32 v29, vcc, 0, v25, vcc
	v_lshl_add_u64 v[56:57], v[34:35], 0, v[32:33]
	v_add_co_u32_e32 v36, vcc, s89, v56
	global_load_dwordx4 v[0:3], v[24:25], off nt
	s_nop 0
	global_load_dwordx4 v[4:7], v[4:5], off nt
	v_addc_co_u32_e32 v37, vcc, 0, v57, vcc
	v_add_co_u32_e32 v40, vcc, s19, v56
	global_load_dwordx4 v[8:11], v[8:9], off nt
	s_nop 0
	global_load_dwordx4 v[12:15], v[12:13], off nt
	v_addc_co_u32_e32 v41, vcc, 0, v57, vcc
	v_add_co_u32_e32 v44, vcc, s12, v56
	global_load_dwordx4 v[16:19], v[16:17], off nt
	s_nop 0
	global_load_dwordx4 v[20:23], v[20:21], off nt
	v_addc_co_u32_e32 v45, vcc, 0, v57, vcc
	v_add_co_u32_e32 v48, vcc, s20, v56
	global_load_dwordx4 v[24:27], v[26:27], off nt
	s_nop 0
	global_load_dwordx4 v[28:31], v[28:29], off nt
	v_addc_co_u32_e32 v49, vcc, 0, v57, vcc
	v_add_co_u32_e32 v52, vcc, s33, v56
	global_load_dwordx4 v[32:35], v[56:57], off nt
	s_nop 0
	global_load_dwordx4 v[36:39], v[36:37], off nt
	v_addc_co_u32_e32 v53, vcc, 0, v57, vcc
	v_add_co_u32_e32 v58, vcc, s38, v56
	global_load_dwordx4 v[40:43], v[40:41], off nt
	s_nop 0
	global_load_dwordx4 v[44:47], v[44:45], off nt
	v_addc_co_u32_e32 v59, vcc, 0, v57, vcc
	v_add_co_u32_e32 v60, vcc, s21, v56
	global_load_dwordx4 v[48:51], v[48:49], off nt
	s_nop 0
	global_load_dwordx4 v[52:55], v[52:53], off nt
	v_addc_co_u32_e32 v61, vcc, 0, v57, vcc
	global_load_dwordx4 v[56:59], v[58:59], off nt
	s_nop 0
	global_load_dwordx4 v[60:63], v[60:61], off nt
	s_lshl_b32 s11, s11, 1
	s_add_u32 s20, s23, s11
	s_addc_u32 s21, s26, 0
	v_or_b32_e32 v65, s22, v64
	v_lshl_add_u64 v[72:73], v[66:67], 1, s[20:21]
	s_mov_b64 s[20:21], 0x22500000
	v_lshl_add_u64 v[74:75], v[72:73], 0, s[20:21]
	v_lshlrev_b32_e32 v172, 12, v65
	s_waitcnt vmcnt(14)
	v_cvt_pk_bf16_f32 v68, v0, v4
	v_lshl_add_u64 v[76:77], v[74:75], 0, v[172:173]
	s_waitcnt vmcnt(12)
	v_cvt_pk_bf16_f32 v69, v8, v12
	s_waitcnt vmcnt(10)
	v_cvt_pk_bf16_f32 v70, v16, v20
	s_waitcnt vmcnt(8)
	v_cvt_pk_bf16_f32 v71, v24, v28
	global_store_dwordx4 v[76:77], v[68:71], off nt
	v_or_b32_e32 v4, 0x1000, v172
	v_or_b32_e32 v8, 0x2000, v172
	v_cvt_pk_bf16_f32 v68, v1, v5
	v_mov_b32_e32 v5, v173
	v_cvt_pk_bf16_f32 v69, v9, v13
	v_lshl_add_u64 v[0:1], v[74:75], 0, v[4:5]
	v_mov_b32_e32 v9, v173
	v_cvt_pk_bf16_f32 v70, v17, v21
	v_cvt_pk_bf16_f32 v71, v25, v29
	global_store_dwordx4 v[0:1], v[68:71], off nt
	v_lshl_add_u64 v[0:1], v[74:75], 0, v[8:9]
	v_or_b32_e32 v172, 0x3000, v172
	v_cvt_pk_bf16_f32 v68, v2, v6
	v_cvt_pk_bf16_f32 v69, v10, v14
	v_cvt_pk_bf16_f32 v70, v18, v22
	v_cvt_pk_bf16_f32 v71, v26, v30
	global_store_dwordx4 v[0:1], v[68:71], off nt
	v_cvt_pk_bf16_f32 v0, v3, v7
	v_lshl_add_u64 v[6:7], v[74:75], 0, v[172:173]
	s_mov_b64 s[20:21], 0x22500040
	v_cvt_pk_bf16_f32 v1, v11, v15
	v_cvt_pk_bf16_f32 v2, v19, v23
	v_cvt_pk_bf16_f32 v3, v27, v31
	global_store_dwordx4 v[6:7], v[0:3], off nt
	v_lshl_add_u64 v[6:7], v[72:73], 0, s[20:21]
	v_lshl_add_u64 v[4:5], v[6:7], 0, v[4:5]
	s_waitcnt vmcnt(10)
	v_cvt_pk_bf16_f32 v0, v32, v36
	s_waitcnt vmcnt(8)
	v_cvt_pk_bf16_f32 v1, v40, v44
	s_waitcnt vmcnt(6)
	v_cvt_pk_bf16_f32 v2, v48, v52
	s_waitcnt vmcnt(4)
	v_cvt_pk_bf16_f32 v3, v56, v60
	global_store_dwordx4 v[76:77], v[0:3], off offset:64 nt
	s_nop 1
	v_cvt_pk_bf16_f32 v0, v33, v37
	v_cvt_pk_bf16_f32 v1, v41, v45
	v_cvt_pk_bf16_f32 v2, v49, v53
	v_cvt_pk_bf16_f32 v3, v57, v61
	global_store_dwordx4 v[4:5], v[0:3], off nt
	v_lshl_add_u64 v[4:5], v[6:7], 0, v[8:9]
	s_nop 0
	v_cvt_pk_bf16_f32 v0, v34, v38
	v_cvt_pk_bf16_f32 v1, v42, v46
	v_cvt_pk_bf16_f32 v2, v50, v54
	v_cvt_pk_bf16_f32 v3, v58, v62
	global_store_dwordx4 v[4:5], v[0:3], off nt
	v_lshl_add_u64 v[4:5], v[6:7], 0, v[172:173]
	s_nop 0
	v_cvt_pk_bf16_f32 v0, v35, v39
	v_cvt_pk_bf16_f32 v1, v43, v47
	v_cvt_pk_bf16_f32 v2, v51, v55
	v_cvt_pk_bf16_f32 v3, v59, v63
	global_store_dwordx4 v[4:5], v[0:3], off nt

; __device__ __forceinline__ unsigned cvt_pk_bf16(float lo, float hi) { unsigned r; asm volatile("v_cvt_pk_bf16_f32 %0, %1, %2" : "=v"(r) : "v"(lo), "v"(hi)); return r; }
; #define INP(i) ((const float*)(const GASP float*)kargs()[(i)])
; __device__ __forceinline__ void tr_item(const float* W, int ldw, int k0, int n0, bf16* WT, int ldk, int drow0, int lane) {
;     const int n4 = (lane & 15) * 4, kg = lane >> 4; f32x4 v[2][8];
; #pragma unroll
;     for (int kh = 0; kh < 2; ++kh) { const float* src = W + (size_t)(k0 + kh * 32 + kg * 8) * ldw + n0 + n4;
; #pragma unroll
;         for (int i = 0; i < 8; ++i) v[kh][i] = __builtin_nontemporal_load((const f32x4*)(src + (size_t)i * ldw)); }
; #pragma unroll
;     for (int kh = 0; kh < 2; ++kh)
; #pragma unroll
;         for (int e = 0; e < 4; ++e) { u32x4 o; o.x = cvt_pk_bf16(v[kh][0][e], v[kh][1][e]); o.y = cvt_pk_bf16(v[kh][2][e], v[kh][3][e]); o.z = cvt_pk_bf16(v[kh][4][e], v[kh][5][e]); o.w = cvt_pk_bf16(v[kh][6][e], v[kh][7][e]);
;             *(u32x4*)(WT + (size_t)(drow0 + n4 + e) * ldk + k0 + kh * 32 + kg * 8) = o; }
; }
; __device__ __forceinline__ void conv_item(int it, int lane) {
;     ...
;     if (r < 2 * IT_INAB) { const int idx = r / IT_INAB; r -= idx * IT_INAB; const int kb = r / 80, nb = r % 80;
;         tr_item(INP(I_WINAB) + (size_t)idx * 2048 * 5120, 5120, 64 * kb, 64 * nb, (bf16*)(ws + WS_WINAB) + (size_t)idx * 5120 * 2048, 2048, 64 * nb, lane); return; }
.LBB0_1513:
	s_andn2_b64 vcc, exec, s[22:23]
	s_cbranch_vccnz .LBB0_1515
	s_add_i32 s11, s6, 0xffff0400
	s_cmpk_gt_u32 s11, 0x9ff
	s_cselect_b64 s[20:21], -1, 0
	s_and_b64 s[22:23], s[20:21], exec
	s_cselect_b32 s12, 0xf600, 0
	s_add_i32 s12, s12, s11
	s_sext_i32_i16 s11, s12
	s_mulk_i32 s11, 0x6667
	s_mov_b64 s[22:23], s[0:1]
	s_lshr_b32 s19, s11, 31
	s_ashr_i32 s11, s11, 21
	s_add_i32 s11, s11, s19
	s_load_dwordx2 s[22:23], s[22:23], 0x78
	s_mul_i32 s19, s11, 0x50
	s_sub_i32 s12, s12, s19
	s_and_b64 s[26:27], s[20:21], exec
	s_cselect_b32 s19, 0x2800000, 0
	s_sext_i32_i16 s12, s12
	s_waitcnt lgkmcnt(0)
	s_add_u32 s19, s22, s19
	s_addc_u32 s23, s23, 0
	s_lshl_b32 s22, s11, 6
	s_lshl_b32 s26, s12, 6
	s_and_b64 s[20:21], s[20:21], exec
	s_cselect_b32 s11, 0x1400000, 0
	s_add_u32 s11, s2, s11
	s_addc_u32 s12, s3, 0
	s_ashr_i32 s27, s26, 31
	s_lshl_b64 s[20:21], s[26:27], 2
	s_add_u32 s20, s19, s20
	s_addc_u32 s21, s23, s21
	v_lshlrev_b32_e32 v172, 2, v64
	v_add_u32_e32 v34, s22, v66
	v_lshl_add_u64 v[32:33], s[20:21], 0, v[172:173]
	s_movk_i32 s27, 0x5000
	v_mad_i64_i32 v[24:25], s[20:21], v34, s27, v[32:33]
	v_add_co_u32_e32 v4, vcc, s27, v24
	s_mov_b32 s19, 0x14000
	s_nop 0
	v_addc_co_u32_e32 v5, vcc, 0, v25, vcc
	v_add_co_u32_e32 v8, vcc, s33, v24
	s_mov_b32 s28, 0x19000
	s_nop 0
	v_addc_co_u32_e32 v9, vcc, 0, v25, vcc
	v_add_co_u32_e32 v12, vcc, s76, v24
	s_mov_b32 s23, 0x1e000
	s_nop 0
	v_addc_co_u32_e32 v13, vcc, 0, v25, vcc
	v_add_co_u32_e32 v16, vcc, s19, v24
	v_add_u32_e32 v34, 32, v34
	s_nop 0
	v_addc_co_u32_e32 v17, vcc, 0, v25, vcc
	v_add_co_u32_e32 v20, vcc, s28, v24
	v_mad_i64_i32 v[56:57], s[20:21], v34, s27, v[32:33]
	s_nop 0
	v_addc_co_u32_e32 v21, vcc, 0, v25, vcc
	v_add_co_u32_e32 v26, vcc, s23, v24
	global_load_dwordx4 v[0:3], v[24:25], off nt
	s_nop 0
	global_load_dwordx4 v[4:7], v[4:5], off nt
	v_addc_co_u32_e32 v27, vcc, 0, v25, vcc
	v_add_co_u32_e32 v28, vcc, s77, v24
	global_load_dwordx4 v[8:11], v[8:9], off nt
	s_nop 0
	global_load_dwordx4 v[12:15], v[12:13], off nt
	v_addc_co_u32_e32 v29, vcc, 0, v25, vcc
	v_add_co_u32_e32 v36, vcc, s27, v56
	global_load_dwordx4 v[16:19], v[16:17], off nt
	s_nop 0
	global_load_dwordx4 v[20:23], v[20:21], off nt
	v_addc_co_u32_e32 v37, vcc, 0, v57, vcc
	v_add_co_u32_e32 v40, vcc, s33, v56
	global_load_dwordx4 v[24:27], v[26:27], off nt
	s_nop 0
	global_load_dwordx4 v[28:31], v[28:29], off nt
	v_addc_co_u32_e32 v41, vcc, 0, v57, vcc
	v_add_co_u32_e32 v44, vcc, s76, v56
	global_load_dwordx4 v[32:35], v[56:57], off nt
	s_nop 0
	global_load_dwordx4 v[36:39], v[36:37], off nt
	v_addc_co_u32_e32 v45, vcc, 0, v57, vcc
	v_add_co_u32_e32 v48, vcc, s19, v56
	global_load_dwordx4 v[40:43], v[40:41], off nt
	s_nop 0
	global_load_dwordx4 v[44:47], v[44:45], off nt
	v_addc_co_u32_e32 v49, vcc, 0, v57, vcc
	v_add_co_u32_e32 v52, vcc, s28, v56
	v_or_b32_e32 v72, s26, v64
	s_nop 0
	v_addc_co_u32_e32 v53, vcc, 0, v57, vcc
	v_add_co_u32_e32 v58, vcc, s23, v56
	global_load_dwordx4 v[48:51], v[48:49], off nt
	s_nop 0
	global_load_dwordx4 v[52:55], v[52:53], off nt
	v_addc_co_u32_e32 v59, vcc, 0, v57, vcc
	v_add_co_u32_e32 v60, vcc, s77, v56
	s_ashr_i32 s23, s22, 31
	s_nop 0
	v_addc_co_u32_e32 v61, vcc, 0, v57, vcc
	global_load_dwordx4 v[56:59], v[58:59], off nt
	s_nop 0
	global_load_dwordx4 v[60:63], v[60:61], off nt
	s_lshl_b64 s[20:21], s[22:23], 1
	s_add_u32 s20, s11, s20
	s_addc_u32 s21, s12, s21
	v_lshl_add_u64 v[68:69], v[66:67], 1, s[20:21]
	s_mov_b64 s[20:21], 0x1f900000
	v_ashrrev_i32_e32 v73, 31, v72
	v_lshl_add_u64 v[74:75], v[68:69], 0, s[20:21]
	v_lshlrev_b64 v[76:77], 12, v[72:73]
	s_waitcnt vmcnt(14)
	v_cvt_pk_bf16_f32 v68, v0, v4
	v_lshl_add_u64 v[76:77], v[74:75], 0, v[76:77]
	v_or_b32_e32 v0, 1, v72
	s_waitcnt vmcnt(12)
	v_cvt_pk_bf16_f32 v69, v8, v12
	s_waitcnt vmcnt(10)
	v_cvt_pk_bf16_f32 v70, v16, v20
	s_waitcnt vmcnt(8)
	v_cvt_pk_bf16_f32 v71, v24, v28
	global_store_dwordx4 v[76:77], v[68:71], off nt
	s_nop 1
	v_cvt_pk_bf16_f32 v68, v1, v5
	v_ashrrev_i32_e32 v1, 31, v0
	v_lshlrev_b64 v[0:1], 12, v[0:1]
	v_lshl_add_u64 v[4:5], v[74:75], 0, v[0:1]
	v_or_b32_e32 v0, 2, v72
	v_ashrrev_i32_e32 v1, 31, v0
	v_lshlrev_b64 v[0:1], 12, v[0:1]
	v_cvt_pk_bf16_f32 v69, v9, v13
	v_cvt_pk_bf16_f32 v70, v17, v21
	v_cvt_pk_bf16_f32 v71, v25, v29
	global_store_dwordx4 v[4:5], v[68:71], off nt
	v_lshl_add_u64 v[8:9], v[74:75], 0, v[0:1]
	s_nop 0
	v_cvt_pk_bf16_f32 v68, v2, v6
	v_or_b32_e32 v6, 3, v72
	v_cvt_pk_bf16_f32 v69, v10, v14
	v_cvt_pk_bf16_f32 v70, v18, v22
	v_cvt_pk_bf16_f32 v71, v26, v30
	global_store_dwordx4 v[8:9], v[68:71], off nt
	v_cvt_pk_bf16_f32 v0, v3, v7
	v_ashrrev_i32_e32 v7, 31, v6
	v_lshlrev_b64 v[6:7], 12, v[6:7]
	v_cvt_pk_bf16_f32 v1, v11, v15
	v_cvt_pk_bf16_f32 v2, v19, v23
	v_cvt_pk_bf16_f32 v3, v27, v31
	v_lshl_add_u64 v[6:7], v[74:75], 0, v[6:7]
	global_store_dwordx4 v[6:7], v[0:3], off nt
	s_waitcnt vmcnt(10)
	s_nop 0
	v_cvt_pk_bf16_f32 v0, v32, v36
	s_waitcnt vmcnt(8)
	v_cvt_pk_bf16_f32 v1, v40, v44
	s_waitcnt vmcnt(6)
	v_cvt_pk_bf16_f32 v2, v48, v52
	s_waitcnt vmcnt(4)
	v_cvt_pk_bf16_f32 v3, v56, v60
	global_store_dwordx4 v[76:77], v[0:3], off offset:64 nt
	s_nop 1
	v_cvt_pk_bf16_f32 v0, v33, v37
	v_cvt_pk_bf16_f32 v1, v41, v45
	v_cvt_pk_bf16_f32 v2, v49, v53
	v_cvt_pk_bf16_f32 v3, v57, v61
	global_store_dwordx4 v[4:5], v[0:3], off offset:64 nt
	s_nop 1
	v_cvt_pk_bf16_f32 v0, v34, v38
	v_cvt_pk_bf16_f32 v1, v42, v46
	v_cvt_pk_bf16_f32 v2, v50, v54
	v_cvt_pk_bf16_f32 v3, v58, v62
	global_store_dwordx4 v[8:9], v[0:3], off offset:64 nt
	s_nop 1
	v_cvt_pk_bf16_f32 v0, v35, v39
	v_cvt_pk_bf16_f32 v1, v43, v47
	v_cvt_pk_bf16_f32 v2, v51, v55
	v_cvt_pk_bf16_f32 v3, v59, v63
	global_store_dwordx4 v[6:7], v[0:3], off offset:64 nt

; __device__ __forceinline__ unsigned cvt_pk_bf16(float lo, float hi) { unsigned r; asm volatile("v_cvt_pk_bf16_f32 %0, %1, %2" : "=v"(r) : "v"(lo), "v"(hi)); return r; }
; #define INP(i) ((const float*)(const GASP float*)kargs()[(i)])
; __device__ __forceinline__ void tr_item(const float* W, int ldw, int k0, int n0, bf16* WT, int ldk, int drow0, int lane) {
;     const int n4 = (lane & 15) * 4, kg = lane >> 4; f32x4 v[2][8];
; #pragma unroll
;     for (int kh = 0; kh < 2; ++kh) { const float* src = W + (size_t)(k0 + kh * 32 + kg * 8) * ldw + n0 + n4;
; #pragma unroll
;         for (int i = 0; i < 8; ++i) v[kh][i] = __builtin_nontemporal_load((const f32x4*)(src + (size_t)i * ldw)); }
; #pragma unroll
;     for (int kh = 0; kh < 2; ++kh)
; #pragma unroll
;         for (int e = 0; e < 4; ++e) { u32x4 o; o.x = cvt_pk_bf16(v[kh][0][e], v[kh][1][e]); o.y = cvt_pk_bf16(v[kh][2][e], v[kh][3][e]); o.z = cvt_pk_bf16(v[kh][4][e], v[kh][5][e]); o.w = cvt_pk_bf16(v[kh][6][e], v[kh][7][e]);
;             *(u32x4*)(WT + (size_t)(drow0 + n4 + e) * ldk + k0 + kh * 32 + kg * 8) = o; }
; }
; __device__ __forceinline__ void conv_item(int it, int lane) {
;     ...
;     if (r < 8 * IT_D) { const int idx = r / IT_D; r -= idx * IT_D; const int kb = r / 32, nb = r % 32;
;         tr_item(INP(I_WD) + (size_t)idx * 5376 * 2048, 2048, 64 * kb, 64 * nb, (bf16*)(ws + WS_WD) + (size_t)idx * 2048 * 5376, 5376, 64 * nb, lane); return; }
.LBB0_1516:
	s_andn2_b64 vcc, exec, s[22:23]
	s_cbranch_vccnz .LBB0_1518
	s_add_i32 s11, s6, 0xffff5800
	s_bfe_u32 s12, s11, 0x100007
	s_mulk_i32 s12, 0xc31
	s_lshr_b32 s12, s12, 16
	s_mul_i32 s19, s12, 0xf580
	s_mov_b64 s[20:21], s[0:1]
	s_add_i32 s11, s19, s11
	s_sext_i32_i16 s19, s11
	s_load_dwordx2 s[20:21], s[20:21], 0x70
	s_bfe_u32 s19, s19, 0x5001a
	s_add_i32 s19, s11, s19
	s_sext_i32_i16 s22, s19
	s_and_b32 s19, s19, 0xffe0
	s_sub_i32 s11, s11, s19
	s_mul_i32 s19, s12, 0x2a00000
	s_waitcnt lgkmcnt(0)
	s_add_u32 s19, s20, s19
	s_sext_i32_i16 s11, s11
	s_addc_u32 s23, s21, 0
	s_lshl_b32 s20, s22, 1
	s_and_b32 s22, s20, 0xffffffc0
	s_lshl_b32 s26, s11, 6
	s_mul_i32 s12, s12, 0x1500000
	s_add_u32 s11, s2, s12
	s_addc_u32 s12, s3, 0
	s_ashr_i32 s27, s26, 31
	s_lshl_b64 s[20:21], s[26:27], 2
	v_add_u32_e32 v32, s22, v66
	s_add_u32 s20, s19, s20
	s_addc_u32 s21, s23, s21
	v_lshlrev_b32_e32 v172, 2, v64
	v_ashrrev_i32_e32 v33, 31, v32
	v_lshl_add_u64 v[34:35], s[20:21], 0, v[172:173]
	v_lshlrev_b64 v[0:1], 13, v[32:33]
	v_lshl_add_u64 v[24:25], v[34:35], 0, v[0:1]
	v_add_co_u32_e32 v4, vcc, s89, v24
	s_movk_i32 s20, 0x4000
	s_nop 0
	v_addc_co_u32_e32 v5, vcc, 0, v25, vcc
	v_add_co_u32_e32 v8, vcc, s20, v24
	s_movk_i32 s19, 0x6000
	s_nop 0
	v_addc_co_u32_e32 v9, vcc, 0, v25, vcc
	v_add_co_u32_e32 v12, vcc, s19, v24
	s_mov_b32 s21, 0x8000
	s_nop 0
	v_addc_co_u32_e32 v13, vcc, 0, v25, vcc
	v_add_co_u32_e32 v16, vcc, s21, v24
	v_add_u32_e32 v32, 32, v32
	s_nop 0
	v_addc_co_u32_e32 v17, vcc, 0, v25, vcc
	v_add_co_u32_e32 v20, vcc, s33, v24
	s_mov_b32 s23, 0xe000
	s_nop 0
	v_addc_co_u32_e32 v21, vcc, 0, v25, vcc
	v_add_co_u32_e32 v26, vcc, s38, v24
	v_ashrrev_i32_e32 v33, 31, v32
	s_nop 0
	v_addc_co_u32_e32 v27, vcc, 0, v25, vcc
	v_add_co_u32_e32 v28, vcc, s23, v24
	v_lshlrev_b64 v[32:33], 13, v[32:33]
	s_nop 0
	v_addc_co_u32_e32 v29, vcc, 0, v25, vcc
	v_lshl_add_u64 v[56:57], v[34:35], 0, v[32:33]
	v_add_co_u32_e32 v36, vcc, s89, v56
	global_load_dwordx4 v[0:3], v[24:25], off nt
	s_nop 0
	global_load_dwordx4 v[4:7], v[4:5], off nt
	v_addc_co_u32_e32 v37, vcc, 0, v57, vcc
	v_add_co_u32_e32 v40, vcc, s20, v56
	global_load_dwordx4 v[8:11], v[8:9], off nt
	s_nop 0
	global_load_dwordx4 v[12:15], v[12:13], off nt
	v_addc_co_u32_e32 v41, vcc, 0, v57, vcc
	v_add_co_u32_e32 v44, vcc, s19, v56
	global_load_dwordx4 v[16:19], v[16:17], off nt
	s_nop 0
	global_load_dwordx4 v[20:23], v[20:21], off nt
	v_addc_co_u32_e32 v45, vcc, 0, v57, vcc
	v_add_co_u32_e32 v48, vcc, s21, v56
	global_load_dwordx4 v[24:27], v[26:27], off nt
	s_nop 0
	global_load_dwordx4 v[28:31], v[28:29], off nt
	v_addc_co_u32_e32 v49, vcc, 0, v57, vcc
	v_add_co_u32_e32 v52, vcc, s33, v56
	global_load_dwordx4 v[32:35], v[56:57], off nt
	s_nop 0
	global_load_dwordx4 v[36:39], v[36:37], off nt
	v_addc_co_u32_e32 v53, vcc, 0, v57, vcc
	v_add_co_u32_e32 v58, vcc, s38, v56
	global_load_dwordx4 v[40:43], v[40:41], off nt
	s_nop 0
	global_load_dwordx4 v[44:47], v[44:45], off nt
	v_addc_co_u32_e32 v59, vcc, 0, v57, vcc
	v_add_co_u32_e32 v60, vcc, s23, v56
	global_load_dwordx4 v[48:51], v[48:49], off nt
	s_nop 0
	global_load_dwordx4 v[52:55], v[52:53], off nt
	v_addc_co_u32_e32 v61, vcc, 0, v57, vcc
	global_load_dwordx4 v[56:59], v[58:59], off nt
	s_nop 0
	global_load_dwordx4 v[60:63], v[60:61], off nt
	s_ashr_i32 s23, s22, 31
	s_lshl_b64 s[20:21], s[22:23], 1
	v_or_b32_e32 v65, s26, v64
	s_add_u32 s20, s11, s20
	s_addc_u32 s21, s12, s21
	v_mul_i32_i24_e32 v74, 0x1500, v65
	v_lshl_add_u64 v[72:73], v[66:67], 1, s[20:21]
	v_ashrrev_i32_e32 v75, 31, v74
	v_lshl_add_u64 v[72:73], v[74:75], 1, v[72:73]
	s_mov_b32 s11, 0x15100000
	v_add_co_u32_e32 v76, vcc, s11, v72
	s_mov_b32 s11, 0x15102000
	s_nop 0
	v_addc_co_u32_e32 v77, vcc, 0, v73, vcc
	s_waitcnt vmcnt(14)
	v_cvt_pk_bf16_f32 v68, v0, v4
	v_add_co_u32_e32 v4, vcc, s11, v72
	s_waitcnt vmcnt(12)
	v_cvt_pk_bf16_f32 v69, v8, v12
	s_waitcnt vmcnt(10)
	v_cvt_pk_bf16_f32 v70, v16, v20
	s_waitcnt vmcnt(8)
	v_cvt_pk_bf16_f32 v71, v24, v28
	global_store_dwordx4 v[76:77], v[68:71], off nt
	s_mov_b32 s11, 0x15105000
	s_mov_b64 s[20:21], 0x15100000
	v_cvt_pk_bf16_f32 v68, v1, v5
	v_addc_co_u32_e32 v5, vcc, 0, v73, vcc
	v_add_co_u32_e32 v8, vcc, s11, v72
	v_cvt_pk_bf16_f32 v69, v9, v13
	s_mov_b32 s11, 0x15107000
	s_nop 0
	v_addc_co_u32_e32 v9, vcc, 0, v73, vcc
	v_cvt_pk_bf16_f32 v70, v17, v21
	v_cvt_pk_bf16_f32 v71, v25, v29
	global_store_dwordx4 v[4:5], v[68:71], off offset:2560 nt
	v_lshl_add_u64 v[74:75], v[72:73], 0, s[20:21]
	s_nop 0
	v_cvt_pk_bf16_f32 v68, v2, v6
	v_add_co_u32_e32 v6, vcc, s11, v72
	v_cvt_pk_bf16_f32 v69, v10, v14
	v_cvt_pk_bf16_f32 v70, v18, v22
	v_cvt_pk_bf16_f32 v71, v26, v30
	global_store_dwordx4 v[8:9], v[68:71], off offset:1024 nt
	v_cvt_pk_bf16_f32 v0, v3, v7
	v_cvt_pk_bf16_f32 v1, v11, v15
	v_cvt_pk_bf16_f32 v2, v19, v23
	v_cvt_pk_bf16_f32 v3, v27, v31
	s_nop 0
	v_addc_co_u32_e32 v7, vcc, 0, v73, vcc
	global_store_dwordx4 v[6:7], v[0:3], off offset:3584 nt
	s_waitcnt vmcnt(10)
	s_nop 0
	v_cvt_pk_bf16_f32 v0, v32, v36
	s_waitcnt vmcnt(8)
	v_cvt_pk_bf16_f32 v1, v40, v44
	s_waitcnt vmcnt(6)
	v_cvt_pk_bf16_f32 v2, v48, v52
	s_waitcnt vmcnt(4)
	v_cvt_pk_bf16_f32 v3, v56, v60
	global_store_dwordx4 v[74:75], v[0:3], off offset:64 nt
	s_nop 1
	v_cvt_pk_bf16_f32 v0, v33, v37
	v_cvt_pk_bf16_f32 v1, v41, v45
	v_cvt_pk_bf16_f32 v2, v49, v53
	v_cvt_pk_bf16_f32 v3, v57, v61
	global_store_dwordx4 v[4:5], v[0:3], off offset:2624 nt
	s_nop 1
	v_cvt_pk_bf16_f32 v0, v34, v38
	v_cvt_pk_bf16_f32 v1, v42, v46
	v_cvt_pk_bf16_f32 v2, v50, v54
	v_cvt_pk_bf16_f32 v3, v58, v62
	global_store_dwordx4 v[8:9], v[0:3], off offset:1088 nt
	s_nop 1
	v_cvt_pk_bf16_f32 v0, v35, v39
	v_cvt_pk_bf16_f32 v1, v43, v47
	v_cvt_pk_bf16_f32 v2, v51, v55
	v_cvt_pk_bf16_f32 v3, v59, v63
	global_store_dwordx4 v[6:7], v[0:3], off offset:3648 nt

; __device__ __forceinline__ void tr_item(const float* W, int ldw, int k0, int n0, bf16* WT, int ldk, int drow0, int lane) {
;     const int n4 = (lane & 15) * 4, kg = lane >> 4; f32x4 v[2][8];
; #pragma unroll
;     for (int kh = 0; kh < 2; ++kh) { const float* src = W + (size_t)(k0 + kh * 32 + kg * 8) * ldw + n0 + n4;
; #pragma unroll
;         for (int i = 0; i < 8; ++i) v[kh][i] = __builtin_nontemporal_load((const f32x4*)(src + (size_t)i * ldw)); }
; #pragma unroll
;     for (int kh = 0; kh < 2; ++kh)
; #pragma unroll
;         for (int e = 0; e < 4; ++e) { u32x4 o; o.x = cvt_pk_bf16(v[kh][0][e], v[kh][1][e]); o.y = cvt_pk_bf16(v[kh][2][e], v[kh][3][e]); o.z = cvt_pk_bf16(v[kh][4][e], v[kh][5][e]); o.w = cvt_pk_bf16(v[kh][6][e], v[kh][7][e]);
;             *(u32x4*)(WT + (size_t)(drow0 + n4 + e) * ldk + k0 + kh * 32 + kg * 8) = o; }
; }
; __device__ __forceinline__ void conv_item(int it, int lane) {
;     unsigned char* ws = WSP; int r = it;
;     if (r < 8 * IT_GU) { const int idx = r / IT_GU; r -= idx * IT_GU; const int kb = r / 168, nb = r % 168, n0 = 64 * nb;
;         const int drow = n0 < DFF ? (n0 >> 7) * 256 + (n0 & 127) : ((n0 - DFF) >> 7) * 256 + 128 + ((n0 - DFF) & 127);
;         tr_item(INP(I_WGU) + (size_t)idx * 2048 * 10752, 10752, 64 * kb, n0, (bf16*)(ws + WS_WGU) + (size_t)idx * 10752 * 2048, 2048, drow, lane); return; }
;     r -= 8 * IT_GU;
;     if (r < 8 * IT_D) { const int idx = r / IT_D; r -= idx * IT_D; const int kb = r / 32, nb = r % 32;
;         tr_item(INP(I_WD) + (size_t)idx * 5376 * 2048, 2048, 64 * kb, 64 * nb, (bf16*)(ws + WS_WD) + (size_t)idx * 2048 * 5376, 5376, 64 * nb, lane); return; }
;     r -= 8 * IT_D;
;     if (r < 2 * IT_INAB) { const int idx = r / IT_INAB; r -= idx * IT_INAB; const int kb = r / 80, nb = r % 80;
;         tr_item(INP(I_WINAB) + (size_t)idx * 2048 * 5120, 5120, 64 * kb, 64 * nb, (bf16*)(ws + WS_WINAB) + (size_t)idx * 5120 * 2048, 2048, 64 * nb, lane); return; }
;     r -= 2 * IT_INAB;
;     if (r < 2 * IT_GLU) { const int idx = r / IT_GLU; r -= idx * IT_GLU; const int kb = r / 16, nb = r % 16;
;         tr_item(INP(I_WGLU) + (size_t)idx * 1024 * 1024, 1024, 64 * kb, 64 * nb, (bf16*)(ws + WS_WGLU) + (size_t)idx * 1024 * 1024, 1024, 64 * nb, lane); return; }
;     r -= 2 * IT_GLU;
;     if (r < 2 * IT_OUTAB) { const int idx = r / IT_OUTAB; r -= idx * IT_OUTAB; const int kb = r / 32, nb = r % 32;
.LBB0_1918:
	s_mov_b64 s[20:21], s[0:1]
	s_load_dwordx2 s[36:37], s[20:21], 0x138
	s_add_i32 s6, s12, s28
	s_mov_b64 s[22:23], -1
	s_cmp_gt_i32 s6, 0xa7ff
	s_cbranch_scc0 .LBB0_1940
	s_cmpk_gt_u32 s6, 0xfbff
	s_cbranch_scc0 .LBB0_1937
	s_cmp_gt_u32 s6, 0x10fff
	s_cbranch_scc0 .LBB0_1934
	s_cmp_gt_u32 s6, 0x111ff
	s_cbranch_scc0 .LBB0_1931
	s_cmp_gt_u32 s6, 0x119ff
	s_cbranch_scc0 .LBB0_1928
	s_cmp_gt_u32 s6, 0x12dff
	s_cbranch_scc0 .LBB0_1925
	s_add_i32 s11, s6, 0xfffed200
	s_mul_hi_u32 s12, s11, 0xcccccccd
	s_lshr_b32 s12, s12, 10
	s_mul_i32 s20, s12, 0xfffffb00
	s_add_i32 s11, s20, s11
	s_ashr_i32 s20, s11, 31
	s_lshr_b32 s20, s20, 27
	s_add_i32 s22, s11, s20
	s_mov_b64 s[20:21], s[0:1]
	s_load_dwordx2 s[20:21], s[20:21], 0x128
	s_and_b32 s23, s22, 0x3ffffe0
	s_sub_i32 s11, s11, s23
	s_mul_i32 s28, s12, 0x1400000
	s_mul_hi_u32 s23, s12, 0x1400000
	s_waitcnt lgkmcnt(0)
	s_add_u32 s28, s20, s28
	s_addc_u32 s23, s21, s23
	s_lshl_b32 s20, s22, 1
	s_and_b32 s22, s20, 0xffffffc0
	s_lshl_b32 s40, s11, 6
	s_mul_hi_u32 s11, s12, 0xa00000
	s_mul_i32 s12, s12, 0xa00000
	s_add_u32 s12, s36, s12
	s_addc_u32 s11, s37, s11
	s_ashr_i32 s41, s40, 31
	s_lshl_b64 s[20:21], s[40:41], 2
	v_add_u32_e32 v32, s22, v66
	s_add_u32 s20, s28, s20
	s_addc_u32 s21, s23, s21
	v_lshlrev_b32_e32 v172, 2, v64
	v_ashrrev_i32_e32 v33, 31, v32
	v_lshl_add_u64 v[34:35], s[20:21], 0, v[172:173]
	v_lshlrev_b64 v[0:1], 13, v[32:33]
	v_lshl_add_u64 v[24:25], v[34:35], 0, v[0:1]
	v_add_co_u32_e32 v4, vcc, s89, v24
	s_movk_i32 s21, 0x4000
	s_nop 0
	v_addc_co_u32_e32 v5, vcc, 0, v25, vcc
	v_add_co_u32_e32 v8, vcc, s21, v24
	s_movk_i32 s20, 0x6000
	s_nop 0
	v_addc_co_u32_e32 v9, vcc, 0, v25, vcc
	v_add_co_u32_e32 v12, vcc, s20, v24
	s_mov_b32 s23, 0x8000
	s_nop 0
	v_addc_co_u32_e32 v13, vcc, 0, v25, vcc
	v_add_co_u32_e32 v16, vcc, s23, v24
	v_add_u32_e32 v32, 32, v32
	s_nop 0
	v_addc_co_u32_e32 v17, vcc, 0, v25, vcc
	v_add_co_u32_e32 v20, vcc, s33, v24
	s_mov_b32 s28, 0xe000
	s_nop 0
	v_addc_co_u32_e32 v21, vcc, 0, v25, vcc
	v_add_co_u32_e32 v26, vcc, s38, v24
	v_ashrrev_i32_e32 v33, 31, v32
	s_nop 0
	v_addc_co_u32_e32 v27, vcc, 0, v25, vcc
	v_add_co_u32_e32 v28, vcc, s28, v24
	v_lshlrev_b64 v[32:33], 13, v[32:33]
	s_nop 0
	v_addc_co_u32_e32 v29, vcc, 0, v25, vcc
	v_lshl_add_u64 v[56:57], v[34:35], 0, v[32:33]
	v_add_co_u32_e32 v36, vcc, s89, v56
	global_load_dwordx4 v[0:3], v[24:25], off nt
	s_nop 0
	global_load_dwordx4 v[4:7], v[4:5], off nt
	v_addc_co_u32_e32 v37, vcc, 0, v57, vcc
	v_add_co_u32_e32 v40, vcc, s21, v56
	global_load_dwordx4 v[8:11], v[8:9], off nt
	s_nop 0
	global_load_dwordx4 v[12:15], v[12:13], off nt
	v_addc_co_u32_e32 v41, vcc, 0, v57, vcc
	v_add_co_u32_e32 v44, vcc, s20, v56
	global_load_dwordx4 v[16:19], v[16:17], off nt
	s_nop 0
	global_load_dwordx4 v[20:23], v[20:21], off nt
	v_addc_co_u32_e32 v45, vcc, 0, v57, vcc
	v_add_co_u32_e32 v48, vcc, s23, v56
	global_load_dwordx4 v[24:27], v[26:27], off nt
	s_nop 0
	global_load_dwordx4 v[28:31], v[28:29], off nt
	v_addc_co_u32_e32 v49, vcc, 0, v57, vcc
	v_add_co_u32_e32 v52, vcc, s33, v56
	global_load_dwordx4 v[32:35], v[56:57], off nt
	s_nop 0
	global_load_dwordx4 v[36:39], v[36:37], off nt
	v_addc_co_u32_e32 v53, vcc, 0, v57, vcc
	v_add_co_u32_e32 v58, vcc, s38, v56
	global_load_dwordx4 v[40:43], v[40:41], off nt
	s_nop 0
	global_load_dwordx4 v[44:47], v[44:45], off nt
	v_addc_co_u32_e32 v59, vcc, 0, v57, vcc
	v_add_co_u32_e32 v60, vcc, s28, v56
	global_load_dwordx4 v[48:51], v[48:49], off nt
	s_nop 0
	global_load_dwordx4 v[52:55], v[52:53], off nt
	v_addc_co_u32_e32 v61, vcc, 0, v57, vcc
	global_load_dwordx4 v[56:59], v[58:59], off nt
	s_nop 0
	global_load_dwordx4 v[60:63], v[60:61], off nt
	s_ashr_i32 s23, s22, 31
	s_lshl_b64 s[20:21], s[22:23], 1
	s_add_u32 s20, s12, s20
	v_or_b32_e32 v74, s40, v64
	s_addc_u32 s21, s11, s21
	s_movk_i32 s11, 0xa00
	v_mul_lo_u32 v74, v74, s11
	v_lshl_add_u64 v[72:73], v[66:67], 1, s[20:21]
	v_ashrrev_i32_e32 v75, 31, v74
	v_lshl_add_u64 v[72:73], v[74:75], 1, v[72:73]
	s_mov_b32 s11, 0x25d00000
	v_add_co_u32_e32 v76, vcc, s11, v72
	s_mov_b32 s11, 0x25d01000
	s_nop 0
	v_addc_co_u32_e32 v77, vcc, 0, v73, vcc
	s_waitcnt vmcnt(14)
	v_cvt_pk_bf16_f32 v68, v0, v4
	v_add_co_u32_e32 v4, vcc, s11, v72
	s_waitcnt vmcnt(12)
	v_cvt_pk_bf16_f32 v69, v8, v12
	s_waitcnt vmcnt(10)
	v_cvt_pk_bf16_f32 v70, v16, v20
	s_waitcnt vmcnt(8)
	v_cvt_pk_bf16_f32 v71, v24, v28
	global_store_dwordx4 v[76:77], v[68:71], off nt
	s_mov_b32 s11, 0x25d02000
	s_mov_b64 s[20:21], 0x25d00000
	v_cvt_pk_bf16_f32 v68, v1, v5
	v_addc_co_u32_e32 v5, vcc, 0, v73, vcc
	v_add_co_u32_e32 v8, vcc, s11, v72
	v_cvt_pk_bf16_f32 v69, v9, v13
	s_mov_b32 s11, 0x25d03000
	s_nop 0
	v_addc_co_u32_e32 v9, vcc, 0, v73, vcc
	v_cvt_pk_bf16_f32 v70, v17, v21
	v_cvt_pk_bf16_f32 v71, v25, v29
	global_store_dwordx4 v[4:5], v[68:71], off offset:1024 nt
	v_lshl_add_u64 v[74:75], v[72:73], 0, s[20:21]
	s_mov_b64 s[22:23], 0
	v_cvt_pk_bf16_f32 v68, v2, v6
	v_add_co_u32_e32 v6, vcc, s11, v72
	v_cvt_pk_bf16_f32 v69, v10, v14
	v_cvt_pk_bf16_f32 v70, v18, v22
	v_cvt_pk_bf16_f32 v71, v26, v30
	global_store_dwordx4 v[8:9], v[68:71], off offset:2048 nt
	v_cvt_pk_bf16_f32 v0, v3, v7
	v_cvt_pk_bf16_f32 v1, v11, v15
	v_cvt_pk_bf16_f32 v2, v19, v23
	v_cvt_pk_bf16_f32 v3, v27, v31
	s_nop 0
	v_addc_co_u32_e32 v7, vcc, 0, v73, vcc
	global_store_dwordx4 v[6:7], v[0:3], off offset:3072 nt
	s_waitcnt vmcnt(10)
	s_nop 0
	v_cvt_pk_bf16_f32 v0, v32, v36
	s_waitcnt vmcnt(8)
	v_cvt_pk_bf16_f32 v1, v40, v44
	s_waitcnt vmcnt(6)
	v_cvt_pk_bf16_f32 v2, v48, v52
	s_waitcnt vmcnt(4)
	v_cvt_pk_bf16_f32 v3, v56, v60
	global_store_dwordx4 v[74:75], v[0:3], off offset:64 nt
	s_nop 1
	v_cvt_pk_bf16_f32 v0, v33, v37
	v_cvt_pk_bf16_f32 v1, v41, v45
	v_cvt_pk_bf16_f32 v2, v49, v53
	v_cvt_pk_bf16_f32 v3, v57, v61
	global_store_dwordx4 v[4:5], v[0:3], off offset:1088 nt
	s_nop 1
	v_cvt_pk_bf16_f32 v0, v34, v38
	v_cvt_pk_bf16_f32 v1, v42, v46
	v_cvt_pk_bf16_f32 v2, v50, v54
	v_cvt_pk_bf16_f32 v3, v58, v62
	global_store_dwordx4 v[8:9], v[0:3], off offset:2112 nt
	s_nop 1
	v_cvt_pk_bf16_f32 v0, v35, v39
	v_cvt_pk_bf16_f32 v1, v43, v47
	v_cvt_pk_bf16_f32 v2, v51, v55
	v_cvt_pk_bf16_f32 v3, v59, v63
	global_store_dwordx4 v[6:7], v[0:3], off offset:3136 nt
; __device__ __forceinline__ unsigned cvt_pk_bf16(float lo, float hi) { unsigned r; asm volatile("v_cvt_pk_bf16_f32 %0, %1, %2" : "=v"(r) : "v"(lo), "v"(hi)); return r; }
; #define INP(i) ((const float*)(const GASP float*)kargs()[(i)])
; __device__ __forceinline__ void tr_item(const float* W, int ldw, int k0, int n0, bf16* WT, int ldk, int drow0, int lane) {
;     const int n4 = (lane & 15) * 4, kg = lane >> 4; f32x4 v[2][8];
; #pragma unroll
;     for (int kh = 0; kh < 2; ++kh) { const float* src = W + (size_t)(k0 + kh * 32 + kg * 8) * ldw + n0 + n4;
; #pragma unroll
;         for (int i = 0; i < 8; ++i) v[kh][i] = __builtin_nontemporal_load((const f32x4*)(src + (size_t)i * ldw)); }
; #pragma unroll
;     for (int kh = 0; kh < 2; ++kh)
; #pragma unroll
;         for (int e = 0; e < 4; ++e) { u32x4 o; o.x = cvt_pk_bf16(v[kh][0][e], v[kh][1][e]); o.y = cvt_pk_bf16(v[kh][2][e], v[kh][3][e]); o.z = cvt_pk_bf16(v[kh][4][e], v[kh][5][e]); o.w = cvt_pk_bf16(v[kh][6][e], v[kh][7][e]);
;             *(u32x4*)(WT + (size_t)(drow0 + n4 + e) * ldk + k0 + kh * 32 + kg * 8) = o; }
; }
; __device__ __forceinline__ void conv_item(int it, int lane) {
;     ...
;     if (r < 2 * IT_INC) { const int idx = r / IT_INC; r -= idx * IT_INC; const int kb = r / 80, nb = r % 80;
;         tr_item(INP(I_WINC) + (size_t)idx * 2048 * 5120, 5120, 64 * kb, 64 * nb, (bf16*)(ws + WS_WINC) + (size_t)idx * 5120 * 2048, 2048, 64 * nb, lane); return; }
.LBB0_1925:
	s_andn2_b64 vcc, exec, s[22:23]
	s_cbranch_vccnz .LBB0_1927
	s_add_i32 s11, s6, 0xfffee600
	s_cmpk_gt_u32 s11, 0x9ff
	s_cselect_b64 s[20:21], -1, 0
	s_and_b64 s[22:23], s[20:21], exec
	s_cselect_b32 s12, 0xf600, 0
	s_add_i32 s12, s12, s11
	s_sext_i32_i16 s11, s12
	s_mulk_i32 s11, 0x6667
	s_lshr_b32 s22, s11, 31
	s_ashr_i32 s11, s11, 21
	s_add_i32 s11, s11, s22
	s_mov_b64 s[22:23], s[0:1]
	s_load_dwordx2 s[22:23], s[22:23], 0xe8
	s_mul_i32 s28, s11, 0x50
	s_sub_i32 s12, s12, s28
	s_and_b64 s[28:29], s[20:21], exec
	s_cselect_b32 s28, 0x2800000, 0
	s_sext_i32_i16 s12, s12
	s_waitcnt lgkmcnt(0)
	s_add_u32 s28, s22, s28
	s_addc_u32 s23, s23, 0
	s_lshl_b32 s22, s11, 6
	s_lshl_b32 s40, s12, 6
	s_and_b64 s[20:21], s[20:21], exec
	s_cselect_b32 s11, 0x1400000, 0
	s_add_u32 s11, s36, s11
	s_addc_u32 s12, s37, 0
	s_ashr_i32 s41, s40, 31
	s_lshl_b64 s[20:21], s[40:41], 2
	s_add_u32 s20, s28, s20
	s_addc_u32 s21, s23, s21
	v_lshlrev_b32_e32 v172, 2, v64
	v_add_u32_e32 v34, s22, v66
	v_lshl_add_u64 v[32:33], s[20:21], 0, v[172:173]
	s_movk_i32 s29, 0x5000
	v_mad_i64_i32 v[24:25], s[20:21], v34, s29, v[32:33]
	v_add_co_u32_e32 v4, vcc, s29, v24
	s_mov_b32 s23, 0x14000
	s_nop 0
	v_addc_co_u32_e32 v5, vcc, 0, v25, vcc
	v_add_co_u32_e32 v8, vcc, s33, v24
	s_mov_b32 s30, 0x19000
	s_nop 0
	v_addc_co_u32_e32 v9, vcc, 0, v25, vcc
	v_add_co_u32_e32 v12, vcc, s76, v24
	s_mov_b32 s28, 0x1e000
	s_nop 0
	v_addc_co_u32_e32 v13, vcc, 0, v25, vcc
	v_add_co_u32_e32 v16, vcc, s23, v24
	v_add_u32_e32 v34, 32, v34
	s_nop 0
	v_addc_co_u32_e32 v17, vcc, 0, v25, vcc
	v_add_co_u32_e32 v20, vcc, s30, v24
	v_mad_i64_i32 v[56:57], s[20:21], v34, s29, v[32:33]
	s_nop 0
	v_addc_co_u32_e32 v21, vcc, 0, v25, vcc
	v_add_co_u32_e32 v26, vcc, s28, v24
	global_load_dwordx4 v[0:3], v[24:25], off nt
	s_nop 0
	global_load_dwordx4 v[4:7], v[4:5], off nt
	v_addc_co_u32_e32 v27, vcc, 0, v25, vcc
	v_add_co_u32_e32 v28, vcc, s77, v24
	global_load_dwordx4 v[8:11], v[8:9], off nt
	s_nop 0
	global_load_dwordx4 v[12:15], v[12:13], off nt
	v_addc_co_u32_e32 v29, vcc, 0, v25, vcc
	v_add_co_u32_e32 v36, vcc, s29, v56
	global_load_dwordx4 v[16:19], v[16:17], off nt
	s_nop 0
	global_load_dwordx4 v[20:23], v[20:21], off nt
	v_addc_co_u32_e32 v37, vcc, 0, v57, vcc
	v_add_co_u32_e32 v40, vcc, s33, v56
	global_load_dwordx4 v[24:27], v[26:27], off nt
	s_nop 0
	global_load_dwordx4 v[28:31], v[28:29], off nt
	v_addc_co_u32_e32 v41, vcc, 0, v57, vcc
	v_add_co_u32_e32 v44, vcc, s76, v56
	global_load_dwordx4 v[32:35], v[56:57], off nt
	s_nop 0
	global_load_dwordx4 v[36:39], v[36:37], off nt
	v_addc_co_u32_e32 v45, vcc, 0, v57, vcc
	v_add_co_u32_e32 v48, vcc, s23, v56
	global_load_dwordx4 v[40:43], v[40:41], off nt
	s_nop 0
	global_load_dwordx4 v[44:47], v[44:45], off nt
	v_addc_co_u32_e32 v49, vcc, 0, v57, vcc
	v_add_co_u32_e32 v52, vcc, s30, v56
	s_ashr_i32 s23, s22, 31
	s_nop 0
	v_addc_co_u32_e32 v53, vcc, 0, v57, vcc
	v_add_co_u32_e32 v58, vcc, s28, v56
	global_load_dwordx4 v[48:51], v[48:49], off nt
	s_nop 0
	global_load_dwordx4 v[52:55], v[52:53], off nt
	v_addc_co_u32_e32 v59, vcc, 0, v57, vcc
	v_add_co_u32_e32 v60, vcc, s77, v56
	s_lshl_b64 s[20:21], s[22:23], 1
	s_nop 0
	v_addc_co_u32_e32 v61, vcc, 0, v57, vcc
	global_load_dwordx4 v[56:59], v[58:59], off nt
	s_nop 0
	global_load_dwordx4 v[60:63], v[60:61], off nt
	s_add_u32 s20, s11, s20
	v_or_b32_e32 v72, s40, v64
	s_addc_u32 s21, s12, s21
	v_lshl_add_u64 v[68:69], v[66:67], 1, s[20:21]
	s_mov_b64 s[20:21], 0x23500000
	v_ashrrev_i32_e32 v73, 31, v72
	v_lshl_add_u64 v[74:75], v[68:69], 0, s[20:21]
	v_lshlrev_b64 v[76:77], 12, v[72:73]
	s_waitcnt vmcnt(14)
	v_cvt_pk_bf16_f32 v68, v0, v4
	v_lshl_add_u64 v[76:77], v[74:75], 0, v[76:77]
	v_or_b32_e32 v0, 1, v72
	s_waitcnt vmcnt(12)
	v_cvt_pk_bf16_f32 v69, v8, v12
	s_waitcnt vmcnt(10)
	v_cvt_pk_bf16_f32 v70, v16, v20
	s_waitcnt vmcnt(8)
	v_cvt_pk_bf16_f32 v71, v24, v28
	global_store_dwordx4 v[76:77], v[68:71], off nt
	s_nop 1
	v_cvt_pk_bf16_f32 v68, v1, v5
	v_ashrrev_i32_e32 v1, 31, v0
	v_lshlrev_b64 v[0:1], 12, v[0:1]
	v_lshl_add_u64 v[4:5], v[74:75], 0, v[0:1]
	v_or_b32_e32 v0, 2, v72
	v_ashrrev_i32_e32 v1, 31, v0
	v_lshlrev_b64 v[0:1], 12, v[0:1]
	v_cvt_pk_bf16_f32 v69, v9, v13
	v_cvt_pk_bf16_f32 v70, v17, v21
	v_cvt_pk_bf16_f32 v71, v25, v29
	global_store_dwordx4 v[4:5], v[68:71], off nt
	v_lshl_add_u64 v[8:9], v[74:75], 0, v[0:1]
	s_nop 0
	v_cvt_pk_bf16_f32 v68, v2, v6
	v_or_b32_e32 v6, 3, v72
	v_cvt_pk_bf16_f32 v69, v10, v14
	v_cvt_pk_bf16_f32 v70, v18, v22
	v_cvt_pk_bf16_f32 v71, v26, v30
	global_store_dwordx4 v[8:9], v[68:71], off nt
	v_cvt_pk_bf16_f32 v0, v3, v7
	v_ashrrev_i32_e32 v7, 31, v6
	v_lshlrev_b64 v[6:7], 12, v[6:7]
	v_cvt_pk_bf16_f32 v1, v11, v15
	v_cvt_pk_bf16_f32 v2, v19, v23
	v_cvt_pk_bf16_f32 v3, v27, v31
	v_lshl_add_u64 v[6:7], v[74:75], 0, v[6:7]
	global_store_dwordx4 v[6:7], v[0:3], off nt
	s_waitcnt vmcnt(10)
	s_nop 0
	v_cvt_pk_bf16_f32 v0, v32, v36
	s_waitcnt vmcnt(8)
	v_cvt_pk_bf16_f32 v1, v40, v44
	s_waitcnt vmcnt(6)
	v_cvt_pk_bf16_f32 v2, v48, v52
	s_waitcnt vmcnt(4)
	v_cvt_pk_bf16_f32 v3, v56, v60
	global_store_dwordx4 v[76:77], v[0:3], off offset:64 nt
	s_nop 1
	v_cvt_pk_bf16_f32 v0, v33, v37
	v_cvt_pk_bf16_f32 v1, v41, v45
	v_cvt_pk_bf16_f32 v2, v49, v53
	v_cvt_pk_bf16_f32 v3, v57, v61
	global_store_dwordx4 v[4:5], v[0:3], off offset:64 nt
	s_nop 1
	v_cvt_pk_bf16_f32 v0, v34, v38
	v_cvt_pk_bf16_f32 v1, v42, v46
	v_cvt_pk_bf16_f32 v2, v50, v54
	v_cvt_pk_bf16_f32 v3, v58, v62
	global_store_dwordx4 v[8:9], v[0:3], off offset:64 nt
	s_nop 1
	v_cvt_pk_bf16_f32 v0, v35, v39
	v_cvt_pk_bf16_f32 v1, v43, v47
	v_cvt_pk_bf16_f32 v2, v51, v55
	v_cvt_pk_bf16_f32 v3, v59, v63
	global_store_dwordx4 v[6:7], v[0:3], off offset:64 nt

; __device__ __forceinline__ unsigned cvt_pk_bf16(float lo, float hi) { unsigned r; asm volatile("v_cvt_pk_bf16_f32 %0, %1, %2" : "=v"(r) : "v"(lo), "v"(hi)); return r; }
; #define INP(i) ((const float*)(const GASP float*)kargs()[(i)])
; __device__ __forceinline__ void tr_item(const float* W, int ldw, int k0, int n0, bf16* WT, int ldk, int drow0, int lane) {
;     const int n4 = (lane & 15) * 4, kg = lane >> 4; f32x4 v[2][8];
; #pragma unroll
;     for (int kh = 0; kh < 2; ++kh) { const float* src = W + (size_t)(k0 + kh * 32 + kg * 8) * ldw + n0 + n4;
; #pragma unroll
;         for (int i = 0; i < 8; ++i) v[kh][i] = __builtin_nontemporal_load((const f32x4*)(src + (size_t)i * ldw)); }
; #pragma unroll
;     for (int kh = 0; kh < 2; ++kh)
; #pragma unroll
;         for (int e = 0; e < 4; ++e) { u32x4 o; o.x = cvt_pk_bf16(v[kh][0][e], v[kh][1][e]); o.y = cvt_pk_bf16(v[kh][2][e], v[kh][3][e]); o.z = cvt_pk_bf16(v[kh][4][e], v[kh][5][e]); o.w = cvt_pk_bf16(v[kh][6][e], v[kh][7][e]);
;             *(u32x4*)(WT + (size_t)(drow0 + n4 + e) * ldk + k0 + kh * 32 + kg * 8) = o; }
; }
; __device__ __forceinline__ void conv_item(int it, int lane) {
;     ...
;     if (r < 2 * IT_OUTAB) { const int idx = r / IT_OUTAB; r -= idx * IT_OUTAB; const int kb = r / 32, nb = r % 32;
;         tr_item(INP(I_WOUTAB) + (size_t)idx * 2048 * 2048, 2048, 64 * kb, 64 * nb, (bf16*)(ws + WS_WOUTAB) + (size_t)idx * 2048 * 2048, 2048, 64 * nb, lane); return; }
.LBB0_1928:
	s_andn2_b64 vcc, exec, s[22:23]
	s_cbranch_vccnz .LBB0_1930
	s_mov_b64 s[20:21], s[0:1]
	s_load_dwordx2 s[20:21], s[20:21], 0xe0
	s_add_i32 s11, s6, 0xfffeee00
	s_lshr_b32 s38, s11, 10
	s_lshl_b64 s[22:23], s[38:39], 24
	v_lshlrev_b32_e32 v172, 2, v64
	s_waitcnt lgkmcnt(0)
	s_add_u32 s12, s20, s22
	s_addc_u32 s22, s21, s23
	s_lshl_b32 s11, s11, 1
	s_lshl_b32 s20, s6, 6
	s_and_b32 s11, s11, 0x7c0
	s_and_b32 s23, s20, 0x7c0
	s_lshl_b64 s[20:21], s[38:39], 23
	s_add_u32 s28, s36, s20
	s_addc_u32 s29, s37, s21
	s_lshl_b32 s20, s23, 2
	v_add_u32_e32 v32, s11, v66
	s_add_u32 s20, s12, s20
	s_addc_u32 s21, s22, 0
	v_ashrrev_i32_e32 v33, 31, v32
	v_lshl_add_u64 v[34:35], s[20:21], 0, v[172:173]
	v_lshlrev_b64 v[0:1], 13, v[32:33]
	v_lshl_add_u64 v[24:25], v[34:35], 0, v[0:1]
	v_add_co_u32_e32 v4, vcc, s89, v24
	s_movk_i32 s20, 0x4000
	s_nop 0
	v_addc_co_u32_e32 v5, vcc, 0, v25, vcc
	v_add_co_u32_e32 v8, vcc, s20, v24
	s_movk_i32 s12, 0x6000
	s_nop 0
	v_addc_co_u32_e32 v9, vcc, 0, v25, vcc
	v_add_co_u32_e32 v12, vcc, s12, v24
	s_mov_b32 s21, 0x8000
	s_nop 0
	v_addc_co_u32_e32 v13, vcc, 0, v25, vcc
	v_add_co_u32_e32 v16, vcc, s21, v24
	s_mov_b32 s38, 0xc000
	s_nop 0
	v_addc_co_u32_e32 v17, vcc, 0, v25, vcc
	v_add_co_u32_e32 v20, vcc, s33, v24
	v_add_u32_e32 v32, 32, v32
	s_nop 0
	v_addc_co_u32_e32 v21, vcc, 0, v25, vcc
	v_add_co_u32_e32 v26, vcc, s38, v24
	s_mov_b32 s22, 0xe000
	s_nop 0
	v_addc_co_u32_e32 v27, vcc, 0, v25, vcc
	v_ashrrev_i32_e32 v33, 31, v32
	v_add_co_u32_e32 v28, vcc, s22, v24
	v_lshlrev_b64 v[32:33], 13, v[32:33]
	s_nop 0
	v_addc_co_u32_e32 v29, vcc, 0, v25, vcc
	v_lshl_add_u64 v[56:57], v[34:35], 0, v[32:33]
	v_add_co_u32_e32 v36, vcc, s89, v56
	global_load_dwordx4 v[0:3], v[24:25], off nt
	s_nop 0
	global_load_dwordx4 v[4:7], v[4:5], off nt
	v_addc_co_u32_e32 v37, vcc, 0, v57, vcc
	v_add_co_u32_e32 v40, vcc, s20, v56
	global_load_dwordx4 v[8:11], v[8:9], off nt
	s_nop 0
	global_load_dwordx4 v[12:15], v[12:13], off nt
	v_addc_co_u32_e32 v41, vcc, 0, v57, vcc
	v_add_co_u32_e32 v44, vcc, s12, v56
	global_load_dwordx4 v[16:19], v[16:17], off nt
	s_nop 0
	global_load_dwordx4 v[20:23], v[20:21], off nt
	v_addc_co_u32_e32 v45, vcc, 0, v57, vcc
	v_add_co_u32_e32 v48, vcc, s21, v56
	global_load_dwordx4 v[24:27], v[26:27], off nt
	s_nop 0
	global_load_dwordx4 v[28:31], v[28:29], off nt
	v_addc_co_u32_e32 v49, vcc, 0, v57, vcc
	v_add_co_u32_e32 v52, vcc, s33, v56
	global_load_dwordx4 v[32:35], v[56:57], off nt
	s_nop 0
	global_load_dwordx4 v[36:39], v[36:37], off nt
	v_addc_co_u32_e32 v53, vcc, 0, v57, vcc
	v_add_co_u32_e32 v58, vcc, s38, v56
	global_load_dwordx4 v[40:43], v[40:41], off nt
	s_nop 0
	global_load_dwordx4 v[44:47], v[44:45], off nt
	v_addc_co_u32_e32 v59, vcc, 0, v57, vcc
	v_add_co_u32_e32 v60, vcc, s22, v56
	global_load_dwordx4 v[48:51], v[48:49], off nt
	s_nop 0
	global_load_dwordx4 v[52:55], v[52:53], off nt
	v_addc_co_u32_e32 v61, vcc, 0, v57, vcc
	global_load_dwordx4 v[56:59], v[58:59], off nt
	s_nop 0
	global_load_dwordx4 v[60:63], v[60:61], off nt
	s_lshl_b32 s11, s11, 1
	s_add_u32 s20, s28, s11
	s_addc_u32 s21, s29, 0
	v_or_b32_e32 v76, s23, v64
	v_lshl_add_u64 v[72:73], v[66:67], 1, s[20:21]
	s_mov_b64 s[20:21], 0x22500000
	v_lshl_add_u64 v[74:75], v[72:73], 0, s[20:21]
	v_lshlrev_b32_e32 v172, 12, v76
	s_waitcnt vmcnt(14)
	v_cvt_pk_bf16_f32 v68, v0, v4
	v_lshl_add_u64 v[76:77], v[74:75], 0, v[172:173]
	s_waitcnt vmcnt(12)
	v_cvt_pk_bf16_f32 v69, v8, v12
	s_waitcnt vmcnt(10)
	v_cvt_pk_bf16_f32 v70, v16, v20
	s_waitcnt vmcnt(8)
	v_cvt_pk_bf16_f32 v71, v24, v28
	global_store_dwordx4 v[76:77], v[68:71], off nt
	v_or_b32_e32 v4, 0x1000, v172
	v_or_b32_e32 v8, 0x2000, v172
	v_cvt_pk_bf16_f32 v68, v1, v5
	v_mov_b32_e32 v5, v173
	v_cvt_pk_bf16_f32 v69, v9, v13
	v_lshl_add_u64 v[0:1], v[74:75], 0, v[4:5]
	v_mov_b32_e32 v9, v173
	v_cvt_pk_bf16_f32 v70, v17, v21
	v_cvt_pk_bf16_f32 v71, v25, v29
	global_store_dwordx4 v[0:1], v[68:71], off nt
	v_lshl_add_u64 v[0:1], v[74:75], 0, v[8:9]
	v_or_b32_e32 v172, 0x3000, v172
	v_cvt_pk_bf16_f32 v68, v2, v6
	v_cvt_pk_bf16_f32 v69, v10, v14
	v_cvt_pk_bf16_f32 v70, v18, v22
	v_cvt_pk_bf16_f32 v71, v26, v30
	global_store_dwordx4 v[0:1], v[68:71], off nt
	v_cvt_pk_bf16_f32 v0, v3, v7
	v_lshl_add_u64 v[6:7], v[74:75], 0, v[172:173]
	s_mov_b64 s[20:21], 0x22500040
	v_cvt_pk_bf16_f32 v1, v11, v15
	v_cvt_pk_bf16_f32 v2, v19, v23
	v_cvt_pk_bf16_f32 v3, v27, v31
	global_store_dwordx4 v[6:7], v[0:3], off nt
	v_lshl_add_u64 v[6:7], v[72:73], 0, s[20:21]
	v_lshl_add_u64 v[4:5], v[6:7], 0, v[4:5]
	s_waitcnt vmcnt(10)
	v_cvt_pk_bf16_f32 v0, v32, v36
	s_waitcnt vmcnt(8)
	v_cvt_pk_bf16_f32 v1, v40, v44
	s_waitcnt vmcnt(6)
	v_cvt_pk_bf16_f32 v2, v48, v52
	s_waitcnt vmcnt(4)
	v_cvt_pk_bf16_f32 v3, v56, v60
	global_store_dwordx4 v[76:77], v[0:3], off offset:64 nt
	s_nop 1
	v_cvt_pk_bf16_f32 v0, v33, v37
	v_cvt_pk_bf16_f32 v1, v41, v45
	v_cvt_pk_bf16_f32 v2, v49, v53
	v_cvt_pk_bf16_f32 v3, v57, v61
	global_store_dwordx4 v[4:5], v[0:3], off nt
	v_lshl_add_u64 v[4:5], v[6:7], 0, v[8:9]
	s_nop 0
	v_cvt_pk_bf16_f32 v0, v34, v38
	v_cvt_pk_bf16_f32 v1, v42, v46
	v_cvt_pk_bf16_f32 v2, v50, v54
	v_cvt_pk_bf16_f32 v3, v58, v62
	global_store_dwordx4 v[4:5], v[0:3], off nt
	v_lshl_add_u64 v[4:5], v[6:7], 0, v[172:173]
	s_nop 0
	v_cvt_pk_bf16_f32 v0, v35, v39
	v_cvt_pk_bf16_f32 v1, v43, v47
	v_cvt_pk_bf16_f32 v2, v51, v55
	v_cvt_pk_bf16_f32 v3, v59, v63
	global_store_dwordx4 v[4:5], v[0:3], off nt

; __device__ __forceinline__ unsigned cvt_pk_bf16(float lo, float hi) { unsigned r; asm volatile("v_cvt_pk_bf16_f32 %0, %1, %2" : "=v"(r) : "v"(lo), "v"(hi)); return r; }
; #define INP(i) ((const float*)(const GASP float*)kargs()[(i)])
; __device__ __forceinline__ void tr_item(const float* W, int ldw, int k0, int n0, bf16* WT, int ldk, int drow0, int lane) {
;     const int n4 = (lane & 15) * 4, kg = lane >> 4; f32x4 v[2][8];
; #pragma unroll
;     for (int kh = 0; kh < 2; ++kh) { const float* src = W + (size_t)(k0 + kh * 32 + kg * 8) * ldw + n0 + n4;
; #pragma unroll
;         for (int i = 0; i < 8; ++i) v[kh][i] = __builtin_nontemporal_load((const f32x4*)(src + (size_t)i * ldw)); }
; #pragma unroll
;     for (int kh = 0; kh < 2; ++kh)
; #pragma unroll
;         for (int e = 0; e < 4; ++e) { u32x4 o; o.x = cvt_pk_bf16(v[kh][0][e], v[kh][1][e]); o.y = cvt_pk_bf16(v[kh][2][e], v[kh][3][e]); o.z = cvt_pk_bf16(v[kh][4][e], v[kh][5][e]); o.w = cvt_pk_bf16(v[kh][6][e], v[kh][7][e]);
;             *(u32x4*)(WT + (size_t)(drow0 + n4 + e) * ldk + k0 + kh * 32 + kg * 8) = o; }
; }
; __device__ __forceinline__ void conv_item(int it, int lane) {
;     ...
;     if (r < 2 * IT_INAB) { const int idx = r / IT_INAB; r -= idx * IT_INAB; const int kb = r / 80, nb = r % 80;
;         tr_item(INP(I_WINAB) + (size_t)idx * 2048 * 5120, 5120, 64 * kb, 64 * nb, (bf16*)(ws + WS_WINAB) + (size_t)idx * 5120 * 2048, 2048, 64 * nb, lane); return; }
.LBB0_1934:
	s_andn2_b64 vcc, exec, s[22:23]
	s_cbranch_vccnz .LBB0_1936
	s_add_i32 s11, s6, 0xffff0400
	s_cmpk_gt_u32 s11, 0x9ff
	s_cselect_b64 s[20:21], -1, 0
	s_and_b64 s[22:23], s[20:21], exec
	s_cselect_b32 s12, 0xf600, 0
	s_add_i32 s12, s12, s11
	s_sext_i32_i16 s11, s12
	s_mulk_i32 s11, 0x6667
	s_lshr_b32 s22, s11, 31
	s_ashr_i32 s11, s11, 21
	s_add_i32 s11, s11, s22
	s_mov_b64 s[22:23], s[0:1]
	s_load_dwordx2 s[22:23], s[22:23], 0x78
	s_mul_i32 s28, s11, 0x50
	s_sub_i32 s12, s12, s28
	s_and_b64 s[28:29], s[20:21], exec
	s_cselect_b32 s28, 0x2800000, 0
	s_sext_i32_i16 s12, s12
	s_waitcnt lgkmcnt(0)
	s_add_u32 s28, s22, s28
	s_addc_u32 s23, s23, 0
	s_lshl_b32 s22, s11, 6
	s_lshl_b32 s40, s12, 6
	s_and_b64 s[20:21], s[20:21], exec
	s_cselect_b32 s11, 0x1400000, 0
	s_add_u32 s11, s36, s11
	s_addc_u32 s12, s37, 0
	s_ashr_i32 s41, s40, 31
	s_lshl_b64 s[20:21], s[40:41], 2
	s_add_u32 s20, s28, s20
	s_addc_u32 s21, s23, s21
	v_lshlrev_b32_e32 v172, 2, v64
	v_add_u32_e32 v34, s22, v66
	v_lshl_add_u64 v[32:33], s[20:21], 0, v[172:173]
	s_movk_i32 s29, 0x5000
	v_mad_i64_i32 v[24:25], s[20:21], v34, s29, v[32:33]
	v_add_co_u32_e32 v4, vcc, s29, v24
	s_mov_b32 s23, 0x14000
	s_nop 0
	v_addc_co_u32_e32 v5, vcc, 0, v25, vcc
	v_add_co_u32_e32 v8, vcc, s33, v24
	s_mov_b32 s30, 0x19000
	s_nop 0
	v_addc_co_u32_e32 v9, vcc, 0, v25, vcc
	v_add_co_u32_e32 v12, vcc, s76, v24
	s_mov_b32 s28, 0x1e000
	s_nop 0
	v_addc_co_u32_e32 v13, vcc, 0, v25, vcc
	v_add_co_u32_e32 v16, vcc, s23, v24
	v_add_u32_e32 v34, 32, v34
	s_nop 0
	v_addc_co_u32_e32 v17, vcc, 0, v25, vcc
	v_add_co_u32_e32 v20, vcc, s30, v24
	v_mad_i64_i32 v[56:57], s[20:21], v34, s29, v[32:33]
	s_nop 0
	v_addc_co_u32_e32 v21, vcc, 0, v25, vcc
	v_add_co_u32_e32 v26, vcc, s28, v24
	global_load_dwordx4 v[0:3], v[24:25], off nt
	s_nop 0
	global_load_dwordx4 v[4:7], v[4:5], off nt
	v_addc_co_u32_e32 v27, vcc, 0, v25, vcc
	v_add_co_u32_e32 v28, vcc, s77, v24
	global_load_dwordx4 v[8:11], v[8:9], off nt
	s_nop 0
	global_load_dwordx4 v[12:15], v[12:13], off nt
	v_addc_co_u32_e32 v29, vcc, 0, v25, vcc
	v_add_co_u32_e32 v36, vcc, s29, v56
	global_load_dwordx4 v[16:19], v[16:17], off nt
	s_nop 0
	global_load_dwordx4 v[20:23], v[20:21], off nt
	v_addc_co_u32_e32 v37, vcc, 0, v57, vcc
	v_add_co_u32_e32 v40, vcc, s33, v56
	global_load_dwordx4 v[24:27], v[26:27], off nt
	s_nop 0
	global_load_dwordx4 v[28:31], v[28:29], off nt
	v_addc_co_u32_e32 v41, vcc, 0, v57, vcc
	v_add_co_u32_e32 v44, vcc, s76, v56
	global_load_dwordx4 v[32:35], v[56:57], off nt
	s_nop 0
	global_load_dwordx4 v[36:39], v[36:37], off nt
	v_addc_co_u32_e32 v45, vcc, 0, v57, vcc
	v_add_co_u32_e32 v48, vcc, s23, v56
	global_load_dwordx4 v[40:43], v[40:41], off nt
	s_nop 0
	global_load_dwordx4 v[44:47], v[44:45], off nt
	v_addc_co_u32_e32 v49, vcc, 0, v57, vcc
	v_add_co_u32_e32 v52, vcc, s30, v56
	s_ashr_i32 s23, s22, 31
	s_nop 0
	v_addc_co_u32_e32 v53, vcc, 0, v57, vcc
	v_add_co_u32_e32 v58, vcc, s28, v56
	global_load_dwordx4 v[48:51], v[48:49], off nt
	s_nop 0
	global_load_dwordx4 v[52:55], v[52:53], off nt
	v_addc_co_u32_e32 v59, vcc, 0, v57, vcc
	v_add_co_u32_e32 v60, vcc, s77, v56
	s_lshl_b64 s[20:21], s[22:23], 1
	s_nop 0
	v_addc_co_u32_e32 v61, vcc, 0, v57, vcc
	global_load_dwordx4 v[56:59], v[58:59], off nt
	s_nop 0
	global_load_dwordx4 v[60:63], v[60:61], off nt
	s_add_u32 s20, s11, s20
	v_or_b32_e32 v72, s40, v64
	s_addc_u32 s21, s12, s21
	v_lshl_add_u64 v[68:69], v[66:67], 1, s[20:21]
	s_mov_b64 s[20:21], 0x1f900000
	v_ashrrev_i32_e32 v73, 31, v72
	v_lshl_add_u64 v[74:75], v[68:69], 0, s[20:21]
	v_lshlrev_b64 v[76:77], 12, v[72:73]
	s_waitcnt vmcnt(14)
	v_cvt_pk_bf16_f32 v68, v0, v4
	v_lshl_add_u64 v[76:77], v[74:75], 0, v[76:77]
	v_or_b32_e32 v0, 1, v72
	s_waitcnt vmcnt(12)
	v_cvt_pk_bf16_f32 v69, v8, v12
	s_waitcnt vmcnt(10)
	v_cvt_pk_bf16_f32 v70, v16, v20
	s_waitcnt vmcnt(8)
	v_cvt_pk_bf16_f32 v71, v24, v28
	global_store_dwordx4 v[76:77], v[68:71], off nt
	s_nop 1
	v_cvt_pk_bf16_f32 v68, v1, v5
	v_ashrrev_i32_e32 v1, 31, v0
	v_lshlrev_b64 v[0:1], 12, v[0:1]
	v_lshl_add_u64 v[4:5], v[74:75], 0, v[0:1]
	v_or_b32_e32 v0, 2, v72
	v_ashrrev_i32_e32 v1, 31, v0
	v_lshlrev_b64 v[0:1], 12, v[0:1]
	v_cvt_pk_bf16_f32 v69, v9, v13
	v_cvt_pk_bf16_f32 v70, v17, v21
	v_cvt_pk_bf16_f32 v71, v25, v29
	global_store_dwordx4 v[4:5], v[68:71], off nt
	v_lshl_add_u64 v[8:9], v[74:75], 0, v[0:1]
	s_nop 0
	v_cvt_pk_bf16_f32 v68, v2, v6
	v_or_b32_e32 v6, 3, v72
	v_cvt_pk_bf16_f32 v69, v10, v14
	v_cvt_pk_bf16_f32 v70, v18, v22
	v_cvt_pk_bf16_f32 v71, v26, v30
	global_store_dwordx4 v[8:9], v[68:71], off nt
	v_cvt_pk_bf16_f32 v0, v3, v7
	v_ashrrev_i32_e32 v7, 31, v6
	v_lshlrev_b64 v[6:7], 12, v[6:7]
	v_cvt_pk_bf16_f32 v1, v11, v15
	v_cvt_pk_bf16_f32 v2, v19, v23
	v_cvt_pk_bf16_f32 v3, v27, v31
	v_lshl_add_u64 v[6:7], v[74:75], 0, v[6:7]
	global_store_dwordx4 v[6:7], v[0:3], off nt
	s_waitcnt vmcnt(10)
	s_nop 0
	v_cvt_pk_bf16_f32 v0, v32, v36
	s_waitcnt vmcnt(8)
	v_cvt_pk_bf16_f32 v1, v40, v44
	s_waitcnt vmcnt(6)
	v_cvt_pk_bf16_f32 v2, v48, v52
	s_waitcnt vmcnt(4)
	v_cvt_pk_bf16_f32 v3, v56, v60
	global_store_dwordx4 v[76:77], v[0:3], off offset:64 nt
	s_nop 1
	v_cvt_pk_bf16_f32 v0, v33, v37
	v_cvt_pk_bf16_f32 v1, v41, v45
	v_cvt_pk_bf16_f32 v2, v49, v53
	v_cvt_pk_bf16_f32 v3, v57, v61
	global_store_dwordx4 v[4:5], v[0:3], off offset:64 nt
	s_nop 1
	v_cvt_pk_bf16_f32 v0, v34, v38
	v_cvt_pk_bf16_f32 v1, v42, v46
	v_cvt_pk_bf16_f32 v2, v50, v54
	v_cvt_pk_bf16_f32 v3, v58, v62
	global_store_dwordx4 v[8:9], v[0:3], off offset:64 nt
	s_nop 1
	v_cvt_pk_bf16_f32 v0, v35, v39
	v_cvt_pk_bf16_f32 v1, v43, v47
	v_cvt_pk_bf16_f32 v2, v51, v55
	v_cvt_pk_bf16_f32 v3, v59, v63
	global_store_dwordx4 v[6:7], v[0:3], off offset:64 nt

; __device__ __forceinline__ unsigned cvt_pk_bf16(float lo, float hi) { unsigned r; asm volatile("v_cvt_pk_bf16_f32 %0, %1, %2" : "=v"(r) : "v"(lo), "v"(hi)); return r; }
; #define INP(i) ((const float*)(const GASP float*)kargs()[(i)])
; __device__ __forceinline__ void tr_item(const float* W, int ldw, int k0, int n0, bf16* WT, int ldk, int drow0, int lane) {
;     const int n4 = (lane & 15) * 4, kg = lane >> 4; f32x4 v[2][8];
; #pragma unroll
;     for (int kh = 0; kh < 2; ++kh) { const float* src = W + (size_t)(k0 + kh * 32 + kg * 8) * ldw + n0 + n4;
; #pragma unroll
;         for (int i = 0; i < 8; ++i) v[kh][i] = __builtin_nontemporal_load((const f32x4*)(src + (size_t)i * ldw)); }
; #pragma unroll
;     for (int kh = 0; kh < 2; ++kh)
; #pragma unroll
;         for (int e = 0; e < 4; ++e) { u32x4 o; o.x = cvt_pk_bf16(v[kh][0][e], v[kh][1][e]); o.y = cvt_pk_bf16(v[kh][2][e], v[kh][3][e]); o.z = cvt_pk_bf16(v[kh][4][e], v[kh][5][e]); o.w = cvt_pk_bf16(v[kh][6][e], v[kh][7][e]);
;             *(u32x4*)(WT + (size_t)(drow0 + n4 + e) * ldk + k0 + kh * 32 + kg * 8) = o; }
; }
; __device__ __forceinline__ void conv_item(int it, int lane) {
;     ...
;     if (r < 8 * IT_D) { const int idx = r / IT_D; r -= idx * IT_D; const int kb = r / 32, nb = r % 32;
;         tr_item(INP(I_WD) + (size_t)idx * 5376 * 2048, 2048, 64 * kb, 64 * nb, (bf16*)(ws + WS_WD) + (size_t)idx * 2048 * 5376, 5376, 64 * nb, lane); return; }
.LBB0_1937:
	s_andn2_b64 vcc, exec, s[22:23]
	s_cbranch_vccnz .LBB0_1939
	s_add_i32 s11, s6, 0xffff5800
	s_bfe_u32 s12, s11, 0x100007
	s_mulk_i32 s12, 0xc31
	s_lshr_b32 s12, s12, 16
	s_mul_i32 s20, s12, 0xf580
	s_add_i32 s11, s20, s11
	s_sext_i32_i16 s20, s11
	s_bfe_u32 s20, s20, 0x5001a
	s_add_i32 s22, s11, s20
	s_mov_b64 s[20:21], s[0:1]
	s_load_dwordx2 s[20:21], s[20:21], 0x70
	s_sext_i32_i16 s23, s22
	s_and_b32 s22, s22, 0xffe0
	s_sub_i32 s11, s11, s22
	s_mul_i32 s22, s12, 0x2a00000
	s_waitcnt lgkmcnt(0)
	s_add_u32 s28, s20, s22
	s_sext_i32_i16 s11, s11
	s_addc_u32 s29, s21, 0
	s_lshl_b32 s20, s23, 1
	s_and_b32 s22, s20, 0xffffffc0
	s_lshl_b32 s40, s11, 6
	s_mul_i32 s12, s12, 0x1500000
	s_add_u32 s11, s36, s12
	s_addc_u32 s12, s37, 0
	s_ashr_i32 s41, s40, 31
	s_lshl_b64 s[20:21], s[40:41], 2
	v_add_u32_e32 v32, s22, v66
	s_add_u32 s20, s28, s20
	s_addc_u32 s21, s29, s21
	v_lshlrev_b32_e32 v172, 2, v64
	v_ashrrev_i32_e32 v33, 31, v32
	v_lshl_add_u64 v[34:35], s[20:21], 0, v[172:173]
	v_lshlrev_b64 v[0:1], 13, v[32:33]
	v_lshl_add_u64 v[24:25], v[34:35], 0, v[0:1]
	v_add_co_u32_e32 v4, vcc, s89, v24
	s_movk_i32 s21, 0x4000
	s_nop 0
	v_addc_co_u32_e32 v5, vcc, 0, v25, vcc
	v_add_co_u32_e32 v8, vcc, s21, v24
	s_movk_i32 s20, 0x6000
	s_nop 0
	v_addc_co_u32_e32 v9, vcc, 0, v25, vcc
	v_add_co_u32_e32 v12, vcc, s20, v24
	s_mov_b32 s23, 0x8000
	s_nop 0
	v_addc_co_u32_e32 v13, vcc, 0, v25, vcc
	v_add_co_u32_e32 v16, vcc, s23, v24
	v_add_u32_e32 v32, 32, v32
	s_nop 0
	v_addc_co_u32_e32 v17, vcc, 0, v25, vcc
	v_add_co_u32_e32 v20, vcc, s33, v24
	s_mov_b32 s28, 0xe000
	s_nop 0
	v_addc_co_u32_e32 v21, vcc, 0, v25, vcc
	v_add_co_u32_e32 v26, vcc, s38, v24
	v_ashrrev_i32_e32 v33, 31, v32
	s_nop 0
	v_addc_co_u32_e32 v27, vcc, 0, v25, vcc
	v_add_co_u32_e32 v28, vcc, s28, v24
	v_lshlrev_b64 v[32:33], 13, v[32:33]
	s_nop 0
	v_addc_co_u32_e32 v29, vcc, 0, v25, vcc
	v_lshl_add_u64 v[56:57], v[34:35], 0, v[32:33]
	v_add_co_u32_e32 v36, vcc, s89, v56
	global_load_dwordx4 v[0:3], v[24:25], off nt
	s_nop 0
	global_load_dwordx4 v[4:7], v[4:5], off nt
	v_addc_co_u32_e32 v37, vcc, 0, v57, vcc
	v_add_co_u32_e32 v40, vcc, s21, v56
	global_load_dwordx4 v[8:11], v[8:9], off nt
	s_nop 0
	global_load_dwordx4 v[12:15], v[12:13], off nt
	v_addc_co_u32_e32 v41, vcc, 0, v57, vcc
	v_add_co_u32_e32 v44, vcc, s20, v56
	global_load_dwordx4 v[16:19], v[16:17], off nt
	s_nop 0
	global_load_dwordx4 v[20:23], v[20:21], off nt
	v_addc_co_u32_e32 v45, vcc, 0, v57, vcc
	v_add_co_u32_e32 v48, vcc, s23, v56
	global_load_dwordx4 v[24:27], v[26:27], off nt
	s_nop 0
	global_load_dwordx4 v[28:31], v[28:29], off nt
	v_addc_co_u32_e32 v49, vcc, 0, v57, vcc
	v_add_co_u32_e32 v52, vcc, s33, v56
	global_load_dwordx4 v[32:35], v[56:57], off nt
	s_nop 0
	global_load_dwordx4 v[36:39], v[36:37], off nt
	v_addc_co_u32_e32 v53, vcc, 0, v57, vcc
	v_add_co_u32_e32 v58, vcc, s38, v56
	global_load_dwordx4 v[40:43], v[40:41], off nt
	s_nop 0
	global_load_dwordx4 v[44:47], v[44:45], off nt
	v_addc_co_u32_e32 v59, vcc, 0, v57, vcc
	v_add_co_u32_e32 v60, vcc, s28, v56
	global_load_dwordx4 v[48:51], v[48:49], off nt
	s_nop 0
	global_load_dwordx4 v[52:55], v[52:53], off nt
	v_addc_co_u32_e32 v61, vcc, 0, v57, vcc
	global_load_dwordx4 v[56:59], v[58:59], off nt
	s_nop 0
	global_load_dwordx4 v[60:63], v[60:61], off nt
	s_ashr_i32 s23, s22, 31
	s_lshl_b64 s[20:21], s[22:23], 1
	v_or_b32_e32 v74, s40, v64
	s_add_u32 s20, s11, s20
	s_addc_u32 s21, s12, s21
	v_mul_i32_i24_e32 v74, 0x1500, v74
	v_lshl_add_u64 v[72:73], v[66:67], 1, s[20:21]
	v_ashrrev_i32_e32 v75, 31, v74
	v_lshl_add_u64 v[72:73], v[74:75], 1, v[72:73]
	s_mov_b32 s11, 0x15100000
	v_add_co_u32_e32 v76, vcc, s11, v72
	s_mov_b32 s11, 0x15102000
	s_nop 0
	v_addc_co_u32_e32 v77, vcc, 0, v73, vcc
	s_waitcnt vmcnt(14)
	v_cvt_pk_bf16_f32 v68, v0, v4
	v_add_co_u32_e32 v4, vcc, s11, v72
	s_waitcnt vmcnt(12)
	v_cvt_pk_bf16_f32 v69, v8, v12
	s_waitcnt vmcnt(10)
	v_cvt_pk_bf16_f32 v70, v16, v20
	s_waitcnt vmcnt(8)
	v_cvt_pk_bf16_f32 v71, v24, v28
	global_store_dwordx4 v[76:77], v[68:71], off nt
	s_mov_b32 s11, 0x15105000
	s_mov_b64 s[20:21], 0x15100000
	v_cvt_pk_bf16_f32 v68, v1, v5
	v_addc_co_u32_e32 v5, vcc, 0, v73, vcc
	v_add_co_u32_e32 v8, vcc, s11, v72
	v_cvt_pk_bf16_f32 v69, v9, v13
	s_mov_b32 s11, 0x15107000
	s_nop 0
	v_addc_co_u32_e32 v9, vcc, 0, v73, vcc
	v_cvt_pk_bf16_f32 v70, v17, v21
	v_cvt_pk_bf16_f32 v71, v25, v29
	global_store_dwordx4 v[4:5], v[68:71], off offset:2560 nt
	v_lshl_add_u64 v[74:75], v[72:73], 0, s[20:21]
	s_nop 0
	v_cvt_pk_bf16_f32 v68, v2, v6
	v_add_co_u32_e32 v6, vcc, s11, v72
	v_cvt_pk_bf16_f32 v69, v10, v14
	v_cvt_pk_bf16_f32 v70, v18, v22
	v_cvt_pk_bf16_f32 v71, v26, v30
	global_store_dwordx4 v[8:9], v[68:71], off offset:1024 nt
	v_cvt_pk_bf16_f32 v0, v3, v7
	v_cvt_pk_bf16_f32 v1, v11, v15
	v_cvt_pk_bf16_f32 v2, v19, v23
	v_cvt_pk_bf16_f32 v3, v27, v31
	s_nop 0
	v_addc_co_u32_e32 v7, vcc, 0, v73, vcc
	global_store_dwordx4 v[6:7], v[0:3], off offset:3584 nt
	s_waitcnt vmcnt(10)
	s_nop 0
	v_cvt_pk_bf16_f32 v0, v32, v36
	s_waitcnt vmcnt(8)
	v_cvt_pk_bf16_f32 v1, v40, v44
	s_waitcnt vmcnt(6)
	v_cvt_pk_bf16_f32 v2, v48, v52
	s_waitcnt vmcnt(4)
	v_cvt_pk_bf16_f32 v3, v56, v60
	global_store_dwordx4 v[74:75], v[0:3], off offset:64 nt
	s_nop 1
	v_cvt_pk_bf16_f32 v0, v33, v37
	v_cvt_pk_bf16_f32 v1, v41, v45
	v_cvt_pk_bf16_f32 v2, v49, v53
	v_cvt_pk_bf16_f32 v3, v57, v61
	global_store_dwordx4 v[4:5], v[0:3], off offset:2624 nt
	s_nop 1
	v_cvt_pk_bf16_f32 v0, v34, v38
	v_cvt_pk_bf16_f32 v1, v42, v46
	v_cvt_pk_bf16_f32 v2, v50, v54
	v_cvt_pk_bf16_f32 v3, v58, v62
	global_store_dwordx4 v[8:9], v[0:3], off offset:1088 nt
	s_nop 1
	v_cvt_pk_bf16_f32 v0, v35, v39
	v_cvt_pk_bf16_f32 v1, v43, v47
	v_cvt_pk_bf16_f32 v2, v51, v55
	v_cvt_pk_bf16_f32 v3, v59, v63
	global_store_dwordx4 v[6:7], v[0:3], off offset:3648 nt

; __device__ __forceinline__ void tr_item(const float* W, int ldw, int k0, int n0, bf16* WT, int ldk, int drow0, int lane) {
;     const int n4 = (lane & 15) * 4, kg = lane >> 4; f32x4 v[2][8];
; #pragma unroll
;     for (int kh = 0; kh < 2; ++kh) { const float* src = W + (size_t)(k0 + kh * 32 + kg * 8) * ldw + n0 + n4;
; #pragma unroll
;         for (int i = 0; i < 8; ++i) v[kh][i] = __builtin_nontemporal_load((const f32x4*)(src + (size_t)i * ldw)); }
; #pragma unroll
;     for (int kh = 0; kh < 2; ++kh)
; #pragma unroll
;         for (int e = 0; e < 4; ++e) { u32x4 o; o.x = cvt_pk_bf16(v[kh][0][e], v[kh][1][e]); o.y = cvt_pk_bf16(v[kh][2][e], v[kh][3][e]); o.z = cvt_pk_bf16(v[kh][4][e], v[kh][5][e]); o.w = cvt_pk_bf16(v[kh][6][e], v[kh][7][e]);
;             *(u32x4*)(WT + (size_t)(drow0 + n4 + e) * ldk + k0 + kh * 32 + kg * 8) = o; }
; }
; __device__ __forceinline__ void conv_item(int it, int lane) {
;     unsigned char* ws = WSP; int r = it;
;     if (r < 8 * IT_GU) { const int idx = r / IT_GU; r -= idx * IT_GU; const int kb = r / 168, nb = r % 168, n0 = 64 * nb;
;         const int drow = n0 < DFF ? (n0 >> 7) * 256 + (n0 & 127) : ((n0 - DFF) >> 7) * 256 + 128 + ((n0 - DFF) & 127);
;         tr_item(INP(I_WGU) + (size_t)idx * 2048 * 10752, 10752, 64 * kb, n0, (bf16*)(ws + WS_WGU) + (size_t)idx * 10752 * 2048, 2048, drow, lane); return; }
;     r -= 8 * IT_GU;
;     if (r < 8 * IT_D) { const int idx = r / IT_D; r -= idx * IT_D; const int kb = r / 32, nb = r % 32;
;         tr_item(INP(I_WD) + (size_t)idx * 5376 * 2048, 2048, 64 * kb, 64 * nb, (bf16*)(ws + WS_WD) + (size_t)idx * 2048 * 5376, 5376, 64 * nb, lane); return; }
;     r -= 8 * IT_D;
;     if (r < 2 * IT_INAB) { const int idx = r / IT_INAB; r -= idx * IT_INAB; const int kb = r / 80, nb = r % 80;
;         tr_item(INP(I_WINAB) + (size_t)idx * 2048 * 5120, 5120, 64 * kb, 64 * nb, (bf16*)(ws + WS_WINAB) + (size_t)idx * 5120 * 2048, 2048, 64 * nb, lane); return; }
;     r -= 2 * IT_INAB;
;     if (r < 2 * IT_GLU) { const int idx = r / IT_GLU; r -= idx * IT_GLU; const int kb = r / 16, nb = r % 16;
;         tr_item(INP(I_WGLU) + (size_t)idx * 1024 * 1024, 1024, 64 * kb, 64 * nb, (bf16*)(ws + WS_WGLU) + (size_t)idx * 1024 * 1024, 1024, 64 * nb, lane); return; }
;     r -= 2 * IT_GLU;
;     if (r < 2 * IT_OUTAB) { const int idx = r / IT_OUTAB; r -= idx * IT_OUTAB; const int kb = r / 32, nb = r % 32;
.LBB0_2118:
	s_add_i32 s6, s12, s16
	s_mov_b64 s[12:13], s[0:1]
	s_load_dwordx2 s[26:27], s[12:13], 0x138
	v_lshlrev_b32_e32 v0, 2, v174
	s_waitcnt vmcnt(0)
	v_and_b32_e32 v72, 60, v0
	v_ashrrev_i32_e32 v0, 1, v174
	v_and_b32_e32 v64, -8, v0
	v_ashrrev_i32_e32 v65, 31, v64
	s_mov_b64 s[22:23], -1
	s_cmp_gt_i32 s6, 0xa7ff
	s_cbranch_scc0 .LBB0_2140
	s_cmpk_gt_u32 s6, 0xfbff
	s_cbranch_scc0 .LBB0_2137
	s_cmp_gt_u32 s6, 0x10fff
	s_cbranch_scc0 .LBB0_2134
	s_cmp_gt_u32 s6, 0x111ff
	s_cbranch_scc0 .LBB0_2131
	s_cmp_gt_u32 s6, 0x119ff
	s_cbranch_scc0 .LBB0_2128
	s_cmp_gt_u32 s6, 0x12dff
	s_cbranch_scc0 .LBB0_2125
	s_add_i32 s11, s6, 0xfffed200
	s_mul_hi_u32 s12, s11, 0xcccccccd
	s_lshr_b32 s15, s12, 10
	s_mul_i32 s12, s15, 0xfffffb00
	s_add_i32 s11, s12, s11
	s_ashr_i32 s12, s11, 31
	s_lshr_b32 s12, s12, 27
	s_add_i32 s16, s11, s12
	s_mov_b64 s[12:13], s[0:1]
	s_load_dwordx2 s[12:13], s[12:13], 0x128
	s_and_b32 s17, s16, 0x3ffffe0
	s_sub_i32 s11, s11, s17
	s_mul_i32 s18, s15, 0x1400000
	s_mul_hi_u32 s17, s15, 0x1400000
	s_waitcnt lgkmcnt(0)
	s_add_u32 s18, s12, s18
	s_addc_u32 s17, s13, s17
	s_lshl_b32 s12, s16, 1
	s_and_b32 s22, s12, 0xffffffc0
	s_lshl_b32 s36, s11, 6
	s_mul_hi_u32 s11, s15, 0xa00000
	s_mul_i32 s15, s15, 0xa00000
	s_add_u32 s15, s26, s15
	s_addc_u32 s11, s27, s11
	s_ashr_i32 s37, s36, 31
	s_lshl_b64 s[12:13], s[36:37], 2
	v_add_u32_e32 v32, s22, v64
	s_add_u32 s12, s18, s12
	s_addc_u32 s13, s17, s13
	v_lshlrev_b32_e32 v172, 2, v72
	v_ashrrev_i32_e32 v33, 31, v32
	v_lshl_add_u64 v[34:35], s[12:13], 0, v[172:173]
	v_lshlrev_b64 v[0:1], 13, v[32:33]
	v_lshl_add_u64 v[24:25], v[34:35], 0, v[0:1]
	v_add_co_u32_e32 v4, vcc, s89, v24
	s_movk_i32 s13, 0x4000
	s_nop 0
	v_addc_co_u32_e32 v5, vcc, 0, v25, vcc
	v_add_co_u32_e32 v8, vcc, s13, v24
	s_movk_i32 s12, 0x6000
	s_nop 0
	v_addc_co_u32_e32 v9, vcc, 0, v25, vcc
	v_add_co_u32_e32 v12, vcc, s12, v24
	s_mov_b32 s16, 0x8000
	s_nop 0
	v_addc_co_u32_e32 v13, vcc, 0, v25, vcc
	v_add_co_u32_e32 v16, vcc, s16, v24
	v_add_u32_e32 v32, 32, v32
	s_nop 0
	v_addc_co_u32_e32 v17, vcc, 0, v25, vcc
	v_add_co_u32_e32 v20, vcc, s33, v24
	s_mov_b32 s17, 0xe000
	s_nop 0
	v_addc_co_u32_e32 v21, vcc, 0, v25, vcc
	v_add_co_u32_e32 v26, vcc, s38, v24
	v_ashrrev_i32_e32 v33, 31, v32
	s_nop 0
	v_addc_co_u32_e32 v27, vcc, 0, v25, vcc
	v_add_co_u32_e32 v28, vcc, s17, v24
	v_lshlrev_b64 v[32:33], 13, v[32:33]
	s_nop 0
	v_addc_co_u32_e32 v29, vcc, 0, v25, vcc
	v_lshl_add_u64 v[56:57], v[34:35], 0, v[32:33]
	v_add_co_u32_e32 v36, vcc, s89, v56
	global_load_dwordx4 v[0:3], v[24:25], off nt
	s_nop 0
	global_load_dwordx4 v[4:7], v[4:5], off nt
	v_addc_co_u32_e32 v37, vcc, 0, v57, vcc
	v_add_co_u32_e32 v40, vcc, s13, v56
	global_load_dwordx4 v[8:11], v[8:9], off nt
	s_nop 0
	global_load_dwordx4 v[12:15], v[12:13], off nt
	v_addc_co_u32_e32 v41, vcc, 0, v57, vcc
	v_add_co_u32_e32 v44, vcc, s12, v56
	global_load_dwordx4 v[16:19], v[16:17], off nt
	s_nop 0
	global_load_dwordx4 v[20:23], v[20:21], off nt
	v_addc_co_u32_e32 v45, vcc, 0, v57, vcc
	v_add_co_u32_e32 v48, vcc, s16, v56
	global_load_dwordx4 v[24:27], v[26:27], off nt
	s_nop 0
	global_load_dwordx4 v[28:31], v[28:29], off nt
	v_addc_co_u32_e32 v49, vcc, 0, v57, vcc
	v_add_co_u32_e32 v52, vcc, s33, v56
	global_load_dwordx4 v[32:35], v[56:57], off nt
	s_nop 0
	global_load_dwordx4 v[36:39], v[36:37], off nt
	v_addc_co_u32_e32 v53, vcc, 0, v57, vcc
	v_add_co_u32_e32 v58, vcc, s38, v56
	global_load_dwordx4 v[40:43], v[40:41], off nt
	s_nop 0
	global_load_dwordx4 v[44:47], v[44:45], off nt
	v_addc_co_u32_e32 v59, vcc, 0, v57, vcc
	v_add_co_u32_e32 v60, vcc, s17, v56
	global_load_dwordx4 v[48:51], v[48:49], off nt
	s_nop 0
	global_load_dwordx4 v[52:55], v[52:53], off nt
	v_addc_co_u32_e32 v61, vcc, 0, v57, vcc
	global_load_dwordx4 v[56:59], v[58:59], off nt
	s_nop 0
	global_load_dwordx4 v[60:63], v[60:61], off nt
	s_ashr_i32 s23, s22, 31
	s_lshl_b64 s[12:13], s[22:23], 1
	s_add_u32 s12, s15, s12
	v_or_b32_e32 v73, s36, v72
	s_addc_u32 s13, s11, s13
	s_movk_i32 s11, 0xa00
	v_mul_lo_u32 v74, v73, s11
	v_lshl_add_u64 v[70:71], v[64:65], 1, s[12:13]
	v_ashrrev_i32_e32 v75, 31, v74
	v_lshl_add_u64 v[70:71], v[74:75], 1, v[70:71]
	s_mov_b32 s11, 0x25d00000
	v_add_co_u32_e32 v76, vcc, s11, v70
	s_mov_b32 s11, 0x25d01000
	s_nop 0
	v_addc_co_u32_e32 v77, vcc, 0, v71, vcc
	s_waitcnt vmcnt(14)
	v_cvt_pk_bf16_f32 v66, v0, v4
	v_add_co_u32_e32 v4, vcc, s11, v70
	s_waitcnt vmcnt(12)
	v_cvt_pk_bf16_f32 v67, v8, v12
	s_waitcnt vmcnt(10)
	v_cvt_pk_bf16_f32 v68, v16, v20
	s_waitcnt vmcnt(8)
	v_cvt_pk_bf16_f32 v69, v24, v28
	global_store_dwordx4 v[76:77], v[66:69], off nt
	s_mov_b32 s11, 0x25d02000
	s_mov_b64 s[12:13], 0x25d00000
	v_cvt_pk_bf16_f32 v66, v1, v5
	v_addc_co_u32_e32 v5, vcc, 0, v71, vcc
	v_add_co_u32_e32 v8, vcc, s11, v70
	v_cvt_pk_bf16_f32 v67, v9, v13
	s_mov_b32 s11, 0x25d03000
	s_nop 0
	v_addc_co_u32_e32 v9, vcc, 0, v71, vcc
	v_cvt_pk_bf16_f32 v68, v17, v21
	v_cvt_pk_bf16_f32 v69, v25, v29
	global_store_dwordx4 v[4:5], v[66:69], off offset:1024 nt
	v_lshl_add_u64 v[74:75], v[70:71], 0, s[12:13]
	s_mov_b64 s[22:23], 0
	v_cvt_pk_bf16_f32 v66, v2, v6
	v_add_co_u32_e32 v6, vcc, s11, v70
	v_cvt_pk_bf16_f32 v67, v10, v14
	v_cvt_pk_bf16_f32 v68, v18, v22
	v_cvt_pk_bf16_f32 v69, v26, v30
	global_store_dwordx4 v[8:9], v[66:69], off offset:2048 nt
	v_cvt_pk_bf16_f32 v0, v3, v7
	v_cvt_pk_bf16_f32 v1, v11, v15
	v_cvt_pk_bf16_f32 v2, v19, v23
	v_cvt_pk_bf16_f32 v3, v27, v31
	s_nop 0
	v_addc_co_u32_e32 v7, vcc, 0, v71, vcc
	global_store_dwordx4 v[6:7], v[0:3], off offset:3072 nt
	s_waitcnt vmcnt(10)
	s_nop 0
	v_cvt_pk_bf16_f32 v0, v32, v36
	s_waitcnt vmcnt(8)
	v_cvt_pk_bf16_f32 v1, v40, v44
	s_waitcnt vmcnt(6)
	v_cvt_pk_bf16_f32 v2, v48, v52
	s_waitcnt vmcnt(4)
	v_cvt_pk_bf16_f32 v3, v56, v60
	global_store_dwordx4 v[74:75], v[0:3], off offset:64 nt
	s_nop 1
	v_cvt_pk_bf16_f32 v0, v33, v37
	v_cvt_pk_bf16_f32 v1, v41, v45
	v_cvt_pk_bf16_f32 v2, v49, v53
	v_cvt_pk_bf16_f32 v3, v57, v61
	global_store_dwordx4 v[4:5], v[0:3], off offset:1088 nt
	s_nop 1
	v_cvt_pk_bf16_f32 v0, v34, v38
	v_cvt_pk_bf16_f32 v1, v42, v46
	v_cvt_pk_bf16_f32 v2, v50, v54
	v_cvt_pk_bf16_f32 v3, v58, v62
	global_store_dwordx4 v[8:9], v[0:3], off offset:2112 nt
	s_nop 1
	v_cvt_pk_bf16_f32 v0, v35, v39
	v_cvt_pk_bf16_f32 v1, v43, v47
	v_cvt_pk_bf16_f32 v2, v51, v55
	v_cvt_pk_bf16_f32 v3, v59, v63
	global_store_dwordx4 v[6:7], v[0:3], off offset:3136 nt
; __device__ __forceinline__ unsigned cvt_pk_bf16(float lo, float hi) { unsigned r; asm volatile("v_cvt_pk_bf16_f32 %0, %1, %2" : "=v"(r) : "v"(lo), "v"(hi)); return r; }
; #define INP(i) ((const float*)(const GASP float*)kargs()[(i)])
; __device__ __forceinline__ void tr_item(const float* W, int ldw, int k0, int n0, bf16* WT, int ldk, int drow0, int lane) {
;     const int n4 = (lane & 15) * 4, kg = lane >> 4; f32x4 v[2][8];
; #pragma unroll
;     for (int kh = 0; kh < 2; ++kh) { const float* src = W + (size_t)(k0 + kh * 32 + kg * 8) * ldw + n0 + n4;
; #pragma unroll
;         for (int i = 0; i < 8; ++i) v[kh][i] = __builtin_nontemporal_load((const f32x4*)(src + (size_t)i * ldw)); }
; #pragma unroll
;     for (int kh = 0; kh < 2; ++kh)
; #pragma unroll
;         for (int e = 0; e < 4; ++e) { u32x4 o; o.x = cvt_pk_bf16(v[kh][0][e], v[kh][1][e]); o.y = cvt_pk_bf16(v[kh][2][e], v[kh][3][e]); o.z = cvt_pk_bf16(v[kh][4][e], v[kh][5][e]); o.w = cvt_pk_bf16(v[kh][6][e], v[kh][7][e]);
;             *(u32x4*)(WT + (size_t)(drow0 + n4 + e) * ldk + k0 + kh * 32 + kg * 8) = o; }
; }
; __device__ __forceinline__ void conv_item(int it, int lane) {
;     ...
;     if (r < 2 * IT_INC) { const int idx = r / IT_INC; r -= idx * IT_INC; const int kb = r / 80, nb = r % 80;
;         tr_item(INP(I_WINC) + (size_t)idx * 2048 * 5120, 5120, 64 * kb, 64 * nb, (bf16*)(ws + WS_WINC) + (size_t)idx * 5120 * 2048, 2048, 64 * nb, lane); return; }
.LBB0_2125:
	s_andn2_b64 vcc, exec, s[22:23]
	s_cbranch_vccnz .LBB0_2127
	s_add_i32 s11, s6, 0xfffee600
	s_cmpk_gt_u32 s11, 0x9ff
	s_cselect_b64 s[12:13], -1, 0
	s_and_b64 s[16:17], s[12:13], exec
	s_cselect_b32 s15, 0xf600, 0
	s_add_i32 s15, s15, s11
	s_sext_i32_i16 s11, s15
	s_mulk_i32 s11, 0x6667
	s_lshr_b32 s16, s11, 31
	s_ashr_i32 s11, s11, 21
	s_add_i32 s11, s11, s16
	s_mov_b64 s[16:17], s[0:1]
	s_load_dwordx2 s[16:17], s[16:17], 0xe8
	s_mul_i32 s18, s11, 0x50
	s_sub_i32 s15, s15, s18
	s_and_b64 s[18:19], s[12:13], exec
	s_cselect_b32 s18, 0x2800000, 0
	s_sext_i32_i16 s15, s15
	s_waitcnt lgkmcnt(0)
	s_add_u32 s16, s16, s18
	s_addc_u32 s17, s17, 0
	s_lshl_b32 s22, s11, 6
	s_lshl_b32 s36, s15, 6
	s_and_b64 s[12:13], s[12:13], exec
	s_cselect_b32 s11, 0x1400000, 0
	s_add_u32 s11, s26, s11
	s_addc_u32 s15, s27, 0
	s_ashr_i32 s37, s36, 31
	s_lshl_b64 s[12:13], s[36:37], 2
	s_add_u32 s12, s16, s12
	s_addc_u32 s13, s17, s13
	v_lshlrev_b32_e32 v172, 2, v72
	v_add_u32_e32 v34, s22, v64
	v_lshl_add_u64 v[32:33], s[12:13], 0, v[172:173]
	s_movk_i32 s18, 0x5000
	v_mad_i64_i32 v[24:25], s[12:13], v34, s18, v[32:33]
	v_add_co_u32_e32 v4, vcc, s18, v24
	s_mov_b32 s16, 0x14000
	s_nop 0
	v_addc_co_u32_e32 v5, vcc, 0, v25, vcc
	v_add_co_u32_e32 v8, vcc, s33, v24
	s_mov_b32 s19, 0x19000
	s_nop 0
	v_addc_co_u32_e32 v9, vcc, 0, v25, vcc
	v_add_co_u32_e32 v12, vcc, s76, v24
	s_mov_b32 s17, 0x1e000
	s_nop 0
	v_addc_co_u32_e32 v13, vcc, 0, v25, vcc
	v_add_co_u32_e32 v16, vcc, s16, v24
	v_add_u32_e32 v34, 32, v34
	s_nop 0
	v_addc_co_u32_e32 v17, vcc, 0, v25, vcc
	v_add_co_u32_e32 v20, vcc, s19, v24
	v_mad_i64_i32 v[56:57], s[12:13], v34, s18, v[32:33]
	s_nop 0
	v_addc_co_u32_e32 v21, vcc, 0, v25, vcc
	v_add_co_u32_e32 v26, vcc, s17, v24
	global_load_dwordx4 v[0:3], v[24:25], off nt
	s_nop 0
	global_load_dwordx4 v[4:7], v[4:5], off nt
	v_addc_co_u32_e32 v27, vcc, 0, v25, vcc
	v_add_co_u32_e32 v28, vcc, s77, v24
	global_load_dwordx4 v[8:11], v[8:9], off nt
	s_nop 0
	global_load_dwordx4 v[12:15], v[12:13], off nt
	v_addc_co_u32_e32 v29, vcc, 0, v25, vcc
	v_add_co_u32_e32 v36, vcc, s18, v56
	global_load_dwordx4 v[16:19], v[16:17], off nt
	s_nop 0
	global_load_dwordx4 v[20:23], v[20:21], off nt
	v_addc_co_u32_e32 v37, vcc, 0, v57, vcc
	v_add_co_u32_e32 v40, vcc, s33, v56
	global_load_dwordx4 v[24:27], v[26:27], off nt
	s_nop 0
	global_load_dwordx4 v[28:31], v[28:29], off nt
	v_addc_co_u32_e32 v41, vcc, 0, v57, vcc
	v_add_co_u32_e32 v44, vcc, s76, v56
	global_load_dwordx4 v[32:35], v[56:57], off nt
	s_nop 0
	global_load_dwordx4 v[36:39], v[36:37], off nt
	v_addc_co_u32_e32 v45, vcc, 0, v57, vcc
	v_add_co_u32_e32 v48, vcc, s16, v56
	global_load_dwordx4 v[40:43], v[40:41], off nt
	s_nop 0
	global_load_dwordx4 v[44:47], v[44:45], off nt
	v_addc_co_u32_e32 v49, vcc, 0, v57, vcc
	v_add_co_u32_e32 v52, vcc, s19, v56
	s_ashr_i32 s23, s22, 31
	s_nop 0
	v_addc_co_u32_e32 v53, vcc, 0, v57, vcc
	v_add_co_u32_e32 v58, vcc, s17, v56
	global_load_dwordx4 v[48:51], v[48:49], off nt
	s_nop 0
	global_load_dwordx4 v[52:55], v[52:53], off nt
	v_addc_co_u32_e32 v59, vcc, 0, v57, vcc
	v_add_co_u32_e32 v60, vcc, s77, v56
	s_lshl_b64 s[12:13], s[22:23], 1
	s_nop 0
	v_addc_co_u32_e32 v61, vcc, 0, v57, vcc
	global_load_dwordx4 v[56:59], v[58:59], off nt
	s_nop 0
	global_load_dwordx4 v[60:63], v[60:61], off nt
	s_add_u32 s12, s11, s12
	v_or_b32_e32 v70, s36, v72
	s_addc_u32 s13, s15, s13
	v_lshl_add_u64 v[66:67], v[64:65], 1, s[12:13]
	s_mov_b64 s[12:13], 0x23500000
	v_ashrrev_i32_e32 v71, 31, v70
	v_lshl_add_u64 v[74:75], v[66:67], 0, s[12:13]
	v_lshlrev_b64 v[76:77], 12, v[70:71]
	s_waitcnt vmcnt(14)
	v_cvt_pk_bf16_f32 v66, v0, v4
	v_lshl_add_u64 v[76:77], v[74:75], 0, v[76:77]
	v_or_b32_e32 v0, 1, v70
	s_waitcnt vmcnt(12)
	v_cvt_pk_bf16_f32 v67, v8, v12
	s_waitcnt vmcnt(10)
	v_cvt_pk_bf16_f32 v68, v16, v20
	s_waitcnt vmcnt(8)
	v_cvt_pk_bf16_f32 v69, v24, v28
	global_store_dwordx4 v[76:77], v[66:69], off nt
	s_nop 1
	v_cvt_pk_bf16_f32 v66, v1, v5
	v_ashrrev_i32_e32 v1, 31, v0
	v_lshlrev_b64 v[0:1], 12, v[0:1]
	v_lshl_add_u64 v[4:5], v[74:75], 0, v[0:1]
	v_or_b32_e32 v0, 2, v70
	v_ashrrev_i32_e32 v1, 31, v0
	v_lshlrev_b64 v[0:1], 12, v[0:1]
	v_cvt_pk_bf16_f32 v67, v9, v13
	v_cvt_pk_bf16_f32 v68, v17, v21
	v_cvt_pk_bf16_f32 v69, v25, v29
	global_store_dwordx4 v[4:5], v[66:69], off nt
	v_lshl_add_u64 v[8:9], v[74:75], 0, v[0:1]
	s_nop 0
	v_cvt_pk_bf16_f32 v66, v2, v6
	v_or_b32_e32 v6, 3, v70
	v_cvt_pk_bf16_f32 v67, v10, v14
	v_cvt_pk_bf16_f32 v68, v18, v22
	v_cvt_pk_bf16_f32 v69, v26, v30
	global_store_dwordx4 v[8:9], v[66:69], off nt
	v_cvt_pk_bf16_f32 v0, v3, v7
	v_ashrrev_i32_e32 v7, 31, v6
	v_lshlrev_b64 v[6:7], 12, v[6:7]
	v_cvt_pk_bf16_f32 v1, v11, v15
	v_cvt_pk_bf16_f32 v2, v19, v23
	v_cvt_pk_bf16_f32 v3, v27, v31
	v_lshl_add_u64 v[6:7], v[74:75], 0, v[6:7]
	global_store_dwordx4 v[6:7], v[0:3], off nt
	s_waitcnt vmcnt(10)
	s_nop 0
	v_cvt_pk_bf16_f32 v0, v32, v36
	s_waitcnt vmcnt(8)
	v_cvt_pk_bf16_f32 v1, v40, v44
	s_waitcnt vmcnt(6)
	v_cvt_pk_bf16_f32 v2, v48, v52
	s_waitcnt vmcnt(4)
	v_cvt_pk_bf16_f32 v3, v56, v60
	global_store_dwordx4 v[76:77], v[0:3], off offset:64 nt
	s_nop 1
	v_cvt_pk_bf16_f32 v0, v33, v37
	v_cvt_pk_bf16_f32 v1, v41, v45
	v_cvt_pk_bf16_f32 v2, v49, v53
	v_cvt_pk_bf16_f32 v3, v57, v61
	global_store_dwordx4 v[4:5], v[0:3], off offset:64 nt
	s_nop 1
	v_cvt_pk_bf16_f32 v0, v34, v38
	v_cvt_pk_bf16_f32 v1, v42, v46
	v_cvt_pk_bf16_f32 v2, v50, v54
	v_cvt_pk_bf16_f32 v3, v58, v62
	global_store_dwordx4 v[8:9], v[0:3], off offset:64 nt
	s_nop 1
	v_cvt_pk_bf16_f32 v0, v35, v39
	v_cvt_pk_bf16_f32 v1, v43, v47
	v_cvt_pk_bf16_f32 v2, v51, v55
	v_cvt_pk_bf16_f32 v3, v59, v63
	global_store_dwordx4 v[6:7], v[0:3], off offset:64 nt

; __device__ __forceinline__ unsigned cvt_pk_bf16(float lo, float hi) { unsigned r; asm volatile("v_cvt_pk_bf16_f32 %0, %1, %2" : "=v"(r) : "v"(lo), "v"(hi)); return r; }
; #define INP(i) ((const float*)(const GASP float*)kargs()[(i)])
; __device__ __forceinline__ void tr_item(const float* W, int ldw, int k0, int n0, bf16* WT, int ldk, int drow0, int lane) {
;     const int n4 = (lane & 15) * 4, kg = lane >> 4; f32x4 v[2][8];
; #pragma unroll
;     for (int kh = 0; kh < 2; ++kh) { const float* src = W + (size_t)(k0 + kh * 32 + kg * 8) * ldw + n0 + n4;
; #pragma unroll
;         for (int i = 0; i < 8; ++i) v[kh][i] = __builtin_nontemporal_load((const f32x4*)(src + (size_t)i * ldw)); }
; #pragma unroll
;     for (int kh = 0; kh < 2; ++kh)
; #pragma unroll
;         for (int e = 0; e < 4; ++e) { u32x4 o; o.x = cvt_pk_bf16(v[kh][0][e], v[kh][1][e]); o.y = cvt_pk_bf16(v[kh][2][e], v[kh][3][e]); o.z = cvt_pk_bf16(v[kh][4][e], v[kh][5][e]); o.w = cvt_pk_bf16(v[kh][6][e], v[kh][7][e]);
;             *(u32x4*)(WT + (size_t)(drow0 + n4 + e) * ldk + k0 + kh * 32 + kg * 8) = o; }
; }
; __device__ __forceinline__ void conv_item(int it, int lane) {
;     ...
;     if (r < 2 * IT_INAB) { const int idx = r / IT_INAB; r -= idx * IT_INAB; const int kb = r / 80, nb = r % 80;
;         tr_item(INP(I_WINAB) + (size_t)idx * 2048 * 5120, 5120, 64 * kb, 64 * nb, (bf16*)(ws + WS_WINAB) + (size_t)idx * 5120 * 2048, 2048, 64 * nb, lane); return; }
.LBB0_2134:
	s_andn2_b64 vcc, exec, s[22:23]
	s_cbranch_vccnz .LBB0_2136
	s_add_i32 s11, s6, 0xffff0400
	s_cmpk_gt_u32 s11, 0x9ff
	s_cselect_b64 s[12:13], -1, 0
	s_and_b64 s[16:17], s[12:13], exec
	s_cselect_b32 s15, 0xf600, 0
	s_add_i32 s15, s15, s11
	s_sext_i32_i16 s11, s15
	s_mulk_i32 s11, 0x6667
	s_lshr_b32 s16, s11, 31
	s_ashr_i32 s11, s11, 21
	s_add_i32 s11, s11, s16
	s_mov_b64 s[16:17], s[0:1]
	s_load_dwordx2 s[16:17], s[16:17], 0x78
	s_mul_i32 s18, s11, 0x50
	s_sub_i32 s15, s15, s18
	s_and_b64 s[18:19], s[12:13], exec
	s_cselect_b32 s18, 0x2800000, 0
	s_sext_i32_i16 s15, s15
	s_waitcnt lgkmcnt(0)
	s_add_u32 s16, s16, s18
	s_addc_u32 s17, s17, 0
	s_lshl_b32 s22, s11, 6
	s_lshl_b32 s36, s15, 6
	s_and_b64 s[12:13], s[12:13], exec
	s_cselect_b32 s11, 0x1400000, 0
	s_add_u32 s11, s26, s11
	s_addc_u32 s15, s27, 0
	s_ashr_i32 s37, s36, 31
	s_lshl_b64 s[12:13], s[36:37], 2
	s_add_u32 s12, s16, s12
	s_addc_u32 s13, s17, s13
	v_lshlrev_b32_e32 v172, 2, v72
	v_add_u32_e32 v34, s22, v64
	v_lshl_add_u64 v[32:33], s[12:13], 0, v[172:173]
	s_movk_i32 s18, 0x5000
	v_mad_i64_i32 v[24:25], s[12:13], v34, s18, v[32:33]
	v_add_co_u32_e32 v4, vcc, s18, v24
	s_mov_b32 s16, 0x14000
	s_nop 0
	v_addc_co_u32_e32 v5, vcc, 0, v25, vcc
	v_add_co_u32_e32 v8, vcc, s33, v24
	s_mov_b32 s19, 0x19000
	s_nop 0
	v_addc_co_u32_e32 v9, vcc, 0, v25, vcc
	v_add_co_u32_e32 v12, vcc, s76, v24
	s_mov_b32 s17, 0x1e000
	s_nop 0
	v_addc_co_u32_e32 v13, vcc, 0, v25, vcc
	v_add_co_u32_e32 v16, vcc, s16, v24
	v_add_u32_e32 v34, 32, v34
	s_nop 0
	v_addc_co_u32_e32 v17, vcc, 0, v25, vcc
	v_add_co_u32_e32 v20, vcc, s19, v24
	v_mad_i64_i32 v[56:57], s[12:13], v34, s18, v[32:33]
	s_nop 0
	v_addc_co_u32_e32 v21, vcc, 0, v25, vcc
	v_add_co_u32_e32 v26, vcc, s17, v24
	global_load_dwordx4 v[0:3], v[24:25], off nt
	s_nop 0
	global_load_dwordx4 v[4:7], v[4:5], off nt
	v_addc_co_u32_e32 v27, vcc, 0, v25, vcc
	v_add_co_u32_e32 v28, vcc, s77, v24
	global_load_dwordx4 v[8:11], v[8:9], off nt
	s_nop 0
	global_load_dwordx4 v[12:15], v[12:13], off nt
	v_addc_co_u32_e32 v29, vcc, 0, v25, vcc
	v_add_co_u32_e32 v36, vcc, s18, v56
	global_load_dwordx4 v[16:19], v[16:17], off nt
	s_nop 0
	global_load_dwordx4 v[20:23], v[20:21], off nt
	v_addc_co_u32_e32 v37, vcc, 0, v57, vcc
	v_add_co_u32_e32 v40, vcc, s33, v56
	global_load_dwordx4 v[24:27], v[26:27], off nt
	s_nop 0
	global_load_dwordx4 v[28:31], v[28:29], off nt
	v_addc_co_u32_e32 v41, vcc, 0, v57, vcc
	v_add_co_u32_e32 v44, vcc, s76, v56
	global_load_dwordx4 v[32:35], v[56:57], off nt
	s_nop 0
	global_load_dwordx4 v[36:39], v[36:37], off nt
	v_addc_co_u32_e32 v45, vcc, 0, v57, vcc
	v_add_co_u32_e32 v48, vcc, s16, v56
	global_load_dwordx4 v[40:43], v[40:41], off nt
	s_nop 0
	global_load_dwordx4 v[44:47], v[44:45], off nt
	v_addc_co_u32_e32 v49, vcc, 0, v57, vcc
	v_add_co_u32_e32 v52, vcc, s19, v56
	s_ashr_i32 s23, s22, 31
	s_nop 0
	v_addc_co_u32_e32 v53, vcc, 0, v57, vcc
	v_add_co_u32_e32 v58, vcc, s17, v56
	global_load_dwordx4 v[48:51], v[48:49], off nt
	s_nop 0
	global_load_dwordx4 v[52:55], v[52:53], off nt
	v_addc_co_u32_e32 v59, vcc, 0, v57, vcc
	v_add_co_u32_e32 v60, vcc, s77, v56
	s_lshl_b64 s[12:13], s[22:23], 1
	s_nop 0
	v_addc_co_u32_e32 v61, vcc, 0, v57, vcc
	global_load_dwordx4 v[56:59], v[58:59], off nt
	s_nop 0
	global_load_dwordx4 v[60:63], v[60:61], off nt
	s_add_u32 s12, s11, s12
	v_or_b32_e32 v70, s36, v72
	s_addc_u32 s13, s15, s13
	v_lshl_add_u64 v[66:67], v[64:65], 1, s[12:13]
	s_mov_b64 s[12:13], 0x1f900000
	v_ashrrev_i32_e32 v71, 31, v70
	v_lshl_add_u64 v[74:75], v[66:67], 0, s[12:13]
	v_lshlrev_b64 v[76:77], 12, v[70:71]
	s_waitcnt vmcnt(14)
	v_cvt_pk_bf16_f32 v66, v0, v4
	v_lshl_add_u64 v[76:77], v[74:75], 0, v[76:77]
	v_or_b32_e32 v0, 1, v70
	s_waitcnt vmcnt(12)
	v_cvt_pk_bf16_f32 v67, v8, v12
	s_waitcnt vmcnt(10)
	v_cvt_pk_bf16_f32 v68, v16, v20
	s_waitcnt vmcnt(8)
	v_cvt_pk_bf16_f32 v69, v24, v28
	global_store_dwordx4 v[76:77], v[66:69], off nt
	s_nop 1
	v_cvt_pk_bf16_f32 v66, v1, v5
	v_ashrrev_i32_e32 v1, 31, v0
	v_lshlrev_b64 v[0:1], 12, v[0:1]
	v_lshl_add_u64 v[4:5], v[74:75], 0, v[0:1]
	v_or_b32_e32 v0, 2, v70
	v_ashrrev_i32_e32 v1, 31, v0
	v_lshlrev_b64 v[0:1], 12, v[0:1]
	v_cvt_pk_bf16_f32 v67, v9, v13
	v_cvt_pk_bf16_f32 v68, v17, v21
	v_cvt_pk_bf16_f32 v69, v25, v29
	global_store_dwordx4 v[4:5], v[66:69], off nt
	v_lshl_add_u64 v[8:9], v[74:75], 0, v[0:1]
	s_nop 0
	v_cvt_pk_bf16_f32 v66, v2, v6
	v_or_b32_e32 v6, 3, v70
	v_cvt_pk_bf16_f32 v67, v10, v14
	v_cvt_pk_bf16_f32 v68, v18, v22
	v_cvt_pk_bf16_f32 v69, v26, v30
	global_store_dwordx4 v[8:9], v[66:69], off nt
	v_cvt_pk_bf16_f32 v0, v3, v7
	v_ashrrev_i32_e32 v7, 31, v6
	v_lshlrev_b64 v[6:7], 12, v[6:7]
	v_cvt_pk_bf16_f32 v1, v11, v15
	v_cvt_pk_bf16_f32 v2, v19, v23
	v_cvt_pk_bf16_f32 v3, v27, v31
	v_lshl_add_u64 v[6:7], v[74:75], 0, v[6:7]
	global_store_dwordx4 v[6:7], v[0:3], off nt
	s_waitcnt vmcnt(10)
	s_nop 0
	v_cvt_pk_bf16_f32 v0, v32, v36
	s_waitcnt vmcnt(8)
	v_cvt_pk_bf16_f32 v1, v40, v44
	s_waitcnt vmcnt(6)
	v_cvt_pk_bf16_f32 v2, v48, v52
	s_waitcnt vmcnt(4)
	v_cvt_pk_bf16_f32 v3, v56, v60
	global_store_dwordx4 v[76:77], v[0:3], off offset:64 nt
	s_nop 1
	v_cvt_pk_bf16_f32 v0, v33, v37
	v_cvt_pk_bf16_f32 v1, v41, v45
	v_cvt_pk_bf16_f32 v2, v49, v53
	v_cvt_pk_bf16_f32 v3, v57, v61
	global_store_dwordx4 v[4:5], v[0:3], off offset:64 nt
	s_nop 1
	v_cvt_pk_bf16_f32 v0, v34, v38
	v_cvt_pk_bf16_f32 v1, v42, v46
	v_cvt_pk_bf16_f32 v2, v50, v54
	v_cvt_pk_bf16_f32 v3, v58, v62
	global_store_dwordx4 v[8:9], v[0:3], off offset:64 nt
	s_nop 1
	v_cvt_pk_bf16_f32 v0, v35, v39
	v_cvt_pk_bf16_f32 v1, v43, v47
	v_cvt_pk_bf16_f32 v2, v51, v55
	v_cvt_pk_bf16_f32 v3, v59, v63
	global_store_dwordx4 v[6:7], v[0:3], off offset:64 nt

; __device__ __forceinline__ unsigned cvt_pk_bf16(float lo, float hi) { unsigned r; asm volatile("v_cvt_pk_bf16_f32 %0, %1, %2" : "=v"(r) : "v"(lo), "v"(hi)); return r; }
; #define INP(i) ((const float*)(const GASP float*)kargs()[(i)])
; __device__ __forceinline__ void tr_item(const float* W, int ldw, int k0, int n0, bf16* WT, int ldk, int drow0, int lane) {
;     const int n4 = (lane & 15) * 4, kg = lane >> 4; f32x4 v[2][8];
; #pragma unroll
;     for (int kh = 0; kh < 2; ++kh) { const float* src = W + (size_t)(k0 + kh * 32 + kg * 8) * ldw + n0 + n4;
; #pragma unroll
;         for (int i = 0; i < 8; ++i) v[kh][i] = __builtin_nontemporal_load((const f32x4*)(src + (size_t)i * ldw)); }
; #pragma unroll
;     for (int kh = 0; kh < 2; ++kh)
; #pragma unroll
;         for (int e = 0; e < 4; ++e) { u32x4 o; o.x = cvt_pk_bf16(v[kh][0][e], v[kh][1][e]); o.y = cvt_pk_bf16(v[kh][2][e], v[kh][3][e]); o.z = cvt_pk_bf16(v[kh][4][e], v[kh][5][e]); o.w = cvt_pk_bf16(v[kh][6][e], v[kh][7][e]);
;             *(u32x4*)(WT + (size_t)(drow0 + n4 + e) * ldk + k0 + kh * 32 + kg * 8) = o; }
; }
; __device__ __forceinline__ void conv_item(int it, int lane) {
;     ...
;     if (r < 8 * IT_D) { const int idx = r / IT_D; r -= idx * IT_D; const int kb = r / 32, nb = r % 32;
;         tr_item(INP(I_WD) + (size_t)idx * 5376 * 2048, 2048, 64 * kb, 64 * nb, (bf16*)(ws + WS_WD) + (size_t)idx * 2048 * 5376, 5376, 64 * nb, lane); return; }
.LBB0_2137:
	s_andn2_b64 vcc, exec, s[22:23]
	s_cbranch_vccnz .LBB0_2139
	s_add_i32 s11, s6, 0xffff5800
	s_bfe_u32 s12, s11, 0x100007
	s_mulk_i32 s12, 0xc31
	s_lshr_b32 s15, s12, 16
	s_mul_i32 s12, s15, 0xf580
	s_add_i32 s11, s12, s11
	s_sext_i32_i16 s12, s11
	s_bfe_u32 s12, s12, 0x5001a
	s_add_i32 s16, s11, s12
	s_mov_b64 s[12:13], s[0:1]
	s_load_dwordx2 s[12:13], s[12:13], 0x70
	s_sext_i32_i16 s17, s16
	s_and_b32 s16, s16, 0xffe0
	s_sub_i32 s11, s11, s16
	s_mul_i32 s16, s15, 0x2a00000
	s_waitcnt lgkmcnt(0)
	s_add_u32 s16, s12, s16
	s_sext_i32_i16 s11, s11
	s_addc_u32 s18, s13, 0
	s_lshl_b32 s12, s17, 1
	s_and_b32 s22, s12, 0xffffffc0
	s_lshl_b32 s36, s11, 6
	s_mul_i32 s15, s15, 0x1500000
	s_add_u32 s11, s26, s15
	s_addc_u32 s15, s27, 0
	s_ashr_i32 s37, s36, 31
	s_lshl_b64 s[12:13], s[36:37], 2
	v_add_u32_e32 v32, s22, v64
	s_add_u32 s12, s16, s12
	s_addc_u32 s13, s18, s13
	v_lshlrev_b32_e32 v172, 2, v72
	v_ashrrev_i32_e32 v33, 31, v32
	v_lshl_add_u64 v[34:35], s[12:13], 0, v[172:173]
	v_lshlrev_b64 v[0:1], 13, v[32:33]
	v_lshl_add_u64 v[24:25], v[34:35], 0, v[0:1]
	v_add_co_u32_e32 v4, vcc, s89, v24
	s_movk_i32 s13, 0x4000
	s_nop 0
	v_addc_co_u32_e32 v5, vcc, 0, v25, vcc
	v_add_co_u32_e32 v8, vcc, s13, v24
	s_movk_i32 s12, 0x6000
	s_nop 0
	v_addc_co_u32_e32 v9, vcc, 0, v25, vcc
	v_add_co_u32_e32 v12, vcc, s12, v24
	s_mov_b32 s16, 0x8000
	s_nop 0
	v_addc_co_u32_e32 v13, vcc, 0, v25, vcc
	v_add_co_u32_e32 v16, vcc, s16, v24
	v_add_u32_e32 v32, 32, v32
	s_nop 0
	v_addc_co_u32_e32 v17, vcc, 0, v25, vcc
	v_add_co_u32_e32 v20, vcc, s33, v24
	s_mov_b32 s17, 0xe000
	s_nop 0
	v_addc_co_u32_e32 v21, vcc, 0, v25, vcc
	v_add_co_u32_e32 v26, vcc, s38, v24
	v_ashrrev_i32_e32 v33, 31, v32
	s_nop 0
	v_addc_co_u32_e32 v27, vcc, 0, v25, vcc
	v_add_co_u32_e32 v28, vcc, s17, v24
	v_lshlrev_b64 v[32:33], 13, v[32:33]
	s_nop 0
	v_addc_co_u32_e32 v29, vcc, 0, v25, vcc
	v_lshl_add_u64 v[56:57], v[34:35], 0, v[32:33]
	v_add_co_u32_e32 v36, vcc, s89, v56
	global_load_dwordx4 v[0:3], v[24:25], off nt
	s_nop 0
	global_load_dwordx4 v[4:7], v[4:5], off nt
	v_addc_co_u32_e32 v37, vcc, 0, v57, vcc
	v_add_co_u32_e32 v40, vcc, s13, v56
	global_load_dwordx4 v[8:11], v[8:9], off nt
	s_nop 0
	global_load_dwordx4 v[12:15], v[12:13], off nt
	v_addc_co_u32_e32 v41, vcc, 0, v57, vcc
	v_add_co_u32_e32 v44, vcc, s12, v56
	global_load_dwordx4 v[16:19], v[16:17], off nt
	s_nop 0
	global_load_dwordx4 v[20:23], v[20:21], off nt
	v_addc_co_u32_e32 v45, vcc, 0, v57, vcc
	v_add_co_u32_e32 v48, vcc, s16, v56
	global_load_dwordx4 v[24:27], v[26:27], off nt
	s_nop 0
	global_load_dwordx4 v[28:31], v[28:29], off nt
	v_addc_co_u32_e32 v49, vcc, 0, v57, vcc
	v_add_co_u32_e32 v52, vcc, s33, v56
	global_load_dwordx4 v[32:35], v[56:57], off nt
	s_nop 0
	global_load_dwordx4 v[36:39], v[36:37], off nt
	v_addc_co_u32_e32 v53, vcc, 0, v57, vcc
	v_add_co_u32_e32 v58, vcc, s38, v56
	global_load_dwordx4 v[40:43], v[40:41], off nt
	s_nop 0
	global_load_dwordx4 v[44:47], v[44:45], off nt
	v_addc_co_u32_e32 v59, vcc, 0, v57, vcc
	v_add_co_u32_e32 v60, vcc, s17, v56
	global_load_dwordx4 v[48:51], v[48:49], off nt
	s_nop 0
	global_load_dwordx4 v[52:55], v[52:53], off nt
	v_addc_co_u32_e32 v61, vcc, 0, v57, vcc
	global_load_dwordx4 v[56:59], v[58:59], off nt
	s_nop 0
	global_load_dwordx4 v[60:63], v[60:61], off nt
	s_ashr_i32 s23, s22, 31
	s_lshl_b64 s[12:13], s[22:23], 1
	v_or_b32_e32 v73, s36, v72
	s_add_u32 s12, s11, s12
	s_addc_u32 s13, s15, s13
	v_mul_i32_i24_e32 v74, 0x1500, v73
	v_lshl_add_u64 v[70:71], v[64:65], 1, s[12:13]
	v_ashrrev_i32_e32 v75, 31, v74
	v_lshl_add_u64 v[70:71], v[74:75], 1, v[70:71]
	s_mov_b32 s11, 0x15100000
	v_add_co_u32_e32 v76, vcc, s11, v70
	s_mov_b32 s11, 0x15102000
	s_nop 0
	v_addc_co_u32_e32 v77, vcc, 0, v71, vcc
	s_waitcnt vmcnt(14)
	v_cvt_pk_bf16_f32 v66, v0, v4
	v_add_co_u32_e32 v4, vcc, s11, v70
	s_waitcnt vmcnt(12)
	v_cvt_pk_bf16_f32 v67, v8, v12
	s_waitcnt vmcnt(10)
	v_cvt_pk_bf16_f32 v68, v16, v20
	s_waitcnt vmcnt(8)
	v_cvt_pk_bf16_f32 v69, v24, v28
	global_store_dwordx4 v[76:77], v[66:69], off nt
	s_mov_b32 s11, 0x15105000
	s_mov_b64 s[12:13], 0x15100000
	v_cvt_pk_bf16_f32 v66, v1, v5
	v_addc_co_u32_e32 v5, vcc, 0, v71, vcc
	v_add_co_u32_e32 v8, vcc, s11, v70
	v_cvt_pk_bf16_f32 v67, v9, v13
	s_mov_b32 s11, 0x15107000
	s_nop 0
	v_addc_co_u32_e32 v9, vcc, 0, v71, vcc
	v_cvt_pk_bf16_f32 v68, v17, v21
	v_cvt_pk_bf16_f32 v69, v25, v29
	global_store_dwordx4 v[4:5], v[66:69], off offset:2560 nt
	v_lshl_add_u64 v[74:75], v[70:71], 0, s[12:13]
	s_nop 0
	v_cvt_pk_bf16_f32 v66, v2, v6
	v_add_co_u32_e32 v6, vcc, s11, v70
	v_cvt_pk_bf16_f32 v67, v10, v14
	v_cvt_pk_bf16_f32 v68, v18, v22
	v_cvt_pk_bf16_f32 v69, v26, v30
	global_store_dwordx4 v[8:9], v[66:69], off offset:1024 nt
	v_cvt_pk_bf16_f32 v0, v3, v7
	v_cvt_pk_bf16_f32 v1, v11, v15
	v_cvt_pk_bf16_f32 v2, v19, v23
	v_cvt_pk_bf16_f32 v3, v27, v31
	s_nop 0
	v_addc_co_u32_e32 v7, vcc, 0, v71, vcc
	global_store_dwordx4 v[6:7], v[0:3], off offset:3584 nt
	s_waitcnt vmcnt(10)
	s_nop 0
	v_cvt_pk_bf16_f32 v0, v32, v36
	s_waitcnt vmcnt(8)
	v_cvt_pk_bf16_f32 v1, v40, v44
	s_waitcnt vmcnt(6)
	v_cvt_pk_bf16_f32 v2, v48, v52
	s_waitcnt vmcnt(4)
	v_cvt_pk_bf16_f32 v3, v56, v60
	global_store_dwordx4 v[74:75], v[0:3], off offset:64 nt
	s_nop 1
	v_cvt_pk_bf16_f32 v0, v33, v37
	v_cvt_pk_bf16_f32 v1, v41, v45
	v_cvt_pk_bf16_f32 v2, v49, v53
	v_cvt_pk_bf16_f32 v3, v57, v61
	global_store_dwordx4 v[4:5], v[0:3], off offset:2624 nt
	s_nop 1
	v_cvt_pk_bf16_f32 v0, v34, v38
	v_cvt_pk_bf16_f32 v1, v42, v46
	v_cvt_pk_bf16_f32 v2, v50, v54
	v_cvt_pk_bf16_f32 v3, v58, v62
	global_store_dwordx4 v[8:9], v[0:3], off offset:1088 nt
	s_nop 1
	v_cvt_pk_bf16_f32 v0, v35, v39
	v_cvt_pk_bf16_f32 v1, v43, v47
	v_cvt_pk_bf16_f32 v2, v51, v55
	v_cvt_pk_bf16_f32 v3, v59, v63
	global_store_dwordx4 v[6:7], v[0:3], off offset:3648 nt

; __device__ __forceinline__ void tr_item(const float* W, int ldw, int k0, int n0, bf16* WT, int ldk, int drow0, int lane) {
;     const int n4 = (lane & 15) * 4, kg = lane >> 4; f32x4 v[2][8];
; #pragma unroll
;     for (int kh = 0; kh < 2; ++kh) { const float* src = W + (size_t)(k0 + kh * 32 + kg * 8) * ldw + n0 + n4;
; #pragma unroll
;         for (int i = 0; i < 8; ++i) v[kh][i] = __builtin_nontemporal_load((const f32x4*)(src + (size_t)i * ldw)); }
; #pragma unroll
;     for (int kh = 0; kh < 2; ++kh)
; #pragma unroll
;         for (int e = 0; e < 4; ++e) { u32x4 o; o.x = cvt_pk_bf16(v[kh][0][e], v[kh][1][e]); o.y = cvt_pk_bf16(v[kh][2][e], v[kh][3][e]); o.z = cvt_pk_bf16(v[kh][4][e], v[kh][5][e]); o.w = cvt_pk_bf16(v[kh][6][e], v[kh][7][e]);
;             *(u32x4*)(WT + (size_t)(drow0 + n4 + e) * ldk + k0 + kh * 32 + kg * 8) = o; }
; }
; __device__ __forceinline__ void conv_item(int it, int lane) {
;     unsigned char* ws = WSP; int r = it;
;     if (r < 8 * IT_GU) { const int idx = r / IT_GU; r -= idx * IT_GU; const int kb = r / 168, nb = r % 168, n0 = 64 * nb;
;         const int drow = n0 < DFF ? (n0 >> 7) * 256 + (n0 & 127) : ((n0 - DFF) >> 7) * 256 + 128 + ((n0 - DFF) & 127);
;         tr_item(INP(I_WGU) + (size_t)idx * 2048 * 10752, 10752, 64 * kb, n0, (bf16*)(ws + WS_WGU) + (size_t)idx * 10752 * 2048, 2048, drow, lane); return; }
;     r -= 8 * IT_GU;
;     if (r < 8 * IT_D) { const int idx = r / IT_D; r -= idx * IT_D; const int kb = r / 32, nb = r % 32;
;         tr_item(INP(I_WD) + (size_t)idx * 5376 * 2048, 2048, 64 * kb, 64 * nb, (bf16*)(ws + WS_WD) + (size_t)idx * 2048 * 5376, 5376, 64 * nb, lane); return; }
;     r -= 8 * IT_D;
;     if (r < 2 * IT_INAB) { const int idx = r / IT_INAB; r -= idx * IT_INAB; const int kb = r / 80, nb = r % 80;
;         tr_item(INP(I_WINAB) + (size_t)idx * 2048 * 5120, 5120, 64 * kb, 64 * nb, (bf16*)(ws + WS_WINAB) + (size_t)idx * 5120 * 2048, 2048, 64 * nb, lane); return; }
;     r -= 2 * IT_INAB;
;     if (r < 2 * IT_GLU) { const int idx = r / IT_GLU; r -= idx * IT_GLU; const int kb = r / 16, nb = r % 16;
;         tr_item(INP(I_WGLU) + (size_t)idx * 1024 * 1024, 1024, 64 * kb, 64 * nb, (bf16*)(ws + WS_WGLU) + (size_t)idx * 1024 * 1024, 1024, 64 * nb, lane); return; }
;     r -= 2 * IT_GLU;
;     if (r < 2 * IT_OUTAB) { const int idx = r / IT_OUTAB; r -= idx * IT_OUTAB; const int kb = r / 32, nb = r % 32;
.LBB0_2504:
	s_mov_b64 s[2:3], s[0:1]
	s_load_dwordx2 s[2:3], s[2:3], 0x138
	s_add_i32 s6, s12, s26
	s_mov_b64 s[22:23], -1
	s_cmp_gt_i32 s6, 0xa7ff
	s_cbranch_scc0 .LBB0_2526
	s_cmpk_gt_u32 s6, 0xfbff
	s_cbranch_scc0 .LBB0_2523
	s_cmp_gt_u32 s6, 0x10fff
	s_cbranch_scc0 .LBB0_2520
	s_cmp_gt_u32 s6, 0x111ff
	s_cbranch_scc0 .LBB0_2517
	s_cmp_gt_u32 s6, 0x119ff
	s_cbranch_scc0 .LBB0_2514
	s_cmp_gt_u32 s6, 0x12dff
	s_cbranch_scc0 .LBB0_2511
	s_add_i32 s11, s6, 0xfffed200
	s_mul_hi_u32 s12, s11, 0xcccccccd
	s_lshr_b32 s12, s12, 10
	s_mul_i32 s20, s12, 0xfffffb00
	s_add_i32 s11, s20, s11
	s_ashr_i32 s20, s11, 31
	s_lshr_b32 s20, s20, 27
	s_add_i32 s22, s11, s20
	s_mov_b64 s[20:21], s[0:1]
	s_load_dwordx2 s[20:21], s[20:21], 0x128
	s_and_b32 s23, s22, 0x3ffffe0
	s_sub_i32 s11, s11, s23
	s_mul_i32 s26, s12, 0x1400000
	s_mul_hi_u32 s23, s12, 0x1400000
	s_waitcnt lgkmcnt(0)
	s_add_u32 s30, s20, s26
	s_addc_u32 s23, s21, s23
	s_lshl_b32 s20, s22, 1
	s_and_b32 s22, s20, 0xffffffc0
	s_lshl_b32 s26, s11, 6
	s_mul_hi_u32 s11, s12, 0xa00000
	s_mul_i32 s12, s12, 0xa00000
	s_add_u32 s12, s2, s12
	s_addc_u32 s11, s3, s11
	s_ashr_i32 s27, s26, 31
	s_lshl_b64 s[20:21], s[26:27], 2
	v_add_u32_e32 v32, s22, v66
	s_add_u32 s20, s30, s20
	s_addc_u32 s21, s23, s21
	v_lshlrev_b32_e32 v172, 2, v64
	v_ashrrev_i32_e32 v33, 31, v32
	v_lshl_add_u64 v[34:35], s[20:21], 0, v[172:173]
	v_lshlrev_b64 v[0:1], 13, v[32:33]
	v_lshl_add_u64 v[24:25], v[34:35], 0, v[0:1]
	v_add_co_u32_e32 v4, vcc, s89, v24
	s_movk_i32 s21, 0x4000
	s_nop 0
	v_addc_co_u32_e32 v5, vcc, 0, v25, vcc
	v_add_co_u32_e32 v8, vcc, s21, v24
	s_movk_i32 s20, 0x6000
	s_nop 0
	v_addc_co_u32_e32 v9, vcc, 0, v25, vcc
	v_add_co_u32_e32 v12, vcc, s20, v24
	s_mov_b32 s23, 0x8000
	s_nop 0
	v_addc_co_u32_e32 v13, vcc, 0, v25, vcc
	v_add_co_u32_e32 v16, vcc, s23, v24
	v_add_u32_e32 v32, 32, v32
	s_nop 0
	v_addc_co_u32_e32 v17, vcc, 0, v25, vcc
	v_add_co_u32_e32 v20, vcc, s33, v24
	s_mov_b32 s27, 0xe000
	s_nop 0
	v_addc_co_u32_e32 v21, vcc, 0, v25, vcc
	v_add_co_u32_e32 v26, vcc, s38, v24
	v_ashrrev_i32_e32 v33, 31, v32
	s_nop 0
	v_addc_co_u32_e32 v27, vcc, 0, v25, vcc
	v_add_co_u32_e32 v28, vcc, s27, v24
	v_lshlrev_b64 v[32:33], 13, v[32:33]
	s_nop 0
	v_addc_co_u32_e32 v29, vcc, 0, v25, vcc
	v_lshl_add_u64 v[56:57], v[34:35], 0, v[32:33]
	v_add_co_u32_e32 v36, vcc, s89, v56
	global_load_dwordx4 v[0:3], v[24:25], off nt
	s_nop 0
	global_load_dwordx4 v[4:7], v[4:5], off nt
	v_addc_co_u32_e32 v37, vcc, 0, v57, vcc
	v_add_co_u32_e32 v40, vcc, s21, v56
	global_load_dwordx4 v[8:11], v[8:9], off nt
	s_nop 0
	global_load_dwordx4 v[12:15], v[12:13], off nt
	v_addc_co_u32_e32 v41, vcc, 0, v57, vcc
	v_add_co_u32_e32 v44, vcc, s20, v56
	global_load_dwordx4 v[16:19], v[16:17], off nt
	s_nop 0
	global_load_dwordx4 v[20:23], v[20:21], off nt
	v_addc_co_u32_e32 v45, vcc, 0, v57, vcc
	v_add_co_u32_e32 v48, vcc, s23, v56
	global_load_dwordx4 v[24:27], v[26:27], off nt
	s_nop 0
	global_load_dwordx4 v[28:31], v[28:29], off nt
	v_addc_co_u32_e32 v49, vcc, 0, v57, vcc
	v_add_co_u32_e32 v52, vcc, s33, v56
	global_load_dwordx4 v[32:35], v[56:57], off nt
	s_nop 0
	global_load_dwordx4 v[36:39], v[36:37], off nt
	v_addc_co_u32_e32 v53, vcc, 0, v57, vcc
	v_add_co_u32_e32 v58, vcc, s38, v56
	global_load_dwordx4 v[40:43], v[40:41], off nt
	s_nop 0
	global_load_dwordx4 v[44:47], v[44:45], off nt
	v_addc_co_u32_e32 v59, vcc, 0, v57, vcc
	v_add_co_u32_e32 v60, vcc, s27, v56
	global_load_dwordx4 v[48:51], v[48:49], off nt
	s_nop 0
	global_load_dwordx4 v[52:55], v[52:53], off nt
	v_addc_co_u32_e32 v61, vcc, 0, v57, vcc
	global_load_dwordx4 v[56:59], v[58:59], off nt
	s_nop 0
	global_load_dwordx4 v[60:63], v[60:61], off nt
	s_ashr_i32 s23, s22, 31
	s_lshl_b64 s[20:21], s[22:23], 1
	s_add_u32 s20, s12, s20
	v_or_b32_e32 v65, s26, v64
	s_addc_u32 s21, s11, s21
	s_movk_i32 s11, 0xa00
	v_mul_lo_u32 v74, v65, s11
	v_lshl_add_u64 v[72:73], v[66:67], 1, s[20:21]
	v_ashrrev_i32_e32 v75, 31, v74
	v_lshl_add_u64 v[72:73], v[74:75], 1, v[72:73]
	s_mov_b32 s11, 0x25d00000
	v_add_co_u32_e32 v76, vcc, s11, v72
	s_mov_b32 s11, 0x25d01000
	s_nop 0
	v_addc_co_u32_e32 v77, vcc, 0, v73, vcc
	s_waitcnt vmcnt(14)
	v_cvt_pk_bf16_f32 v68, v0, v4
	v_add_co_u32_e32 v4, vcc, s11, v72
	s_waitcnt vmcnt(12)
	v_cvt_pk_bf16_f32 v69, v8, v12
	s_waitcnt vmcnt(10)
	v_cvt_pk_bf16_f32 v70, v16, v20
	s_waitcnt vmcnt(8)
	v_cvt_pk_bf16_f32 v71, v24, v28
	global_store_dwordx4 v[76:77], v[68:71], off nt
	s_mov_b32 s11, 0x25d02000
	s_mov_b64 s[20:21], 0x25d00000
	v_cvt_pk_bf16_f32 v68, v1, v5
	v_addc_co_u32_e32 v5, vcc, 0, v73, vcc
	v_add_co_u32_e32 v8, vcc, s11, v72
	v_cvt_pk_bf16_f32 v69, v9, v13
	s_mov_b32 s11, 0x25d03000
	s_nop 0
	v_addc_co_u32_e32 v9, vcc, 0, v73, vcc
	v_cvt_pk_bf16_f32 v70, v17, v21
	v_cvt_pk_bf16_f32 v71, v25, v29
	global_store_dwordx4 v[4:5], v[68:71], off offset:1024 nt
	v_lshl_add_u64 v[74:75], v[72:73], 0, s[20:21]
	s_mov_b64 s[22:23], 0
	v_cvt_pk_bf16_f32 v68, v2, v6
	v_add_co_u32_e32 v6, vcc, s11, v72
	v_cvt_pk_bf16_f32 v69, v10, v14
	v_cvt_pk_bf16_f32 v70, v18, v22
	v_cvt_pk_bf16_f32 v71, v26, v30
	global_store_dwordx4 v[8:9], v[68:71], off offset:2048 nt
	v_cvt_pk_bf16_f32 v0, v3, v7
	v_cvt_pk_bf16_f32 v1, v11, v15
	v_cvt_pk_bf16_f32 v2, v19, v23
	v_cvt_pk_bf16_f32 v3, v27, v31
	s_nop 0
	v_addc_co_u32_e32 v7, vcc, 0, v73, vcc
	global_store_dwordx4 v[6:7], v[0:3], off offset:3072 nt
	s_waitcnt vmcnt(10)
	s_nop 0
	v_cvt_pk_bf16_f32 v0, v32, v36
	s_waitcnt vmcnt(8)
	v_cvt_pk_bf16_f32 v1, v40, v44
	s_waitcnt vmcnt(6)
	v_cvt_pk_bf16_f32 v2, v48, v52
	s_waitcnt vmcnt(4)
	v_cvt_pk_bf16_f32 v3, v56, v60
	global_store_dwordx4 v[74:75], v[0:3], off offset:64 nt
	s_nop 1
	v_cvt_pk_bf16_f32 v0, v33, v37
	v_cvt_pk_bf16_f32 v1, v41, v45
	v_cvt_pk_bf16_f32 v2, v49, v53
	v_cvt_pk_bf16_f32 v3, v57, v61
	global_store_dwordx4 v[4:5], v[0:3], off offset:1088 nt
	s_nop 1
	v_cvt_pk_bf16_f32 v0, v34, v38
	v_cvt_pk_bf16_f32 v1, v42, v46
	v_cvt_pk_bf16_f32 v2, v50, v54
	v_cvt_pk_bf16_f32 v3, v58, v62
	global_store_dwordx4 v[8:9], v[0:3], off offset:2112 nt
	s_nop 1
	v_cvt_pk_bf16_f32 v0, v35, v39
	v_cvt_pk_bf16_f32 v1, v43, v47
	v_cvt_pk_bf16_f32 v2, v51, v55
	v_cvt_pk_bf16_f32 v3, v59, v63
	global_store_dwordx4 v[6:7], v[0:3], off offset:3136 nt
; __device__ __forceinline__ unsigned cvt_pk_bf16(float lo, float hi) { unsigned r; asm volatile("v_cvt_pk_bf16_f32 %0, %1, %2" : "=v"(r) : "v"(lo), "v"(hi)); return r; }
; #define INP(i) ((const float*)(const GASP float*)kargs()[(i)])
; __device__ __forceinline__ void tr_item(const float* W, int ldw, int k0, int n0, bf16* WT, int ldk, int drow0, int lane) {
;     const int n4 = (lane & 15) * 4, kg = lane >> 4; f32x4 v[2][8];
; #pragma unroll
;     for (int kh = 0; kh < 2; ++kh) { const float* src = W + (size_t)(k0 + kh * 32 + kg * 8) * ldw + n0 + n4;
; #pragma unroll
;         for (int i = 0; i < 8; ++i) v[kh][i] = __builtin_nontemporal_load((const f32x4*)(src + (size_t)i * ldw)); }
; #pragma unroll
;     for (int kh = 0; kh < 2; ++kh)
; #pragma unroll
;         for (int e = 0; e < 4; ++e) { u32x4 o; o.x = cvt_pk_bf16(v[kh][0][e], v[kh][1][e]); o.y = cvt_pk_bf16(v[kh][2][e], v[kh][3][e]); o.z = cvt_pk_bf16(v[kh][4][e], v[kh][5][e]); o.w = cvt_pk_bf16(v[kh][6][e], v[kh][7][e]);
;             *(u32x4*)(WT + (size_t)(drow0 + n4 + e) * ldk + k0 + kh * 32 + kg * 8) = o; }
; }
; __device__ __forceinline__ void conv_item(int it, int lane) {
;     ...
;     if (r < 2 * IT_INC) { const int idx = r / IT_INC; r -= idx * IT_INC; const int kb = r / 80, nb = r % 80;
;         tr_item(INP(I_WINC) + (size_t)idx * 2048 * 5120, 5120, 64 * kb, 64 * nb, (bf16*)(ws + WS_WINC) + (size_t)idx * 5120 * 2048, 2048, 64 * nb, lane); return; }
.LBB0_2511:
	s_andn2_b64 vcc, exec, s[22:23]
	s_cbranch_vccnz .LBB0_2513
	s_add_i32 s11, s6, 0xfffee600
	s_cmpk_gt_u32 s11, 0x9ff
	s_cselect_b64 s[20:21], -1, 0
	s_and_b64 s[22:23], s[20:21], exec
	s_cselect_b32 s12, 0xf600, 0
	s_add_i32 s12, s12, s11
	s_sext_i32_i16 s11, s12
	s_mulk_i32 s11, 0x6667
	s_lshr_b32 s22, s11, 31
	s_ashr_i32 s11, s11, 21
	s_add_i32 s11, s11, s22
	s_mov_b64 s[22:23], s[0:1]
	s_load_dwordx2 s[22:23], s[22:23], 0xe8
	s_mul_i32 s26, s11, 0x50
	s_sub_i32 s12, s12, s26
	s_and_b64 s[26:27], s[20:21], exec
	s_cselect_b32 s26, 0x2800000, 0
	s_sext_i32_i16 s12, s12
	s_waitcnt lgkmcnt(0)
	s_add_u32 s30, s22, s26
	s_addc_u32 s23, s23, 0
	s_lshl_b32 s22, s11, 6
	s_lshl_b32 s26, s12, 6
	s_and_b64 s[20:21], s[20:21], exec
	s_cselect_b32 s11, 0x1400000, 0
	s_add_u32 s11, s2, s11
	s_addc_u32 s12, s3, 0
	s_ashr_i32 s27, s26, 31
	s_lshl_b64 s[20:21], s[26:27], 2
	s_add_u32 s20, s30, s20
	s_addc_u32 s21, s23, s21
	v_lshlrev_b32_e32 v172, 2, v64
	v_add_u32_e32 v34, s22, v66
	v_lshl_add_u64 v[32:33], s[20:21], 0, v[172:173]
	s_movk_i32 s30, 0x5000
	v_mad_i64_i32 v[24:25], s[20:21], v34, s30, v[32:33]
	v_add_co_u32_e32 v4, vcc, s30, v24
	s_mov_b32 s23, 0x14000
	s_nop 0
	v_addc_co_u32_e32 v5, vcc, 0, v25, vcc
	v_add_co_u32_e32 v8, vcc, s33, v24
	s_mov_b32 s31, 0x19000
	s_nop 0
	v_addc_co_u32_e32 v9, vcc, 0, v25, vcc
	v_add_co_u32_e32 v12, vcc, s76, v24
	s_mov_b32 s27, 0x1e000
	s_nop 0
	v_addc_co_u32_e32 v13, vcc, 0, v25, vcc
	v_add_co_u32_e32 v16, vcc, s23, v24
	v_add_u32_e32 v34, 32, v34
	s_nop 0
	v_addc_co_u32_e32 v17, vcc, 0, v25, vcc
	v_add_co_u32_e32 v20, vcc, s31, v24
	v_mad_i64_i32 v[56:57], s[20:21], v34, s30, v[32:33]
	s_nop 0
	v_addc_co_u32_e32 v21, vcc, 0, v25, vcc
	v_add_co_u32_e32 v26, vcc, s27, v24
	global_load_dwordx4 v[0:3], v[24:25], off nt
	s_nop 0
	global_load_dwordx4 v[4:7], v[4:5], off nt
	v_addc_co_u32_e32 v27, vcc, 0, v25, vcc
	v_add_co_u32_e32 v28, vcc, s77, v24
	global_load_dwordx4 v[8:11], v[8:9], off nt
	s_nop 0
	global_load_dwordx4 v[12:15], v[12:13], off nt
	v_addc_co_u32_e32 v29, vcc, 0, v25, vcc
	v_add_co_u32_e32 v36, vcc, s30, v56
	global_load_dwordx4 v[16:19], v[16:17], off nt
	s_nop 0
	global_load_dwordx4 v[20:23], v[20:21], off nt
	v_addc_co_u32_e32 v37, vcc, 0, v57, vcc
	v_add_co_u32_e32 v40, vcc, s33, v56
	global_load_dwordx4 v[24:27], v[26:27], off nt
	s_nop 0
	global_load_dwordx4 v[28:31], v[28:29], off nt
	v_addc_co_u32_e32 v41, vcc, 0, v57, vcc
	v_add_co_u32_e32 v44, vcc, s76, v56
	global_load_dwordx4 v[32:35], v[56:57], off nt
	s_nop 0
	global_load_dwordx4 v[36:39], v[36:37], off nt
	v_addc_co_u32_e32 v45, vcc, 0, v57, vcc
	v_add_co_u32_e32 v48, vcc, s23, v56
	global_load_dwordx4 v[40:43], v[40:41], off nt
	s_nop 0
	global_load_dwordx4 v[44:47], v[44:45], off nt
	v_addc_co_u32_e32 v49, vcc, 0, v57, vcc
	v_add_co_u32_e32 v52, vcc, s31, v56
	s_ashr_i32 s23, s22, 31
	s_nop 0
	v_addc_co_u32_e32 v53, vcc, 0, v57, vcc
	v_add_co_u32_e32 v58, vcc, s27, v56
	global_load_dwordx4 v[48:51], v[48:49], off nt
	s_nop 0
	global_load_dwordx4 v[52:55], v[52:53], off nt
	v_addc_co_u32_e32 v59, vcc, 0, v57, vcc
	v_add_co_u32_e32 v60, vcc, s77, v56
	s_lshl_b64 s[20:21], s[22:23], 1
	s_nop 0
	v_addc_co_u32_e32 v61, vcc, 0, v57, vcc
	global_load_dwordx4 v[56:59], v[58:59], off nt
	s_nop 0
	global_load_dwordx4 v[60:63], v[60:61], off nt
	s_add_u32 s20, s11, s20
	v_or_b32_e32 v72, s26, v64
	s_addc_u32 s21, s12, s21
	v_lshl_add_u64 v[68:69], v[66:67], 1, s[20:21]
	s_mov_b64 s[20:21], 0x23500000
	v_ashrrev_i32_e32 v73, 31, v72
	v_lshl_add_u64 v[74:75], v[68:69], 0, s[20:21]
	v_lshlrev_b64 v[76:77], 12, v[72:73]
	s_waitcnt vmcnt(14)
	v_cvt_pk_bf16_f32 v68, v0, v4
	v_lshl_add_u64 v[76:77], v[74:75], 0, v[76:77]
	v_or_b32_e32 v0, 1, v72
	s_waitcnt vmcnt(12)
	v_cvt_pk_bf16_f32 v69, v8, v12
	s_waitcnt vmcnt(10)
	v_cvt_pk_bf16_f32 v70, v16, v20
	s_waitcnt vmcnt(8)
	v_cvt_pk_bf16_f32 v71, v24, v28
	global_store_dwordx4 v[76:77], v[68:71], off nt
	s_nop 1
	v_cvt_pk_bf16_f32 v68, v1, v5
	v_ashrrev_i32_e32 v1, 31, v0
	v_lshlrev_b64 v[0:1], 12, v[0:1]
	v_lshl_add_u64 v[4:5], v[74:75], 0, v[0:1]
	v_or_b32_e32 v0, 2, v72
	v_ashrrev_i32_e32 v1, 31, v0
	v_lshlrev_b64 v[0:1], 12, v[0:1]
	v_cvt_pk_bf16_f32 v69, v9, v13
	v_cvt_pk_bf16_f32 v70, v17, v21
	v_cvt_pk_bf16_f32 v71, v25, v29
	global_store_dwordx4 v[4:5], v[68:71], off nt
	v_lshl_add_u64 v[8:9], v[74:75], 0, v[0:1]
	s_nop 0
	v_cvt_pk_bf16_f32 v68, v2, v6
	v_or_b32_e32 v6, 3, v72
	v_cvt_pk_bf16_f32 v69, v10, v14
	v_cvt_pk_bf16_f32 v70, v18, v22
	v_cvt_pk_bf16_f32 v71, v26, v30
	global_store_dwordx4 v[8:9], v[68:71], off nt
	v_cvt_pk_bf16_f32 v0, v3, v7
	v_ashrrev_i32_e32 v7, 31, v6
	v_lshlrev_b64 v[6:7], 12, v[6:7]
	v_cvt_pk_bf16_f32 v1, v11, v15
	v_cvt_pk_bf16_f32 v2, v19, v23
	v_cvt_pk_bf16_f32 v3, v27, v31
	v_lshl_add_u64 v[6:7], v[74:75], 0, v[6:7]
	global_store_dwordx4 v[6:7], v[0:3], off nt
	s_waitcnt vmcnt(10)
	s_nop 0
	v_cvt_pk_bf16_f32 v0, v32, v36
	s_waitcnt vmcnt(8)
	v_cvt_pk_bf16_f32 v1, v40, v44
	s_waitcnt vmcnt(6)
	v_cvt_pk_bf16_f32 v2, v48, v52
	s_waitcnt vmcnt(4)
	v_cvt_pk_bf16_f32 v3, v56, v60
	global_store_dwordx4 v[76:77], v[0:3], off offset:64 nt
	s_nop 1
	v_cvt_pk_bf16_f32 v0, v33, v37
	v_cvt_pk_bf16_f32 v1, v41, v45
	v_cvt_pk_bf16_f32 v2, v49, v53
	v_cvt_pk_bf16_f32 v3, v57, v61
	global_store_dwordx4 v[4:5], v[0:3], off offset:64 nt
	s_nop 1
	v_cvt_pk_bf16_f32 v0, v34, v38
	v_cvt_pk_bf16_f32 v1, v42, v46
	v_cvt_pk_bf16_f32 v2, v50, v54
	v_cvt_pk_bf16_f32 v3, v58, v62
	global_store_dwordx4 v[8:9], v[0:3], off offset:64 nt
	s_nop 1
	v_cvt_pk_bf16_f32 v0, v35, v39
	v_cvt_pk_bf16_f32 v1, v43, v47
	v_cvt_pk_bf16_f32 v2, v51, v55
	v_cvt_pk_bf16_f32 v3, v59, v63
	global_store_dwordx4 v[6:7], v[0:3], off offset:64 nt

; __device__ __forceinline__ unsigned cvt_pk_bf16(float lo, float hi) { unsigned r; asm volatile("v_cvt_pk_bf16_f32 %0, %1, %2" : "=v"(r) : "v"(lo), "v"(hi)); return r; }
; #define INP(i) ((const float*)(const GASP float*)kargs()[(i)])
; __device__ __forceinline__ void tr_item(const float* W, int ldw, int k0, int n0, bf16* WT, int ldk, int drow0, int lane) {
;     const int n4 = (lane & 15) * 4, kg = lane >> 4; f32x4 v[2][8];
; #pragma unroll
;     for (int kh = 0; kh < 2; ++kh) { const float* src = W + (size_t)(k0 + kh * 32 + kg * 8) * ldw + n0 + n4;
; #pragma unroll
;         for (int i = 0; i < 8; ++i) v[kh][i] = __builtin_nontemporal_load((const f32x4*)(src + (size_t)i * ldw)); }
; #pragma unroll
;     for (int kh = 0; kh < 2; ++kh)
; #pragma unroll
;         for (int e = 0; e < 4; ++e) { u32x4 o; o.x = cvt_pk_bf16(v[kh][0][e], v[kh][1][e]); o.y = cvt_pk_bf16(v[kh][2][e], v[kh][3][e]); o.z = cvt_pk_bf16(v[kh][4][e], v[kh][5][e]); o.w = cvt_pk_bf16(v[kh][6][e], v[kh][7][e]);
;             *(u32x4*)(WT + (size_t)(drow0 + n4 + e) * ldk + k0 + kh * 32 + kg * 8) = o; }
; }
; __device__ __forceinline__ void conv_item(int it, int lane) {
;     ...
;     if (r < 2 * IT_OUTAB) { const int idx = r / IT_OUTAB; r -= idx * IT_OUTAB; const int kb = r / 32, nb = r % 32;
;         tr_item(INP(I_WOUTAB) + (size_t)idx * 2048 * 2048, 2048, 64 * kb, 64 * nb, (bf16*)(ws + WS_WOUTAB) + (size_t)idx * 2048 * 2048, 2048, 64 * nb, lane); return; }
.LBB0_2514:
	s_andn2_b64 vcc, exec, s[22:23]
	s_cbranch_vccnz .LBB0_2516
	s_mov_b64 s[20:21], s[0:1]
	s_load_dwordx2 s[20:21], s[20:21], 0xe0
	s_add_i32 s11, s6, 0xfffeee00
	s_lshr_b32 s38, s11, 10
	s_lshl_b64 s[22:23], s[38:39], 24
	v_lshlrev_b32_e32 v172, 2, v64
	s_waitcnt lgkmcnt(0)
	s_add_u32 s12, s20, s22
	s_addc_u32 s22, s21, s23
	s_lshl_b32 s11, s11, 1
	s_lshl_b32 s20, s6, 6
	s_and_b32 s11, s11, 0x7c0
	s_and_b32 s23, s20, 0x7c0
	s_lshl_b64 s[20:21], s[38:39], 23
	s_add_u32 s26, s2, s20
	s_addc_u32 s27, s3, s21
	s_lshl_b32 s20, s23, 2
	v_add_u32_e32 v32, s11, v66
	s_add_u32 s20, s12, s20
	s_addc_u32 s21, s22, 0
	v_ashrrev_i32_e32 v33, 31, v32
	v_lshl_add_u64 v[34:35], s[20:21], 0, v[172:173]
	v_lshlrev_b64 v[0:1], 13, v[32:33]
	v_lshl_add_u64 v[24:25], v[34:35], 0, v[0:1]
	v_add_co_u32_e32 v4, vcc, s89, v24
	s_movk_i32 s20, 0x4000
	s_nop 0
	v_addc_co_u32_e32 v5, vcc, 0, v25, vcc
	v_add_co_u32_e32 v8, vcc, s20, v24
	s_movk_i32 s12, 0x6000
	s_nop 0
	v_addc_co_u32_e32 v9, vcc, 0, v25, vcc
	v_add_co_u32_e32 v12, vcc, s12, v24
	s_mov_b32 s21, 0x8000
	s_nop 0
	v_addc_co_u32_e32 v13, vcc, 0, v25, vcc
	v_add_co_u32_e32 v16, vcc, s21, v24
	s_mov_b32 s38, 0xc000
	s_nop 0
	v_addc_co_u32_e32 v17, vcc, 0, v25, vcc
	v_add_co_u32_e32 v20, vcc, s33, v24
	v_add_u32_e32 v32, 32, v32
	s_nop 0
	v_addc_co_u32_e32 v21, vcc, 0, v25, vcc
	v_add_co_u32_e32 v26, vcc, s38, v24
	s_mov_b32 s22, 0xe000
	s_nop 0
	v_addc_co_u32_e32 v27, vcc, 0, v25, vcc
	v_ashrrev_i32_e32 v33, 31, v32
	v_add_co_u32_e32 v28, vcc, s22, v24
	v_lshlrev_b64 v[32:33], 13, v[32:33]
	s_nop 0
	v_addc_co_u32_e32 v29, vcc, 0, v25, vcc
	v_lshl_add_u64 v[56:57], v[34:35], 0, v[32:33]
	v_add_co_u32_e32 v36, vcc, s89, v56
	global_load_dwordx4 v[0:3], v[24:25], off nt
	s_nop 0
	global_load_dwordx4 v[4:7], v[4:5], off nt
	v_addc_co_u32_e32 v37, vcc, 0, v57, vcc
	v_add_co_u32_e32 v40, vcc, s20, v56
	global_load_dwordx4 v[8:11], v[8:9], off nt
	s_nop 0
	global_load_dwordx4 v[12:15], v[12:13], off nt
	v_addc_co_u32_e32 v41, vcc, 0, v57, vcc
	v_add_co_u32_e32 v44, vcc, s12, v56
	global_load_dwordx4 v[16:19], v[16:17], off nt
	s_nop 0
	global_load_dwordx4 v[20:23], v[20:21], off nt
	v_addc_co_u32_e32 v45, vcc, 0, v57, vcc
	v_add_co_u32_e32 v48, vcc, s21, v56
	global_load_dwordx4 v[24:27], v[26:27], off nt
	s_nop 0
	global_load_dwordx4 v[28:31], v[28:29], off nt
	v_addc_co_u32_e32 v49, vcc, 0, v57, vcc
	v_add_co_u32_e32 v52, vcc, s33, v56
	global_load_dwordx4 v[32:35], v[56:57], off nt
	s_nop 0
	global_load_dwordx4 v[36:39], v[36:37], off nt
	v_addc_co_u32_e32 v53, vcc, 0, v57, vcc
	v_add_co_u32_e32 v58, vcc, s38, v56
	global_load_dwordx4 v[40:43], v[40:41], off nt
	s_nop 0
	global_load_dwordx4 v[44:47], v[44:45], off nt
	v_addc_co_u32_e32 v59, vcc, 0, v57, vcc
	v_add_co_u32_e32 v60, vcc, s22, v56
	global_load_dwordx4 v[48:51], v[48:49], off nt
	s_nop 0
	global_load_dwordx4 v[52:55], v[52:53], off nt
	v_addc_co_u32_e32 v61, vcc, 0, v57, vcc
	global_load_dwordx4 v[56:59], v[58:59], off nt
	s_nop 0
	global_load_dwordx4 v[60:63], v[60:61], off nt
	s_lshl_b32 s11, s11, 1
	s_add_u32 s20, s26, s11
	s_addc_u32 s21, s27, 0
	v_or_b32_e32 v65, s23, v64
	v_lshl_add_u64 v[72:73], v[66:67], 1, s[20:21]
	s_mov_b64 s[20:21], 0x22500000
	v_lshl_add_u64 v[74:75], v[72:73], 0, s[20:21]
	v_lshlrev_b32_e32 v172, 12, v65
	s_waitcnt vmcnt(14)
	v_cvt_pk_bf16_f32 v68, v0, v4
	v_lshl_add_u64 v[76:77], v[74:75], 0, v[172:173]
	s_waitcnt vmcnt(12)
	v_cvt_pk_bf16_f32 v69, v8, v12
	s_waitcnt vmcnt(10)
	v_cvt_pk_bf16_f32 v70, v16, v20
	s_waitcnt vmcnt(8)
	v_cvt_pk_bf16_f32 v71, v24, v28
	global_store_dwordx4 v[76:77], v[68:71], off nt
	v_or_b32_e32 v4, 0x1000, v172
	v_or_b32_e32 v8, 0x2000, v172
	v_cvt_pk_bf16_f32 v68, v1, v5
	v_mov_b32_e32 v5, v173
	v_cvt_pk_bf16_f32 v69, v9, v13
	v_lshl_add_u64 v[0:1], v[74:75], 0, v[4:5]
	v_mov_b32_e32 v9, v173
	v_cvt_pk_bf16_f32 v70, v17, v21
	v_cvt_pk_bf16_f32 v71, v25, v29
	global_store_dwordx4 v[0:1], v[68:71], off nt
	v_lshl_add_u64 v[0:1], v[74:75], 0, v[8:9]
	v_or_b32_e32 v172, 0x3000, v172
	v_cvt_pk_bf16_f32 v68, v2, v6
	v_cvt_pk_bf16_f32 v69, v10, v14
	v_cvt_pk_bf16_f32 v70, v18, v22
	v_cvt_pk_bf16_f32 v71, v26, v30
	global_store_dwordx4 v[0:1], v[68:71], off nt
	v_cvt_pk_bf16_f32 v0, v3, v7
	v_lshl_add_u64 v[6:7], v[74:75], 0, v[172:173]
	s_mov_b64 s[20:21], 0x22500040
	v_cvt_pk_bf16_f32 v1, v11, v15
	v_cvt_pk_bf16_f32 v2, v19, v23
	v_cvt_pk_bf16_f32 v3, v27, v31
	global_store_dwordx4 v[6:7], v[0:3], off nt
	v_lshl_add_u64 v[6:7], v[72:73], 0, s[20:21]
	v_lshl_add_u64 v[4:5], v[6:7], 0, v[4:5]
	s_waitcnt vmcnt(10)
	v_cvt_pk_bf16_f32 v0, v32, v36
	s_waitcnt vmcnt(8)
	v_cvt_pk_bf16_f32 v1, v40, v44
	s_waitcnt vmcnt(6)
	v_cvt_pk_bf16_f32 v2, v48, v52
	s_waitcnt vmcnt(4)
	v_cvt_pk_bf16_f32 v3, v56, v60
	global_store_dwordx4 v[76:77], v[0:3], off offset:64 nt
	s_nop 1
	v_cvt_pk_bf16_f32 v0, v33, v37
	v_cvt_pk_bf16_f32 v1, v41, v45
	v_cvt_pk_bf16_f32 v2, v49, v53
	v_cvt_pk_bf16_f32 v3, v57, v61
	global_store_dwordx4 v[4:5], v[0:3], off nt
	v_lshl_add_u64 v[4:5], v[6:7], 0, v[8:9]
	s_nop 0
	v_cvt_pk_bf16_f32 v0, v34, v38
	v_cvt_pk_bf16_f32 v1, v42, v46
	v_cvt_pk_bf16_f32 v2, v50, v54
	v_cvt_pk_bf16_f32 v3, v58, v62
	global_store_dwordx4 v[4:5], v[0:3], off nt
	v_lshl_add_u64 v[4:5], v[6:7], 0, v[172:173]
	s_nop 0
	v_cvt_pk_bf16_f32 v0, v35, v39
	v_cvt_pk_bf16_f32 v1, v43, v47
	v_cvt_pk_bf16_f32 v2, v51, v55
	v_cvt_pk_bf16_f32 v3, v59, v63
	global_store_dwordx4 v[4:5], v[0:3], off nt

; __device__ __forceinline__ unsigned cvt_pk_bf16(float lo, float hi) { unsigned r; asm volatile("v_cvt_pk_bf16_f32 %0, %1, %2" : "=v"(r) : "v"(lo), "v"(hi)); return r; }
; #define INP(i) ((const float*)(const GASP float*)kargs()[(i)])
; __device__ __forceinline__ void tr_item(const float* W, int ldw, int k0, int n0, bf16* WT, int ldk, int drow0, int lane) {
;     const int n4 = (lane & 15) * 4, kg = lane >> 4; f32x4 v[2][8];
; #pragma unroll
;     for (int kh = 0; kh < 2; ++kh) { const float* src = W + (size_t)(k0 + kh * 32 + kg * 8) * ldw + n0 + n4;
; #pragma unroll
;         for (int i = 0; i < 8; ++i) v[kh][i] = __builtin_nontemporal_load((const f32x4*)(src + (size_t)i * ldw)); }
; #pragma unroll
;     for (int kh = 0; kh < 2; ++kh)
; #pragma unroll
;         for (int e = 0; e < 4; ++e) { u32x4 o; o.x = cvt_pk_bf16(v[kh][0][e], v[kh][1][e]); o.y = cvt_pk_bf16(v[kh][2][e], v[kh][3][e]); o.z = cvt_pk_bf16(v[kh][4][e], v[kh][5][e]); o.w = cvt_pk_bf16(v[kh][6][e], v[kh][7][e]);
;             *(u32x4*)(WT + (size_t)(drow0 + n4 + e) * ldk + k0 + kh * 32 + kg * 8) = o; }
; }
; __device__ __forceinline__ void conv_item(int it, int lane) {
;     ...
;     if (r < 2 * IT_INAB) { const int idx = r / IT_INAB; r -= idx * IT_INAB; const int kb = r / 80, nb = r % 80;
;         tr_item(INP(I_WINAB) + (size_t)idx * 2048 * 5120, 5120, 64 * kb, 64 * nb, (bf16*)(ws + WS_WINAB) + (size_t)idx * 5120 * 2048, 2048, 64 * nb, lane); return; }
.LBB0_2520:
	s_andn2_b64 vcc, exec, s[22:23]
	s_cbranch_vccnz .LBB0_2522
	s_add_i32 s11, s6, 0xffff0400
	s_cmpk_gt_u32 s11, 0x9ff
	s_cselect_b64 s[20:21], -1, 0
	s_and_b64 s[22:23], s[20:21], exec
	s_cselect_b32 s12, 0xf600, 0
	s_add_i32 s12, s12, s11
	s_sext_i32_i16 s11, s12
	s_mulk_i32 s11, 0x6667
	s_lshr_b32 s22, s11, 31
	s_ashr_i32 s11, s11, 21
	s_add_i32 s11, s11, s22
	s_mov_b64 s[22:23], s[0:1]
	s_load_dwordx2 s[22:23], s[22:23], 0x78
	s_mul_i32 s26, s11, 0x50
	s_sub_i32 s12, s12, s26
	s_and_b64 s[26:27], s[20:21], exec
	s_cselect_b32 s26, 0x2800000, 0
	s_sext_i32_i16 s12, s12
	s_waitcnt lgkmcnt(0)
	s_add_u32 s30, s22, s26
	s_addc_u32 s23, s23, 0
	s_lshl_b32 s22, s11, 6
	s_lshl_b32 s26, s12, 6
	s_and_b64 s[20:21], s[20:21], exec
	s_cselect_b32 s11, 0x1400000, 0
	s_add_u32 s11, s2, s11
	s_addc_u32 s12, s3, 0
	s_ashr_i32 s27, s26, 31
	s_lshl_b64 s[20:21], s[26:27], 2
	s_add_u32 s20, s30, s20
	s_addc_u32 s21, s23, s21
	v_lshlrev_b32_e32 v172, 2, v64
	v_add_u32_e32 v34, s22, v66
	v_lshl_add_u64 v[32:33], s[20:21], 0, v[172:173]
	s_movk_i32 s30, 0x5000
	v_mad_i64_i32 v[24:25], s[20:21], v34, s30, v[32:33]
	v_add_co_u32_e32 v4, vcc, s30, v24
	s_mov_b32 s23, 0x14000
	s_nop 0
	v_addc_co_u32_e32 v5, vcc, 0, v25, vcc
	v_add_co_u32_e32 v8, vcc, s33, v24
	s_mov_b32 s31, 0x19000
	s_nop 0
	v_addc_co_u32_e32 v9, vcc, 0, v25, vcc
	v_add_co_u32_e32 v12, vcc, s76, v24
	s_mov_b32 s27, 0x1e000
	s_nop 0
	v_addc_co_u32_e32 v13, vcc, 0, v25, vcc
	v_add_co_u32_e32 v16, vcc, s23, v24
	v_add_u32_e32 v34, 32, v34
	s_nop 0
	v_addc_co_u32_e32 v17, vcc, 0, v25, vcc
	v_add_co_u32_e32 v20, vcc, s31, v24
	v_mad_i64_i32 v[56:57], s[20:21], v34, s30, v[32:33]
	s_nop 0
	v_addc_co_u32_e32 v21, vcc, 0, v25, vcc
	v_add_co_u32_e32 v26, vcc, s27, v24
	global_load_dwordx4 v[0:3], v[24:25], off nt
	s_nop 0
	global_load_dwordx4 v[4:7], v[4:5], off nt
	v_addc_co_u32_e32 v27, vcc, 0, v25, vcc
	v_add_co_u32_e32 v28, vcc, s77, v24
	global_load_dwordx4 v[8:11], v[8:9], off nt
	s_nop 0
	global_load_dwordx4 v[12:15], v[12:13], off nt
	v_addc_co_u32_e32 v29, vcc, 0, v25, vcc
	v_add_co_u32_e32 v36, vcc, s30, v56
	global_load_dwordx4 v[16:19], v[16:17], off nt
	s_nop 0
	global_load_dwordx4 v[20:23], v[20:21], off nt
	v_addc_co_u32_e32 v37, vcc, 0, v57, vcc
	v_add_co_u32_e32 v40, vcc, s33, v56
	global_load_dwordx4 v[24:27], v[26:27], off nt
	s_nop 0
	global_load_dwordx4 v[28:31], v[28:29], off nt
	v_addc_co_u32_e32 v41, vcc, 0, v57, vcc
	v_add_co_u32_e32 v44, vcc, s76, v56
	global_load_dwordx4 v[32:35], v[56:57], off nt
	s_nop 0
	global_load_dwordx4 v[36:39], v[36:37], off nt
	v_addc_co_u32_e32 v45, vcc, 0, v57, vcc
	v_add_co_u32_e32 v48, vcc, s23, v56
	global_load_dwordx4 v[40:43], v[40:41], off nt
	s_nop 0
	global_load_dwordx4 v[44:47], v[44:45], off nt
	v_addc_co_u32_e32 v49, vcc, 0, v57, vcc
	v_add_co_u32_e32 v52, vcc, s31, v56
	s_ashr_i32 s23, s22, 31
	s_nop 0
	v_addc_co_u32_e32 v53, vcc, 0, v57, vcc
	v_add_co_u32_e32 v58, vcc, s27, v56
	global_load_dwordx4 v[48:51], v[48:49], off nt
	s_nop 0
	global_load_dwordx4 v[52:55], v[52:53], off nt
	v_addc_co_u32_e32 v59, vcc, 0, v57, vcc
	v_add_co_u32_e32 v60, vcc, s77, v56
	s_lshl_b64 s[20:21], s[22:23], 1
	s_nop 0
	v_addc_co_u32_e32 v61, vcc, 0, v57, vcc
	global_load_dwordx4 v[56:59], v[58:59], off nt
	s_nop 0
	global_load_dwordx4 v[60:63], v[60:61], off nt
	s_add_u32 s20, s11, s20
	v_or_b32_e32 v72, s26, v64
	s_addc_u32 s21, s12, s21
	v_lshl_add_u64 v[68:69], v[66:67], 1, s[20:21]
	s_mov_b64 s[20:21], 0x1f900000
	v_ashrrev_i32_e32 v73, 31, v72
	v_lshl_add_u64 v[74:75], v[68:69], 0, s[20:21]
	v_lshlrev_b64 v[76:77], 12, v[72:73]
	s_waitcnt vmcnt(14)
	v_cvt_pk_bf16_f32 v68, v0, v4
	v_lshl_add_u64 v[76:77], v[74:75], 0, v[76:77]
	v_or_b32_e32 v0, 1, v72
	s_waitcnt vmcnt(12)
	v_cvt_pk_bf16_f32 v69, v8, v12
	s_waitcnt vmcnt(10)
	v_cvt_pk_bf16_f32 v70, v16, v20
	s_waitcnt vmcnt(8)
	v_cvt_pk_bf16_f32 v71, v24, v28
	global_store_dwordx4 v[76:77], v[68:71], off nt
	s_nop 1
	v_cvt_pk_bf16_f32 v68, v1, v5
	v_ashrrev_i32_e32 v1, 31, v0
	v_lshlrev_b64 v[0:1], 12, v[0:1]
	v_lshl_add_u64 v[4:5], v[74:75], 0, v[0:1]
	v_or_b32_e32 v0, 2, v72
	v_ashrrev_i32_e32 v1, 31, v0
	v_lshlrev_b64 v[0:1], 12, v[0:1]
	v_cvt_pk_bf16_f32 v69, v9, v13
	v_cvt_pk_bf16_f32 v70, v17, v21
	v_cvt_pk_bf16_f32 v71, v25, v29
	global_store_dwordx4 v[4:5], v[68:71], off nt
	v_lshl_add_u64 v[8:9], v[74:75], 0, v[0:1]
	s_nop 0
	v_cvt_pk_bf16_f32 v68, v2, v6
	v_or_b32_e32 v6, 3, v72
	v_cvt_pk_bf16_f32 v69, v10, v14
	v_cvt_pk_bf16_f32 v70, v18, v22
	v_cvt_pk_bf16_f32 v71, v26, v30
	global_store_dwordx4 v[8:9], v[68:71], off nt
	v_cvt_pk_bf16_f32 v0, v3, v7
	v_ashrrev_i32_e32 v7, 31, v6
	v_lshlrev_b64 v[6:7], 12, v[6:7]
	v_cvt_pk_bf16_f32 v1, v11, v15
	v_cvt_pk_bf16_f32 v2, v19, v23
	v_cvt_pk_bf16_f32 v3, v27, v31
	v_lshl_add_u64 v[6:7], v[74:75], 0, v[6:7]
	global_store_dwordx4 v[6:7], v[0:3], off nt
	s_waitcnt vmcnt(10)
	s_nop 0
	v_cvt_pk_bf16_f32 v0, v32, v36
	s_waitcnt vmcnt(8)
	v_cvt_pk_bf16_f32 v1, v40, v44
	s_waitcnt vmcnt(6)
	v_cvt_pk_bf16_f32 v2, v48, v52
	s_waitcnt vmcnt(4)
	v_cvt_pk_bf16_f32 v3, v56, v60
	global_store_dwordx4 v[76:77], v[0:3], off offset:64 nt
	s_nop 1
	v_cvt_pk_bf16_f32 v0, v33, v37
	v_cvt_pk_bf16_f32 v1, v41, v45
	v_cvt_pk_bf16_f32 v2, v49, v53
	v_cvt_pk_bf16_f32 v3, v57, v61
	global_store_dwordx4 v[4:5], v[0:3], off offset:64 nt
	s_nop 1
	v_cvt_pk_bf16_f32 v0, v34, v38
	v_cvt_pk_bf16_f32 v1, v42, v46
	v_cvt_pk_bf16_f32 v2, v50, v54
	v_cvt_pk_bf16_f32 v3, v58, v62
	global_store_dwordx4 v[8:9], v[0:3], off offset:64 nt
	s_nop 1
	v_cvt_pk_bf16_f32 v0, v35, v39
	v_cvt_pk_bf16_f32 v1, v43, v47
	v_cvt_pk_bf16_f32 v2, v51, v55
	v_cvt_pk_bf16_f32 v3, v59, v63
	global_store_dwordx4 v[6:7], v[0:3], off offset:64 nt

; __device__ __forceinline__ unsigned cvt_pk_bf16(float lo, float hi) { unsigned r; asm volatile("v_cvt_pk_bf16_f32 %0, %1, %2" : "=v"(r) : "v"(lo), "v"(hi)); return r; }
; #define INP(i) ((const float*)(const GASP float*)kargs()[(i)])
; __device__ __forceinline__ void tr_item(const float* W, int ldw, int k0, int n0, bf16* WT, int ldk, int drow0, int lane) {
;     const int n4 = (lane & 15) * 4, kg = lane >> 4; f32x4 v[2][8];
; #pragma unroll
;     for (int kh = 0; kh < 2; ++kh) { const float* src = W + (size_t)(k0 + kh * 32 + kg * 8) * ldw + n0 + n4;
; #pragma unroll
;         for (int i = 0; i < 8; ++i) v[kh][i] = __builtin_nontemporal_load((const f32x4*)(src + (size_t)i * ldw)); }
; #pragma unroll
;     for (int kh = 0; kh < 2; ++kh)
; #pragma unroll
;         for (int e = 0; e < 4; ++e) { u32x4 o; o.x = cvt_pk_bf16(v[kh][0][e], v[kh][1][e]); o.y = cvt_pk_bf16(v[kh][2][e], v[kh][3][e]); o.z = cvt_pk_bf16(v[kh][4][e], v[kh][5][e]); o.w = cvt_pk_bf16(v[kh][6][e], v[kh][7][e]);
;             *(u32x4*)(WT + (size_t)(drow0 + n4 + e) * ldk + k0 + kh * 32 + kg * 8) = o; }
; }
; __device__ __forceinline__ void conv_item(int it, int lane) {
;     ...
;     if (r < 8 * IT_D) { const int idx = r / IT_D; r -= idx * IT_D; const int kb = r / 32, nb = r % 32;
;         tr_item(INP(I_WD) + (size_t)idx * 5376 * 2048, 2048, 64 * kb, 64 * nb, (bf16*)(ws + WS_WD) + (size_t)idx * 2048 * 5376, 5376, 64 * nb, lane); return; }
.LBB0_2523:
	s_andn2_b64 vcc, exec, s[22:23]
	s_cbranch_vccnz .LBB0_2525
	s_add_i32 s11, s6, 0xffff5800
	s_bfe_u32 s12, s11, 0x100007
	s_mulk_i32 s12, 0xc31
	s_lshr_b32 s12, s12, 16
	s_mul_i32 s20, s12, 0xf580
	s_add_i32 s11, s20, s11
	s_sext_i32_i16 s20, s11
	s_bfe_u32 s20, s20, 0x5001a
	s_add_i32 s22, s11, s20
	s_mov_b64 s[20:21], s[0:1]
	s_load_dwordx2 s[20:21], s[20:21], 0x70
	s_sext_i32_i16 s23, s22
	s_and_b32 s22, s22, 0xffe0
	s_sub_i32 s11, s11, s22
	s_mul_i32 s22, s12, 0x2a00000
	s_waitcnt lgkmcnt(0)
	s_add_u32 s30, s20, s22
	s_sext_i32_i16 s11, s11
	s_addc_u32 s31, s21, 0
	s_lshl_b32 s20, s23, 1
	s_and_b32 s22, s20, 0xffffffc0
	s_lshl_b32 s26, s11, 6
	s_mul_i32 s12, s12, 0x1500000
	s_add_u32 s11, s2, s12
	s_addc_u32 s12, s3, 0
	s_ashr_i32 s27, s26, 31
	s_lshl_b64 s[20:21], s[26:27], 2
	v_add_u32_e32 v32, s22, v66
	s_add_u32 s20, s30, s20
	s_addc_u32 s21, s31, s21
	v_lshlrev_b32_e32 v172, 2, v64
	v_ashrrev_i32_e32 v33, 31, v32
	v_lshl_add_u64 v[34:35], s[20:21], 0, v[172:173]
	v_lshlrev_b64 v[0:1], 13, v[32:33]
	v_lshl_add_u64 v[24:25], v[34:35], 0, v[0:1]
	v_add_co_u32_e32 v4, vcc, s89, v24
	s_movk_i32 s21, 0x4000
	s_nop 0
	v_addc_co_u32_e32 v5, vcc, 0, v25, vcc
	v_add_co_u32_e32 v8, vcc, s21, v24
	s_movk_i32 s20, 0x6000
	s_nop 0
	v_addc_co_u32_e32 v9, vcc, 0, v25, vcc
	v_add_co_u32_e32 v12, vcc, s20, v24
	s_mov_b32 s23, 0x8000
	s_nop 0
	v_addc_co_u32_e32 v13, vcc, 0, v25, vcc
	v_add_co_u32_e32 v16, vcc, s23, v24
	v_add_u32_e32 v32, 32, v32
	s_nop 0
	v_addc_co_u32_e32 v17, vcc, 0, v25, vcc
	v_add_co_u32_e32 v20, vcc, s33, v24
	s_mov_b32 s27, 0xe000
	s_nop 0
	v_addc_co_u32_e32 v21, vcc, 0, v25, vcc
	v_add_co_u32_e32 v26, vcc, s38, v24
	v_ashrrev_i32_e32 v33, 31, v32
	s_nop 0
	v_addc_co_u32_e32 v27, vcc, 0, v25, vcc
	v_add_co_u32_e32 v28, vcc, s27, v24
	v_lshlrev_b64 v[32:33], 13, v[32:33]
	s_nop 0
	v_addc_co_u32_e32 v29, vcc, 0, v25, vcc
	v_lshl_add_u64 v[56:57], v[34:35], 0, v[32:33]
	v_add_co_u32_e32 v36, vcc, s89, v56
	global_load_dwordx4 v[0:3], v[24:25], off nt
	s_nop 0
	global_load_dwordx4 v[4:7], v[4:5], off nt
	v_addc_co_u32_e32 v37, vcc, 0, v57, vcc
	v_add_co_u32_e32 v40, vcc, s21, v56
	global_load_dwordx4 v[8:11], v[8:9], off nt
	s_nop 0
	global_load_dwordx4 v[12:15], v[12:13], off nt
	v_addc_co_u32_e32 v41, vcc, 0, v57, vcc
	v_add_co_u32_e32 v44, vcc, s20, v56
	global_load_dwordx4 v[16:19], v[16:17], off nt
	s_nop 0
	global_load_dwordx4 v[20:23], v[20:21], off nt
	v_addc_co_u32_e32 v45, vcc, 0, v57, vcc
	v_add_co_u32_e32 v48, vcc, s23, v56
	global_load_dwordx4 v[24:27], v[26:27], off nt
	s_nop 0
	global_load_dwordx4 v[28:31], v[28:29], off nt
	v_addc_co_u32_e32 v49, vcc, 0, v57, vcc
	v_add_co_u32_e32 v52, vcc, s33, v56
	global_load_dwordx4 v[32:35], v[56:57], off nt
	s_nop 0
	global_load_dwordx4 v[36:39], v[36:37], off nt
	v_addc_co_u32_e32 v53, vcc, 0, v57, vcc
	v_add_co_u32_e32 v58, vcc, s38, v56
	global_load_dwordx4 v[40:43], v[40:41], off nt
	s_nop 0
	global_load_dwordx4 v[44:47], v[44:45], off nt
	v_addc_co_u32_e32 v59, vcc, 0, v57, vcc
	v_add_co_u32_e32 v60, vcc, s27, v56
	global_load_dwordx4 v[48:51], v[48:49], off nt
	s_nop 0
	global_load_dwordx4 v[52:55], v[52:53], off nt
	v_addc_co_u32_e32 v61, vcc, 0, v57, vcc
	global_load_dwordx4 v[56:59], v[58:59], off nt
	s_nop 0
	global_load_dwordx4 v[60:63], v[60:61], off nt
	s_ashr_i32 s23, s22, 31
	s_lshl_b64 s[20:21], s[22:23], 1
	v_or_b32_e32 v65, s26, v64
	s_add_u32 s20, s11, s20
	s_addc_u32 s21, s12, s21
	v_mul_i32_i24_e32 v74, 0x1500, v65
	v_lshl_add_u64 v[72:73], v[66:67], 1, s[20:21]
	v_ashrrev_i32_e32 v75, 31, v74
	v_lshl_add_u64 v[72:73], v[74:75], 1, v[72:73]
	s_mov_b32 s11, 0x15100000
	v_add_co_u32_e32 v76, vcc, s11, v72
	s_mov_b32 s11, 0x15102000
	s_nop 0
	v_addc_co_u32_e32 v77, vcc, 0, v73, vcc
	s_waitcnt vmcnt(14)
	v_cvt_pk_bf16_f32 v68, v0, v4
	v_add_co_u32_e32 v4, vcc, s11, v72
	s_waitcnt vmcnt(12)
	v_cvt_pk_bf16_f32 v69, v8, v12
	s_waitcnt vmcnt(10)
	v_cvt_pk_bf16_f32 v70, v16, v20
	s_waitcnt vmcnt(8)
	v_cvt_pk_bf16_f32 v71, v24, v28
	global_store_dwordx4 v[76:77], v[68:71], off nt
	s_mov_b32 s11, 0x15105000
	s_mov_b64 s[20:21], 0x15100000
	v_cvt_pk_bf16_f32 v68, v1, v5
	v_addc_co_u32_e32 v5, vcc, 0, v73, vcc
	v_add_co_u32_e32 v8, vcc, s11, v72
	v_cvt_pk_bf16_f32 v69, v9, v13
	s_mov_b32 s11, 0x15107000
	s_nop 0
	v_addc_co_u32_e32 v9, vcc, 0, v73, vcc
	v_cvt_pk_bf16_f32 v70, v17, v21
	v_cvt_pk_bf16_f32 v71, v25, v29
	global_store_dwordx4 v[4:5], v[68:71], off offset:2560 nt
	v_lshl_add_u64 v[74:75], v[72:73], 0, s[20:21]
	s_nop 0
	v_cvt_pk_bf16_f32 v68, v2, v6
	v_add_co_u32_e32 v6, vcc, s11, v72
	v_cvt_pk_bf16_f32 v69, v10, v14
	v_cvt_pk_bf16_f32 v70, v18, v22
	v_cvt_pk_bf16_f32 v71, v26, v30
	global_store_dwordx4 v[8:9], v[68:71], off offset:1024 nt
	v_cvt_pk_bf16_f32 v0, v3, v7
	v_cvt_pk_bf16_f32 v1, v11, v15
	v_cvt_pk_bf16_f32 v2, v19, v23
	v_cvt_pk_bf16_f32 v3, v27, v31
	s_nop 0
	v_addc_co_u32_e32 v7, vcc, 0, v73, vcc
	global_store_dwordx4 v[6:7], v[0:3], off offset:3584 nt
	s_waitcnt vmcnt(10)
	s_nop 0
	v_cvt_pk_bf16_f32 v0, v32, v36
	s_waitcnt vmcnt(8)
	v_cvt_pk_bf16_f32 v1, v40, v44
	s_waitcnt vmcnt(6)
	v_cvt_pk_bf16_f32 v2, v48, v52
	s_waitcnt vmcnt(4)
	v_cvt_pk_bf16_f32 v3, v56, v60
	global_store_dwordx4 v[74:75], v[0:3], off offset:64 nt
	s_nop 1
	v_cvt_pk_bf16_f32 v0, v33, v37
	v_cvt_pk_bf16_f32 v1, v41, v45
	v_cvt_pk_bf16_f32 v2, v49, v53
	v_cvt_pk_bf16_f32 v3, v57, v61
	global_store_dwordx4 v[4:5], v[0:3], off offset:2624 nt
	s_nop 1
	v_cvt_pk_bf16_f32 v0, v34, v38
	v_cvt_pk_bf16_f32 v1, v42, v46
	v_cvt_pk_bf16_f32 v2, v50, v54
	v_cvt_pk_bf16_f32 v3, v58, v62
	global_store_dwordx4 v[8:9], v[0:3], off offset:1088 nt
	s_nop 1
	v_cvt_pk_bf16_f32 v0, v35, v39
	v_cvt_pk_bf16_f32 v1, v43, v47
	v_cvt_pk_bf16_f32 v2, v51, v55
	v_cvt_pk_bf16_f32 v3, v59, v63
	global_store_dwordx4 v[6:7], v[0:3], off offset:3648 nt
